# c_fl (panel 15) epilogue split over two waves on different SIMDs (rows 4..7 handed over through LDS)
# speedup vs baseline: 1.0116x; 1.0034x over previous
.LBB0_477:
	s_mov_b64 s[42:43], exec
	v_readfirstlane_b32 s101, v184
	s_nop 3
	s_lshr_b32 s101, s101, 6
	s_lshr_b32 s100, s101, 2
	s_and_b32 s101, s101, 3
	s_mov_b64 exec, 0xffff
	v_and_b32_e32 v255, 15, v227
	v_lshlrev_b32_e32 v255, 7, v255
	s_lshl_b32 s100, s100, 11
	s_add_i32 s100, s100, 0x20800
	s_nop 0
	v_add_u32_e32 v255, s100, v255
	s_cmp_lg_u32 s101, 0
	s_cbranch_scc1 .Lcfl_nowrite
	ds_write_b128 v255, v[0:3]
	ds_write_b128 v255, v[4:7] offset:16
	ds_write_b128 v255, v[8:11] offset:32
	ds_write_b128 v255, v[12:15] offset:48
	ds_write_b128 v255, v[16:19] offset:64
	ds_write_b128 v255, v[20:23] offset:80
	ds_write_b128 v255, v[24:27] offset:96
	ds_write_b128 v255, v[28:31] offset:112
.Lcfl_nowrite:
	s_waitcnt lgkmcnt(0)
	s_barrier
	s_cmp_gt_u32 s101, 1
	s_cbranch_scc1 .LBB0_479
	s_cmp_lg_u32 s101, 1
	s_cbranch_scc1 .Lcfl_common
	ds_read_b128 v[0:3], v255
	ds_read_b128 v[4:7], v255 offset:16
	ds_read_b128 v[8:11], v255 offset:32
	ds_read_b128 v[12:15], v255 offset:48
	ds_read_b128 v[16:19], v255 offset:64
	ds_read_b128 v[20:23], v255 offset:80
	ds_read_b128 v[24:27], v255 offset:96
	ds_read_b128 v[28:31], v255 offset:112
	s_waitcnt lgkmcnt(0)
.Lcfl_common:
	v_lshlrev_b32_e32 v255, 2, v227
	global_load_dword v254, v255, s[56:57]
	s_waitcnt vmcnt(0)
	v_and_b32_e32 v64, 0xfcf, v174
	v_lshlrev_b32_e32 v190, 2, v64
	v_readlane_b32 s100, v254, 0
	s_nop 1
	v_mov_b32_e32 v64, s100
	s_ashr_i32 s23, s23, 9
	s_and_b32 s30, s23, -8
	s_ashr_i32 s31, s30, 31
	v_lshl_add_u64 v[72:73], s[52:53], 0, v[190:191]
	s_lshl_b64 s[34:35], s[30:31], 14
	s_cmp_eq_u32 s101, 1
	s_cbranch_scc1 .Lcfl_half2
	v_fmac_f32_e32 v64, v60, v172
	v_mul_f32_e64 v65, |v64|, s94
	v_fma_f32 v66, |v64|, s94, -v65
	v_rndne_f32_e32 v67, v65
	v_fma_f32 v66, |v64|, s64, v66
	v_sub_f32_e32 v65, v65, v67
	v_add_f32_e32 v65, v65, v66
	v_exp_f32_e32 v65, v65
	v_cvt_i32_f32_e32 v66, v67
	v_cmp_ngt_f32_e64 vcc, |v64|, s58
	v_min_f32_e32 v60, 0, v64
	v_ldexp_f32 v65, v65, v66
	v_cndmask_b32_e32 v65, 0, v65, vcc
	v_cmp_nlt_f32_e64 vcc, |v64|, s59
	s_nop 1
	v_cndmask_b32_e32 v66, v226, v65, vcc
	v_add_f32_e32 v67, 1.0, v66
	v_add_f32_e32 v64, -1.0, v67
	v_sub_f32_e32 v65, v64, v67
	v_add_f32_e32 v65, 1.0, v65
	v_sub_f32_e32 v64, v66, v64
	v_add_f32_e32 v68, v64, v65
	v_frexp_mant_f32_e32 v64, v67
	v_cmp_gt_f32_e32 vcc, s77, v64
	v_cvt_f64_f32_e32 v[64:65], v67
	v_frexp_exp_i32_f64_e32 v64, v[64:65]
	v_subbrev_co_u32_e32 v64, vcc, 0, v64, vcc
	v_sub_u32_e32 v65, 0, v64
	v_ldexp_f32 v67, v67, v65
	v_ldexp_f32 v65, v68, v65
	v_add_f32_e32 v68, -1.0, v67
	v_add_f32_e32 v69, 1.0, v68
	v_sub_f32_e32 v69, v67, v69
	v_add_f32_e32 v69, v65, v69
	v_add_f32_e32 v70, v68, v69
	v_sub_f32_e32 v68, v68, v70
	v_add_f32_e32 v68, v69, v68
	v_add_f32_e32 v69, 1.0, v67
	v_add_f32_e32 v71, -1.0, v69
	v_sub_f32_e32 v67, v67, v71
	v_add_f32_e32 v65, v65, v67
	v_add_f32_e32 v67, v69, v65
	v_sub_f32_e32 v69, v69, v67
	v_add_f32_e32 v65, v65, v69
	v_rcp_f32_e32 v69, v67
	v_cvt_f32_i32_e32 v64, v64
	v_cmp_neq_f32_e32 vcc, s62, v66
	v_mul_f32_e32 v71, v70, v69
	v_mul_f32_e32 v74, v67, v71
	v_fma_f32 v75, v71, v67, -v74
	v_fmac_f32_e32 v75, v71, v65
	v_add_f32_e32 v76, v74, v75
	v_sub_f32_e32 v77, v70, v76
	v_sub_f32_e32 v70, v70, v77
	v_sub_f32_e32 v74, v76, v74
	v_sub_f32_e32 v70, v70, v76
	v_add_f32_e32 v68, v68, v70
	v_sub_f32_e32 v70, v74, v75
	v_add_f32_e32 v68, v70, v68
	v_add_f32_e32 v70, v77, v68
	v_mul_f32_e32 v74, v69, v70
	v_mul_f32_e32 v75, v67, v74
	v_fma_f32 v67, v74, v67, -v75
	v_fmac_f32_e32 v67, v74, v65
	v_sub_f32_e32 v65, v77, v70
	v_add_f32_e32 v65, v68, v65
	v_add_f32_e32 v68, v75, v67
	v_sub_f32_e32 v76, v70, v68
	v_sub_f32_e32 v70, v70, v76
	v_sub_f32_e32 v75, v68, v75
	v_sub_f32_e32 v68, v70, v68
	v_add_f32_e32 v65, v65, v68
	v_sub_f32_e32 v67, v75, v67
	v_add_f32_e32 v65, v67, v65
	v_add_f32_e32 v67, v71, v74
	v_add_f32_e32 v65, v76, v65
	v_sub_f32_e32 v68, v67, v71
	v_mul_f32_e32 v65, v69, v65
	v_sub_f32_e32 v68, v74, v68
	v_add_f32_e32 v65, v68, v65
	v_mul_f32_e32 v71, 0x3f317218, v64
	v_add_f32_e32 v68, v67, v65
	v_fma_f32 v74, v64, s78, -v71
	v_mul_f32_e32 v69, v68, v68
	v_fmac_f32_e32 v74, 0xb102e308, v64
	v_sub_f32_e32 v64, v68, v67
	v_fmamk_f32 v70, v69, 0x3e9b6dac, v185
	v_sub_f32_e32 v64, v65, v64
	v_add_f32_e32 v65, v71, v74
	v_fmaak_f32 v70, v69, v70, 0x3f2aaada
	v_sub_f32_e32 v67, v65, v71
	v_ldexp_f32 v71, v68, 1
	v_mul_f32_e32 v68, v68, v69
	v_mul_f32_e32 v68, v68, v70
	v_add_f32_e32 v69, v71, v68
	v_sub_f32_e32 v70, v69, v71
	v_ldexp_f32 v64, v64, 1
	v_sub_f32_e32 v68, v68, v70
	v_add_f32_e32 v64, v64, v68
	v_add_f32_e32 v68, v69, v64
	v_sub_f32_e32 v69, v68, v69
	v_sub_f32_e32 v64, v64, v69
	v_add_f32_e32 v69, v65, v68
	v_sub_f32_e32 v70, v69, v65
	v_sub_f32_e32 v71, v69, v70
	v_sub_f32_e32 v67, v74, v67
	v_sub_f32_e32 v65, v65, v71
	v_sub_f32_e32 v68, v68, v70
	v_add_f32_e32 v65, v68, v65
	v_add_f32_e32 v68, v67, v64
	v_sub_f32_e32 v70, v68, v67
	v_sub_f32_e32 v71, v68, v70
	v_sub_f32_e32 v67, v67, v71
	v_sub_f32_e32 v64, v64, v70
	v_add_f32_e32 v65, v68, v65
	v_add_f32_e32 v64, v64, v67
	v_add_f32_e32 v67, v69, v65
	v_sub_f32_e32 v68, v67, v69
	v_sub_f32_e32 v65, v65, v68
	v_add_f32_e32 v64, v64, v65
	v_add_f32_e32 v64, v67, v64
	v_cndmask_b32_e32 v64, v226, v64, vcc
	v_cmp_lt_f32_e64 vcc, |v66|, s63
	s_nop 1
	v_cndmask_b32_e32 v64, v64, v66, vcc
	v_sub_f32_e32 v60, v60, v64
	v_mul_f32_e32 v60, 0x3fb8aa3b, v60
	v_lshl_add_u64 v[64:65], v[72:73], 0, s[34:35]
	global_store_dword v[64:65], v60, off
	v_readlane_b32 s100, v254, 1
	s_nop 1
	v_mov_b32_e32 v60, s100
	s_or_b32 s34, s30, 1
	s_ashr_i32 s35, s34, 31
	s_lshl_b64 s[34:35], s[34:35], 14
	v_fmac_f32_e32 v60, v61, v172
	v_mul_f32_e64 v61, |v60|, s94
	v_fma_f32 v67, |v60|, s94, -v61
	v_rndne_f32_e32 v68, v61
	v_fma_f32 v67, |v60|, s64, v67
	v_sub_f32_e32 v61, v61, v68
	v_add_f32_e32 v61, v61, v67
	v_exp_f32_e32 v61, v61
	v_cvt_i32_f32_e32 v67, v68
	v_cmp_ngt_f32_e64 vcc, |v60|, s58
	v_min_f32_e32 v66, 0, v60
	v_ldexp_f32 v61, v61, v67
	v_cndmask_b32_e32 v61, 0, v61, vcc
	v_cmp_nlt_f32_e64 vcc, |v60|, s59
	s_nop 1
	v_cndmask_b32_e32 v67, v226, v61, vcc
	v_add_f32_e32 v68, 1.0, v67
	v_add_f32_e32 v60, -1.0, v68
	v_sub_f32_e32 v61, v60, v68
	v_add_f32_e32 v61, 1.0, v61
	v_sub_f32_e32 v60, v67, v60
	v_add_f32_e32 v69, v60, v61
	v_frexp_mant_f32_e32 v60, v68
	v_cmp_gt_f32_e32 vcc, s77, v60
	v_cvt_f64_f32_e32 v[60:61], v68
	v_frexp_exp_i32_f64_e32 v60, v[60:61]
	v_subbrev_co_u32_e32 v60, vcc, 0, v60, vcc
	v_sub_u32_e32 v61, 0, v60
	v_ldexp_f32 v68, v68, v61
	v_ldexp_f32 v61, v69, v61
	v_add_f32_e32 v69, -1.0, v68
	v_add_f32_e32 v70, 1.0, v69
	v_sub_f32_e32 v70, v68, v70
	v_add_f32_e32 v70, v61, v70
	v_add_f32_e32 v71, v69, v70
	v_sub_f32_e32 v69, v69, v71
	v_add_f32_e32 v69, v70, v69
	v_add_f32_e32 v70, 1.0, v68
	v_add_f32_e32 v74, -1.0, v70
	v_sub_f32_e32 v68, v68, v74
	v_add_f32_e32 v61, v61, v68
	v_add_f32_e32 v68, v70, v61
	v_sub_f32_e32 v70, v70, v68
	v_add_f32_e32 v61, v61, v70
	v_rcp_f32_e32 v70, v68
	v_cvt_f32_i32_e32 v60, v60
	v_cmp_neq_f32_e32 vcc, s62, v67
	v_mul_f32_e32 v74, v71, v70
	v_mul_f32_e32 v75, v68, v74
	v_fma_f32 v76, v74, v68, -v75
	v_fmac_f32_e32 v76, v74, v61
	v_add_f32_e32 v77, v75, v76
	v_sub_f32_e32 v78, v71, v77
	v_sub_f32_e32 v71, v71, v78
	v_sub_f32_e32 v75, v77, v75
	v_sub_f32_e32 v71, v71, v77
	v_add_f32_e32 v69, v69, v71
	v_sub_f32_e32 v71, v75, v76
	v_add_f32_e32 v69, v71, v69
	v_add_f32_e32 v71, v78, v69
	v_mul_f32_e32 v75, v70, v71
	v_mul_f32_e32 v76, v68, v75
	v_fma_f32 v68, v75, v68, -v76
	v_fmac_f32_e32 v68, v75, v61
	v_sub_f32_e32 v61, v78, v71
	v_add_f32_e32 v61, v69, v61
	v_add_f32_e32 v69, v76, v68
	v_sub_f32_e32 v77, v71, v69
	v_sub_f32_e32 v71, v71, v77
	v_sub_f32_e32 v76, v69, v76
	v_sub_f32_e32 v69, v71, v69
	v_add_f32_e32 v61, v61, v69
	v_sub_f32_e32 v68, v76, v68
	v_add_f32_e32 v61, v68, v61
	v_add_f32_e32 v68, v74, v75
	v_add_f32_e32 v61, v77, v61
	v_sub_f32_e32 v69, v68, v74
	v_mul_f32_e32 v61, v70, v61
	v_sub_f32_e32 v69, v75, v69
	v_add_f32_e32 v61, v69, v61
	v_mul_f32_e32 v74, 0x3f317218, v60
	v_add_f32_e32 v69, v68, v61
	v_fma_f32 v75, v60, s78, -v74
	v_mul_f32_e32 v70, v69, v69
	v_fmac_f32_e32 v75, 0xb102e308, v60
	v_sub_f32_e32 v60, v69, v68
	v_fmamk_f32 v71, v70, 0x3e9b6dac, v185
	v_sub_f32_e32 v60, v61, v60
	v_add_f32_e32 v61, v74, v75
	v_fmaak_f32 v71, v70, v71, 0x3f2aaada
	v_sub_f32_e32 v68, v61, v74
	v_ldexp_f32 v74, v69, 1
	v_mul_f32_e32 v69, v69, v70
	v_mul_f32_e32 v69, v69, v71
	v_add_f32_e32 v70, v74, v69
	v_sub_f32_e32 v71, v70, v74
	v_ldexp_f32 v60, v60, 1
	v_sub_f32_e32 v69, v69, v71
	v_add_f32_e32 v60, v60, v69
	v_add_f32_e32 v69, v70, v60
	v_sub_f32_e32 v70, v69, v70
	v_sub_f32_e32 v60, v60, v70
	v_add_f32_e32 v70, v61, v69
	v_sub_f32_e32 v71, v70, v61
	v_sub_f32_e32 v74, v70, v71
	v_sub_f32_e32 v68, v75, v68
	v_sub_f32_e32 v61, v61, v74
	v_sub_f32_e32 v69, v69, v71
	v_add_f32_e32 v61, v69, v61
	v_add_f32_e32 v69, v68, v60
	v_sub_f32_e32 v71, v69, v68
	v_sub_f32_e32 v74, v69, v71
	v_sub_f32_e32 v68, v68, v74
	v_sub_f32_e32 v60, v60, v71
	v_add_f32_e32 v61, v69, v61
	v_add_f32_e32 v60, v60, v68
	v_add_f32_e32 v68, v70, v61
	v_sub_f32_e32 v69, v68, v70
	v_sub_f32_e32 v61, v61, v69
	v_add_f32_e32 v60, v60, v61
	v_add_f32_e32 v60, v68, v60
	v_cndmask_b32_e32 v60, v226, v60, vcc
	v_cmp_lt_f32_e64 vcc, |v67|, s63
	s_nop 1
	v_cndmask_b32_e32 v60, v60, v67, vcc
	v_sub_f32_e32 v60, v66, v60
	v_mul_f32_e32 v66, 0x3fb8aa3b, v60
	v_lshl_add_u64 v[60:61], v[72:73], 0, s[34:35]
	global_store_dword v[60:61], v66, off
	v_readlane_b32 s100, v254, 2
	s_nop 1
	v_mov_b32_e32 v66, s100
	s_or_b32 s34, s30, 2
	s_ashr_i32 s35, s34, 31
	s_lshl_b64 s[34:35], s[34:35], 14
	v_fmac_f32_e32 v66, v62, v172
	v_mul_f32_e64 v67, |v66|, s94
	v_fma_f32 v68, |v66|, s94, -v67
	v_rndne_f32_e32 v69, v67
	v_fma_f32 v68, |v66|, s64, v68
	v_sub_f32_e32 v67, v67, v69
	v_add_f32_e32 v67, v67, v68
	v_exp_f32_e32 v67, v67
	v_cvt_i32_f32_e32 v68, v69
	v_cmp_ngt_f32_e64 vcc, |v66|, s58
	v_min_f32_e32 v62, 0, v66
	v_ldexp_f32 v67, v67, v68
	v_cndmask_b32_e32 v67, 0, v67, vcc
	v_cmp_nlt_f32_e64 vcc, |v66|, s59
	s_nop 1
	v_cndmask_b32_e32 v68, v226, v67, vcc
	v_add_f32_e32 v69, 1.0, v68
	v_add_f32_e32 v66, -1.0, v69
	v_sub_f32_e32 v67, v66, v69
	v_add_f32_e32 v67, 1.0, v67
	v_sub_f32_e32 v66, v68, v66
	v_add_f32_e32 v70, v66, v67
	v_frexp_mant_f32_e32 v66, v69
	v_cmp_gt_f32_e32 vcc, s77, v66
	v_cvt_f64_f32_e32 v[66:67], v69
	v_frexp_exp_i32_f64_e32 v66, v[66:67]
	v_subbrev_co_u32_e32 v66, vcc, 0, v66, vcc
	v_sub_u32_e32 v67, 0, v66
	v_ldexp_f32 v69, v69, v67
	v_ldexp_f32 v67, v70, v67
	v_add_f32_e32 v70, -1.0, v69
	v_add_f32_e32 v71, 1.0, v70
	v_sub_f32_e32 v71, v69, v71
	v_add_f32_e32 v71, v67, v71
	v_add_f32_e32 v74, v70, v71
	v_sub_f32_e32 v70, v70, v74
	v_add_f32_e32 v70, v71, v70
	v_add_f32_e32 v71, 1.0, v69
	v_add_f32_e32 v75, -1.0, v71
	v_sub_f32_e32 v69, v69, v75
	v_add_f32_e32 v67, v67, v69
	v_add_f32_e32 v69, v71, v67
	v_sub_f32_e32 v71, v71, v69
	v_add_f32_e32 v67, v67, v71
	v_rcp_f32_e32 v71, v69
	v_cvt_f32_i32_e32 v66, v66
	v_cmp_neq_f32_e32 vcc, s62, v68
	v_mul_f32_e32 v75, v74, v71
	v_mul_f32_e32 v76, v69, v75
	v_fma_f32 v77, v75, v69, -v76
	v_fmac_f32_e32 v77, v75, v67
	v_add_f32_e32 v78, v76, v77
	v_sub_f32_e32 v79, v74, v78
	v_sub_f32_e32 v74, v74, v79
	v_sub_f32_e32 v76, v78, v76
	v_sub_f32_e32 v74, v74, v78
	v_add_f32_e32 v70, v70, v74
	v_sub_f32_e32 v74, v76, v77
	v_add_f32_e32 v70, v74, v70
	v_add_f32_e32 v74, v79, v70
	v_mul_f32_e32 v76, v71, v74
	v_mul_f32_e32 v77, v69, v76
	v_fma_f32 v69, v76, v69, -v77
	v_fmac_f32_e32 v69, v76, v67
	v_sub_f32_e32 v67, v79, v74
	v_add_f32_e32 v67, v70, v67
	v_add_f32_e32 v70, v77, v69
	v_sub_f32_e32 v78, v74, v70
	v_sub_f32_e32 v74, v74, v78
	v_sub_f32_e32 v77, v70, v77
	v_sub_f32_e32 v70, v74, v70
	v_add_f32_e32 v67, v67, v70
	v_sub_f32_e32 v69, v77, v69
	v_add_f32_e32 v67, v69, v67
	v_add_f32_e32 v69, v75, v76
	v_add_f32_e32 v67, v78, v67
	v_sub_f32_e32 v70, v69, v75
	v_mul_f32_e32 v67, v71, v67
	v_sub_f32_e32 v70, v76, v70
	v_add_f32_e32 v67, v70, v67
	v_mul_f32_e32 v75, 0x3f317218, v66
	v_add_f32_e32 v70, v69, v67
	v_fma_f32 v76, v66, s78, -v75
	v_mul_f32_e32 v71, v70, v70
	v_fmac_f32_e32 v76, 0xb102e308, v66
	v_sub_f32_e32 v66, v70, v69
	v_fmamk_f32 v74, v71, 0x3e9b6dac, v185
	v_sub_f32_e32 v66, v67, v66
	v_add_f32_e32 v67, v75, v76
	v_fmaak_f32 v74, v71, v74, 0x3f2aaada
	v_sub_f32_e32 v69, v67, v75
	v_ldexp_f32 v75, v70, 1
	v_mul_f32_e32 v70, v70, v71
	v_mul_f32_e32 v70, v70, v74
	v_add_f32_e32 v71, v75, v70
	v_sub_f32_e32 v74, v71, v75
	v_ldexp_f32 v66, v66, 1
	v_sub_f32_e32 v70, v70, v74
	v_add_f32_e32 v66, v66, v70
	v_add_f32_e32 v70, v71, v66
	v_sub_f32_e32 v71, v70, v71
	v_sub_f32_e32 v66, v66, v71
	v_add_f32_e32 v71, v67, v70
	v_sub_f32_e32 v74, v71, v67
	v_sub_f32_e32 v75, v71, v74
	v_sub_f32_e32 v69, v76, v69
	v_sub_f32_e32 v67, v67, v75
	v_sub_f32_e32 v70, v70, v74
	v_add_f32_e32 v67, v70, v67
	v_add_f32_e32 v70, v69, v66
	v_sub_f32_e32 v74, v70, v69
	v_sub_f32_e32 v75, v70, v74
	v_sub_f32_e32 v69, v69, v75
	v_sub_f32_e32 v66, v66, v74
	v_add_f32_e32 v67, v70, v67
	v_add_f32_e32 v66, v66, v69
	v_add_f32_e32 v69, v71, v67
	v_sub_f32_e32 v70, v69, v71
	v_sub_f32_e32 v67, v67, v70
	v_add_f32_e32 v66, v66, v67
	v_add_f32_e32 v66, v69, v66
	v_cndmask_b32_e32 v66, v226, v66, vcc
	v_cmp_lt_f32_e64 vcc, |v68|, s63
	s_nop 1
	v_cndmask_b32_e32 v66, v66, v68, vcc
	v_sub_f32_e32 v62, v62, v66
	v_mul_f32_e32 v62, 0x3fb8aa3b, v62
	v_lshl_add_u64 v[66:67], v[72:73], 0, s[34:35]
	global_store_dword v[66:67], v62, off
	v_readlane_b32 s100, v254, 3
	s_nop 1
	v_mov_b32_e32 v62, s100
	s_or_b32 s34, s30, 3
	s_ashr_i32 s35, s34, 31
	s_lshl_b64 s[34:35], s[34:35], 14
	v_fmac_f32_e32 v62, v63, v172
	v_mul_f32_e64 v63, |v62|, s94
	v_fma_f32 v69, |v62|, s94, -v63
	v_rndne_f32_e32 v70, v63
	v_fma_f32 v69, |v62|, s64, v69
	v_sub_f32_e32 v63, v63, v70
	v_add_f32_e32 v63, v63, v69
	v_exp_f32_e32 v63, v63
	v_cvt_i32_f32_e32 v69, v70
	v_cmp_ngt_f32_e64 vcc, |v62|, s58
	v_min_f32_e32 v68, 0, v62
	v_ldexp_f32 v63, v63, v69
	v_cndmask_b32_e32 v63, 0, v63, vcc
	v_cmp_nlt_f32_e64 vcc, |v62|, s59
	s_nop 1
	v_cndmask_b32_e32 v69, v226, v63, vcc
	v_add_f32_e32 v70, 1.0, v69
	v_add_f32_e32 v62, -1.0, v70
	v_sub_f32_e32 v63, v62, v70
	v_add_f32_e32 v63, 1.0, v63
	v_sub_f32_e32 v62, v69, v62
	v_add_f32_e32 v71, v62, v63
	v_frexp_mant_f32_e32 v62, v70
	v_cmp_gt_f32_e32 vcc, s77, v62
	v_cvt_f64_f32_e32 v[62:63], v70
	v_frexp_exp_i32_f64_e32 v62, v[62:63]
	v_subbrev_co_u32_e32 v62, vcc, 0, v62, vcc
	v_sub_u32_e32 v63, 0, v62
	v_ldexp_f32 v70, v70, v63
	v_ldexp_f32 v63, v71, v63
	v_add_f32_e32 v71, -1.0, v70
	v_add_f32_e32 v74, 1.0, v71
	v_sub_f32_e32 v74, v70, v74
	v_add_f32_e32 v74, v63, v74
	v_add_f32_e32 v75, v71, v74
	v_sub_f32_e32 v71, v71, v75
	v_add_f32_e32 v71, v74, v71
	v_add_f32_e32 v74, 1.0, v70
	v_add_f32_e32 v76, -1.0, v74
	v_sub_f32_e32 v70, v70, v76
	v_add_f32_e32 v63, v63, v70
	v_add_f32_e32 v70, v74, v63
	v_sub_f32_e32 v74, v74, v70
	v_add_f32_e32 v63, v63, v74
	v_rcp_f32_e32 v74, v70
	v_cvt_f32_i32_e32 v62, v62
	v_cmp_neq_f32_e32 vcc, s62, v69
	v_mul_f32_e32 v76, v75, v74
	v_mul_f32_e32 v77, v70, v76
	v_fma_f32 v78, v76, v70, -v77
	v_fmac_f32_e32 v78, v76, v63
	v_add_f32_e32 v79, v77, v78
	v_sub_f32_e32 v80, v75, v79
	v_sub_f32_e32 v75, v75, v80
	v_sub_f32_e32 v77, v79, v77
	v_sub_f32_e32 v75, v75, v79
	v_add_f32_e32 v71, v71, v75
	v_sub_f32_e32 v75, v77, v78
	v_add_f32_e32 v71, v75, v71
	v_add_f32_e32 v75, v80, v71
	v_mul_f32_e32 v77, v74, v75
	v_mul_f32_e32 v78, v70, v77
	v_fma_f32 v70, v77, v70, -v78
	v_fmac_f32_e32 v70, v77, v63
	v_sub_f32_e32 v63, v80, v75
	v_add_f32_e32 v63, v71, v63
	v_add_f32_e32 v71, v78, v70
	v_sub_f32_e32 v79, v75, v71
	v_sub_f32_e32 v75, v75, v79
	v_sub_f32_e32 v78, v71, v78
	v_sub_f32_e32 v71, v75, v71
	v_add_f32_e32 v63, v63, v71
	v_sub_f32_e32 v70, v78, v70
	v_add_f32_e32 v63, v70, v63
	v_add_f32_e32 v70, v76, v77
	v_add_f32_e32 v63, v79, v63
	v_sub_f32_e32 v71, v70, v76
	v_mul_f32_e32 v63, v74, v63
	v_sub_f32_e32 v71, v77, v71
	v_add_f32_e32 v63, v71, v63
	v_mul_f32_e32 v76, 0x3f317218, v62
	v_add_f32_e32 v71, v70, v63
	v_fma_f32 v77, v62, s78, -v76
	v_mul_f32_e32 v74, v71, v71
	v_fmac_f32_e32 v77, 0xb102e308, v62
	v_sub_f32_e32 v62, v71, v70
	v_fmamk_f32 v75, v74, 0x3e9b6dac, v185
	v_sub_f32_e32 v62, v63, v62
	v_add_f32_e32 v63, v76, v77
	v_fmaak_f32 v75, v74, v75, 0x3f2aaada
	v_sub_f32_e32 v70, v63, v76
	v_ldexp_f32 v76, v71, 1
	v_mul_f32_e32 v71, v71, v74
	v_mul_f32_e32 v71, v71, v75
	v_add_f32_e32 v74, v76, v71
	v_sub_f32_e32 v75, v74, v76
	v_ldexp_f32 v62, v62, 1
	v_sub_f32_e32 v71, v71, v75
	v_add_f32_e32 v62, v62, v71
	v_add_f32_e32 v71, v74, v62
	v_sub_f32_e32 v74, v71, v74
	v_sub_f32_e32 v62, v62, v74
	v_add_f32_e32 v74, v63, v71
	v_sub_f32_e32 v75, v74, v63
	v_sub_f32_e32 v76, v74, v75
	v_sub_f32_e32 v70, v77, v70
	v_sub_f32_e32 v63, v63, v76
	v_sub_f32_e32 v71, v71, v75
	v_add_f32_e32 v63, v71, v63
	v_add_f32_e32 v71, v70, v62
	v_sub_f32_e32 v75, v71, v70
	v_sub_f32_e32 v76, v71, v75
	v_sub_f32_e32 v70, v70, v76
	v_sub_f32_e32 v62, v62, v75
	v_add_f32_e32 v63, v71, v63
	v_add_f32_e32 v62, v62, v70
	v_add_f32_e32 v70, v74, v63
	v_sub_f32_e32 v71, v70, v74
	v_sub_f32_e32 v63, v63, v71
	v_add_f32_e32 v62, v62, v63
	v_add_f32_e32 v62, v70, v62
	v_cndmask_b32_e32 v62, v226, v62, vcc
	v_cmp_lt_f32_e64 vcc, |v69|, s63
	s_nop 1
	v_cndmask_b32_e32 v62, v62, v69, vcc
	v_sub_f32_e32 v62, v68, v62
	v_mul_f32_e32 v68, 0x3fb8aa3b, v62
	v_lshl_add_u64 v[62:63], v[72:73], 0, s[34:35]
	global_store_dword v[62:63], v68, off
	v_readlane_b32 s100, v254, 4
	s_nop 1
	v_mov_b32_e32 v68, s100
	s_or_b32 s34, s30, 4
	s_ashr_i32 s35, s34, 31
	s_lshl_b64 s[34:35], s[34:35], 14
	v_fmac_f32_e32 v68, v56, v172
	v_mul_f32_e64 v69, |v68|, s94
	v_fma_f32 v70, |v68|, s94, -v69
	v_rndne_f32_e32 v71, v69
	v_fma_f32 v70, |v68|, s64, v70
	v_sub_f32_e32 v69, v69, v71
	v_add_f32_e32 v69, v69, v70
	v_exp_f32_e32 v69, v69
	v_cvt_i32_f32_e32 v70, v71
	v_cmp_ngt_f32_e64 vcc, |v68|, s58
	v_min_f32_e32 v56, 0, v68
	v_ldexp_f32 v69, v69, v70
	v_cndmask_b32_e32 v69, 0, v69, vcc
	v_cmp_nlt_f32_e64 vcc, |v68|, s59
	s_nop 1
	v_cndmask_b32_e32 v70, v226, v69, vcc
	v_add_f32_e32 v71, 1.0, v70
	v_add_f32_e32 v68, -1.0, v71
	v_sub_f32_e32 v69, v68, v71
	v_add_f32_e32 v69, 1.0, v69
	v_sub_f32_e32 v68, v70, v68
	v_add_f32_e32 v74, v68, v69
	v_frexp_mant_f32_e32 v68, v71
	v_cmp_gt_f32_e32 vcc, s77, v68
	v_cvt_f64_f32_e32 v[68:69], v71
	v_frexp_exp_i32_f64_e32 v68, v[68:69]
	v_subbrev_co_u32_e32 v68, vcc, 0, v68, vcc
	v_sub_u32_e32 v69, 0, v68
	v_ldexp_f32 v71, v71, v69
	v_ldexp_f32 v69, v74, v69
	v_add_f32_e32 v74, -1.0, v71
	v_add_f32_e32 v75, 1.0, v74
	v_sub_f32_e32 v75, v71, v75
	v_add_f32_e32 v75, v69, v75
	v_add_f32_e32 v76, v74, v75
	v_sub_f32_e32 v74, v74, v76
	v_add_f32_e32 v74, v75, v74
	v_add_f32_e32 v75, 1.0, v71
	v_add_f32_e32 v77, -1.0, v75
	v_sub_f32_e32 v71, v71, v77
	v_add_f32_e32 v69, v69, v71
	v_add_f32_e32 v71, v75, v69
	v_sub_f32_e32 v75, v75, v71
	v_add_f32_e32 v69, v69, v75
	v_rcp_f32_e32 v75, v71
	v_cvt_f32_i32_e32 v68, v68
	v_cmp_neq_f32_e32 vcc, s62, v70
	v_mul_f32_e32 v77, v76, v75
	v_mul_f32_e32 v78, v71, v77
	v_fma_f32 v79, v77, v71, -v78
	v_fmac_f32_e32 v79, v77, v69
	v_add_f32_e32 v80, v78, v79
	v_sub_f32_e32 v81, v76, v80
	v_sub_f32_e32 v76, v76, v81
	v_sub_f32_e32 v78, v80, v78
	v_sub_f32_e32 v76, v76, v80
	v_add_f32_e32 v74, v74, v76
	v_sub_f32_e32 v76, v78, v79
	v_add_f32_e32 v74, v76, v74
	v_add_f32_e32 v76, v81, v74
	v_mul_f32_e32 v78, v75, v76
	v_mul_f32_e32 v79, v71, v78
	v_fma_f32 v71, v78, v71, -v79
	v_fmac_f32_e32 v71, v78, v69
	v_sub_f32_e32 v69, v81, v76
	v_add_f32_e32 v69, v74, v69
	v_add_f32_e32 v74, v79, v71
	v_sub_f32_e32 v80, v76, v74
	v_sub_f32_e32 v76, v76, v80
	v_sub_f32_e32 v79, v74, v79
	v_sub_f32_e32 v74, v76, v74
	v_add_f32_e32 v69, v69, v74
	v_sub_f32_e32 v71, v79, v71
	v_add_f32_e32 v69, v71, v69
	v_add_f32_e32 v71, v77, v78
	v_add_f32_e32 v69, v80, v69
	v_sub_f32_e32 v74, v71, v77
	v_mul_f32_e32 v69, v75, v69
	v_sub_f32_e32 v74, v78, v74
	v_add_f32_e32 v69, v74, v69
	v_mul_f32_e32 v77, 0x3f317218, v68
	v_add_f32_e32 v74, v71, v69
	v_fma_f32 v78, v68, s78, -v77
	v_mul_f32_e32 v75, v74, v74
	v_fmac_f32_e32 v78, 0xb102e308, v68
	v_sub_f32_e32 v68, v74, v71
	v_fmamk_f32 v76, v75, 0x3e9b6dac, v185
	v_sub_f32_e32 v68, v69, v68
	v_add_f32_e32 v69, v77, v78
	v_fmaak_f32 v76, v75, v76, 0x3f2aaada
	v_sub_f32_e32 v71, v69, v77
	v_ldexp_f32 v77, v74, 1
	v_mul_f32_e32 v74, v74, v75
	v_mul_f32_e32 v74, v74, v76
	v_add_f32_e32 v75, v77, v74
	v_sub_f32_e32 v76, v75, v77
	v_ldexp_f32 v68, v68, 1
	v_sub_f32_e32 v74, v74, v76
	v_add_f32_e32 v68, v68, v74
	v_add_f32_e32 v74, v75, v68
	v_sub_f32_e32 v75, v74, v75
	v_sub_f32_e32 v68, v68, v75
	v_add_f32_e32 v75, v69, v74
	v_sub_f32_e32 v76, v75, v69
	v_sub_f32_e32 v77, v75, v76
	v_sub_f32_e32 v71, v78, v71
	v_sub_f32_e32 v69, v69, v77
	v_sub_f32_e32 v74, v74, v76
	v_add_f32_e32 v69, v74, v69
	v_add_f32_e32 v74, v71, v68
	v_sub_f32_e32 v76, v74, v71
	v_sub_f32_e32 v77, v74, v76
	v_sub_f32_e32 v71, v71, v77
	v_sub_f32_e32 v68, v68, v76
	v_add_f32_e32 v69, v74, v69
	v_add_f32_e32 v68, v68, v71
	v_add_f32_e32 v71, v75, v69
	v_sub_f32_e32 v74, v71, v75
	v_sub_f32_e32 v69, v69, v74
	v_add_f32_e32 v68, v68, v69
	v_add_f32_e32 v68, v71, v68
	v_cndmask_b32_e32 v68, v226, v68, vcc
	v_cmp_lt_f32_e64 vcc, |v70|, s63
	s_nop 1
	v_cndmask_b32_e32 v68, v68, v70, vcc
	v_sub_f32_e32 v56, v56, v68
	v_mul_f32_e32 v56, 0x3fb8aa3b, v56
	v_lshl_add_u64 v[68:69], v[72:73], 0, s[34:35]
	global_store_dword v[68:69], v56, off
	v_readlane_b32 s100, v254, 5
	s_nop 1
	v_mov_b32_e32 v56, s100
	s_or_b32 s34, s30, 5
	s_ashr_i32 s35, s34, 31
	s_lshl_b64 s[34:35], s[34:35], 14
	s_or_b32 s30, s30, 6
	s_ashr_i32 s31, s30, 31
	s_lshl_b64 s[30:31], s[30:31], 14
	v_fmac_f32_e32 v56, v57, v172
	v_mul_f32_e64 v57, |v56|, s94
	v_fma_f32 v71, |v56|, s94, -v57
	v_rndne_f32_e32 v74, v57
	v_fma_f32 v71, |v56|, s64, v71
	v_sub_f32_e32 v57, v57, v74
	v_add_f32_e32 v57, v57, v71
	v_exp_f32_e32 v57, v57
	v_cvt_i32_f32_e32 v71, v74
	v_cmp_ngt_f32_e64 vcc, |v56|, s58
	v_min_f32_e32 v70, 0, v56
	v_ldexp_f32 v57, v57, v71
	v_cndmask_b32_e32 v57, 0, v57, vcc
	v_cmp_nlt_f32_e64 vcc, |v56|, s59
	s_nop 1
	v_cndmask_b32_e32 v71, v226, v57, vcc
	v_add_f32_e32 v74, 1.0, v71
	v_add_f32_e32 v56, -1.0, v74
	v_sub_f32_e32 v57, v56, v74
	v_add_f32_e32 v57, 1.0, v57
	v_sub_f32_e32 v56, v71, v56
	v_add_f32_e32 v75, v56, v57
	v_frexp_mant_f32_e32 v56, v74
	v_cmp_gt_f32_e32 vcc, s77, v56
	v_cvt_f64_f32_e32 v[56:57], v74
	v_frexp_exp_i32_f64_e32 v56, v[56:57]
	v_subbrev_co_u32_e32 v56, vcc, 0, v56, vcc
	v_sub_u32_e32 v57, 0, v56
	v_ldexp_f32 v74, v74, v57
	v_ldexp_f32 v57, v75, v57
	v_add_f32_e32 v75, -1.0, v74
	v_add_f32_e32 v76, 1.0, v75
	v_sub_f32_e32 v76, v74, v76
	v_add_f32_e32 v76, v57, v76
	v_add_f32_e32 v77, v75, v76
	v_sub_f32_e32 v75, v75, v77
	v_add_f32_e32 v75, v76, v75
	v_add_f32_e32 v76, 1.0, v74
	v_add_f32_e32 v78, -1.0, v76
	v_sub_f32_e32 v74, v74, v78
	v_add_f32_e32 v57, v57, v74
	v_add_f32_e32 v74, v76, v57
	v_sub_f32_e32 v76, v76, v74
	v_add_f32_e32 v57, v57, v76
	v_rcp_f32_e32 v76, v74
	v_cvt_f32_i32_e32 v56, v56
	v_cmp_neq_f32_e32 vcc, s62, v71
	v_mul_f32_e32 v78, v77, v76
	v_mul_f32_e32 v79, v74, v78
	v_fma_f32 v80, v78, v74, -v79
	v_fmac_f32_e32 v80, v78, v57
	v_add_f32_e32 v81, v79, v80
	v_sub_f32_e32 v82, v77, v81
	v_sub_f32_e32 v77, v77, v82
	v_sub_f32_e32 v79, v81, v79
	v_sub_f32_e32 v77, v77, v81
	v_add_f32_e32 v75, v75, v77
	v_sub_f32_e32 v77, v79, v80
	v_add_f32_e32 v75, v77, v75
	v_add_f32_e32 v77, v82, v75
	v_mul_f32_e32 v79, v76, v77
	v_mul_f32_e32 v80, v74, v79
	v_fma_f32 v74, v79, v74, -v80
	v_fmac_f32_e32 v74, v79, v57
	v_sub_f32_e32 v57, v82, v77
	v_add_f32_e32 v57, v75, v57
	v_add_f32_e32 v75, v80, v74
	v_sub_f32_e32 v81, v77, v75
	v_sub_f32_e32 v77, v77, v81
	v_sub_f32_e32 v80, v75, v80
	v_sub_f32_e32 v75, v77, v75
	v_add_f32_e32 v57, v57, v75
	v_sub_f32_e32 v74, v80, v74
	v_add_f32_e32 v57, v74, v57
	v_add_f32_e32 v74, v78, v79
	v_add_f32_e32 v57, v81, v57
	v_sub_f32_e32 v75, v74, v78
	v_mul_f32_e32 v57, v76, v57
	v_sub_f32_e32 v75, v79, v75
	v_add_f32_e32 v57, v75, v57
	v_mul_f32_e32 v78, 0x3f317218, v56
	v_add_f32_e32 v75, v74, v57
	v_fma_f32 v79, v56, s78, -v78
	v_mul_f32_e32 v76, v75, v75
	v_fmac_f32_e32 v79, 0xb102e308, v56
	v_sub_f32_e32 v56, v75, v74
	v_fmamk_f32 v77, v76, 0x3e9b6dac, v185
	v_sub_f32_e32 v56, v57, v56
	v_add_f32_e32 v57, v78, v79
	v_fmaak_f32 v77, v76, v77, 0x3f2aaada
	v_sub_f32_e32 v74, v57, v78
	v_ldexp_f32 v78, v75, 1
	v_mul_f32_e32 v75, v75, v76
	v_mul_f32_e32 v75, v75, v77
	v_add_f32_e32 v76, v78, v75
	v_sub_f32_e32 v77, v76, v78
	v_ldexp_f32 v56, v56, 1
	v_sub_f32_e32 v75, v75, v77
	v_add_f32_e32 v56, v56, v75
	v_add_f32_e32 v75, v76, v56
	v_sub_f32_e32 v76, v75, v76
	v_sub_f32_e32 v56, v56, v76
	v_add_f32_e32 v76, v57, v75
	v_sub_f32_e32 v77, v76, v57
	v_sub_f32_e32 v78, v76, v77
	v_sub_f32_e32 v74, v79, v74
	v_sub_f32_e32 v57, v57, v78
	v_sub_f32_e32 v75, v75, v77
	v_add_f32_e32 v57, v75, v57
	v_add_f32_e32 v75, v74, v56
	v_sub_f32_e32 v77, v75, v74
	v_sub_f32_e32 v78, v75, v77
	v_sub_f32_e32 v74, v74, v78
	v_sub_f32_e32 v56, v56, v77
	v_add_f32_e32 v57, v75, v57
	v_add_f32_e32 v56, v56, v74
	v_add_f32_e32 v74, v76, v57
	v_sub_f32_e32 v75, v74, v76
	v_sub_f32_e32 v57, v57, v75
	v_add_f32_e32 v56, v56, v57
	v_add_f32_e32 v56, v74, v56
	v_cndmask_b32_e32 v56, v226, v56, vcc
	v_cmp_lt_f32_e64 vcc, |v71|, s63
	s_nop 1
	v_cndmask_b32_e32 v56, v56, v71, vcc
	v_sub_f32_e32 v56, v70, v56
	v_mul_f32_e32 v70, 0x3fb8aa3b, v56
	v_lshl_add_u64 v[56:57], v[72:73], 0, s[34:35]
	global_store_dword v[56:57], v70, off
	v_readlane_b32 s100, v254, 6
	s_nop 1
	v_mov_b32_e32 v70, s100
	v_fmac_f32_e32 v70, v58, v172
	v_mul_f32_e64 v71, |v70|, s94
	v_fma_f32 v74, |v70|, s94, -v71
	v_rndne_f32_e32 v75, v71
	v_fma_f32 v74, |v70|, s64, v74
	v_sub_f32_e32 v71, v71, v75
	v_add_f32_e32 v71, v71, v74
	v_exp_f32_e32 v71, v71
	v_cvt_i32_f32_e32 v74, v75
	v_cmp_ngt_f32_e64 vcc, |v70|, s58
	v_min_f32_e32 v58, 0, v70
	v_ldexp_f32 v71, v71, v74
	v_cndmask_b32_e32 v71, 0, v71, vcc
	v_cmp_nlt_f32_e64 vcc, |v70|, s59
	s_nop 1
	v_cndmask_b32_e32 v74, v226, v71, vcc
	v_add_f32_e32 v75, 1.0, v74
	v_add_f32_e32 v70, -1.0, v75
	v_sub_f32_e32 v71, v70, v75
	v_add_f32_e32 v71, 1.0, v71
	v_sub_f32_e32 v70, v74, v70
	v_add_f32_e32 v76, v70, v71
	v_frexp_mant_f32_e32 v70, v75
	v_cmp_gt_f32_e32 vcc, s77, v70
	v_cvt_f64_f32_e32 v[70:71], v75
	v_frexp_exp_i32_f64_e32 v70, v[70:71]
	v_subbrev_co_u32_e32 v70, vcc, 0, v70, vcc
	v_sub_u32_e32 v71, 0, v70
	v_ldexp_f32 v75, v75, v71
	v_ldexp_f32 v71, v76, v71
	v_add_f32_e32 v76, -1.0, v75
	v_add_f32_e32 v77, 1.0, v76
	v_sub_f32_e32 v77, v75, v77
	v_add_f32_e32 v77, v71, v77
	v_add_f32_e32 v78, v76, v77
	v_sub_f32_e32 v76, v76, v78
	v_add_f32_e32 v76, v77, v76
	v_add_f32_e32 v77, 1.0, v75
	v_add_f32_e32 v79, -1.0, v77
	v_sub_f32_e32 v75, v75, v79
	v_add_f32_e32 v71, v71, v75
	v_add_f32_e32 v75, v77, v71
	v_sub_f32_e32 v77, v77, v75
	v_add_f32_e32 v71, v71, v77
	v_rcp_f32_e32 v77, v75
	v_cvt_f32_i32_e32 v70, v70
	v_cmp_neq_f32_e32 vcc, s62, v74
	v_mul_f32_e32 v79, v78, v77
	v_mul_f32_e32 v80, v75, v79
	v_fma_f32 v81, v79, v75, -v80
	v_fmac_f32_e32 v81, v79, v71
	v_add_f32_e32 v82, v80, v81
	v_sub_f32_e32 v83, v78, v82
	v_sub_f32_e32 v78, v78, v83
	v_sub_f32_e32 v80, v82, v80
	v_sub_f32_e32 v78, v78, v82
	v_add_f32_e32 v76, v76, v78
	v_sub_f32_e32 v78, v80, v81
	v_add_f32_e32 v76, v78, v76
	v_add_f32_e32 v78, v83, v76
	v_mul_f32_e32 v80, v77, v78
	v_mul_f32_e32 v81, v75, v80
	v_fma_f32 v75, v80, v75, -v81
	v_fmac_f32_e32 v75, v80, v71
	v_sub_f32_e32 v71, v83, v78
	v_add_f32_e32 v71, v76, v71
	v_add_f32_e32 v76, v81, v75
	v_sub_f32_e32 v82, v78, v76
	v_sub_f32_e32 v78, v78, v82
	v_sub_f32_e32 v81, v76, v81
	v_sub_f32_e32 v76, v78, v76
	v_add_f32_e32 v71, v71, v76
	v_sub_f32_e32 v75, v81, v75
	v_add_f32_e32 v71, v75, v71
	v_add_f32_e32 v75, v79, v80
	v_add_f32_e32 v71, v82, v71
	v_sub_f32_e32 v76, v75, v79
	v_mul_f32_e32 v71, v77, v71
	v_sub_f32_e32 v76, v80, v76
	v_add_f32_e32 v71, v76, v71
	v_mul_f32_e32 v79, 0x3f317218, v70
	v_add_f32_e32 v76, v75, v71
	v_fma_f32 v80, v70, s78, -v79
	v_mul_f32_e32 v77, v76, v76
	v_fmac_f32_e32 v80, 0xb102e308, v70
	v_sub_f32_e32 v70, v76, v75
	v_fmamk_f32 v78, v77, 0x3e9b6dac, v185
	v_sub_f32_e32 v70, v71, v70
	v_add_f32_e32 v71, v79, v80
	v_fmaak_f32 v78, v77, v78, 0x3f2aaada
	v_sub_f32_e32 v75, v71, v79
	v_ldexp_f32 v79, v76, 1
	v_mul_f32_e32 v76, v76, v77
	v_mul_f32_e32 v76, v76, v78
	v_add_f32_e32 v77, v79, v76
	v_sub_f32_e32 v78, v77, v79
	v_ldexp_f32 v70, v70, 1
	v_sub_f32_e32 v76, v76, v78
	v_add_f32_e32 v70, v70, v76
	v_add_f32_e32 v76, v77, v70
	v_sub_f32_e32 v77, v76, v77
	v_sub_f32_e32 v70, v70, v77
	v_add_f32_e32 v77, v71, v76
	v_sub_f32_e32 v78, v77, v71
	v_sub_f32_e32 v79, v77, v78
	v_sub_f32_e32 v75, v80, v75
	v_sub_f32_e32 v71, v71, v79
	v_sub_f32_e32 v76, v76, v78
	v_add_f32_e32 v71, v76, v71
	v_add_f32_e32 v76, v75, v70
	v_sub_f32_e32 v78, v76, v75
	v_sub_f32_e32 v79, v76, v78
	v_sub_f32_e32 v75, v75, v79
	v_sub_f32_e32 v70, v70, v78
	v_add_f32_e32 v71, v76, v71
	v_add_f32_e32 v70, v70, v75
	v_add_f32_e32 v75, v77, v71
	v_sub_f32_e32 v76, v75, v77
	v_sub_f32_e32 v71, v71, v76
	v_add_f32_e32 v70, v70, v71
	v_add_f32_e32 v70, v75, v70
	v_cndmask_b32_e32 v70, v226, v70, vcc
	v_cmp_lt_f32_e64 vcc, |v74|, s63
	s_nop 1
	v_cndmask_b32_e32 v70, v70, v74, vcc
	v_sub_f32_e32 v58, v58, v70
	v_mul_f32_e32 v58, 0x3fb8aa3b, v58
	v_lshl_add_u64 v[70:71], v[72:73], 0, s[30:31]
	global_store_dword v[70:71], v58, off
	v_readlane_b32 s100, v254, 7
	s_nop 1
	v_mov_b32_e32 v58, s100
	s_or_b32 s30, s23, 7
	s_ashr_i32 s31, s30, 31
	s_lshl_b64 s[30:31], s[30:31], 14
	v_fmac_f32_e32 v58, v59, v172
	v_mul_f32_e64 v59, |v58|, s94
	v_fma_f32 v75, |v58|, s94, -v59
	v_rndne_f32_e32 v76, v59
	v_fma_f32 v75, |v58|, s64, v75
	v_sub_f32_e32 v59, v59, v76
	v_add_f32_e32 v59, v59, v75
	v_exp_f32_e32 v59, v59
	v_cvt_i32_f32_e32 v75, v76
	v_cmp_ngt_f32_e64 vcc, |v58|, s58
	v_min_f32_e32 v74, 0, v58
	v_ldexp_f32 v59, v59, v75
	v_cndmask_b32_e32 v59, 0, v59, vcc
	v_cmp_nlt_f32_e64 vcc, |v58|, s59
	s_nop 1
	v_cndmask_b32_e32 v75, v226, v59, vcc
	v_add_f32_e32 v76, 1.0, v75
	v_add_f32_e32 v58, -1.0, v76
	v_sub_f32_e32 v59, v58, v76
	v_add_f32_e32 v59, 1.0, v59
	v_sub_f32_e32 v58, v75, v58
	v_add_f32_e32 v77, v58, v59
	v_frexp_mant_f32_e32 v58, v76
	v_cmp_gt_f32_e32 vcc, s77, v58
	v_cvt_f64_f32_e32 v[58:59], v76
	v_frexp_exp_i32_f64_e32 v58, v[58:59]
	v_subbrev_co_u32_e32 v58, vcc, 0, v58, vcc
	v_sub_u32_e32 v59, 0, v58
	v_ldexp_f32 v76, v76, v59
	v_ldexp_f32 v59, v77, v59
	v_add_f32_e32 v77, -1.0, v76
	v_add_f32_e32 v78, 1.0, v77
	v_sub_f32_e32 v78, v76, v78
	v_add_f32_e32 v78, v59, v78
	v_add_f32_e32 v79, v77, v78
	v_sub_f32_e32 v77, v77, v79
	v_add_f32_e32 v77, v78, v77
	v_add_f32_e32 v78, 1.0, v76
	v_add_f32_e32 v80, -1.0, v78
	v_sub_f32_e32 v76, v76, v80
	v_add_f32_e32 v59, v59, v76
	v_add_f32_e32 v76, v78, v59
	v_sub_f32_e32 v78, v78, v76
	v_add_f32_e32 v59, v59, v78
	v_rcp_f32_e32 v78, v76
	v_cvt_f32_i32_e32 v58, v58
	v_cmp_neq_f32_e32 vcc, s62, v75
	v_mul_f32_e32 v80, v79, v78
	v_mul_f32_e32 v81, v76, v80
	v_fma_f32 v82, v80, v76, -v81
	v_fmac_f32_e32 v82, v80, v59
	v_add_f32_e32 v83, v81, v82
	v_sub_f32_e32 v84, v79, v83
	v_sub_f32_e32 v79, v79, v84
	v_sub_f32_e32 v81, v83, v81
	v_sub_f32_e32 v79, v79, v83
	v_add_f32_e32 v77, v77, v79
	v_sub_f32_e32 v79, v81, v82
	v_add_f32_e32 v77, v79, v77
	v_add_f32_e32 v79, v84, v77
	v_mul_f32_e32 v81, v78, v79
	v_mul_f32_e32 v82, v76, v81
	v_fma_f32 v76, v81, v76, -v82
	v_fmac_f32_e32 v76, v81, v59
	v_sub_f32_e32 v59, v84, v79
	v_add_f32_e32 v59, v77, v59
	v_add_f32_e32 v77, v82, v76
	v_sub_f32_e32 v83, v79, v77
	v_sub_f32_e32 v79, v79, v83
	v_sub_f32_e32 v82, v77, v82
	v_sub_f32_e32 v77, v79, v77
	v_add_f32_e32 v59, v59, v77
	v_sub_f32_e32 v76, v82, v76
	v_add_f32_e32 v59, v76, v59
	v_add_f32_e32 v76, v80, v81
	v_add_f32_e32 v59, v83, v59
	v_sub_f32_e32 v77, v76, v80
	v_mul_f32_e32 v59, v78, v59
	v_sub_f32_e32 v77, v81, v77
	v_add_f32_e32 v59, v77, v59
	v_mul_f32_e32 v80, 0x3f317218, v58
	v_add_f32_e32 v77, v76, v59
	v_fma_f32 v81, v58, s78, -v80
	v_mul_f32_e32 v78, v77, v77
	v_fmac_f32_e32 v81, 0xb102e308, v58
	v_sub_f32_e32 v58, v77, v76
	v_fmamk_f32 v79, v78, 0x3e9b6dac, v185
	v_sub_f32_e32 v58, v59, v58
	v_add_f32_e32 v59, v80, v81
	v_fmaak_f32 v79, v78, v79, 0x3f2aaada
	v_sub_f32_e32 v76, v59, v80
	v_ldexp_f32 v80, v77, 1
	v_mul_f32_e32 v77, v77, v78
	v_mul_f32_e32 v77, v77, v79
	v_add_f32_e32 v78, v80, v77
	v_sub_f32_e32 v79, v78, v80
	v_ldexp_f32 v58, v58, 1
	v_sub_f32_e32 v77, v77, v79
	v_add_f32_e32 v58, v58, v77
	v_add_f32_e32 v77, v78, v58
	v_sub_f32_e32 v78, v77, v78
	v_sub_f32_e32 v58, v58, v78
	v_add_f32_e32 v78, v59, v77
	v_sub_f32_e32 v79, v78, v59
	v_sub_f32_e32 v80, v78, v79
	v_sub_f32_e32 v76, v81, v76
	v_sub_f32_e32 v59, v59, v80
	v_sub_f32_e32 v77, v77, v79
	v_add_f32_e32 v59, v77, v59
	v_add_f32_e32 v77, v76, v58
	v_sub_f32_e32 v79, v77, v76
	v_sub_f32_e32 v80, v77, v79
	v_sub_f32_e32 v76, v76, v80
	v_sub_f32_e32 v58, v58, v79
	v_add_f32_e32 v59, v77, v59
	v_add_f32_e32 v58, v58, v76
	v_add_f32_e32 v76, v78, v59
	v_sub_f32_e32 v77, v76, v78
	v_sub_f32_e32 v59, v59, v77
	v_add_f32_e32 v58, v58, v59
	v_add_f32_e32 v58, v76, v58
	v_cndmask_b32_e32 v58, v226, v58, vcc
	v_cmp_lt_f32_e64 vcc, |v75|, s63
	s_nop 1
	v_cndmask_b32_e32 v58, v58, v75, vcc
	v_sub_f32_e32 v58, v74, v58
	v_mul_f32_e32 v74, 0x3fb8aa3b, v58
	v_lshl_add_u64 v[58:59], v[72:73], 0, s[30:31]
	global_store_dword v[58:59], v74, off
	v_readlane_b32 s100, v254, 0
	s_nop 1
	v_mov_b32_e32 v72, s100
	v_fmac_f32_e32 v72, v52, v170
	v_mul_f32_e64 v73, |v72|, s94
	v_fma_f32 v74, |v72|, s94, -v73
	v_rndne_f32_e32 v75, v73
	v_fma_f32 v74, |v72|, s64, v74
	v_sub_f32_e32 v73, v73, v75
	v_add_f32_e32 v73, v73, v74
	v_exp_f32_e32 v73, v73
	v_cvt_i32_f32_e32 v74, v75
	v_cmp_ngt_f32_e64 vcc, |v72|, s58
	v_min_f32_e32 v52, 0, v72
	v_ldexp_f32 v73, v73, v74
	v_cndmask_b32_e32 v73, 0, v73, vcc
	v_cmp_nlt_f32_e64 vcc, |v72|, s59
	s_nop 1
	v_cndmask_b32_e32 v72, v226, v73, vcc
	v_add_f32_e32 v73, 1.0, v72
	v_add_f32_e32 v74, -1.0, v73
	v_sub_f32_e32 v75, v74, v73
	v_add_f32_e32 v75, 1.0, v75
	v_sub_f32_e32 v74, v72, v74
	v_add_f32_e32 v76, v74, v75
	v_frexp_mant_f32_e32 v74, v73
	v_cmp_gt_f32_e32 vcc, s77, v74
	v_cvt_f64_f32_e32 v[74:75], v73
	v_frexp_exp_i32_f64_e32 v74, v[74:75]
	v_subbrev_co_u32_e32 v74, vcc, 0, v74, vcc
	v_sub_u32_e32 v75, 0, v74
	v_ldexp_f32 v73, v73, v75
	v_ldexp_f32 v75, v76, v75
	v_add_f32_e32 v76, -1.0, v73
	v_add_f32_e32 v77, 1.0, v76
	v_sub_f32_e32 v77, v73, v77
	v_add_f32_e32 v77, v75, v77
	v_add_f32_e32 v78, v76, v77
	v_sub_f32_e32 v76, v76, v78
	v_add_f32_e32 v76, v77, v76
	v_add_f32_e32 v77, 1.0, v73
	v_add_f32_e32 v79, -1.0, v77
	v_sub_f32_e32 v73, v73, v79
	v_add_f32_e32 v73, v75, v73
	v_add_f32_e32 v75, v77, v73
	v_sub_f32_e32 v77, v77, v75
	v_add_f32_e32 v73, v73, v77
	v_rcp_f32_e32 v77, v75
	v_cvt_f32_i32_e32 v74, v74
	v_cmp_neq_f32_e32 vcc, s62, v72
	v_mul_f32_e32 v79, v78, v77
	v_mul_f32_e32 v80, v75, v79
	v_fma_f32 v81, v79, v75, -v80
	v_fmac_f32_e32 v81, v79, v73
	v_add_f32_e32 v82, v80, v81
	v_sub_f32_e32 v83, v78, v82
	v_sub_f32_e32 v78, v78, v83
	v_sub_f32_e32 v80, v82, v80
	v_sub_f32_e32 v78, v78, v82
	v_add_f32_e32 v76, v76, v78
	v_sub_f32_e32 v78, v80, v81
	v_add_f32_e32 v76, v78, v76
	v_add_f32_e32 v78, v83, v76
	v_mul_f32_e32 v80, v77, v78
	v_mul_f32_e32 v81, v75, v80
	v_fma_f32 v75, v80, v75, -v81
	v_fmac_f32_e32 v75, v80, v73
	v_sub_f32_e32 v73, v83, v78
	v_add_f32_e32 v73, v76, v73
	v_add_f32_e32 v76, v81, v75
	v_sub_f32_e32 v82, v78, v76
	v_sub_f32_e32 v78, v78, v82
	v_sub_f32_e32 v81, v76, v81
	v_sub_f32_e32 v76, v78, v76
	v_add_f32_e32 v73, v73, v76
	v_sub_f32_e32 v75, v81, v75
	v_add_f32_e32 v73, v75, v73
	v_add_f32_e32 v75, v79, v80
	v_add_f32_e32 v73, v82, v73
	v_sub_f32_e32 v76, v75, v79
	v_mul_f32_e32 v73, v77, v73
	v_sub_f32_e32 v76, v80, v76
	v_add_f32_e32 v73, v76, v73
	v_mul_f32_e32 v79, 0x3f317218, v74
	v_add_f32_e32 v76, v75, v73
	v_fma_f32 v80, v74, s78, -v79
	v_mul_f32_e32 v77, v76, v76
	v_fmac_f32_e32 v80, 0xb102e308, v74
	v_sub_f32_e32 v74, v76, v75
	v_fmamk_f32 v78, v77, 0x3e9b6dac, v185
	v_sub_f32_e32 v73, v73, v74
	v_add_f32_e32 v74, v79, v80
	v_fmaak_f32 v78, v77, v78, 0x3f2aaada
	v_sub_f32_e32 v75, v74, v79
	v_ldexp_f32 v79, v76, 1
	v_mul_f32_e32 v76, v76, v77
	v_mul_f32_e32 v76, v76, v78
	v_add_f32_e32 v77, v79, v76
	v_sub_f32_e32 v78, v77, v79
	v_ldexp_f32 v73, v73, 1
	v_sub_f32_e32 v76, v76, v78
	v_add_f32_e32 v73, v73, v76
	v_add_f32_e32 v76, v77, v73
	v_sub_f32_e32 v77, v76, v77
	v_sub_f32_e32 v73, v73, v77
	v_add_f32_e32 v77, v74, v76
	v_sub_f32_e32 v78, v77, v74
	v_sub_f32_e32 v79, v77, v78
	v_sub_f32_e32 v75, v80, v75
	v_sub_f32_e32 v74, v74, v79
	v_sub_f32_e32 v76, v76, v78
	v_add_f32_e32 v74, v76, v74
	v_add_f32_e32 v76, v75, v73
	v_sub_f32_e32 v78, v76, v75
	v_sub_f32_e32 v79, v76, v78
	v_sub_f32_e32 v75, v75, v79
	v_sub_f32_e32 v73, v73, v78
	v_add_f32_e32 v74, v76, v74
	v_add_f32_e32 v73, v73, v75
	v_add_f32_e32 v75, v77, v74
	v_sub_f32_e32 v76, v75, v77
	v_sub_f32_e32 v74, v74, v76
	v_add_f32_e32 v73, v73, v74
	v_add_f32_e32 v73, v75, v73
	v_cndmask_b32_e32 v73, v226, v73, vcc
	v_cmp_lt_f32_e64 vcc, |v72|, s63
	s_nop 1
	v_cndmask_b32_e32 v72, v73, v72, vcc
	v_sub_f32_e32 v52, v52, v72
	v_mul_f32_e32 v52, 0x3fb8aa3b, v52
	global_store_dword v[64:65], v52, off offset:64
	v_readlane_b32 s100, v254, 1
	s_nop 1
	v_mov_b32_e32 v72, s100
	v_fmac_f32_e32 v72, v53, v170
	v_mul_f32_e64 v53, |v72|, s94
	v_fma_f32 v73, |v72|, s94, -v53
	v_rndne_f32_e32 v74, v53
	v_fma_f32 v73, |v72|, s64, v73
	v_sub_f32_e32 v53, v53, v74
	v_add_f32_e32 v53, v53, v73
	v_exp_f32_e32 v53, v53
	v_cvt_i32_f32_e32 v73, v74
	v_cmp_ngt_f32_e64 vcc, |v72|, s58
	v_min_f32_e32 v52, 0, v72
	v_ldexp_f32 v53, v53, v73
	v_cndmask_b32_e32 v53, 0, v53, vcc
	v_cmp_nlt_f32_e64 vcc, |v72|, s59
	s_nop 1
	v_cndmask_b32_e32 v53, v226, v53, vcc
	v_add_f32_e32 v74, 1.0, v53
	v_add_f32_e32 v72, -1.0, v74
	v_sub_f32_e32 v73, v72, v74
	v_add_f32_e32 v73, 1.0, v73
	v_sub_f32_e32 v72, v53, v72
	v_add_f32_e32 v75, v72, v73
	v_frexp_mant_f32_e32 v72, v74
	v_cmp_gt_f32_e32 vcc, s77, v72
	v_cvt_f64_f32_e32 v[72:73], v74
	v_frexp_exp_i32_f64_e32 v72, v[72:73]
	v_subbrev_co_u32_e32 v72, vcc, 0, v72, vcc
	v_sub_u32_e32 v73, 0, v72
	v_ldexp_f32 v74, v74, v73
	v_ldexp_f32 v73, v75, v73
	v_add_f32_e32 v75, -1.0, v74
	v_add_f32_e32 v76, 1.0, v75
	v_sub_f32_e32 v76, v74, v76
	v_add_f32_e32 v76, v73, v76
	v_add_f32_e32 v77, v75, v76
	v_sub_f32_e32 v75, v75, v77
	v_add_f32_e32 v75, v76, v75
	v_add_f32_e32 v76, 1.0, v74
	v_add_f32_e32 v78, -1.0, v76
	v_sub_f32_e32 v74, v74, v78
	v_add_f32_e32 v73, v73, v74
	v_add_f32_e32 v74, v76, v73
	v_sub_f32_e32 v76, v76, v74
	v_add_f32_e32 v73, v73, v76
	v_rcp_f32_e32 v76, v74
	v_cvt_f32_i32_e32 v72, v72
	v_cmp_neq_f32_e32 vcc, s62, v53
	v_mul_f32_e32 v78, v77, v76
	v_mul_f32_e32 v79, v74, v78
	v_fma_f32 v80, v78, v74, -v79
	v_fmac_f32_e32 v80, v78, v73
	v_add_f32_e32 v81, v79, v80
	v_sub_f32_e32 v82, v77, v81
	v_sub_f32_e32 v77, v77, v82
	v_sub_f32_e32 v79, v81, v79
	v_sub_f32_e32 v77, v77, v81
	v_add_f32_e32 v75, v75, v77
	v_sub_f32_e32 v77, v79, v80
	v_add_f32_e32 v75, v77, v75
	v_add_f32_e32 v77, v82, v75
	v_mul_f32_e32 v79, v76, v77
	v_mul_f32_e32 v80, v74, v79
	v_fma_f32 v74, v79, v74, -v80
	v_fmac_f32_e32 v74, v79, v73
	v_sub_f32_e32 v73, v82, v77
	v_add_f32_e32 v73, v75, v73
	v_add_f32_e32 v75, v80, v74
	v_sub_f32_e32 v81, v77, v75
	v_sub_f32_e32 v77, v77, v81
	v_sub_f32_e32 v80, v75, v80
	v_sub_f32_e32 v75, v77, v75
	v_add_f32_e32 v73, v73, v75
	v_sub_f32_e32 v74, v80, v74
	v_add_f32_e32 v73, v74, v73
	v_add_f32_e32 v74, v78, v79
	v_add_f32_e32 v73, v81, v73
	v_sub_f32_e32 v75, v74, v78
	v_mul_f32_e32 v73, v76, v73
	v_sub_f32_e32 v75, v79, v75
	v_add_f32_e32 v73, v75, v73
	v_mul_f32_e32 v78, 0x3f317218, v72
	v_add_f32_e32 v75, v74, v73
	v_fma_f32 v79, v72, s78, -v78
	v_mul_f32_e32 v76, v75, v75
	v_fmac_f32_e32 v79, 0xb102e308, v72
	v_sub_f32_e32 v72, v75, v74
	v_fmamk_f32 v77, v76, 0x3e9b6dac, v185
	v_sub_f32_e32 v72, v73, v72
	v_add_f32_e32 v73, v78, v79
	v_fmaak_f32 v77, v76, v77, 0x3f2aaada
	v_sub_f32_e32 v74, v73, v78
	v_ldexp_f32 v78, v75, 1
	v_mul_f32_e32 v75, v75, v76
	v_mul_f32_e32 v75, v75, v77
	v_add_f32_e32 v76, v78, v75
	v_sub_f32_e32 v77, v76, v78
	v_ldexp_f32 v72, v72, 1
	v_sub_f32_e32 v75, v75, v77
	v_add_f32_e32 v72, v72, v75
	v_add_f32_e32 v75, v76, v72
	v_sub_f32_e32 v76, v75, v76
	v_sub_f32_e32 v72, v72, v76
	v_add_f32_e32 v76, v73, v75
	v_sub_f32_e32 v77, v76, v73
	v_sub_f32_e32 v78, v76, v77
	v_sub_f32_e32 v74, v79, v74
	v_sub_f32_e32 v73, v73, v78
	v_sub_f32_e32 v75, v75, v77
	v_add_f32_e32 v73, v75, v73
	v_add_f32_e32 v75, v74, v72
	v_sub_f32_e32 v77, v75, v74
	v_sub_f32_e32 v78, v75, v77
	v_sub_f32_e32 v74, v74, v78
	v_sub_f32_e32 v72, v72, v77
	v_add_f32_e32 v73, v75, v73
	v_add_f32_e32 v72, v72, v74
	v_add_f32_e32 v74, v76, v73
	v_sub_f32_e32 v75, v74, v76
	v_sub_f32_e32 v73, v73, v75
	v_add_f32_e32 v72, v72, v73
	v_add_f32_e32 v72, v74, v72
	v_cndmask_b32_e32 v72, v226, v72, vcc
	v_cmp_lt_f32_e64 vcc, |v53|, s63
	s_nop 1
	v_cndmask_b32_e32 v53, v72, v53, vcc
	v_sub_f32_e32 v52, v52, v53
	v_mul_f32_e32 v52, 0x3fb8aa3b, v52
	global_store_dword v[60:61], v52, off offset:64
	v_readlane_b32 s100, v254, 2
	s_nop 1
	v_mov_b32_e32 v53, s100
	v_fmac_f32_e32 v53, v54, v170
	v_mul_f32_e64 v54, |v53|, s94
	v_fma_f32 v72, |v53|, s94, -v54
	v_rndne_f32_e32 v73, v54
	v_fma_f32 v72, |v53|, s64, v72
	v_sub_f32_e32 v54, v54, v73
	v_add_f32_e32 v54, v54, v72
	v_exp_f32_e32 v54, v54
	v_cvt_i32_f32_e32 v72, v73
	v_cmp_ngt_f32_e64 vcc, |v53|, s58
	v_min_f32_e32 v52, 0, v53
	v_ldexp_f32 v54, v54, v72
	v_cndmask_b32_e32 v54, 0, v54, vcc
	v_cmp_nlt_f32_e64 vcc, |v53|, s59
	s_nop 1
	v_cndmask_b32_e32 v53, v226, v54, vcc
	v_add_f32_e32 v54, 1.0, v53
	v_add_f32_e32 v72, -1.0, v54
	v_sub_f32_e32 v73, v72, v54
	v_add_f32_e32 v73, 1.0, v73
	v_sub_f32_e32 v72, v53, v72
	v_add_f32_e32 v74, v72, v73
	v_frexp_mant_f32_e32 v72, v54
	v_cmp_gt_f32_e32 vcc, s77, v72
	v_cvt_f64_f32_e32 v[72:73], v54
	v_frexp_exp_i32_f64_e32 v72, v[72:73]
	v_subbrev_co_u32_e32 v72, vcc, 0, v72, vcc
	v_sub_u32_e32 v73, 0, v72
	v_ldexp_f32 v54, v54, v73
	v_ldexp_f32 v73, v74, v73
	v_add_f32_e32 v74, -1.0, v54
	v_add_f32_e32 v75, 1.0, v74
	v_sub_f32_e32 v75, v54, v75
	v_add_f32_e32 v75, v73, v75
	v_add_f32_e32 v76, v74, v75
	v_sub_f32_e32 v74, v74, v76
	v_add_f32_e32 v74, v75, v74
	v_add_f32_e32 v75, 1.0, v54
	v_add_f32_e32 v77, -1.0, v75
	v_sub_f32_e32 v54, v54, v77
	v_add_f32_e32 v54, v73, v54
	v_add_f32_e32 v73, v75, v54
	v_sub_f32_e32 v75, v75, v73
	v_add_f32_e32 v54, v54, v75
	v_rcp_f32_e32 v75, v73
	v_cvt_f32_i32_e32 v72, v72
	v_cmp_neq_f32_e32 vcc, s62, v53
	v_mul_f32_e32 v77, v76, v75
	v_mul_f32_e32 v78, v73, v77
	v_fma_f32 v79, v77, v73, -v78
	v_fmac_f32_e32 v79, v77, v54
	v_add_f32_e32 v80, v78, v79
	v_sub_f32_e32 v81, v76, v80
	v_sub_f32_e32 v76, v76, v81
	v_sub_f32_e32 v78, v80, v78
	v_sub_f32_e32 v76, v76, v80
	v_add_f32_e32 v74, v74, v76
	v_sub_f32_e32 v76, v78, v79
	v_add_f32_e32 v74, v76, v74
	v_add_f32_e32 v76, v81, v74
	v_mul_f32_e32 v78, v75, v76
	v_mul_f32_e32 v79, v73, v78
	v_fma_f32 v73, v78, v73, -v79
	v_fmac_f32_e32 v73, v78, v54
	v_sub_f32_e32 v54, v81, v76
	v_add_f32_e32 v54, v74, v54
	v_add_f32_e32 v74, v79, v73
	v_sub_f32_e32 v80, v76, v74
	v_sub_f32_e32 v76, v76, v80
	v_sub_f32_e32 v79, v74, v79
	v_sub_f32_e32 v74, v76, v74
	v_add_f32_e32 v54, v54, v74
	v_sub_f32_e32 v73, v79, v73
	v_add_f32_e32 v54, v73, v54
	v_add_f32_e32 v73, v77, v78
	v_add_f32_e32 v54, v80, v54
	v_sub_f32_e32 v74, v73, v77
	v_mul_f32_e32 v54, v75, v54
	v_sub_f32_e32 v74, v78, v74
	v_add_f32_e32 v54, v74, v54
	v_mul_f32_e32 v77, 0x3f317218, v72
	v_add_f32_e32 v74, v73, v54
	v_fma_f32 v78, v72, s78, -v77
	v_mul_f32_e32 v75, v74, v74
	v_fmac_f32_e32 v78, 0xb102e308, v72
	v_sub_f32_e32 v72, v74, v73
	v_fmamk_f32 v76, v75, 0x3e9b6dac, v185
	v_sub_f32_e32 v54, v54, v72
	v_add_f32_e32 v72, v77, v78
	v_fmaak_f32 v76, v75, v76, 0x3f2aaada
	v_sub_f32_e32 v73, v72, v77
	v_ldexp_f32 v77, v74, 1
	v_mul_f32_e32 v74, v74, v75
	v_mul_f32_e32 v74, v74, v76
	v_add_f32_e32 v75, v77, v74
	v_sub_f32_e32 v76, v75, v77
	v_ldexp_f32 v54, v54, 1
	v_sub_f32_e32 v74, v74, v76
	v_add_f32_e32 v54, v54, v74
	v_add_f32_e32 v74, v75, v54
	v_sub_f32_e32 v75, v74, v75
	v_sub_f32_e32 v54, v54, v75
	v_add_f32_e32 v75, v72, v74
	v_sub_f32_e32 v76, v75, v72
	v_sub_f32_e32 v77, v75, v76
	v_sub_f32_e32 v73, v78, v73
	v_sub_f32_e32 v72, v72, v77
	v_sub_f32_e32 v74, v74, v76
	v_add_f32_e32 v72, v74, v72
	v_add_f32_e32 v74, v73, v54
	v_sub_f32_e32 v76, v74, v73
	v_sub_f32_e32 v77, v74, v76
	v_sub_f32_e32 v73, v73, v77
	v_sub_f32_e32 v54, v54, v76
	v_add_f32_e32 v72, v74, v72
	v_add_f32_e32 v54, v54, v73
	v_add_f32_e32 v73, v75, v72
	v_sub_f32_e32 v74, v73, v75
	v_sub_f32_e32 v72, v72, v74
	v_add_f32_e32 v54, v54, v72
	v_add_f32_e32 v54, v73, v54
	v_cndmask_b32_e32 v54, v226, v54, vcc
	v_cmp_lt_f32_e64 vcc, |v53|, s63
	s_nop 1
	v_cndmask_b32_e32 v53, v54, v53, vcc
	v_sub_f32_e32 v52, v52, v53
	v_mul_f32_e32 v52, 0x3fb8aa3b, v52
	global_store_dword v[66:67], v52, off offset:64
	v_readlane_b32 s100, v254, 3
	s_nop 1
	v_mov_b32_e32 v53, s100
	v_fmac_f32_e32 v53, v55, v170
	v_mul_f32_e64 v54, |v53|, s94
	v_fma_f32 v55, |v53|, s94, -v54
	v_rndne_f32_e32 v72, v54
	v_fma_f32 v55, |v53|, s64, v55
	v_sub_f32_e32 v54, v54, v72
	v_add_f32_e32 v54, v54, v55
	v_exp_f32_e32 v54, v54
	v_cvt_i32_f32_e32 v55, v72
	v_cmp_ngt_f32_e64 vcc, |v53|, s58
	v_min_f32_e32 v52, 0, v53
	v_ldexp_f32 v54, v54, v55
	v_cndmask_b32_e32 v54, 0, v54, vcc
	v_cmp_nlt_f32_e64 vcc, |v53|, s59
	s_nop 1
	v_cndmask_b32_e32 v53, v226, v54, vcc
	v_add_f32_e32 v72, 1.0, v53
	v_add_f32_e32 v54, -1.0, v72
	v_sub_f32_e32 v55, v54, v72
	v_add_f32_e32 v55, 1.0, v55
	v_sub_f32_e32 v54, v53, v54
	v_add_f32_e32 v73, v54, v55
	v_frexp_mant_f32_e32 v54, v72
	v_cmp_gt_f32_e32 vcc, s77, v54
	v_cvt_f64_f32_e32 v[54:55], v72
	v_frexp_exp_i32_f64_e32 v54, v[54:55]
	v_subbrev_co_u32_e32 v54, vcc, 0, v54, vcc
	v_sub_u32_e32 v55, 0, v54
	v_ldexp_f32 v72, v72, v55
	v_ldexp_f32 v55, v73, v55
	v_add_f32_e32 v73, -1.0, v72
	v_add_f32_e32 v74, 1.0, v73
	v_sub_f32_e32 v74, v72, v74
	v_add_f32_e32 v74, v55, v74
	v_add_f32_e32 v75, v73, v74
	v_sub_f32_e32 v73, v73, v75
	v_add_f32_e32 v73, v74, v73
	v_add_f32_e32 v74, 1.0, v72
	v_add_f32_e32 v76, -1.0, v74
	v_sub_f32_e32 v72, v72, v76
	v_add_f32_e32 v55, v55, v72
	v_add_f32_e32 v72, v74, v55
	v_sub_f32_e32 v74, v74, v72
	v_add_f32_e32 v55, v55, v74
	v_rcp_f32_e32 v74, v72
	v_cvt_f32_i32_e32 v54, v54
	v_cmp_neq_f32_e32 vcc, s62, v53
	v_mul_f32_e32 v76, v75, v74
	v_mul_f32_e32 v77, v72, v76
	v_fma_f32 v78, v76, v72, -v77
	v_fmac_f32_e32 v78, v76, v55
	v_add_f32_e32 v79, v77, v78
	v_sub_f32_e32 v80, v75, v79
	v_sub_f32_e32 v75, v75, v80
	v_sub_f32_e32 v77, v79, v77
	v_sub_f32_e32 v75, v75, v79
	v_add_f32_e32 v73, v73, v75
	v_sub_f32_e32 v75, v77, v78
	v_add_f32_e32 v73, v75, v73
	v_add_f32_e32 v75, v80, v73
	v_mul_f32_e32 v77, v74, v75
	v_mul_f32_e32 v78, v72, v77
	v_fma_f32 v72, v77, v72, -v78
	v_fmac_f32_e32 v72, v77, v55
	v_sub_f32_e32 v55, v80, v75
	v_add_f32_e32 v55, v73, v55
	v_add_f32_e32 v73, v78, v72
	v_sub_f32_e32 v79, v75, v73
	v_sub_f32_e32 v75, v75, v79
	v_sub_f32_e32 v78, v73, v78
	v_sub_f32_e32 v73, v75, v73
	v_add_f32_e32 v55, v55, v73
	v_sub_f32_e32 v72, v78, v72
	v_add_f32_e32 v55, v72, v55
	v_add_f32_e32 v72, v76, v77
	v_add_f32_e32 v55, v79, v55
	v_sub_f32_e32 v73, v72, v76
	v_mul_f32_e32 v55, v74, v55
	v_sub_f32_e32 v73, v77, v73
	v_add_f32_e32 v55, v73, v55
	v_mul_f32_e32 v76, 0x3f317218, v54
	v_add_f32_e32 v73, v72, v55
	v_fma_f32 v77, v54, s78, -v76
	v_mul_f32_e32 v74, v73, v73
	v_fmac_f32_e32 v77, 0xb102e308, v54
	v_sub_f32_e32 v54, v73, v72
	v_fmamk_f32 v75, v74, 0x3e9b6dac, v185
	v_sub_f32_e32 v54, v55, v54
	v_add_f32_e32 v55, v76, v77
	v_fmaak_f32 v75, v74, v75, 0x3f2aaada
	v_sub_f32_e32 v72, v55, v76
	v_ldexp_f32 v76, v73, 1
	v_mul_f32_e32 v73, v73, v74
	v_mul_f32_e32 v73, v73, v75
	v_add_f32_e32 v74, v76, v73
	v_sub_f32_e32 v75, v74, v76
	v_ldexp_f32 v54, v54, 1
	v_sub_f32_e32 v73, v73, v75
	v_add_f32_e32 v54, v54, v73
	v_add_f32_e32 v73, v74, v54
	v_sub_f32_e32 v74, v73, v74
	v_sub_f32_e32 v54, v54, v74
	v_add_f32_e32 v74, v55, v73
	v_sub_f32_e32 v75, v74, v55
	v_sub_f32_e32 v76, v74, v75
	v_sub_f32_e32 v72, v77, v72
	v_sub_f32_e32 v55, v55, v76
	v_sub_f32_e32 v73, v73, v75
	v_add_f32_e32 v55, v73, v55
	v_add_f32_e32 v73, v72, v54
	v_sub_f32_e32 v75, v73, v72
	v_sub_f32_e32 v76, v73, v75
	v_sub_f32_e32 v72, v72, v76
	v_sub_f32_e32 v54, v54, v75
	v_add_f32_e32 v55, v73, v55
	v_add_f32_e32 v54, v54, v72
	v_add_f32_e32 v72, v74, v55
	v_sub_f32_e32 v73, v72, v74
	v_sub_f32_e32 v55, v55, v73
	v_add_f32_e32 v54, v54, v55
	v_add_f32_e32 v54, v72, v54
	v_cndmask_b32_e32 v54, v226, v54, vcc
	v_cmp_lt_f32_e64 vcc, |v53|, s63
	s_nop 1
	v_cndmask_b32_e32 v53, v54, v53, vcc
	v_sub_f32_e32 v52, v52, v53
	v_mul_f32_e32 v52, 0x3fb8aa3b, v52
	global_store_dword v[62:63], v52, off offset:64
	v_readlane_b32 s100, v254, 4
	s_nop 1
	v_mov_b32_e32 v52, s100
	v_fmac_f32_e32 v52, v48, v170
	v_mul_f32_e64 v53, |v52|, s94
	v_fma_f32 v54, |v52|, s94, -v53
	v_rndne_f32_e32 v55, v53
	v_fma_f32 v54, |v52|, s64, v54
	v_sub_f32_e32 v53, v53, v55
	v_add_f32_e32 v53, v53, v54
	v_exp_f32_e32 v53, v53
	v_cvt_i32_f32_e32 v54, v55
	v_cmp_ngt_f32_e64 vcc, |v52|, s58
	v_min_f32_e32 v48, 0, v52
	v_ldexp_f32 v53, v53, v54
	v_cndmask_b32_e32 v53, 0, v53, vcc
	v_cmp_nlt_f32_e64 vcc, |v52|, s59
	s_nop 1
	v_cndmask_b32_e32 v52, v226, v53, vcc
	v_add_f32_e32 v53, 1.0, v52
	v_add_f32_e32 v54, -1.0, v53
	v_sub_f32_e32 v55, v54, v53
	v_add_f32_e32 v55, 1.0, v55
	v_sub_f32_e32 v54, v52, v54
	v_add_f32_e32 v72, v54, v55
	v_frexp_mant_f32_e32 v54, v53
	v_cmp_gt_f32_e32 vcc, s77, v54
	v_cvt_f64_f32_e32 v[54:55], v53
	v_frexp_exp_i32_f64_e32 v54, v[54:55]
	v_subbrev_co_u32_e32 v54, vcc, 0, v54, vcc
	v_sub_u32_e32 v55, 0, v54
	v_ldexp_f32 v53, v53, v55
	v_ldexp_f32 v55, v72, v55
	v_add_f32_e32 v72, -1.0, v53
	v_add_f32_e32 v73, 1.0, v72
	v_sub_f32_e32 v73, v53, v73
	v_add_f32_e32 v73, v55, v73
	v_add_f32_e32 v74, v72, v73
	v_sub_f32_e32 v72, v72, v74
	v_add_f32_e32 v72, v73, v72
	v_add_f32_e32 v73, 1.0, v53
	v_add_f32_e32 v75, -1.0, v73
	v_sub_f32_e32 v53, v53, v75
	v_add_f32_e32 v53, v55, v53
	v_add_f32_e32 v55, v73, v53
	v_sub_f32_e32 v73, v73, v55
	v_add_f32_e32 v53, v53, v73
	v_rcp_f32_e32 v73, v55
	v_cvt_f32_i32_e32 v54, v54
	v_cmp_neq_f32_e32 vcc, s62, v52
	v_mul_f32_e32 v75, v74, v73
	v_mul_f32_e32 v76, v55, v75
	v_fma_f32 v77, v75, v55, -v76
	v_fmac_f32_e32 v77, v75, v53
	v_add_f32_e32 v78, v76, v77
	v_sub_f32_e32 v79, v74, v78
	v_sub_f32_e32 v74, v74, v79
	v_sub_f32_e32 v76, v78, v76
	v_sub_f32_e32 v74, v74, v78
	v_add_f32_e32 v72, v72, v74
	v_sub_f32_e32 v74, v76, v77
	v_add_f32_e32 v72, v74, v72
	v_add_f32_e32 v74, v79, v72
	v_mul_f32_e32 v76, v73, v74
	v_mul_f32_e32 v77, v55, v76
	v_fma_f32 v55, v76, v55, -v77
	v_fmac_f32_e32 v55, v76, v53
	v_sub_f32_e32 v53, v79, v74
	v_add_f32_e32 v53, v72, v53
	v_add_f32_e32 v72, v77, v55
	v_sub_f32_e32 v78, v74, v72
	v_sub_f32_e32 v74, v74, v78
	v_sub_f32_e32 v77, v72, v77
	v_sub_f32_e32 v72, v74, v72
	v_add_f32_e32 v53, v53, v72
	v_sub_f32_e32 v55, v77, v55
	v_add_f32_e32 v53, v55, v53
	v_add_f32_e32 v55, v75, v76
	v_add_f32_e32 v53, v78, v53
	v_sub_f32_e32 v72, v55, v75
	v_mul_f32_e32 v53, v73, v53
	v_sub_f32_e32 v72, v76, v72
	v_add_f32_e32 v53, v72, v53
	v_mul_f32_e32 v75, 0x3f317218, v54
	v_add_f32_e32 v72, v55, v53
	v_fma_f32 v76, v54, s78, -v75
	v_mul_f32_e32 v73, v72, v72
	v_fmac_f32_e32 v76, 0xb102e308, v54
	v_sub_f32_e32 v54, v72, v55
	v_fmamk_f32 v74, v73, 0x3e9b6dac, v185
	v_sub_f32_e32 v53, v53, v54
	v_add_f32_e32 v54, v75, v76
	v_fmaak_f32 v74, v73, v74, 0x3f2aaada
	v_sub_f32_e32 v55, v54, v75
	v_ldexp_f32 v75, v72, 1
	v_mul_f32_e32 v72, v72, v73
	v_mul_f32_e32 v72, v72, v74
	v_add_f32_e32 v73, v75, v72
	v_sub_f32_e32 v74, v73, v75
	v_ldexp_f32 v53, v53, 1
	v_sub_f32_e32 v72, v72, v74
	v_add_f32_e32 v53, v53, v72
	v_add_f32_e32 v72, v73, v53
	v_sub_f32_e32 v73, v72, v73
	v_sub_f32_e32 v53, v53, v73
	v_add_f32_e32 v73, v54, v72
	v_sub_f32_e32 v74, v73, v54
	v_sub_f32_e32 v75, v73, v74
	v_sub_f32_e32 v55, v76, v55
	v_sub_f32_e32 v54, v54, v75
	v_sub_f32_e32 v72, v72, v74
	v_add_f32_e32 v54, v72, v54
	v_add_f32_e32 v72, v55, v53
	v_sub_f32_e32 v74, v72, v55
	v_sub_f32_e32 v75, v72, v74
	v_sub_f32_e32 v55, v55, v75
	v_sub_f32_e32 v53, v53, v74
	v_add_f32_e32 v54, v72, v54
	v_add_f32_e32 v53, v53, v55
	v_add_f32_e32 v55, v73, v54
	v_sub_f32_e32 v72, v55, v73
	v_sub_f32_e32 v54, v54, v72
	v_add_f32_e32 v53, v53, v54
	v_add_f32_e32 v53, v55, v53
	v_cndmask_b32_e32 v53, v226, v53, vcc
	v_cmp_lt_f32_e64 vcc, |v52|, s63
	s_nop 1
	v_cndmask_b32_e32 v52, v53, v52, vcc
	v_sub_f32_e32 v48, v48, v52
	v_mul_f32_e32 v48, 0x3fb8aa3b, v48
	global_store_dword v[68:69], v48, off offset:64
	v_readlane_b32 s100, v254, 5
	s_nop 1
	v_mov_b32_e32 v52, s100
	v_fmac_f32_e32 v52, v49, v170
	v_mul_f32_e64 v49, |v52|, s94
	v_fma_f32 v53, |v52|, s94, -v49
	v_rndne_f32_e32 v54, v49
	v_fma_f32 v53, |v52|, s64, v53
	v_sub_f32_e32 v49, v49, v54
	v_add_f32_e32 v49, v49, v53
	v_exp_f32_e32 v49, v49
	v_cvt_i32_f32_e32 v53, v54
	v_cmp_ngt_f32_e64 vcc, |v52|, s58
	v_min_f32_e32 v48, 0, v52
	v_ldexp_f32 v49, v49, v53
	v_cndmask_b32_e32 v49, 0, v49, vcc
	v_cmp_nlt_f32_e64 vcc, |v52|, s59
	s_nop 1
	v_cndmask_b32_e32 v49, v226, v49, vcc
	v_add_f32_e32 v54, 1.0, v49
	v_add_f32_e32 v52, -1.0, v54
	v_sub_f32_e32 v53, v52, v54
	v_add_f32_e32 v53, 1.0, v53
	v_sub_f32_e32 v52, v49, v52
	v_add_f32_e32 v55, v52, v53
	v_frexp_mant_f32_e32 v52, v54
	v_cmp_gt_f32_e32 vcc, s77, v52
	v_cvt_f64_f32_e32 v[52:53], v54
	v_frexp_exp_i32_f64_e32 v52, v[52:53]
	v_subbrev_co_u32_e32 v52, vcc, 0, v52, vcc
	v_sub_u32_e32 v53, 0, v52
	v_ldexp_f32 v54, v54, v53
	v_ldexp_f32 v53, v55, v53
	v_add_f32_e32 v55, -1.0, v54
	v_add_f32_e32 v72, 1.0, v55
	v_sub_f32_e32 v72, v54, v72
	v_add_f32_e32 v72, v53, v72
	v_add_f32_e32 v73, v55, v72
	v_sub_f32_e32 v55, v55, v73
	v_add_f32_e32 v55, v72, v55
	v_add_f32_e32 v72, 1.0, v54
	v_add_f32_e32 v74, -1.0, v72
	v_sub_f32_e32 v54, v54, v74
	v_add_f32_e32 v53, v53, v54
	v_add_f32_e32 v54, v72, v53
	v_sub_f32_e32 v72, v72, v54
	v_add_f32_e32 v53, v53, v72
	v_rcp_f32_e32 v72, v54
	v_cvt_f32_i32_e32 v52, v52
	v_cmp_neq_f32_e32 vcc, s62, v49
	v_mul_f32_e32 v74, v73, v72
	v_mul_f32_e32 v75, v54, v74
	v_fma_f32 v76, v74, v54, -v75
	v_fmac_f32_e32 v76, v74, v53
	v_add_f32_e32 v77, v75, v76
	v_sub_f32_e32 v78, v73, v77
	v_sub_f32_e32 v73, v73, v78
	v_sub_f32_e32 v75, v77, v75
	v_sub_f32_e32 v73, v73, v77
	v_add_f32_e32 v55, v55, v73
	v_sub_f32_e32 v73, v75, v76
	v_add_f32_e32 v55, v73, v55
	v_add_f32_e32 v73, v78, v55
	v_mul_f32_e32 v75, v72, v73
	v_mul_f32_e32 v76, v54, v75
	v_fma_f32 v54, v75, v54, -v76
	v_fmac_f32_e32 v54, v75, v53
	v_sub_f32_e32 v53, v78, v73
	v_add_f32_e32 v53, v55, v53
	v_add_f32_e32 v55, v76, v54
	v_sub_f32_e32 v77, v73, v55
	v_sub_f32_e32 v73, v73, v77
	v_sub_f32_e32 v76, v55, v76
	v_sub_f32_e32 v55, v73, v55
	v_add_f32_e32 v53, v53, v55
	v_sub_f32_e32 v54, v76, v54
	v_add_f32_e32 v53, v54, v53
	v_add_f32_e32 v54, v74, v75
	v_add_f32_e32 v53, v77, v53
	v_sub_f32_e32 v55, v54, v74
	v_mul_f32_e32 v53, v72, v53
	v_sub_f32_e32 v55, v75, v55
	v_add_f32_e32 v53, v55, v53
	v_mul_f32_e32 v74, 0x3f317218, v52
	v_add_f32_e32 v55, v54, v53
	v_fma_f32 v75, v52, s78, -v74
	v_mul_f32_e32 v72, v55, v55
	v_fmac_f32_e32 v75, 0xb102e308, v52
	v_sub_f32_e32 v52, v55, v54
	v_fmamk_f32 v73, v72, 0x3e9b6dac, v185
	v_sub_f32_e32 v52, v53, v52
	v_add_f32_e32 v53, v74, v75
	v_fmaak_f32 v73, v72, v73, 0x3f2aaada
	v_sub_f32_e32 v54, v53, v74
	v_ldexp_f32 v74, v55, 1
	v_mul_f32_e32 v55, v55, v72
	v_mul_f32_e32 v55, v55, v73
	v_add_f32_e32 v72, v74, v55
	v_sub_f32_e32 v73, v72, v74
	v_ldexp_f32 v52, v52, 1
	v_sub_f32_e32 v55, v55, v73
	v_add_f32_e32 v52, v52, v55
	v_add_f32_e32 v55, v72, v52
	v_sub_f32_e32 v72, v55, v72
	v_sub_f32_e32 v52, v52, v72
	v_add_f32_e32 v72, v53, v55
	v_sub_f32_e32 v73, v72, v53
	v_sub_f32_e32 v74, v72, v73
	v_sub_f32_e32 v54, v75, v54
	v_sub_f32_e32 v53, v53, v74
	v_sub_f32_e32 v55, v55, v73
	v_add_f32_e32 v53, v55, v53
	v_add_f32_e32 v55, v54, v52
	v_sub_f32_e32 v73, v55, v54
	v_sub_f32_e32 v74, v55, v73
	v_sub_f32_e32 v54, v54, v74
	v_sub_f32_e32 v52, v52, v73
	v_add_f32_e32 v53, v55, v53
	v_add_f32_e32 v52, v52, v54
	v_add_f32_e32 v54, v72, v53
	v_sub_f32_e32 v55, v54, v72
	v_sub_f32_e32 v53, v53, v55
	v_add_f32_e32 v52, v52, v53
	v_add_f32_e32 v52, v54, v52
	v_cndmask_b32_e32 v52, v226, v52, vcc
	v_cmp_lt_f32_e64 vcc, |v49|, s63
	s_nop 1
	v_cndmask_b32_e32 v49, v52, v49, vcc
	v_sub_f32_e32 v48, v48, v49
	v_mul_f32_e32 v48, 0x3fb8aa3b, v48
	global_store_dword v[56:57], v48, off offset:64
	v_readlane_b32 s100, v254, 6
	s_nop 1
	v_mov_b32_e32 v49, s100
	v_fmac_f32_e32 v49, v50, v170
	v_mul_f32_e64 v50, |v49|, s94
	v_fma_f32 v52, |v49|, s94, -v50
	v_rndne_f32_e32 v53, v50
	v_fma_f32 v52, |v49|, s64, v52
	v_sub_f32_e32 v50, v50, v53
	v_add_f32_e32 v50, v50, v52
	v_exp_f32_e32 v50, v50
	v_cvt_i32_f32_e32 v52, v53
	v_cmp_ngt_f32_e64 vcc, |v49|, s58
	v_min_f32_e32 v48, 0, v49
	v_ldexp_f32 v50, v50, v52
	v_cndmask_b32_e32 v50, 0, v50, vcc
	v_cmp_nlt_f32_e64 vcc, |v49|, s59
	s_nop 1
	v_cndmask_b32_e32 v49, v226, v50, vcc
	v_add_f32_e32 v50, 1.0, v49
	v_add_f32_e32 v52, -1.0, v50
	v_sub_f32_e32 v53, v52, v50
	v_add_f32_e32 v53, 1.0, v53
	v_sub_f32_e32 v52, v49, v52
	v_add_f32_e32 v54, v52, v53
	v_frexp_mant_f32_e32 v52, v50
	v_cmp_gt_f32_e32 vcc, s77, v52
	v_cvt_f64_f32_e32 v[52:53], v50
	v_frexp_exp_i32_f64_e32 v52, v[52:53]
	v_subbrev_co_u32_e32 v52, vcc, 0, v52, vcc
	v_sub_u32_e32 v53, 0, v52
	v_ldexp_f32 v50, v50, v53
	v_ldexp_f32 v53, v54, v53
	v_add_f32_e32 v54, -1.0, v50
	v_add_f32_e32 v55, 1.0, v54
	v_sub_f32_e32 v55, v50, v55
	v_add_f32_e32 v55, v53, v55
	v_add_f32_e32 v72, v54, v55
	v_sub_f32_e32 v54, v54, v72
	v_add_f32_e32 v54, v55, v54
	v_add_f32_e32 v55, 1.0, v50
	v_add_f32_e32 v73, -1.0, v55
	v_sub_f32_e32 v50, v50, v73
	v_add_f32_e32 v50, v53, v50
	v_add_f32_e32 v53, v55, v50
	v_sub_f32_e32 v55, v55, v53
	v_add_f32_e32 v50, v50, v55
	v_rcp_f32_e32 v55, v53
	v_cvt_f32_i32_e32 v52, v52
	v_cmp_neq_f32_e32 vcc, s62, v49
	v_mul_f32_e32 v73, v72, v55
	v_mul_f32_e32 v74, v53, v73
	v_fma_f32 v75, v73, v53, -v74
	v_fmac_f32_e32 v75, v73, v50
	v_add_f32_e32 v76, v74, v75
	v_sub_f32_e32 v77, v72, v76
	v_sub_f32_e32 v72, v72, v77
	v_sub_f32_e32 v74, v76, v74
	v_sub_f32_e32 v72, v72, v76
	v_add_f32_e32 v54, v54, v72
	v_sub_f32_e32 v72, v74, v75
	v_add_f32_e32 v54, v72, v54
	v_add_f32_e32 v72, v77, v54
	v_mul_f32_e32 v74, v55, v72
	v_mul_f32_e32 v75, v53, v74
	v_fma_f32 v53, v74, v53, -v75
	v_fmac_f32_e32 v53, v74, v50
	v_sub_f32_e32 v50, v77, v72
	v_add_f32_e32 v50, v54, v50
	v_add_f32_e32 v54, v75, v53
	v_sub_f32_e32 v76, v72, v54
	v_sub_f32_e32 v72, v72, v76
	v_sub_f32_e32 v75, v54, v75
	v_sub_f32_e32 v54, v72, v54
	v_add_f32_e32 v50, v50, v54
	v_sub_f32_e32 v53, v75, v53
	v_add_f32_e32 v50, v53, v50
	v_add_f32_e32 v53, v73, v74
	v_add_f32_e32 v50, v76, v50
	v_sub_f32_e32 v54, v53, v73
	v_mul_f32_e32 v50, v55, v50
	v_sub_f32_e32 v54, v74, v54
	v_add_f32_e32 v50, v54, v50
	v_mul_f32_e32 v73, 0x3f317218, v52
	v_add_f32_e32 v54, v53, v50
	v_fma_f32 v74, v52, s78, -v73
	v_mul_f32_e32 v55, v54, v54
	v_fmac_f32_e32 v74, 0xb102e308, v52
	v_sub_f32_e32 v52, v54, v53
	v_fmamk_f32 v72, v55, 0x3e9b6dac, v185
	v_sub_f32_e32 v50, v50, v52
	v_add_f32_e32 v52, v73, v74
	v_fmaak_f32 v72, v55, v72, 0x3f2aaada
	v_sub_f32_e32 v53, v52, v73
	v_ldexp_f32 v73, v54, 1
	v_mul_f32_e32 v54, v54, v55
	v_mul_f32_e32 v54, v54, v72
	v_add_f32_e32 v55, v73, v54
	v_sub_f32_e32 v72, v55, v73
	v_ldexp_f32 v50, v50, 1
	v_sub_f32_e32 v54, v54, v72
	v_add_f32_e32 v50, v50, v54
	v_add_f32_e32 v54, v55, v50
	v_sub_f32_e32 v55, v54, v55
	v_sub_f32_e32 v50, v50, v55
	v_add_f32_e32 v55, v52, v54
	v_sub_f32_e32 v72, v55, v52
	v_sub_f32_e32 v73, v55, v72
	v_sub_f32_e32 v53, v74, v53
	v_sub_f32_e32 v52, v52, v73
	v_sub_f32_e32 v54, v54, v72
	v_add_f32_e32 v52, v54, v52
	v_add_f32_e32 v54, v53, v50
	v_sub_f32_e32 v72, v54, v53
	v_sub_f32_e32 v73, v54, v72
	v_sub_f32_e32 v53, v53, v73
	v_sub_f32_e32 v50, v50, v72
	v_add_f32_e32 v52, v54, v52
	v_add_f32_e32 v50, v50, v53
	v_add_f32_e32 v53, v55, v52
	v_sub_f32_e32 v54, v53, v55
	v_sub_f32_e32 v52, v52, v54
	v_add_f32_e32 v50, v50, v52
	v_add_f32_e32 v50, v53, v50
	v_cndmask_b32_e32 v50, v226, v50, vcc
	v_cmp_lt_f32_e64 vcc, |v49|, s63
	s_nop 1
	v_cndmask_b32_e32 v49, v50, v49, vcc
	v_sub_f32_e32 v48, v48, v49
	v_mul_f32_e32 v48, 0x3fb8aa3b, v48
	global_store_dword v[70:71], v48, off offset:64
	v_readlane_b32 s100, v254, 7
	s_nop 1
	v_mov_b32_e32 v49, s100
	v_fmac_f32_e32 v49, v51, v170
	v_mul_f32_e64 v50, |v49|, s94
	v_fma_f32 v51, |v49|, s94, -v50
	v_rndne_f32_e32 v52, v50
	v_fma_f32 v51, |v49|, s64, v51
	v_sub_f32_e32 v50, v50, v52
	v_add_f32_e32 v50, v50, v51
	v_exp_f32_e32 v50, v50
	v_cvt_i32_f32_e32 v51, v52
	v_cmp_ngt_f32_e64 vcc, |v49|, s58
	v_min_f32_e32 v48, 0, v49
	v_ldexp_f32 v50, v50, v51
	v_cndmask_b32_e32 v50, 0, v50, vcc
	v_cmp_nlt_f32_e64 vcc, |v49|, s59
	s_nop 1
	v_cndmask_b32_e32 v49, v226, v50, vcc
	v_add_f32_e32 v52, 1.0, v49
	v_add_f32_e32 v50, -1.0, v52
	v_sub_f32_e32 v51, v50, v52
	v_add_f32_e32 v51, 1.0, v51
	v_sub_f32_e32 v50, v49, v50
	v_add_f32_e32 v53, v50, v51
	v_frexp_mant_f32_e32 v50, v52
	v_cmp_gt_f32_e32 vcc, s77, v50
	v_cvt_f64_f32_e32 v[50:51], v52
	v_frexp_exp_i32_f64_e32 v50, v[50:51]
	v_subbrev_co_u32_e32 v50, vcc, 0, v50, vcc
	v_sub_u32_e32 v51, 0, v50
	v_ldexp_f32 v52, v52, v51
	v_ldexp_f32 v51, v53, v51
	v_add_f32_e32 v53, -1.0, v52
	v_add_f32_e32 v54, 1.0, v53
	v_sub_f32_e32 v54, v52, v54
	v_add_f32_e32 v54, v51, v54
	v_add_f32_e32 v55, v53, v54
	v_sub_f32_e32 v53, v53, v55
	v_add_f32_e32 v53, v54, v53
	v_add_f32_e32 v54, 1.0, v52
	v_add_f32_e32 v72, -1.0, v54
	v_sub_f32_e32 v52, v52, v72
	v_add_f32_e32 v51, v51, v52
	v_add_f32_e32 v52, v54, v51
	v_sub_f32_e32 v54, v54, v52
	v_add_f32_e32 v51, v51, v54
	v_rcp_f32_e32 v54, v52
	v_cvt_f32_i32_e32 v50, v50
	v_cmp_neq_f32_e32 vcc, s62, v49
	v_mul_f32_e32 v72, v55, v54
	v_mul_f32_e32 v73, v52, v72
	v_fma_f32 v74, v72, v52, -v73
	v_fmac_f32_e32 v74, v72, v51
	v_add_f32_e32 v75, v73, v74
	v_sub_f32_e32 v76, v55, v75
	v_sub_f32_e32 v55, v55, v76
	v_sub_f32_e32 v73, v75, v73
	v_sub_f32_e32 v55, v55, v75
	v_add_f32_e32 v53, v53, v55
	v_sub_f32_e32 v55, v73, v74
	v_add_f32_e32 v53, v55, v53
	v_add_f32_e32 v55, v76, v53
	v_mul_f32_e32 v73, v54, v55
	v_mul_f32_e32 v74, v52, v73
	v_fma_f32 v52, v73, v52, -v74
	v_fmac_f32_e32 v52, v73, v51
	v_sub_f32_e32 v51, v76, v55
	v_add_f32_e32 v51, v53, v51
	v_add_f32_e32 v53, v74, v52
	v_sub_f32_e32 v75, v55, v53
	v_sub_f32_e32 v55, v55, v75
	v_sub_f32_e32 v74, v53, v74
	v_sub_f32_e32 v53, v55, v53
	v_add_f32_e32 v51, v51, v53
	v_sub_f32_e32 v52, v74, v52
	v_add_f32_e32 v51, v52, v51
	v_add_f32_e32 v52, v72, v73
	v_add_f32_e32 v51, v75, v51
	v_sub_f32_e32 v53, v52, v72
	v_mul_f32_e32 v51, v54, v51
	v_sub_f32_e32 v53, v73, v53
	v_add_f32_e32 v51, v53, v51
	v_mul_f32_e32 v72, 0x3f317218, v50
	v_add_f32_e32 v53, v52, v51
	v_fma_f32 v73, v50, s78, -v72
	v_mul_f32_e32 v54, v53, v53
	v_fmac_f32_e32 v73, 0xb102e308, v50
	v_sub_f32_e32 v50, v53, v52
	v_fmamk_f32 v55, v54, 0x3e9b6dac, v185
	v_sub_f32_e32 v50, v51, v50
	v_add_f32_e32 v51, v72, v73
	v_fmaak_f32 v55, v54, v55, 0x3f2aaada
	v_sub_f32_e32 v52, v51, v72
	v_ldexp_f32 v72, v53, 1
	v_mul_f32_e32 v53, v53, v54
	v_mul_f32_e32 v53, v53, v55
	v_add_f32_e32 v54, v72, v53
	v_sub_f32_e32 v55, v54, v72
	v_ldexp_f32 v50, v50, 1
	v_sub_f32_e32 v53, v53, v55
	v_add_f32_e32 v50, v50, v53
	v_add_f32_e32 v53, v54, v50
	v_sub_f32_e32 v54, v53, v54
	v_sub_f32_e32 v50, v50, v54
	v_add_f32_e32 v54, v51, v53
	v_sub_f32_e32 v55, v54, v51
	v_sub_f32_e32 v72, v54, v55
	v_sub_f32_e32 v52, v73, v52
	v_sub_f32_e32 v51, v51, v72
	v_sub_f32_e32 v53, v53, v55
	v_add_f32_e32 v51, v53, v51
	v_add_f32_e32 v53, v52, v50
	v_sub_f32_e32 v55, v53, v52
	v_sub_f32_e32 v72, v53, v55
	v_sub_f32_e32 v52, v52, v72
	v_sub_f32_e32 v50, v50, v55
	v_add_f32_e32 v51, v53, v51
	v_add_f32_e32 v50, v50, v52
	v_add_f32_e32 v52, v54, v51
	v_sub_f32_e32 v53, v52, v54
	v_sub_f32_e32 v51, v51, v53
	v_add_f32_e32 v50, v50, v51
	v_add_f32_e32 v50, v52, v50
	v_cndmask_b32_e32 v50, v226, v50, vcc
	v_cmp_lt_f32_e64 vcc, |v49|, s63
	s_nop 1
	v_cndmask_b32_e32 v49, v50, v49, vcc
	v_sub_f32_e32 v48, v48, v49
	v_mul_f32_e32 v48, 0x3fb8aa3b, v48
	global_store_dword v[58:59], v48, off offset:64
	v_readlane_b32 s100, v254, 0
	s_nop 1
	v_mov_b32_e32 v48, s100
	v_fmac_f32_e32 v48, v44, v168
	v_mul_f32_e64 v49, |v48|, s94
	v_fma_f32 v50, |v48|, s94, -v49
	v_rndne_f32_e32 v51, v49
	v_fma_f32 v50, |v48|, s64, v50
	v_sub_f32_e32 v49, v49, v51
	v_add_f32_e32 v49, v49, v50
	v_exp_f32_e32 v49, v49
	v_cvt_i32_f32_e32 v50, v51
	v_cmp_ngt_f32_e64 vcc, |v48|, s58
	v_min_f32_e32 v44, 0, v48
	v_ldexp_f32 v49, v49, v50
	v_cndmask_b32_e32 v49, 0, v49, vcc
	v_cmp_nlt_f32_e64 vcc, |v48|, s59
	s_nop 1
	v_cndmask_b32_e32 v48, v226, v49, vcc
	v_add_f32_e32 v49, 1.0, v48
	v_add_f32_e32 v50, -1.0, v49
	v_sub_f32_e32 v51, v50, v49
	v_add_f32_e32 v51, 1.0, v51
	v_sub_f32_e32 v50, v48, v50
	v_add_f32_e32 v52, v50, v51
	v_frexp_mant_f32_e32 v50, v49
	v_cmp_gt_f32_e32 vcc, s77, v50
	v_cvt_f64_f32_e32 v[50:51], v49
	v_frexp_exp_i32_f64_e32 v50, v[50:51]
	v_subbrev_co_u32_e32 v50, vcc, 0, v50, vcc
	v_sub_u32_e32 v51, 0, v50
	v_ldexp_f32 v49, v49, v51
	v_ldexp_f32 v51, v52, v51
	v_add_f32_e32 v52, -1.0, v49
	v_add_f32_e32 v53, 1.0, v52
	v_sub_f32_e32 v53, v49, v53
	v_add_f32_e32 v53, v51, v53
	v_add_f32_e32 v54, v52, v53
	v_sub_f32_e32 v52, v52, v54
	v_add_f32_e32 v52, v53, v52
	v_add_f32_e32 v53, 1.0, v49
	v_add_f32_e32 v55, -1.0, v53
	v_sub_f32_e32 v49, v49, v55
	v_add_f32_e32 v49, v51, v49
	v_add_f32_e32 v51, v53, v49
	v_sub_f32_e32 v53, v53, v51
	v_add_f32_e32 v49, v49, v53
	v_rcp_f32_e32 v53, v51
	v_cvt_f32_i32_e32 v50, v50
	v_cmp_neq_f32_e32 vcc, s62, v48
	v_mul_f32_e32 v55, v54, v53
	v_mul_f32_e32 v72, v51, v55
	v_fma_f32 v73, v55, v51, -v72
	v_fmac_f32_e32 v73, v55, v49
	v_add_f32_e32 v74, v72, v73
	v_sub_f32_e32 v75, v54, v74
	v_sub_f32_e32 v54, v54, v75
	v_sub_f32_e32 v72, v74, v72
	v_sub_f32_e32 v54, v54, v74
	v_add_f32_e32 v52, v52, v54
	v_sub_f32_e32 v54, v72, v73
	v_add_f32_e32 v52, v54, v52
	v_add_f32_e32 v54, v75, v52
	v_mul_f32_e32 v72, v53, v54
	v_mul_f32_e32 v73, v51, v72
	v_fma_f32 v51, v72, v51, -v73
	v_fmac_f32_e32 v51, v72, v49
	v_sub_f32_e32 v49, v75, v54
	v_add_f32_e32 v49, v52, v49
	v_add_f32_e32 v52, v73, v51
	v_sub_f32_e32 v74, v54, v52
	v_sub_f32_e32 v54, v54, v74
	v_sub_f32_e32 v73, v52, v73
	v_sub_f32_e32 v52, v54, v52
	v_add_f32_e32 v49, v49, v52
	v_sub_f32_e32 v51, v73, v51
	v_add_f32_e32 v49, v51, v49
	v_add_f32_e32 v51, v55, v72
	v_add_f32_e32 v49, v74, v49
	v_sub_f32_e32 v52, v51, v55
	v_mul_f32_e32 v49, v53, v49
	v_sub_f32_e32 v52, v72, v52
	v_add_f32_e32 v49, v52, v49
	v_mul_f32_e32 v55, 0x3f317218, v50
	v_add_f32_e32 v52, v51, v49
	v_fma_f32 v72, v50, s78, -v55
	v_mul_f32_e32 v53, v52, v52
	v_fmac_f32_e32 v72, 0xb102e308, v50
	v_sub_f32_e32 v50, v52, v51
	v_fmamk_f32 v54, v53, 0x3e9b6dac, v185
	v_sub_f32_e32 v49, v49, v50
	v_add_f32_e32 v50, v55, v72
	v_fmaak_f32 v54, v53, v54, 0x3f2aaada
	v_sub_f32_e32 v51, v50, v55
	v_ldexp_f32 v55, v52, 1
	v_mul_f32_e32 v52, v52, v53
	v_mul_f32_e32 v52, v52, v54
	v_add_f32_e32 v53, v55, v52
	v_sub_f32_e32 v54, v53, v55
	v_ldexp_f32 v49, v49, 1
	v_sub_f32_e32 v52, v52, v54
	v_add_f32_e32 v49, v49, v52
	v_add_f32_e32 v52, v53, v49
	v_sub_f32_e32 v53, v52, v53
	v_sub_f32_e32 v49, v49, v53
	v_add_f32_e32 v53, v50, v52
	v_sub_f32_e32 v54, v53, v50
	v_sub_f32_e32 v55, v53, v54
	v_sub_f32_e32 v51, v72, v51
	v_sub_f32_e32 v50, v50, v55
	v_sub_f32_e32 v52, v52, v54
	v_add_f32_e32 v50, v52, v50
	v_add_f32_e32 v52, v51, v49
	v_sub_f32_e32 v54, v52, v51
	v_sub_f32_e32 v55, v52, v54
	v_sub_f32_e32 v51, v51, v55
	v_sub_f32_e32 v49, v49, v54
	v_add_f32_e32 v50, v52, v50
	v_add_f32_e32 v49, v49, v51
	v_add_f32_e32 v51, v53, v50
	v_sub_f32_e32 v52, v51, v53
	v_sub_f32_e32 v50, v50, v52
	v_add_f32_e32 v49, v49, v50
	v_add_f32_e32 v49, v51, v49
	v_cndmask_b32_e32 v49, v226, v49, vcc
	v_cmp_lt_f32_e64 vcc, |v48|, s63
	s_nop 1
	v_cndmask_b32_e32 v48, v49, v48, vcc
	v_sub_f32_e32 v44, v44, v48
	v_mul_f32_e32 v44, 0x3fb8aa3b, v44
	global_store_dword v[64:65], v44, off offset:128
	v_readlane_b32 s100, v254, 1
	s_nop 1
	v_mov_b32_e32 v48, s100
	v_fmac_f32_e32 v48, v45, v168
	v_mul_f32_e64 v45, |v48|, s94
	v_fma_f32 v49, |v48|, s94, -v45
	v_rndne_f32_e32 v50, v45
	v_fma_f32 v49, |v48|, s64, v49
	v_sub_f32_e32 v45, v45, v50
	v_add_f32_e32 v45, v45, v49
	v_exp_f32_e32 v45, v45
	v_cvt_i32_f32_e32 v49, v50
	v_cmp_ngt_f32_e64 vcc, |v48|, s58
	v_min_f32_e32 v44, 0, v48
	v_ldexp_f32 v45, v45, v49
	v_cndmask_b32_e32 v45, 0, v45, vcc
	v_cmp_nlt_f32_e64 vcc, |v48|, s59
	s_nop 1
	v_cndmask_b32_e32 v45, v226, v45, vcc
	v_add_f32_e32 v50, 1.0, v45
	v_add_f32_e32 v48, -1.0, v50
	v_sub_f32_e32 v49, v48, v50
	v_add_f32_e32 v49, 1.0, v49
	v_sub_f32_e32 v48, v45, v48
	v_add_f32_e32 v51, v48, v49
	v_frexp_mant_f32_e32 v48, v50
	v_cmp_gt_f32_e32 vcc, s77, v48
	v_cvt_f64_f32_e32 v[48:49], v50
	v_frexp_exp_i32_f64_e32 v48, v[48:49]
	v_subbrev_co_u32_e32 v48, vcc, 0, v48, vcc
	v_sub_u32_e32 v49, 0, v48
	v_ldexp_f32 v50, v50, v49
	v_ldexp_f32 v49, v51, v49
	v_add_f32_e32 v51, -1.0, v50
	v_add_f32_e32 v52, 1.0, v51
	v_sub_f32_e32 v52, v50, v52
	v_add_f32_e32 v52, v49, v52
	v_add_f32_e32 v53, v51, v52
	v_sub_f32_e32 v51, v51, v53
	v_add_f32_e32 v51, v52, v51
	v_add_f32_e32 v52, 1.0, v50
	v_add_f32_e32 v54, -1.0, v52
	v_sub_f32_e32 v50, v50, v54
	v_add_f32_e32 v49, v49, v50
	v_add_f32_e32 v50, v52, v49
	v_sub_f32_e32 v52, v52, v50
	v_add_f32_e32 v49, v49, v52
	v_rcp_f32_e32 v52, v50
	v_cvt_f32_i32_e32 v48, v48
	v_cmp_neq_f32_e32 vcc, s62, v45
	v_mul_f32_e32 v54, v53, v52
	v_mul_f32_e32 v55, v50, v54
	v_fma_f32 v72, v54, v50, -v55
	v_fmac_f32_e32 v72, v54, v49
	v_add_f32_e32 v73, v55, v72
	v_sub_f32_e32 v74, v53, v73
	v_sub_f32_e32 v53, v53, v74
	v_sub_f32_e32 v55, v73, v55
	v_sub_f32_e32 v53, v53, v73
	v_add_f32_e32 v51, v51, v53
	v_sub_f32_e32 v53, v55, v72
	v_add_f32_e32 v51, v53, v51
	v_add_f32_e32 v53, v74, v51
	v_mul_f32_e32 v55, v52, v53
	v_mul_f32_e32 v72, v50, v55
	v_fma_f32 v50, v55, v50, -v72
	v_fmac_f32_e32 v50, v55, v49
	v_sub_f32_e32 v49, v74, v53
	v_add_f32_e32 v49, v51, v49
	v_add_f32_e32 v51, v72, v50
	v_sub_f32_e32 v73, v53, v51
	v_sub_f32_e32 v53, v53, v73
	v_sub_f32_e32 v72, v51, v72
	v_sub_f32_e32 v51, v53, v51
	v_add_f32_e32 v49, v49, v51
	v_sub_f32_e32 v50, v72, v50
	v_add_f32_e32 v49, v50, v49
	v_add_f32_e32 v50, v54, v55
	v_add_f32_e32 v49, v73, v49
	v_sub_f32_e32 v51, v50, v54
	v_mul_f32_e32 v49, v52, v49
	v_sub_f32_e32 v51, v55, v51
	v_add_f32_e32 v49, v51, v49
	v_mul_f32_e32 v54, 0x3f317218, v48
	v_add_f32_e32 v51, v50, v49
	v_fma_f32 v55, v48, s78, -v54
	v_mul_f32_e32 v52, v51, v51
	v_fmac_f32_e32 v55, 0xb102e308, v48
	v_sub_f32_e32 v48, v51, v50
	v_fmamk_f32 v53, v52, 0x3e9b6dac, v185
	v_sub_f32_e32 v48, v49, v48
	v_add_f32_e32 v49, v54, v55
	v_fmaak_f32 v53, v52, v53, 0x3f2aaada
	v_sub_f32_e32 v50, v49, v54
	v_ldexp_f32 v54, v51, 1
	v_mul_f32_e32 v51, v51, v52
	v_mul_f32_e32 v51, v51, v53
	v_add_f32_e32 v52, v54, v51
	v_sub_f32_e32 v53, v52, v54
	v_ldexp_f32 v48, v48, 1
	v_sub_f32_e32 v51, v51, v53
	v_add_f32_e32 v48, v48, v51
	v_add_f32_e32 v51, v52, v48
	v_sub_f32_e32 v52, v51, v52
	v_sub_f32_e32 v48, v48, v52
	v_add_f32_e32 v52, v49, v51
	v_sub_f32_e32 v53, v52, v49
	v_sub_f32_e32 v54, v52, v53
	v_sub_f32_e32 v50, v55, v50
	v_sub_f32_e32 v49, v49, v54
	v_sub_f32_e32 v51, v51, v53
	v_add_f32_e32 v49, v51, v49
	v_add_f32_e32 v51, v50, v48
	v_sub_f32_e32 v53, v51, v50
	v_sub_f32_e32 v54, v51, v53
	v_sub_f32_e32 v50, v50, v54
	v_sub_f32_e32 v48, v48, v53
	v_add_f32_e32 v49, v51, v49
	v_add_f32_e32 v48, v48, v50
	v_add_f32_e32 v50, v52, v49
	v_sub_f32_e32 v51, v50, v52
	v_sub_f32_e32 v49, v49, v51
	v_add_f32_e32 v48, v48, v49
	v_add_f32_e32 v48, v50, v48
	v_cndmask_b32_e32 v48, v226, v48, vcc
	v_cmp_lt_f32_e64 vcc, |v45|, s63
	s_nop 1
	v_cndmask_b32_e32 v45, v48, v45, vcc
	v_sub_f32_e32 v44, v44, v45
	v_mul_f32_e32 v44, 0x3fb8aa3b, v44
	global_store_dword v[60:61], v44, off offset:128
	v_readlane_b32 s100, v254, 2
	s_nop 1
	v_mov_b32_e32 v45, s100
	v_fmac_f32_e32 v45, v46, v168
	v_mul_f32_e64 v46, |v45|, s94
	v_fma_f32 v48, |v45|, s94, -v46
	v_rndne_f32_e32 v49, v46
	v_fma_f32 v48, |v45|, s64, v48
	v_sub_f32_e32 v46, v46, v49
	v_add_f32_e32 v46, v46, v48
	v_exp_f32_e32 v46, v46
	v_cvt_i32_f32_e32 v48, v49
	v_cmp_ngt_f32_e64 vcc, |v45|, s58
	v_min_f32_e32 v44, 0, v45
	v_ldexp_f32 v46, v46, v48
	v_cndmask_b32_e32 v46, 0, v46, vcc
	v_cmp_nlt_f32_e64 vcc, |v45|, s59
	s_nop 1
	v_cndmask_b32_e32 v45, v226, v46, vcc
	v_add_f32_e32 v46, 1.0, v45
	v_add_f32_e32 v48, -1.0, v46
	v_sub_f32_e32 v49, v48, v46
	v_add_f32_e32 v49, 1.0, v49
	v_sub_f32_e32 v48, v45, v48
	v_add_f32_e32 v50, v48, v49
	v_frexp_mant_f32_e32 v48, v46
	v_cmp_gt_f32_e32 vcc, s77, v48
	v_cvt_f64_f32_e32 v[48:49], v46
	v_frexp_exp_i32_f64_e32 v48, v[48:49]
	v_subbrev_co_u32_e32 v48, vcc, 0, v48, vcc
	v_sub_u32_e32 v49, 0, v48
	v_ldexp_f32 v46, v46, v49
	v_ldexp_f32 v49, v50, v49
	v_add_f32_e32 v50, -1.0, v46
	v_add_f32_e32 v51, 1.0, v50
	v_sub_f32_e32 v51, v46, v51
	v_add_f32_e32 v51, v49, v51
	v_add_f32_e32 v52, v50, v51
	v_sub_f32_e32 v50, v50, v52
	v_add_f32_e32 v50, v51, v50
	v_add_f32_e32 v51, 1.0, v46
	v_add_f32_e32 v53, -1.0, v51
	v_sub_f32_e32 v46, v46, v53
	v_add_f32_e32 v46, v49, v46
	v_add_f32_e32 v49, v51, v46
	v_sub_f32_e32 v51, v51, v49
	v_add_f32_e32 v46, v46, v51
	v_rcp_f32_e32 v51, v49
	v_cvt_f32_i32_e32 v48, v48
	v_cmp_neq_f32_e32 vcc, s62, v45
	v_mul_f32_e32 v53, v52, v51
	v_mul_f32_e32 v54, v49, v53
	v_fma_f32 v55, v53, v49, -v54
	v_fmac_f32_e32 v55, v53, v46
	v_add_f32_e32 v72, v54, v55
	v_sub_f32_e32 v73, v52, v72
	v_sub_f32_e32 v52, v52, v73
	v_sub_f32_e32 v54, v72, v54
	v_sub_f32_e32 v52, v52, v72
	v_add_f32_e32 v50, v50, v52
	v_sub_f32_e32 v52, v54, v55
	v_add_f32_e32 v50, v52, v50
	v_add_f32_e32 v52, v73, v50
	v_mul_f32_e32 v54, v51, v52
	v_mul_f32_e32 v55, v49, v54
	v_fma_f32 v49, v54, v49, -v55
	v_fmac_f32_e32 v49, v54, v46
	v_sub_f32_e32 v46, v73, v52
	v_add_f32_e32 v46, v50, v46
	v_add_f32_e32 v50, v55, v49
	v_sub_f32_e32 v72, v52, v50
	v_sub_f32_e32 v52, v52, v72
	v_sub_f32_e32 v55, v50, v55
	v_sub_f32_e32 v50, v52, v50
	v_add_f32_e32 v46, v46, v50
	v_sub_f32_e32 v49, v55, v49
	v_add_f32_e32 v46, v49, v46
	v_add_f32_e32 v49, v53, v54
	v_add_f32_e32 v46, v72, v46
	v_sub_f32_e32 v50, v49, v53
	v_mul_f32_e32 v46, v51, v46
	v_sub_f32_e32 v50, v54, v50
	v_add_f32_e32 v46, v50, v46
	v_mul_f32_e32 v53, 0x3f317218, v48
	v_add_f32_e32 v50, v49, v46
	v_fma_f32 v54, v48, s78, -v53
	v_mul_f32_e32 v51, v50, v50
	v_fmac_f32_e32 v54, 0xb102e308, v48
	v_sub_f32_e32 v48, v50, v49
	v_fmamk_f32 v52, v51, 0x3e9b6dac, v185
	v_sub_f32_e32 v46, v46, v48
	v_add_f32_e32 v48, v53, v54
	v_fmaak_f32 v52, v51, v52, 0x3f2aaada
	v_sub_f32_e32 v49, v48, v53
	v_ldexp_f32 v53, v50, 1
	v_mul_f32_e32 v50, v50, v51
	v_mul_f32_e32 v50, v50, v52
	v_add_f32_e32 v51, v53, v50
	v_sub_f32_e32 v52, v51, v53
	v_ldexp_f32 v46, v46, 1
	v_sub_f32_e32 v50, v50, v52
	v_add_f32_e32 v46, v46, v50
	v_add_f32_e32 v50, v51, v46
	v_sub_f32_e32 v51, v50, v51
	v_sub_f32_e32 v46, v46, v51
	v_add_f32_e32 v51, v48, v50
	v_sub_f32_e32 v52, v51, v48
	v_sub_f32_e32 v53, v51, v52
	v_sub_f32_e32 v49, v54, v49
	v_sub_f32_e32 v48, v48, v53
	v_sub_f32_e32 v50, v50, v52
	v_add_f32_e32 v48, v50, v48
	v_add_f32_e32 v50, v49, v46
	v_sub_f32_e32 v52, v50, v49
	v_sub_f32_e32 v53, v50, v52
	v_sub_f32_e32 v49, v49, v53
	v_sub_f32_e32 v46, v46, v52
	v_add_f32_e32 v48, v50, v48
	v_add_f32_e32 v46, v46, v49
	v_add_f32_e32 v49, v51, v48
	v_sub_f32_e32 v50, v49, v51
	v_sub_f32_e32 v48, v48, v50
	v_add_f32_e32 v46, v46, v48
	v_add_f32_e32 v46, v49, v46
	v_cndmask_b32_e32 v46, v226, v46, vcc
	v_cmp_lt_f32_e64 vcc, |v45|, s63
	s_nop 1
	v_cndmask_b32_e32 v45, v46, v45, vcc
	v_sub_f32_e32 v44, v44, v45
	v_mul_f32_e32 v44, 0x3fb8aa3b, v44
	global_store_dword v[66:67], v44, off offset:128
	v_readlane_b32 s100, v254, 3
	s_nop 1
	v_mov_b32_e32 v45, s100
	v_fmac_f32_e32 v45, v47, v168
	v_mul_f32_e64 v46, |v45|, s94
	v_fma_f32 v47, |v45|, s94, -v46
	v_rndne_f32_e32 v48, v46
	v_fma_f32 v47, |v45|, s64, v47
	v_sub_f32_e32 v46, v46, v48
	v_add_f32_e32 v46, v46, v47
	v_exp_f32_e32 v46, v46
	v_cvt_i32_f32_e32 v47, v48
	v_cmp_ngt_f32_e64 vcc, |v45|, s58
	v_min_f32_e32 v44, 0, v45
	v_ldexp_f32 v46, v46, v47
	v_cndmask_b32_e32 v46, 0, v46, vcc
	v_cmp_nlt_f32_e64 vcc, |v45|, s59
	s_nop 1
	v_cndmask_b32_e32 v45, v226, v46, vcc
	v_add_f32_e32 v48, 1.0, v45
	v_add_f32_e32 v46, -1.0, v48
	v_sub_f32_e32 v47, v46, v48
	v_add_f32_e32 v47, 1.0, v47
	v_sub_f32_e32 v46, v45, v46
	v_add_f32_e32 v49, v46, v47
	v_frexp_mant_f32_e32 v46, v48
	v_cmp_gt_f32_e32 vcc, s77, v46
	v_cvt_f64_f32_e32 v[46:47], v48
	v_frexp_exp_i32_f64_e32 v46, v[46:47]
	v_subbrev_co_u32_e32 v46, vcc, 0, v46, vcc
	v_sub_u32_e32 v47, 0, v46
	v_ldexp_f32 v48, v48, v47
	v_ldexp_f32 v47, v49, v47
	v_add_f32_e32 v49, -1.0, v48
	v_add_f32_e32 v50, 1.0, v49
	v_sub_f32_e32 v50, v48, v50
	v_add_f32_e32 v50, v47, v50
	v_add_f32_e32 v51, v49, v50
	v_sub_f32_e32 v49, v49, v51
	v_add_f32_e32 v49, v50, v49
	v_add_f32_e32 v50, 1.0, v48
	v_add_f32_e32 v52, -1.0, v50
	v_sub_f32_e32 v48, v48, v52
	v_add_f32_e32 v47, v47, v48
	v_add_f32_e32 v48, v50, v47
	v_sub_f32_e32 v50, v50, v48
	v_add_f32_e32 v47, v47, v50
	v_rcp_f32_e32 v50, v48
	v_cvt_f32_i32_e32 v46, v46
	v_cmp_neq_f32_e32 vcc, s62, v45
	v_mul_f32_e32 v52, v51, v50
	v_mul_f32_e32 v53, v48, v52
	v_fma_f32 v54, v52, v48, -v53
	v_fmac_f32_e32 v54, v52, v47
	v_add_f32_e32 v55, v53, v54
	v_sub_f32_e32 v72, v51, v55
	v_sub_f32_e32 v51, v51, v72
	v_sub_f32_e32 v53, v55, v53
	v_sub_f32_e32 v51, v51, v55
	v_add_f32_e32 v49, v49, v51
	v_sub_f32_e32 v51, v53, v54
	v_add_f32_e32 v49, v51, v49
	v_add_f32_e32 v51, v72, v49
	v_mul_f32_e32 v53, v50, v51
	v_mul_f32_e32 v54, v48, v53
	v_fma_f32 v48, v53, v48, -v54
	v_fmac_f32_e32 v48, v53, v47
	v_sub_f32_e32 v47, v72, v51
	v_add_f32_e32 v47, v49, v47
	v_add_f32_e32 v49, v54, v48
	v_sub_f32_e32 v55, v51, v49
	v_sub_f32_e32 v51, v51, v55
	v_sub_f32_e32 v54, v49, v54
	v_sub_f32_e32 v49, v51, v49
	v_add_f32_e32 v47, v47, v49
	v_sub_f32_e32 v48, v54, v48
	v_add_f32_e32 v47, v48, v47
	v_add_f32_e32 v48, v52, v53
	v_add_f32_e32 v47, v55, v47
	v_sub_f32_e32 v49, v48, v52
	v_mul_f32_e32 v47, v50, v47
	v_sub_f32_e32 v49, v53, v49
	v_add_f32_e32 v47, v49, v47
	v_mul_f32_e32 v52, 0x3f317218, v46
	v_add_f32_e32 v49, v48, v47
	v_fma_f32 v53, v46, s78, -v52
	v_mul_f32_e32 v50, v49, v49
	v_fmac_f32_e32 v53, 0xb102e308, v46
	v_sub_f32_e32 v46, v49, v48
	v_fmamk_f32 v51, v50, 0x3e9b6dac, v185
	v_sub_f32_e32 v46, v47, v46
	v_add_f32_e32 v47, v52, v53
	v_fmaak_f32 v51, v50, v51, 0x3f2aaada
	v_sub_f32_e32 v48, v47, v52
	v_ldexp_f32 v52, v49, 1
	v_mul_f32_e32 v49, v49, v50
	v_mul_f32_e32 v49, v49, v51
	v_add_f32_e32 v50, v52, v49
	v_sub_f32_e32 v51, v50, v52
	v_ldexp_f32 v46, v46, 1
	v_sub_f32_e32 v49, v49, v51
	v_add_f32_e32 v46, v46, v49
	v_add_f32_e32 v49, v50, v46
	v_sub_f32_e32 v50, v49, v50
	v_sub_f32_e32 v46, v46, v50
	v_add_f32_e32 v50, v47, v49
	v_sub_f32_e32 v51, v50, v47
	v_sub_f32_e32 v52, v50, v51
	v_sub_f32_e32 v48, v53, v48
	v_sub_f32_e32 v47, v47, v52
	v_sub_f32_e32 v49, v49, v51
	v_add_f32_e32 v47, v49, v47
	v_add_f32_e32 v49, v48, v46
	v_sub_f32_e32 v51, v49, v48
	v_sub_f32_e32 v52, v49, v51
	v_sub_f32_e32 v48, v48, v52
	v_sub_f32_e32 v46, v46, v51
	v_add_f32_e32 v47, v49, v47
	v_add_f32_e32 v46, v46, v48
	v_add_f32_e32 v48, v50, v47
	v_sub_f32_e32 v49, v48, v50
	v_sub_f32_e32 v47, v47, v49
	v_add_f32_e32 v46, v46, v47
	v_add_f32_e32 v46, v48, v46
	v_cndmask_b32_e32 v46, v226, v46, vcc
	v_cmp_lt_f32_e64 vcc, |v45|, s63
	s_nop 1
	v_cndmask_b32_e32 v45, v46, v45, vcc
	v_sub_f32_e32 v44, v44, v45
	v_mul_f32_e32 v44, 0x3fb8aa3b, v44
	global_store_dword v[62:63], v44, off offset:128
	v_readlane_b32 s100, v254, 4
	s_nop 1
	v_mov_b32_e32 v44, s100
	v_fmac_f32_e32 v44, v40, v168
	v_mul_f32_e64 v45, |v44|, s94
	v_fma_f32 v46, |v44|, s94, -v45
	v_rndne_f32_e32 v47, v45
	v_fma_f32 v46, |v44|, s64, v46
	v_sub_f32_e32 v45, v45, v47
	v_add_f32_e32 v45, v45, v46
	v_exp_f32_e32 v45, v45
	v_cvt_i32_f32_e32 v46, v47
	v_cmp_ngt_f32_e64 vcc, |v44|, s58
	v_min_f32_e32 v40, 0, v44
	v_ldexp_f32 v45, v45, v46
	v_cndmask_b32_e32 v45, 0, v45, vcc
	v_cmp_nlt_f32_e64 vcc, |v44|, s59
	s_nop 1
	v_cndmask_b32_e32 v44, v226, v45, vcc
	v_add_f32_e32 v45, 1.0, v44
	v_add_f32_e32 v46, -1.0, v45
	v_sub_f32_e32 v47, v46, v45
	v_add_f32_e32 v47, 1.0, v47
	v_sub_f32_e32 v46, v44, v46
	v_add_f32_e32 v48, v46, v47
	v_frexp_mant_f32_e32 v46, v45
	v_cmp_gt_f32_e32 vcc, s77, v46
	v_cvt_f64_f32_e32 v[46:47], v45
	v_frexp_exp_i32_f64_e32 v46, v[46:47]
	v_subbrev_co_u32_e32 v46, vcc, 0, v46, vcc
	v_sub_u32_e32 v47, 0, v46
	v_ldexp_f32 v45, v45, v47
	v_ldexp_f32 v47, v48, v47
	v_add_f32_e32 v48, -1.0, v45
	v_add_f32_e32 v49, 1.0, v48
	v_sub_f32_e32 v49, v45, v49
	v_add_f32_e32 v49, v47, v49
	v_add_f32_e32 v50, v48, v49
	v_sub_f32_e32 v48, v48, v50
	v_add_f32_e32 v48, v49, v48
	v_add_f32_e32 v49, 1.0, v45
	v_add_f32_e32 v51, -1.0, v49
	v_sub_f32_e32 v45, v45, v51
	v_add_f32_e32 v45, v47, v45
	v_add_f32_e32 v47, v49, v45
	v_sub_f32_e32 v49, v49, v47
	v_add_f32_e32 v45, v45, v49
	v_rcp_f32_e32 v49, v47
	v_cvt_f32_i32_e32 v46, v46
	v_cmp_neq_f32_e32 vcc, s62, v44
	v_mul_f32_e32 v51, v50, v49
	v_mul_f32_e32 v52, v47, v51
	v_fma_f32 v53, v51, v47, -v52
	v_fmac_f32_e32 v53, v51, v45
	v_add_f32_e32 v54, v52, v53
	v_sub_f32_e32 v55, v50, v54
	v_sub_f32_e32 v50, v50, v55
	v_sub_f32_e32 v52, v54, v52
	v_sub_f32_e32 v50, v50, v54
	v_add_f32_e32 v48, v48, v50
	v_sub_f32_e32 v50, v52, v53
	v_add_f32_e32 v48, v50, v48
	v_add_f32_e32 v50, v55, v48
	v_mul_f32_e32 v52, v49, v50
	v_mul_f32_e32 v53, v47, v52
	v_fma_f32 v47, v52, v47, -v53
	v_fmac_f32_e32 v47, v52, v45
	v_sub_f32_e32 v45, v55, v50
	v_add_f32_e32 v45, v48, v45
	v_add_f32_e32 v48, v53, v47
	v_sub_f32_e32 v54, v50, v48
	v_sub_f32_e32 v50, v50, v54
	v_sub_f32_e32 v53, v48, v53
	v_sub_f32_e32 v48, v50, v48
	v_add_f32_e32 v45, v45, v48
	v_sub_f32_e32 v47, v53, v47
	v_add_f32_e32 v45, v47, v45
	v_add_f32_e32 v47, v51, v52
	v_add_f32_e32 v45, v54, v45
	v_sub_f32_e32 v48, v47, v51
	v_mul_f32_e32 v45, v49, v45
	v_sub_f32_e32 v48, v52, v48
	v_add_f32_e32 v45, v48, v45
	v_mul_f32_e32 v51, 0x3f317218, v46
	v_add_f32_e32 v48, v47, v45
	v_fma_f32 v52, v46, s78, -v51
	v_mul_f32_e32 v49, v48, v48
	v_fmac_f32_e32 v52, 0xb102e308, v46
	v_sub_f32_e32 v46, v48, v47
	v_fmamk_f32 v50, v49, 0x3e9b6dac, v185
	v_sub_f32_e32 v45, v45, v46
	v_add_f32_e32 v46, v51, v52
	v_fmaak_f32 v50, v49, v50, 0x3f2aaada
	v_sub_f32_e32 v47, v46, v51
	v_ldexp_f32 v51, v48, 1
	v_mul_f32_e32 v48, v48, v49
	v_mul_f32_e32 v48, v48, v50
	v_add_f32_e32 v49, v51, v48
	v_sub_f32_e32 v50, v49, v51
	v_ldexp_f32 v45, v45, 1
	v_sub_f32_e32 v48, v48, v50
	v_add_f32_e32 v45, v45, v48
	v_add_f32_e32 v48, v49, v45
	v_sub_f32_e32 v49, v48, v49
	v_sub_f32_e32 v45, v45, v49
	v_add_f32_e32 v49, v46, v48
	v_sub_f32_e32 v50, v49, v46
	v_sub_f32_e32 v51, v49, v50
	v_sub_f32_e32 v47, v52, v47
	v_sub_f32_e32 v46, v46, v51
	v_sub_f32_e32 v48, v48, v50
	v_add_f32_e32 v46, v48, v46
	v_add_f32_e32 v48, v47, v45
	v_sub_f32_e32 v50, v48, v47
	v_sub_f32_e32 v51, v48, v50
	v_sub_f32_e32 v47, v47, v51
	v_sub_f32_e32 v45, v45, v50
	v_add_f32_e32 v46, v48, v46
	v_add_f32_e32 v45, v45, v47
	v_add_f32_e32 v47, v49, v46
	v_sub_f32_e32 v48, v47, v49
	v_sub_f32_e32 v46, v46, v48
	v_add_f32_e32 v45, v45, v46
	v_add_f32_e32 v45, v47, v45
	v_cndmask_b32_e32 v45, v226, v45, vcc
	v_cmp_lt_f32_e64 vcc, |v44|, s63
	s_nop 1
	v_cndmask_b32_e32 v44, v45, v44, vcc
	v_sub_f32_e32 v40, v40, v44
	v_mul_f32_e32 v40, 0x3fb8aa3b, v40
	global_store_dword v[68:69], v40, off offset:128
	v_readlane_b32 s100, v254, 5
	s_nop 1
	v_mov_b32_e32 v44, s100
	v_fmac_f32_e32 v44, v41, v168
	v_mul_f32_e64 v41, |v44|, s94
	v_fma_f32 v45, |v44|, s94, -v41
	v_rndne_f32_e32 v46, v41
	v_fma_f32 v45, |v44|, s64, v45
	v_sub_f32_e32 v41, v41, v46
	v_add_f32_e32 v41, v41, v45
	v_exp_f32_e32 v41, v41
	v_cvt_i32_f32_e32 v45, v46
	v_cmp_ngt_f32_e64 vcc, |v44|, s58
	v_min_f32_e32 v40, 0, v44
	v_ldexp_f32 v41, v41, v45
	v_cndmask_b32_e32 v41, 0, v41, vcc
	v_cmp_nlt_f32_e64 vcc, |v44|, s59
	s_nop 1
	v_cndmask_b32_e32 v41, v226, v41, vcc
	v_add_f32_e32 v46, 1.0, v41
	v_add_f32_e32 v44, -1.0, v46
	v_sub_f32_e32 v45, v44, v46
	v_add_f32_e32 v45, 1.0, v45
	v_sub_f32_e32 v44, v41, v44
	v_add_f32_e32 v47, v44, v45
	v_frexp_mant_f32_e32 v44, v46
	v_cmp_gt_f32_e32 vcc, s77, v44
	v_cvt_f64_f32_e32 v[44:45], v46
	v_frexp_exp_i32_f64_e32 v44, v[44:45]
	v_subbrev_co_u32_e32 v44, vcc, 0, v44, vcc
	v_sub_u32_e32 v45, 0, v44
	v_ldexp_f32 v46, v46, v45
	v_ldexp_f32 v45, v47, v45
	v_add_f32_e32 v47, -1.0, v46
	v_add_f32_e32 v48, 1.0, v47
	v_sub_f32_e32 v48, v46, v48
	v_add_f32_e32 v48, v45, v48
	v_add_f32_e32 v49, v47, v48
	v_sub_f32_e32 v47, v47, v49
	v_add_f32_e32 v47, v48, v47
	v_add_f32_e32 v48, 1.0, v46
	v_add_f32_e32 v50, -1.0, v48
	v_sub_f32_e32 v46, v46, v50
	v_add_f32_e32 v45, v45, v46
	v_add_f32_e32 v46, v48, v45
	v_sub_f32_e32 v48, v48, v46
	v_add_f32_e32 v45, v45, v48
	v_rcp_f32_e32 v48, v46
	v_cvt_f32_i32_e32 v44, v44
	v_cmp_neq_f32_e32 vcc, s62, v41
	v_mul_f32_e32 v50, v49, v48
	v_mul_f32_e32 v51, v46, v50
	v_fma_f32 v52, v50, v46, -v51
	v_fmac_f32_e32 v52, v50, v45
	v_add_f32_e32 v53, v51, v52
	v_sub_f32_e32 v54, v49, v53
	v_sub_f32_e32 v49, v49, v54
	v_sub_f32_e32 v51, v53, v51
	v_sub_f32_e32 v49, v49, v53
	v_add_f32_e32 v47, v47, v49
	v_sub_f32_e32 v49, v51, v52
	v_add_f32_e32 v47, v49, v47
	v_add_f32_e32 v49, v54, v47
	v_mul_f32_e32 v51, v48, v49
	v_mul_f32_e32 v52, v46, v51
	v_fma_f32 v46, v51, v46, -v52
	v_fmac_f32_e32 v46, v51, v45
	v_sub_f32_e32 v45, v54, v49
	v_add_f32_e32 v45, v47, v45
	v_add_f32_e32 v47, v52, v46
	v_sub_f32_e32 v53, v49, v47
	v_sub_f32_e32 v49, v49, v53
	v_sub_f32_e32 v52, v47, v52
	v_sub_f32_e32 v47, v49, v47
	v_add_f32_e32 v45, v45, v47
	v_sub_f32_e32 v46, v52, v46
	v_add_f32_e32 v45, v46, v45
	v_add_f32_e32 v46, v50, v51
	v_add_f32_e32 v45, v53, v45
	v_sub_f32_e32 v47, v46, v50
	v_mul_f32_e32 v45, v48, v45
	v_sub_f32_e32 v47, v51, v47
	v_add_f32_e32 v45, v47, v45
	v_mul_f32_e32 v50, 0x3f317218, v44
	v_add_f32_e32 v47, v46, v45
	v_fma_f32 v51, v44, s78, -v50
	v_mul_f32_e32 v48, v47, v47
	v_fmac_f32_e32 v51, 0xb102e308, v44
	v_sub_f32_e32 v44, v47, v46
	v_fmamk_f32 v49, v48, 0x3e9b6dac, v185
	v_sub_f32_e32 v44, v45, v44
	v_add_f32_e32 v45, v50, v51
	v_fmaak_f32 v49, v48, v49, 0x3f2aaada
	v_sub_f32_e32 v46, v45, v50
	v_ldexp_f32 v50, v47, 1
	v_mul_f32_e32 v47, v47, v48
	v_mul_f32_e32 v47, v47, v49
	v_add_f32_e32 v48, v50, v47
	v_sub_f32_e32 v49, v48, v50
	v_ldexp_f32 v44, v44, 1
	v_sub_f32_e32 v47, v47, v49
	v_add_f32_e32 v44, v44, v47
	v_add_f32_e32 v47, v48, v44
	v_sub_f32_e32 v48, v47, v48
	v_sub_f32_e32 v44, v44, v48
	v_add_f32_e32 v48, v45, v47
	v_sub_f32_e32 v49, v48, v45
	v_sub_f32_e32 v50, v48, v49
	v_sub_f32_e32 v46, v51, v46
	v_sub_f32_e32 v45, v45, v50
	v_sub_f32_e32 v47, v47, v49
	v_add_f32_e32 v45, v47, v45
	v_add_f32_e32 v47, v46, v44
	v_sub_f32_e32 v49, v47, v46
	v_sub_f32_e32 v50, v47, v49
	v_sub_f32_e32 v46, v46, v50
	v_sub_f32_e32 v44, v44, v49
	v_add_f32_e32 v45, v47, v45
	v_add_f32_e32 v44, v44, v46
	v_add_f32_e32 v46, v48, v45
	v_sub_f32_e32 v47, v46, v48
	v_sub_f32_e32 v45, v45, v47
	v_add_f32_e32 v44, v44, v45
	v_add_f32_e32 v44, v46, v44
	v_cndmask_b32_e32 v44, v226, v44, vcc
	v_cmp_lt_f32_e64 vcc, |v41|, s63
	s_nop 1
	v_cndmask_b32_e32 v41, v44, v41, vcc
	v_sub_f32_e32 v40, v40, v41
	v_mul_f32_e32 v40, 0x3fb8aa3b, v40
	global_store_dword v[56:57], v40, off offset:128
	v_readlane_b32 s100, v254, 6
	s_nop 1
	v_mov_b32_e32 v41, s100
	v_fmac_f32_e32 v41, v42, v168
	v_mul_f32_e64 v42, |v41|, s94
	v_fma_f32 v44, |v41|, s94, -v42
	v_rndne_f32_e32 v45, v42
	v_fma_f32 v44, |v41|, s64, v44
	v_sub_f32_e32 v42, v42, v45
	v_add_f32_e32 v42, v42, v44
	v_exp_f32_e32 v42, v42
	v_cvt_i32_f32_e32 v44, v45
	v_cmp_ngt_f32_e64 vcc, |v41|, s58
	v_min_f32_e32 v40, 0, v41
	v_ldexp_f32 v42, v42, v44
	v_cndmask_b32_e32 v42, 0, v42, vcc
	v_cmp_nlt_f32_e64 vcc, |v41|, s59
	s_nop 1
	v_cndmask_b32_e32 v41, v226, v42, vcc
	v_add_f32_e32 v42, 1.0, v41
	v_add_f32_e32 v44, -1.0, v42
	v_sub_f32_e32 v45, v44, v42
	v_add_f32_e32 v45, 1.0, v45
	v_sub_f32_e32 v44, v41, v44
	v_add_f32_e32 v46, v44, v45
	v_frexp_mant_f32_e32 v44, v42
	v_cmp_gt_f32_e32 vcc, s77, v44
	v_cvt_f64_f32_e32 v[44:45], v42
	v_frexp_exp_i32_f64_e32 v44, v[44:45]
	v_subbrev_co_u32_e32 v44, vcc, 0, v44, vcc
	v_sub_u32_e32 v45, 0, v44
	v_ldexp_f32 v42, v42, v45
	v_ldexp_f32 v45, v46, v45
	v_add_f32_e32 v46, -1.0, v42
	v_add_f32_e32 v47, 1.0, v46
	v_sub_f32_e32 v47, v42, v47
	v_add_f32_e32 v47, v45, v47
	v_add_f32_e32 v48, v46, v47
	v_sub_f32_e32 v46, v46, v48
	v_add_f32_e32 v46, v47, v46
	v_add_f32_e32 v47, 1.0, v42
	v_add_f32_e32 v49, -1.0, v47
	v_sub_f32_e32 v42, v42, v49
	v_add_f32_e32 v42, v45, v42
	v_add_f32_e32 v45, v47, v42
	v_sub_f32_e32 v47, v47, v45
	v_add_f32_e32 v42, v42, v47
	v_rcp_f32_e32 v47, v45
	v_cvt_f32_i32_e32 v44, v44
	v_cmp_neq_f32_e32 vcc, s62, v41
	v_mul_f32_e32 v49, v48, v47
	v_mul_f32_e32 v50, v45, v49
	v_fma_f32 v51, v49, v45, -v50
	v_fmac_f32_e32 v51, v49, v42
	v_add_f32_e32 v52, v50, v51
	v_sub_f32_e32 v53, v48, v52
	v_sub_f32_e32 v48, v48, v53
	v_sub_f32_e32 v50, v52, v50
	v_sub_f32_e32 v48, v48, v52
	v_add_f32_e32 v46, v46, v48
	v_sub_f32_e32 v48, v50, v51
	v_add_f32_e32 v46, v48, v46
	v_add_f32_e32 v48, v53, v46
	v_mul_f32_e32 v50, v47, v48
	v_mul_f32_e32 v51, v45, v50
	v_fma_f32 v45, v50, v45, -v51
	v_fmac_f32_e32 v45, v50, v42
	v_sub_f32_e32 v42, v53, v48
	v_add_f32_e32 v42, v46, v42
	v_add_f32_e32 v46, v51, v45
	v_sub_f32_e32 v52, v48, v46
	v_sub_f32_e32 v48, v48, v52
	v_sub_f32_e32 v51, v46, v51
	v_sub_f32_e32 v46, v48, v46
	v_add_f32_e32 v42, v42, v46
	v_sub_f32_e32 v45, v51, v45
	v_add_f32_e32 v42, v45, v42
	v_add_f32_e32 v45, v49, v50
	v_add_f32_e32 v42, v52, v42
	v_sub_f32_e32 v46, v45, v49
	v_mul_f32_e32 v42, v47, v42
	v_sub_f32_e32 v46, v50, v46
	v_add_f32_e32 v42, v46, v42
	v_mul_f32_e32 v49, 0x3f317218, v44
	v_add_f32_e32 v46, v45, v42
	v_fma_f32 v50, v44, s78, -v49
	v_mul_f32_e32 v47, v46, v46
	v_fmac_f32_e32 v50, 0xb102e308, v44
	v_sub_f32_e32 v44, v46, v45
	v_fmamk_f32 v48, v47, 0x3e9b6dac, v185
	v_sub_f32_e32 v42, v42, v44
	v_add_f32_e32 v44, v49, v50
	v_fmaak_f32 v48, v47, v48, 0x3f2aaada
	v_sub_f32_e32 v45, v44, v49
	v_ldexp_f32 v49, v46, 1
	v_mul_f32_e32 v46, v46, v47
	v_mul_f32_e32 v46, v46, v48
	v_add_f32_e32 v47, v49, v46
	v_sub_f32_e32 v48, v47, v49
	v_ldexp_f32 v42, v42, 1
	v_sub_f32_e32 v46, v46, v48
	v_add_f32_e32 v42, v42, v46
	v_add_f32_e32 v46, v47, v42
	v_sub_f32_e32 v47, v46, v47
	v_sub_f32_e32 v42, v42, v47
	v_add_f32_e32 v47, v44, v46
	v_sub_f32_e32 v48, v47, v44
	v_sub_f32_e32 v49, v47, v48
	v_sub_f32_e32 v45, v50, v45
	v_sub_f32_e32 v44, v44, v49
	v_sub_f32_e32 v46, v46, v48
	v_add_f32_e32 v44, v46, v44
	v_add_f32_e32 v46, v45, v42
	v_sub_f32_e32 v48, v46, v45
	v_sub_f32_e32 v49, v46, v48
	v_sub_f32_e32 v45, v45, v49
	v_sub_f32_e32 v42, v42, v48
	v_add_f32_e32 v44, v46, v44
	v_add_f32_e32 v42, v42, v45
	v_add_f32_e32 v45, v47, v44
	v_sub_f32_e32 v46, v45, v47
	v_sub_f32_e32 v44, v44, v46
	v_add_f32_e32 v42, v42, v44
	v_add_f32_e32 v42, v45, v42
	v_cndmask_b32_e32 v42, v226, v42, vcc
	v_cmp_lt_f32_e64 vcc, |v41|, s63
	s_nop 1
	v_cndmask_b32_e32 v41, v42, v41, vcc
	v_sub_f32_e32 v40, v40, v41
	v_mul_f32_e32 v40, 0x3fb8aa3b, v40
	global_store_dword v[70:71], v40, off offset:128
	v_readlane_b32 s100, v254, 7
	s_nop 1
	v_mov_b32_e32 v41, s100
	v_fmac_f32_e32 v41, v43, v168
	v_mul_f32_e64 v42, |v41|, s94
	v_fma_f32 v43, |v41|, s94, -v42
	v_rndne_f32_e32 v44, v42
	v_fma_f32 v43, |v41|, s64, v43
	v_sub_f32_e32 v42, v42, v44
	v_add_f32_e32 v42, v42, v43
	v_exp_f32_e32 v42, v42
	v_cvt_i32_f32_e32 v43, v44
	v_cmp_ngt_f32_e64 vcc, |v41|, s58
	v_min_f32_e32 v40, 0, v41
	v_ldexp_f32 v42, v42, v43
	v_cndmask_b32_e32 v42, 0, v42, vcc
	v_cmp_nlt_f32_e64 vcc, |v41|, s59
	s_nop 1
	v_cndmask_b32_e32 v41, v226, v42, vcc
	v_add_f32_e32 v44, 1.0, v41
	v_add_f32_e32 v42, -1.0, v44
	v_sub_f32_e32 v43, v42, v44
	v_add_f32_e32 v43, 1.0, v43
	v_sub_f32_e32 v42, v41, v42
	v_add_f32_e32 v45, v42, v43
	v_frexp_mant_f32_e32 v42, v44
	v_cmp_gt_f32_e32 vcc, s77, v42
	v_cvt_f64_f32_e32 v[42:43], v44
	v_frexp_exp_i32_f64_e32 v42, v[42:43]
	v_subbrev_co_u32_e32 v42, vcc, 0, v42, vcc
	v_sub_u32_e32 v43, 0, v42
	v_ldexp_f32 v44, v44, v43
	v_ldexp_f32 v43, v45, v43
	v_add_f32_e32 v45, -1.0, v44
	v_add_f32_e32 v46, 1.0, v45
	v_sub_f32_e32 v46, v44, v46
	v_add_f32_e32 v46, v43, v46
	v_add_f32_e32 v47, v45, v46
	v_sub_f32_e32 v45, v45, v47
	v_add_f32_e32 v45, v46, v45
	v_add_f32_e32 v46, 1.0, v44
	v_add_f32_e32 v48, -1.0, v46
	v_sub_f32_e32 v44, v44, v48
	v_add_f32_e32 v43, v43, v44
	v_add_f32_e32 v44, v46, v43
	v_sub_f32_e32 v46, v46, v44
	v_add_f32_e32 v43, v43, v46
	v_rcp_f32_e32 v46, v44
	v_cvt_f32_i32_e32 v42, v42
	v_cmp_neq_f32_e32 vcc, s62, v41
	v_mul_f32_e32 v48, v47, v46
	v_mul_f32_e32 v49, v44, v48
	v_fma_f32 v50, v48, v44, -v49
	v_fmac_f32_e32 v50, v48, v43
	v_add_f32_e32 v51, v49, v50
	v_sub_f32_e32 v52, v47, v51
	v_sub_f32_e32 v47, v47, v52
	v_sub_f32_e32 v49, v51, v49
	v_sub_f32_e32 v47, v47, v51
	v_add_f32_e32 v45, v45, v47
	v_sub_f32_e32 v47, v49, v50
	v_add_f32_e32 v45, v47, v45
	v_add_f32_e32 v47, v52, v45
	v_mul_f32_e32 v49, v46, v47
	v_mul_f32_e32 v50, v44, v49
	v_fma_f32 v44, v49, v44, -v50
	v_fmac_f32_e32 v44, v49, v43
	v_sub_f32_e32 v43, v52, v47
	v_add_f32_e32 v43, v45, v43
	v_add_f32_e32 v45, v50, v44
	v_sub_f32_e32 v51, v47, v45
	v_sub_f32_e32 v47, v47, v51
	v_sub_f32_e32 v50, v45, v50
	v_sub_f32_e32 v45, v47, v45
	v_add_f32_e32 v43, v43, v45
	v_sub_f32_e32 v44, v50, v44
	v_add_f32_e32 v43, v44, v43
	v_add_f32_e32 v44, v48, v49
	v_add_f32_e32 v43, v51, v43
	v_sub_f32_e32 v45, v44, v48
	v_mul_f32_e32 v43, v46, v43
	v_sub_f32_e32 v45, v49, v45
	v_add_f32_e32 v43, v45, v43
	v_mul_f32_e32 v48, 0x3f317218, v42
	v_add_f32_e32 v45, v44, v43
	v_fma_f32 v49, v42, s78, -v48
	v_mul_f32_e32 v46, v45, v45
	v_fmac_f32_e32 v49, 0xb102e308, v42
	v_sub_f32_e32 v42, v45, v44
	v_fmamk_f32 v47, v46, 0x3e9b6dac, v185
	v_sub_f32_e32 v42, v43, v42
	v_add_f32_e32 v43, v48, v49
	v_fmaak_f32 v47, v46, v47, 0x3f2aaada
	v_sub_f32_e32 v44, v43, v48
	v_ldexp_f32 v48, v45, 1
	v_mul_f32_e32 v45, v45, v46
	v_mul_f32_e32 v45, v45, v47
	v_add_f32_e32 v46, v48, v45
	v_sub_f32_e32 v47, v46, v48
	v_ldexp_f32 v42, v42, 1
	v_sub_f32_e32 v45, v45, v47
	v_add_f32_e32 v42, v42, v45
	v_add_f32_e32 v45, v46, v42
	v_sub_f32_e32 v46, v45, v46
	v_sub_f32_e32 v42, v42, v46
	v_add_f32_e32 v46, v43, v45
	v_sub_f32_e32 v47, v46, v43
	v_sub_f32_e32 v48, v46, v47
	v_sub_f32_e32 v44, v49, v44
	v_sub_f32_e32 v43, v43, v48
	v_sub_f32_e32 v45, v45, v47
	v_add_f32_e32 v43, v45, v43
	v_add_f32_e32 v45, v44, v42
	v_sub_f32_e32 v47, v45, v44
	v_sub_f32_e32 v48, v45, v47
	v_sub_f32_e32 v44, v44, v48
	v_sub_f32_e32 v42, v42, v47
	v_add_f32_e32 v43, v45, v43
	v_add_f32_e32 v42, v42, v44
	v_add_f32_e32 v44, v46, v43
	v_sub_f32_e32 v45, v44, v46
	v_sub_f32_e32 v43, v43, v45
	v_add_f32_e32 v42, v42, v43
	v_add_f32_e32 v42, v44, v42
	v_cndmask_b32_e32 v42, v226, v42, vcc
	v_cmp_lt_f32_e64 vcc, |v41|, s63
	s_nop 1
	v_cndmask_b32_e32 v41, v42, v41, vcc
	v_sub_f32_e32 v40, v40, v41
	v_mul_f32_e32 v40, 0x3fb8aa3b, v40
	global_store_dword v[58:59], v40, off offset:128
	v_readlane_b32 s100, v254, 0
	s_nop 1
	v_mov_b32_e32 v40, s100
	v_fmac_f32_e32 v40, v36, v166
	v_mul_f32_e64 v41, |v40|, s94
	v_fma_f32 v42, |v40|, s94, -v41
	v_rndne_f32_e32 v43, v41
	v_fma_f32 v42, |v40|, s64, v42
	v_sub_f32_e32 v41, v41, v43
	v_add_f32_e32 v41, v41, v42
	v_exp_f32_e32 v41, v41
	v_cvt_i32_f32_e32 v42, v43
	v_cmp_ngt_f32_e64 vcc, |v40|, s58
	v_min_f32_e32 v36, 0, v40
	v_ldexp_f32 v41, v41, v42
	v_cndmask_b32_e32 v41, 0, v41, vcc
	v_cmp_nlt_f32_e64 vcc, |v40|, s59
	s_nop 1
	v_cndmask_b32_e32 v40, v226, v41, vcc
	v_add_f32_e32 v41, 1.0, v40
	v_add_f32_e32 v42, -1.0, v41
	v_sub_f32_e32 v43, v42, v41
	v_add_f32_e32 v43, 1.0, v43
	v_sub_f32_e32 v42, v40, v42
	v_add_f32_e32 v44, v42, v43
	v_frexp_mant_f32_e32 v42, v41
	v_cmp_gt_f32_e32 vcc, s77, v42
	v_cvt_f64_f32_e32 v[42:43], v41
	v_frexp_exp_i32_f64_e32 v42, v[42:43]
	v_subbrev_co_u32_e32 v42, vcc, 0, v42, vcc
	v_sub_u32_e32 v43, 0, v42
	v_ldexp_f32 v41, v41, v43
	v_ldexp_f32 v43, v44, v43
	v_add_f32_e32 v44, -1.0, v41
	v_add_f32_e32 v45, 1.0, v44
	v_sub_f32_e32 v45, v41, v45
	v_add_f32_e32 v45, v43, v45
	v_add_f32_e32 v46, v44, v45
	v_sub_f32_e32 v44, v44, v46
	v_add_f32_e32 v44, v45, v44
	v_add_f32_e32 v45, 1.0, v41
	v_add_f32_e32 v47, -1.0, v45
	v_sub_f32_e32 v41, v41, v47
	v_add_f32_e32 v41, v43, v41
	v_add_f32_e32 v43, v45, v41
	v_sub_f32_e32 v45, v45, v43
	v_add_f32_e32 v41, v41, v45
	v_rcp_f32_e32 v45, v43
	v_cvt_f32_i32_e32 v42, v42
	v_cmp_neq_f32_e32 vcc, s62, v40
	v_mul_f32_e32 v47, v46, v45
	v_mul_f32_e32 v48, v43, v47
	v_fma_f32 v49, v47, v43, -v48
	v_fmac_f32_e32 v49, v47, v41
	v_add_f32_e32 v50, v48, v49
	v_sub_f32_e32 v51, v46, v50
	v_sub_f32_e32 v46, v46, v51
	v_sub_f32_e32 v48, v50, v48
	v_sub_f32_e32 v46, v46, v50
	v_add_f32_e32 v44, v44, v46
	v_sub_f32_e32 v46, v48, v49
	v_add_f32_e32 v44, v46, v44
	v_add_f32_e32 v46, v51, v44
	v_mul_f32_e32 v48, v45, v46
	v_mul_f32_e32 v49, v43, v48
	v_fma_f32 v43, v48, v43, -v49
	v_fmac_f32_e32 v43, v48, v41
	v_sub_f32_e32 v41, v51, v46
	v_add_f32_e32 v41, v44, v41
	v_add_f32_e32 v44, v49, v43
	v_sub_f32_e32 v50, v46, v44
	v_sub_f32_e32 v46, v46, v50
	v_sub_f32_e32 v49, v44, v49
	v_sub_f32_e32 v44, v46, v44
	v_add_f32_e32 v41, v41, v44
	v_sub_f32_e32 v43, v49, v43
	v_add_f32_e32 v41, v43, v41
	v_add_f32_e32 v43, v47, v48
	v_add_f32_e32 v41, v50, v41
	v_sub_f32_e32 v44, v43, v47
	v_mul_f32_e32 v41, v45, v41
	v_sub_f32_e32 v44, v48, v44
	v_add_f32_e32 v41, v44, v41
	v_mul_f32_e32 v47, 0x3f317218, v42
	v_add_f32_e32 v44, v43, v41
	v_fma_f32 v48, v42, s78, -v47
	v_mul_f32_e32 v45, v44, v44
	v_fmac_f32_e32 v48, 0xb102e308, v42
	v_sub_f32_e32 v42, v44, v43
	v_fmamk_f32 v46, v45, 0x3e9b6dac, v185
	v_sub_f32_e32 v41, v41, v42
	v_add_f32_e32 v42, v47, v48
	v_fmaak_f32 v46, v45, v46, 0x3f2aaada
	v_sub_f32_e32 v43, v42, v47
	v_ldexp_f32 v47, v44, 1
	v_mul_f32_e32 v44, v44, v45
	v_mul_f32_e32 v44, v44, v46
	v_add_f32_e32 v45, v47, v44
	v_sub_f32_e32 v46, v45, v47
	v_ldexp_f32 v41, v41, 1
	v_sub_f32_e32 v44, v44, v46
	v_add_f32_e32 v41, v41, v44
	v_add_f32_e32 v44, v45, v41
	v_sub_f32_e32 v45, v44, v45
	v_sub_f32_e32 v41, v41, v45
	v_add_f32_e32 v45, v42, v44
	v_sub_f32_e32 v46, v45, v42
	v_sub_f32_e32 v47, v45, v46
	v_sub_f32_e32 v43, v48, v43
	v_sub_f32_e32 v42, v42, v47
	v_sub_f32_e32 v44, v44, v46
	v_add_f32_e32 v42, v44, v42
	v_add_f32_e32 v44, v43, v41
	v_sub_f32_e32 v46, v44, v43
	v_sub_f32_e32 v47, v44, v46
	v_sub_f32_e32 v43, v43, v47
	v_sub_f32_e32 v41, v41, v46
	v_add_f32_e32 v42, v44, v42
	v_add_f32_e32 v41, v41, v43
	v_add_f32_e32 v43, v45, v42
	v_sub_f32_e32 v44, v43, v45
	v_sub_f32_e32 v42, v42, v44
	v_add_f32_e32 v41, v41, v42
	v_add_f32_e32 v41, v43, v41
	v_cndmask_b32_e32 v41, v226, v41, vcc
	v_cmp_lt_f32_e64 vcc, |v40|, s63
	s_nop 1
	v_cndmask_b32_e32 v40, v41, v40, vcc
	v_sub_f32_e32 v36, v36, v40
	v_mul_f32_e32 v36, 0x3fb8aa3b, v36
	global_store_dword v[64:65], v36, off offset:192
	v_readlane_b32 s100, v254, 1
	s_nop 1
	v_mov_b32_e32 v40, s100
	v_fmac_f32_e32 v40, v37, v166
	v_mul_f32_e64 v37, |v40|, s94
	v_fma_f32 v41, |v40|, s94, -v37
	v_rndne_f32_e32 v42, v37
	v_fma_f32 v41, |v40|, s64, v41
	v_sub_f32_e32 v37, v37, v42
	v_add_f32_e32 v37, v37, v41
	v_exp_f32_e32 v37, v37
	v_cvt_i32_f32_e32 v41, v42
	v_cmp_ngt_f32_e64 vcc, |v40|, s58
	v_min_f32_e32 v36, 0, v40
	v_ldexp_f32 v37, v37, v41
	v_cndmask_b32_e32 v37, 0, v37, vcc
	v_cmp_nlt_f32_e64 vcc, |v40|, s59
	s_nop 1
	v_cndmask_b32_e32 v37, v226, v37, vcc
	v_add_f32_e32 v42, 1.0, v37
	v_add_f32_e32 v40, -1.0, v42
	v_sub_f32_e32 v41, v40, v42
	v_add_f32_e32 v41, 1.0, v41
	v_sub_f32_e32 v40, v37, v40
	v_add_f32_e32 v43, v40, v41
	v_frexp_mant_f32_e32 v40, v42
	v_cmp_gt_f32_e32 vcc, s77, v40
	v_cvt_f64_f32_e32 v[40:41], v42
	v_frexp_exp_i32_f64_e32 v40, v[40:41]
	v_subbrev_co_u32_e32 v40, vcc, 0, v40, vcc
	v_sub_u32_e32 v41, 0, v40
	v_ldexp_f32 v42, v42, v41
	v_ldexp_f32 v41, v43, v41
	v_add_f32_e32 v43, -1.0, v42
	v_add_f32_e32 v44, 1.0, v43
	v_sub_f32_e32 v44, v42, v44
	v_add_f32_e32 v44, v41, v44
	v_add_f32_e32 v45, v43, v44
	v_sub_f32_e32 v43, v43, v45
	v_add_f32_e32 v43, v44, v43
	v_add_f32_e32 v44, 1.0, v42
	v_add_f32_e32 v46, -1.0, v44
	v_sub_f32_e32 v42, v42, v46
	v_add_f32_e32 v41, v41, v42
	v_add_f32_e32 v42, v44, v41
	v_sub_f32_e32 v44, v44, v42
	v_add_f32_e32 v41, v41, v44
	v_rcp_f32_e32 v44, v42
	v_cvt_f32_i32_e32 v40, v40
	v_cmp_neq_f32_e32 vcc, s62, v37
	v_mul_f32_e32 v46, v45, v44
	v_mul_f32_e32 v47, v42, v46
	v_fma_f32 v48, v46, v42, -v47
	v_fmac_f32_e32 v48, v46, v41
	v_add_f32_e32 v49, v47, v48
	v_sub_f32_e32 v50, v45, v49
	v_sub_f32_e32 v45, v45, v50
	v_sub_f32_e32 v47, v49, v47
	v_sub_f32_e32 v45, v45, v49
	v_add_f32_e32 v43, v43, v45
	v_sub_f32_e32 v45, v47, v48
	v_add_f32_e32 v43, v45, v43
	v_add_f32_e32 v45, v50, v43
	v_mul_f32_e32 v47, v44, v45
	v_mul_f32_e32 v48, v42, v47
	v_fma_f32 v42, v47, v42, -v48
	v_fmac_f32_e32 v42, v47, v41
	v_sub_f32_e32 v41, v50, v45
	v_add_f32_e32 v41, v43, v41
	v_add_f32_e32 v43, v48, v42
	v_sub_f32_e32 v49, v45, v43
	v_sub_f32_e32 v45, v45, v49
	v_sub_f32_e32 v48, v43, v48
	v_sub_f32_e32 v43, v45, v43
	v_add_f32_e32 v41, v41, v43
	v_sub_f32_e32 v42, v48, v42
	v_add_f32_e32 v41, v42, v41
	v_add_f32_e32 v42, v46, v47
	v_add_f32_e32 v41, v49, v41
	v_sub_f32_e32 v43, v42, v46
	v_mul_f32_e32 v41, v44, v41
	v_sub_f32_e32 v43, v47, v43
	v_add_f32_e32 v41, v43, v41
	v_mul_f32_e32 v46, 0x3f317218, v40
	v_add_f32_e32 v43, v42, v41
	v_fma_f32 v47, v40, s78, -v46
	v_mul_f32_e32 v44, v43, v43
	v_fmac_f32_e32 v47, 0xb102e308, v40
	v_sub_f32_e32 v40, v43, v42
	v_fmamk_f32 v45, v44, 0x3e9b6dac, v185
	v_sub_f32_e32 v40, v41, v40
	v_add_f32_e32 v41, v46, v47
	v_fmaak_f32 v45, v44, v45, 0x3f2aaada
	v_sub_f32_e32 v42, v41, v46
	v_ldexp_f32 v46, v43, 1
	v_mul_f32_e32 v43, v43, v44
	v_mul_f32_e32 v43, v43, v45
	v_add_f32_e32 v44, v46, v43
	v_sub_f32_e32 v45, v44, v46
	v_ldexp_f32 v40, v40, 1
	v_sub_f32_e32 v43, v43, v45
	v_add_f32_e32 v40, v40, v43
	v_add_f32_e32 v43, v44, v40
	v_sub_f32_e32 v44, v43, v44
	v_sub_f32_e32 v40, v40, v44
	v_add_f32_e32 v44, v41, v43
	v_sub_f32_e32 v45, v44, v41
	v_sub_f32_e32 v46, v44, v45
	v_sub_f32_e32 v42, v47, v42
	v_sub_f32_e32 v41, v41, v46
	v_sub_f32_e32 v43, v43, v45
	v_add_f32_e32 v41, v43, v41
	v_add_f32_e32 v43, v42, v40
	v_sub_f32_e32 v45, v43, v42
	v_sub_f32_e32 v46, v43, v45
	v_sub_f32_e32 v42, v42, v46
	v_sub_f32_e32 v40, v40, v45
	v_add_f32_e32 v41, v43, v41
	v_add_f32_e32 v40, v40, v42
	v_add_f32_e32 v42, v44, v41
	v_sub_f32_e32 v43, v42, v44
	v_sub_f32_e32 v41, v41, v43
	v_add_f32_e32 v40, v40, v41
	v_add_f32_e32 v40, v42, v40
	v_cndmask_b32_e32 v40, v226, v40, vcc
	v_cmp_lt_f32_e64 vcc, |v37|, s63
	s_nop 1
	v_cndmask_b32_e32 v37, v40, v37, vcc
	v_sub_f32_e32 v36, v36, v37
	v_mul_f32_e32 v36, 0x3fb8aa3b, v36
	global_store_dword v[60:61], v36, off offset:192
	v_readlane_b32 s100, v254, 2
	s_nop 1
	v_mov_b32_e32 v37, s100
	v_fmac_f32_e32 v37, v38, v166
	v_mul_f32_e64 v38, |v37|, s94
	v_fma_f32 v40, |v37|, s94, -v38
	v_rndne_f32_e32 v41, v38
	v_fma_f32 v40, |v37|, s64, v40
	v_sub_f32_e32 v38, v38, v41
	v_add_f32_e32 v38, v38, v40
	v_exp_f32_e32 v38, v38
	v_cvt_i32_f32_e32 v40, v41
	v_cmp_ngt_f32_e64 vcc, |v37|, s58
	v_min_f32_e32 v36, 0, v37
	v_ldexp_f32 v38, v38, v40
	v_cndmask_b32_e32 v38, 0, v38, vcc
	v_cmp_nlt_f32_e64 vcc, |v37|, s59
	s_nop 1
	v_cndmask_b32_e32 v37, v226, v38, vcc
	v_add_f32_e32 v38, 1.0, v37
	v_add_f32_e32 v40, -1.0, v38
	v_sub_f32_e32 v41, v40, v38
	v_add_f32_e32 v41, 1.0, v41
	v_sub_f32_e32 v40, v37, v40
	v_add_f32_e32 v42, v40, v41
	v_frexp_mant_f32_e32 v40, v38
	v_cmp_gt_f32_e32 vcc, s77, v40
	v_cvt_f64_f32_e32 v[40:41], v38
	v_frexp_exp_i32_f64_e32 v40, v[40:41]
	v_subbrev_co_u32_e32 v40, vcc, 0, v40, vcc
	v_sub_u32_e32 v41, 0, v40
	v_ldexp_f32 v38, v38, v41
	v_ldexp_f32 v41, v42, v41
	v_add_f32_e32 v42, -1.0, v38
	v_add_f32_e32 v43, 1.0, v42
	v_sub_f32_e32 v43, v38, v43
	v_add_f32_e32 v43, v41, v43
	v_add_f32_e32 v44, v42, v43
	v_sub_f32_e32 v42, v42, v44
	v_add_f32_e32 v42, v43, v42
	v_add_f32_e32 v43, 1.0, v38
	v_add_f32_e32 v45, -1.0, v43
	v_sub_f32_e32 v38, v38, v45
	v_add_f32_e32 v38, v41, v38
	v_add_f32_e32 v41, v43, v38
	v_sub_f32_e32 v43, v43, v41
	v_add_f32_e32 v38, v38, v43
	v_rcp_f32_e32 v43, v41
	v_cvt_f32_i32_e32 v40, v40
	v_cmp_neq_f32_e32 vcc, s62, v37
	v_mul_f32_e32 v45, v44, v43
	v_mul_f32_e32 v46, v41, v45
	v_fma_f32 v47, v45, v41, -v46
	v_fmac_f32_e32 v47, v45, v38
	v_add_f32_e32 v48, v46, v47
	v_sub_f32_e32 v49, v44, v48
	v_sub_f32_e32 v44, v44, v49
	v_sub_f32_e32 v46, v48, v46
	v_sub_f32_e32 v44, v44, v48
	v_add_f32_e32 v42, v42, v44
	v_sub_f32_e32 v44, v46, v47
	v_add_f32_e32 v42, v44, v42
	v_add_f32_e32 v44, v49, v42
	v_mul_f32_e32 v46, v43, v44
	v_mul_f32_e32 v47, v41, v46
	v_fma_f32 v41, v46, v41, -v47
	v_fmac_f32_e32 v41, v46, v38
	v_sub_f32_e32 v38, v49, v44
	v_add_f32_e32 v38, v42, v38
	v_add_f32_e32 v42, v47, v41
	v_sub_f32_e32 v48, v44, v42
	v_sub_f32_e32 v44, v44, v48
	v_sub_f32_e32 v47, v42, v47
	v_sub_f32_e32 v42, v44, v42
	v_add_f32_e32 v38, v38, v42
	v_sub_f32_e32 v41, v47, v41
	v_add_f32_e32 v38, v41, v38
	v_add_f32_e32 v41, v45, v46
	v_add_f32_e32 v38, v48, v38
	v_sub_f32_e32 v42, v41, v45
	v_mul_f32_e32 v38, v43, v38
	v_sub_f32_e32 v42, v46, v42
	v_add_f32_e32 v38, v42, v38
	v_mul_f32_e32 v45, 0x3f317218, v40
	v_add_f32_e32 v42, v41, v38
	v_fma_f32 v46, v40, s78, -v45
	v_mul_f32_e32 v43, v42, v42
	v_fmac_f32_e32 v46, 0xb102e308, v40
	v_sub_f32_e32 v40, v42, v41
	v_fmamk_f32 v44, v43, 0x3e9b6dac, v185
	v_sub_f32_e32 v38, v38, v40
	v_add_f32_e32 v40, v45, v46
	v_fmaak_f32 v44, v43, v44, 0x3f2aaada
	v_sub_f32_e32 v41, v40, v45
	v_ldexp_f32 v45, v42, 1
	v_mul_f32_e32 v42, v42, v43
	v_mul_f32_e32 v42, v42, v44
	v_add_f32_e32 v43, v45, v42
	v_sub_f32_e32 v44, v43, v45
	v_ldexp_f32 v38, v38, 1
	v_sub_f32_e32 v42, v42, v44
	v_add_f32_e32 v38, v38, v42
	v_add_f32_e32 v42, v43, v38
	v_sub_f32_e32 v43, v42, v43
	v_sub_f32_e32 v38, v38, v43
	v_add_f32_e32 v43, v40, v42
	v_sub_f32_e32 v44, v43, v40
	v_sub_f32_e32 v45, v43, v44
	v_sub_f32_e32 v41, v46, v41
	v_sub_f32_e32 v40, v40, v45
	v_sub_f32_e32 v42, v42, v44
	v_add_f32_e32 v40, v42, v40
	v_add_f32_e32 v42, v41, v38
	v_sub_f32_e32 v44, v42, v41
	v_sub_f32_e32 v45, v42, v44
	v_sub_f32_e32 v41, v41, v45
	v_sub_f32_e32 v38, v38, v44
	v_add_f32_e32 v40, v42, v40
	v_add_f32_e32 v38, v38, v41
	v_add_f32_e32 v41, v43, v40
	v_sub_f32_e32 v42, v41, v43
	v_sub_f32_e32 v40, v40, v42
	v_add_f32_e32 v38, v38, v40
	v_add_f32_e32 v38, v41, v38
	v_cndmask_b32_e32 v38, v226, v38, vcc
	v_cmp_lt_f32_e64 vcc, |v37|, s63
	s_nop 1
	v_cndmask_b32_e32 v37, v38, v37, vcc
	v_sub_f32_e32 v36, v36, v37
	v_mul_f32_e32 v36, 0x3fb8aa3b, v36
	global_store_dword v[66:67], v36, off offset:192
	v_readlane_b32 s100, v254, 3
	s_nop 1
	v_mov_b32_e32 v37, s100
	v_fmac_f32_e32 v37, v39, v166
	v_mul_f32_e64 v38, |v37|, s94
	v_fma_f32 v39, |v37|, s94, -v38
	v_rndne_f32_e32 v40, v38
	v_fma_f32 v39, |v37|, s64, v39
	v_sub_f32_e32 v38, v38, v40
	v_add_f32_e32 v38, v38, v39
	v_exp_f32_e32 v38, v38
	v_cvt_i32_f32_e32 v39, v40
	v_cmp_ngt_f32_e64 vcc, |v37|, s58
	v_min_f32_e32 v36, 0, v37
	v_ldexp_f32 v38, v38, v39
	v_cndmask_b32_e32 v38, 0, v38, vcc
	v_cmp_nlt_f32_e64 vcc, |v37|, s59
	s_nop 1
	v_cndmask_b32_e32 v37, v226, v38, vcc
	v_add_f32_e32 v40, 1.0, v37
	v_add_f32_e32 v38, -1.0, v40
	v_sub_f32_e32 v39, v38, v40
	v_add_f32_e32 v39, 1.0, v39
	v_sub_f32_e32 v38, v37, v38
	v_add_f32_e32 v41, v38, v39
	v_frexp_mant_f32_e32 v38, v40
	v_cmp_gt_f32_e32 vcc, s77, v38
	v_cvt_f64_f32_e32 v[38:39], v40
	v_frexp_exp_i32_f64_e32 v38, v[38:39]
	v_subbrev_co_u32_e32 v38, vcc, 0, v38, vcc
	v_sub_u32_e32 v39, 0, v38
	v_ldexp_f32 v40, v40, v39
	v_ldexp_f32 v39, v41, v39
	v_add_f32_e32 v41, -1.0, v40
	v_add_f32_e32 v42, 1.0, v41
	v_sub_f32_e32 v42, v40, v42
	v_add_f32_e32 v42, v39, v42
	v_add_f32_e32 v43, v41, v42
	v_sub_f32_e32 v41, v41, v43
	v_add_f32_e32 v41, v42, v41
	v_add_f32_e32 v42, 1.0, v40
	v_add_f32_e32 v44, -1.0, v42
	v_sub_f32_e32 v40, v40, v44
	v_add_f32_e32 v39, v39, v40
	v_add_f32_e32 v40, v42, v39
	v_sub_f32_e32 v42, v42, v40
	v_add_f32_e32 v39, v39, v42
	v_rcp_f32_e32 v42, v40
	v_cvt_f32_i32_e32 v38, v38
	v_cmp_neq_f32_e32 vcc, s62, v37
	v_mul_f32_e32 v44, v43, v42
	v_mul_f32_e32 v45, v40, v44
	v_fma_f32 v46, v44, v40, -v45
	v_fmac_f32_e32 v46, v44, v39
	v_add_f32_e32 v47, v45, v46
	v_sub_f32_e32 v48, v43, v47
	v_sub_f32_e32 v43, v43, v48
	v_sub_f32_e32 v45, v47, v45
	v_sub_f32_e32 v43, v43, v47
	v_add_f32_e32 v41, v41, v43
	v_sub_f32_e32 v43, v45, v46
	v_add_f32_e32 v41, v43, v41
	v_add_f32_e32 v43, v48, v41
	v_mul_f32_e32 v45, v42, v43
	v_mul_f32_e32 v46, v40, v45
	v_fma_f32 v40, v45, v40, -v46
	v_fmac_f32_e32 v40, v45, v39
	v_sub_f32_e32 v39, v48, v43
	v_add_f32_e32 v39, v41, v39
	v_add_f32_e32 v41, v46, v40
	v_sub_f32_e32 v47, v43, v41
	v_sub_f32_e32 v43, v43, v47
	v_sub_f32_e32 v46, v41, v46
	v_sub_f32_e32 v41, v43, v41
	v_add_f32_e32 v39, v39, v41
	v_sub_f32_e32 v40, v46, v40
	v_add_f32_e32 v39, v40, v39
	v_add_f32_e32 v40, v44, v45
	v_add_f32_e32 v39, v47, v39
	v_sub_f32_e32 v41, v40, v44
	v_mul_f32_e32 v39, v42, v39
	v_sub_f32_e32 v41, v45, v41
	v_add_f32_e32 v39, v41, v39
	v_mul_f32_e32 v44, 0x3f317218, v38
	v_add_f32_e32 v41, v40, v39
	v_fma_f32 v45, v38, s78, -v44
	v_mul_f32_e32 v42, v41, v41
	v_fmac_f32_e32 v45, 0xb102e308, v38
	v_sub_f32_e32 v38, v41, v40
	v_fmamk_f32 v43, v42, 0x3e9b6dac, v185
	v_sub_f32_e32 v38, v39, v38
	v_add_f32_e32 v39, v44, v45
	v_fmaak_f32 v43, v42, v43, 0x3f2aaada
	v_sub_f32_e32 v40, v39, v44
	v_ldexp_f32 v44, v41, 1
	v_mul_f32_e32 v41, v41, v42
	v_mul_f32_e32 v41, v41, v43
	v_add_f32_e32 v42, v44, v41
	v_sub_f32_e32 v43, v42, v44
	v_ldexp_f32 v38, v38, 1
	v_sub_f32_e32 v41, v41, v43
	v_add_f32_e32 v38, v38, v41
	v_add_f32_e32 v41, v42, v38
	v_sub_f32_e32 v42, v41, v42
	v_sub_f32_e32 v38, v38, v42
	v_add_f32_e32 v42, v39, v41
	v_sub_f32_e32 v43, v42, v39
	v_sub_f32_e32 v44, v42, v43
	v_sub_f32_e32 v40, v45, v40
	v_sub_f32_e32 v39, v39, v44
	v_sub_f32_e32 v41, v41, v43
	v_add_f32_e32 v39, v41, v39
	v_add_f32_e32 v41, v40, v38
	v_sub_f32_e32 v43, v41, v40
	v_sub_f32_e32 v44, v41, v43
	v_sub_f32_e32 v40, v40, v44
	v_sub_f32_e32 v38, v38, v43
	v_add_f32_e32 v39, v41, v39
	v_add_f32_e32 v38, v38, v40
	v_add_f32_e32 v40, v42, v39
	v_sub_f32_e32 v41, v40, v42
	v_sub_f32_e32 v39, v39, v41
	v_add_f32_e32 v38, v38, v39
	v_add_f32_e32 v38, v40, v38
	v_cndmask_b32_e32 v38, v226, v38, vcc
	v_cmp_lt_f32_e64 vcc, |v37|, s63
	s_nop 1
	v_cndmask_b32_e32 v37, v38, v37, vcc
	v_sub_f32_e32 v36, v36, v37
	v_mul_f32_e32 v36, 0x3fb8aa3b, v36
	global_store_dword v[62:63], v36, off offset:192
	v_readlane_b32 s100, v254, 4
	s_nop 1
	v_mov_b32_e32 v36, s100
	v_fmac_f32_e32 v36, v32, v166
	v_mul_f32_e64 v37, |v36|, s94
	v_fma_f32 v38, |v36|, s94, -v37
	v_rndne_f32_e32 v39, v37
	v_fma_f32 v38, |v36|, s64, v38
	v_sub_f32_e32 v37, v37, v39
	v_add_f32_e32 v37, v37, v38
	v_exp_f32_e32 v37, v37
	v_cvt_i32_f32_e32 v38, v39
	v_cmp_ngt_f32_e64 vcc, |v36|, s58
	v_min_f32_e32 v32, 0, v36
	v_ldexp_f32 v37, v37, v38
	v_cndmask_b32_e32 v37, 0, v37, vcc
	v_cmp_nlt_f32_e64 vcc, |v36|, s59
	s_nop 1
	v_cndmask_b32_e32 v36, v226, v37, vcc
	v_add_f32_e32 v37, 1.0, v36
	v_add_f32_e32 v38, -1.0, v37
	v_sub_f32_e32 v39, v38, v37
	v_add_f32_e32 v39, 1.0, v39
	v_sub_f32_e32 v38, v36, v38
	v_add_f32_e32 v40, v38, v39
	v_frexp_mant_f32_e32 v38, v37
	v_cmp_gt_f32_e32 vcc, s77, v38
	v_cvt_f64_f32_e32 v[38:39], v37
	v_frexp_exp_i32_f64_e32 v38, v[38:39]
	v_subbrev_co_u32_e32 v38, vcc, 0, v38, vcc
	v_sub_u32_e32 v39, 0, v38
	v_ldexp_f32 v37, v37, v39
	v_ldexp_f32 v39, v40, v39
	v_add_f32_e32 v40, -1.0, v37
	v_add_f32_e32 v41, 1.0, v40
	v_sub_f32_e32 v41, v37, v41
	v_add_f32_e32 v41, v39, v41
	v_add_f32_e32 v42, v40, v41
	v_sub_f32_e32 v40, v40, v42
	v_add_f32_e32 v40, v41, v40
	v_add_f32_e32 v41, 1.0, v37
	v_add_f32_e32 v43, -1.0, v41
	v_sub_f32_e32 v37, v37, v43
	v_add_f32_e32 v37, v39, v37
	v_add_f32_e32 v39, v41, v37
	v_sub_f32_e32 v41, v41, v39
	v_add_f32_e32 v37, v37, v41
	v_rcp_f32_e32 v41, v39
	v_cvt_f32_i32_e32 v38, v38
	v_cmp_neq_f32_e32 vcc, s62, v36
	v_mul_f32_e32 v43, v42, v41
	v_mul_f32_e32 v44, v39, v43
	v_fma_f32 v45, v43, v39, -v44
	v_fmac_f32_e32 v45, v43, v37
	v_add_f32_e32 v46, v44, v45
	v_sub_f32_e32 v47, v42, v46
	v_sub_f32_e32 v42, v42, v47
	v_sub_f32_e32 v44, v46, v44
	v_sub_f32_e32 v42, v42, v46
	v_add_f32_e32 v40, v40, v42
	v_sub_f32_e32 v42, v44, v45
	v_add_f32_e32 v40, v42, v40
	v_add_f32_e32 v42, v47, v40
	v_mul_f32_e32 v44, v41, v42
	v_mul_f32_e32 v45, v39, v44
	v_fma_f32 v39, v44, v39, -v45
	v_fmac_f32_e32 v39, v44, v37
	v_sub_f32_e32 v37, v47, v42
	v_add_f32_e32 v37, v40, v37
	v_add_f32_e32 v40, v45, v39
	v_sub_f32_e32 v46, v42, v40
	v_sub_f32_e32 v42, v42, v46
	v_sub_f32_e32 v45, v40, v45
	v_sub_f32_e32 v40, v42, v40
	v_add_f32_e32 v37, v37, v40
	v_sub_f32_e32 v39, v45, v39
	v_add_f32_e32 v37, v39, v37
	v_add_f32_e32 v39, v43, v44
	v_add_f32_e32 v37, v46, v37
	v_sub_f32_e32 v40, v39, v43
	v_mul_f32_e32 v37, v41, v37
	v_sub_f32_e32 v40, v44, v40
	v_add_f32_e32 v37, v40, v37
	v_mul_f32_e32 v43, 0x3f317218, v38
	v_add_f32_e32 v40, v39, v37
	v_fma_f32 v44, v38, s78, -v43
	v_mul_f32_e32 v41, v40, v40
	v_fmac_f32_e32 v44, 0xb102e308, v38
	v_sub_f32_e32 v38, v40, v39
	v_fmamk_f32 v42, v41, 0x3e9b6dac, v185
	v_sub_f32_e32 v37, v37, v38
	v_add_f32_e32 v38, v43, v44
	v_fmaak_f32 v42, v41, v42, 0x3f2aaada
	v_sub_f32_e32 v39, v38, v43
	v_ldexp_f32 v43, v40, 1
	v_mul_f32_e32 v40, v40, v41
	v_mul_f32_e32 v40, v40, v42
	v_add_f32_e32 v41, v43, v40
	v_sub_f32_e32 v42, v41, v43
	v_ldexp_f32 v37, v37, 1
	v_sub_f32_e32 v40, v40, v42
	v_add_f32_e32 v37, v37, v40
	v_add_f32_e32 v40, v41, v37
	v_sub_f32_e32 v41, v40, v41
	v_sub_f32_e32 v37, v37, v41
	v_add_f32_e32 v41, v38, v40
	v_sub_f32_e32 v42, v41, v38
	v_sub_f32_e32 v43, v41, v42
	v_sub_f32_e32 v39, v44, v39
	v_sub_f32_e32 v38, v38, v43
	v_sub_f32_e32 v40, v40, v42
	v_add_f32_e32 v38, v40, v38
	v_add_f32_e32 v40, v39, v37
	v_sub_f32_e32 v42, v40, v39
	v_sub_f32_e32 v43, v40, v42
	v_sub_f32_e32 v39, v39, v43
	v_sub_f32_e32 v37, v37, v42
	v_add_f32_e32 v38, v40, v38
	v_add_f32_e32 v37, v37, v39
	v_add_f32_e32 v39, v41, v38
	v_sub_f32_e32 v40, v39, v41
	v_sub_f32_e32 v38, v38, v40
	v_add_f32_e32 v37, v37, v38
	v_add_f32_e32 v37, v39, v37
	v_cndmask_b32_e32 v37, v226, v37, vcc
	v_cmp_lt_f32_e64 vcc, |v36|, s63
	s_nop 1
	v_cndmask_b32_e32 v36, v37, v36, vcc
	v_sub_f32_e32 v32, v32, v36
	v_mul_f32_e32 v32, 0x3fb8aa3b, v32
	global_store_dword v[68:69], v32, off offset:192
	v_readlane_b32 s100, v254, 5
	s_nop 1
	v_mov_b32_e32 v36, s100
	v_fmac_f32_e32 v36, v33, v166
	v_mul_f32_e64 v33, |v36|, s94
	v_fma_f32 v37, |v36|, s94, -v33
	v_rndne_f32_e32 v38, v33
	v_fma_f32 v37, |v36|, s64, v37
	v_sub_f32_e32 v33, v33, v38
	v_add_f32_e32 v33, v33, v37
	v_exp_f32_e32 v33, v33
	v_cvt_i32_f32_e32 v37, v38
	v_cmp_ngt_f32_e64 vcc, |v36|, s58
	v_min_f32_e32 v32, 0, v36
	v_ldexp_f32 v33, v33, v37
	v_cndmask_b32_e32 v33, 0, v33, vcc
	v_cmp_nlt_f32_e64 vcc, |v36|, s59
	s_nop 1
	v_cndmask_b32_e32 v33, v226, v33, vcc
	v_add_f32_e32 v38, 1.0, v33
	v_add_f32_e32 v36, -1.0, v38
	v_sub_f32_e32 v37, v36, v38
	v_add_f32_e32 v37, 1.0, v37
	v_sub_f32_e32 v36, v33, v36
	v_add_f32_e32 v39, v36, v37
	v_frexp_mant_f32_e32 v36, v38
	v_cmp_gt_f32_e32 vcc, s77, v36
	v_cvt_f64_f32_e32 v[36:37], v38
	v_frexp_exp_i32_f64_e32 v36, v[36:37]
	v_subbrev_co_u32_e32 v36, vcc, 0, v36, vcc
	v_sub_u32_e32 v37, 0, v36
	v_ldexp_f32 v38, v38, v37
	v_ldexp_f32 v37, v39, v37
	v_add_f32_e32 v39, -1.0, v38
	v_add_f32_e32 v40, 1.0, v39
	v_sub_f32_e32 v40, v38, v40
	v_add_f32_e32 v40, v37, v40
	v_add_f32_e32 v41, v39, v40
	v_sub_f32_e32 v39, v39, v41
	v_add_f32_e32 v39, v40, v39
	v_add_f32_e32 v40, 1.0, v38
	v_add_f32_e32 v42, -1.0, v40
	v_sub_f32_e32 v38, v38, v42
	v_add_f32_e32 v37, v37, v38
	v_add_f32_e32 v38, v40, v37
	v_sub_f32_e32 v40, v40, v38
	v_add_f32_e32 v37, v37, v40
	v_rcp_f32_e32 v40, v38
	v_cvt_f32_i32_e32 v36, v36
	v_cmp_neq_f32_e32 vcc, s62, v33
	v_mul_f32_e32 v42, v41, v40
	v_mul_f32_e32 v43, v38, v42
	v_fma_f32 v44, v42, v38, -v43
	v_fmac_f32_e32 v44, v42, v37
	v_add_f32_e32 v45, v43, v44
	v_sub_f32_e32 v46, v41, v45
	v_sub_f32_e32 v41, v41, v46
	v_sub_f32_e32 v43, v45, v43
	v_sub_f32_e32 v41, v41, v45
	v_add_f32_e32 v39, v39, v41
	v_sub_f32_e32 v41, v43, v44
	v_add_f32_e32 v39, v41, v39
	v_add_f32_e32 v41, v46, v39
	v_mul_f32_e32 v43, v40, v41
	v_mul_f32_e32 v44, v38, v43
	v_fma_f32 v38, v43, v38, -v44
	v_fmac_f32_e32 v38, v43, v37
	v_sub_f32_e32 v37, v46, v41
	v_add_f32_e32 v37, v39, v37
	v_add_f32_e32 v39, v44, v38
	v_sub_f32_e32 v45, v41, v39
	v_sub_f32_e32 v41, v41, v45
	v_sub_f32_e32 v44, v39, v44
	v_sub_f32_e32 v39, v41, v39
	v_add_f32_e32 v37, v37, v39
	v_sub_f32_e32 v38, v44, v38
	v_add_f32_e32 v37, v38, v37
	v_add_f32_e32 v38, v42, v43
	v_add_f32_e32 v37, v45, v37
	v_sub_f32_e32 v39, v38, v42
	v_mul_f32_e32 v37, v40, v37
	v_sub_f32_e32 v39, v43, v39
	v_add_f32_e32 v37, v39, v37
	v_mul_f32_e32 v42, 0x3f317218, v36
	v_add_f32_e32 v39, v38, v37
	v_fma_f32 v43, v36, s78, -v42
	v_mul_f32_e32 v40, v39, v39
	v_fmac_f32_e32 v43, 0xb102e308, v36
	v_sub_f32_e32 v36, v39, v38
	v_fmamk_f32 v41, v40, 0x3e9b6dac, v185
	v_sub_f32_e32 v36, v37, v36
	v_add_f32_e32 v37, v42, v43
	v_fmaak_f32 v41, v40, v41, 0x3f2aaada
	v_sub_f32_e32 v38, v37, v42
	v_ldexp_f32 v42, v39, 1
	v_mul_f32_e32 v39, v39, v40
	v_mul_f32_e32 v39, v39, v41
	v_add_f32_e32 v40, v42, v39
	v_sub_f32_e32 v41, v40, v42
	v_ldexp_f32 v36, v36, 1
	v_sub_f32_e32 v39, v39, v41
	v_add_f32_e32 v36, v36, v39
	v_add_f32_e32 v39, v40, v36
	v_sub_f32_e32 v40, v39, v40
	v_sub_f32_e32 v36, v36, v40
	v_add_f32_e32 v40, v37, v39
	v_sub_f32_e32 v41, v40, v37
	v_sub_f32_e32 v42, v40, v41
	v_sub_f32_e32 v38, v43, v38
	v_sub_f32_e32 v37, v37, v42
	v_sub_f32_e32 v39, v39, v41
	v_add_f32_e32 v37, v39, v37
	v_add_f32_e32 v39, v38, v36
	v_sub_f32_e32 v41, v39, v38
	v_sub_f32_e32 v42, v39, v41
	v_sub_f32_e32 v38, v38, v42
	v_sub_f32_e32 v36, v36, v41
	v_add_f32_e32 v37, v39, v37
	v_add_f32_e32 v36, v36, v38
	v_add_f32_e32 v38, v40, v37
	v_sub_f32_e32 v39, v38, v40
	v_sub_f32_e32 v37, v37, v39
	v_add_f32_e32 v36, v36, v37
	v_add_f32_e32 v36, v38, v36
	v_cndmask_b32_e32 v36, v226, v36, vcc
	v_cmp_lt_f32_e64 vcc, |v33|, s63
	s_nop 1
	v_cndmask_b32_e32 v33, v36, v33, vcc
	v_sub_f32_e32 v32, v32, v33
	v_mul_f32_e32 v32, 0x3fb8aa3b, v32
	global_store_dword v[56:57], v32, off offset:192
	v_readlane_b32 s100, v254, 6
	s_nop 1
	v_mov_b32_e32 v33, s100
	v_fmac_f32_e32 v33, v34, v166
	v_mul_f32_e64 v34, |v33|, s94
	v_fma_f32 v36, |v33|, s94, -v34
	v_rndne_f32_e32 v37, v34
	v_fma_f32 v36, |v33|, s64, v36
	v_sub_f32_e32 v34, v34, v37
	v_add_f32_e32 v34, v34, v36
	v_exp_f32_e32 v34, v34
	v_cvt_i32_f32_e32 v36, v37
	v_cmp_ngt_f32_e64 vcc, |v33|, s58
	v_min_f32_e32 v32, 0, v33
	v_ldexp_f32 v34, v34, v36
	v_cndmask_b32_e32 v34, 0, v34, vcc
	v_cmp_nlt_f32_e64 vcc, |v33|, s59
	s_nop 1
	v_cndmask_b32_e32 v33, v226, v34, vcc
	v_add_f32_e32 v34, 1.0, v33
	v_add_f32_e32 v36, -1.0, v34
	v_sub_f32_e32 v37, v36, v34
	v_add_f32_e32 v37, 1.0, v37
	v_sub_f32_e32 v36, v33, v36
	v_add_f32_e32 v38, v36, v37
	v_frexp_mant_f32_e32 v36, v34
	v_cmp_gt_f32_e32 vcc, s77, v36
	v_cvt_f64_f32_e32 v[36:37], v34
	v_frexp_exp_i32_f64_e32 v36, v[36:37]
	v_subbrev_co_u32_e32 v36, vcc, 0, v36, vcc
	v_sub_u32_e32 v37, 0, v36
	v_ldexp_f32 v34, v34, v37
	v_ldexp_f32 v37, v38, v37
	v_add_f32_e32 v38, -1.0, v34
	v_add_f32_e32 v39, 1.0, v38
	v_sub_f32_e32 v39, v34, v39
	v_add_f32_e32 v39, v37, v39
	v_add_f32_e32 v40, v38, v39
	v_sub_f32_e32 v38, v38, v40
	v_add_f32_e32 v38, v39, v38
	v_add_f32_e32 v39, 1.0, v34
	v_add_f32_e32 v41, -1.0, v39
	v_sub_f32_e32 v34, v34, v41
	v_add_f32_e32 v34, v37, v34
	v_add_f32_e32 v37, v39, v34
	v_sub_f32_e32 v39, v39, v37
	v_add_f32_e32 v34, v34, v39
	v_rcp_f32_e32 v39, v37
	v_cvt_f32_i32_e32 v36, v36
	v_cmp_neq_f32_e32 vcc, s62, v33
	v_mul_f32_e32 v41, v40, v39
	v_mul_f32_e32 v42, v37, v41
	v_fma_f32 v43, v41, v37, -v42
	v_fmac_f32_e32 v43, v41, v34
	v_add_f32_e32 v44, v42, v43
	v_sub_f32_e32 v45, v40, v44
	v_sub_f32_e32 v40, v40, v45
	v_sub_f32_e32 v42, v44, v42
	v_sub_f32_e32 v40, v40, v44
	v_add_f32_e32 v38, v38, v40
	v_sub_f32_e32 v40, v42, v43
	v_add_f32_e32 v38, v40, v38
	v_add_f32_e32 v40, v45, v38
	v_mul_f32_e32 v42, v39, v40
	v_mul_f32_e32 v43, v37, v42
	v_fma_f32 v37, v42, v37, -v43
	v_fmac_f32_e32 v37, v42, v34
	v_sub_f32_e32 v34, v45, v40
	v_add_f32_e32 v34, v38, v34
	v_add_f32_e32 v38, v43, v37
	v_sub_f32_e32 v44, v40, v38
	v_sub_f32_e32 v40, v40, v44
	v_sub_f32_e32 v43, v38, v43
	v_sub_f32_e32 v38, v40, v38
	v_add_f32_e32 v34, v34, v38
	v_sub_f32_e32 v37, v43, v37
	v_add_f32_e32 v34, v37, v34
	v_add_f32_e32 v37, v41, v42
	v_add_f32_e32 v34, v44, v34
	v_sub_f32_e32 v38, v37, v41
	v_mul_f32_e32 v34, v39, v34
	v_sub_f32_e32 v38, v42, v38
	v_add_f32_e32 v34, v38, v34
	v_mul_f32_e32 v41, 0x3f317218, v36
	v_add_f32_e32 v38, v37, v34
	v_fma_f32 v42, v36, s78, -v41
	v_mul_f32_e32 v39, v38, v38
	v_fmac_f32_e32 v42, 0xb102e308, v36
	v_sub_f32_e32 v36, v38, v37
	v_fmamk_f32 v40, v39, 0x3e9b6dac, v185
	v_sub_f32_e32 v34, v34, v36
	v_add_f32_e32 v36, v41, v42
	v_fmaak_f32 v40, v39, v40, 0x3f2aaada
	v_sub_f32_e32 v37, v36, v41
	v_ldexp_f32 v41, v38, 1
	v_mul_f32_e32 v38, v38, v39
	v_mul_f32_e32 v38, v38, v40
	v_add_f32_e32 v39, v41, v38
	v_sub_f32_e32 v40, v39, v41
	v_ldexp_f32 v34, v34, 1
	v_sub_f32_e32 v38, v38, v40
	v_add_f32_e32 v34, v34, v38
	v_add_f32_e32 v38, v39, v34
	v_sub_f32_e32 v39, v38, v39
	v_sub_f32_e32 v34, v34, v39
	v_add_f32_e32 v39, v36, v38
	v_sub_f32_e32 v40, v39, v36
	v_sub_f32_e32 v41, v39, v40
	v_sub_f32_e32 v37, v42, v37
	v_sub_f32_e32 v36, v36, v41
	v_sub_f32_e32 v38, v38, v40
	v_add_f32_e32 v36, v38, v36
	v_add_f32_e32 v38, v37, v34
	v_sub_f32_e32 v40, v38, v37
	v_sub_f32_e32 v41, v38, v40
	v_sub_f32_e32 v37, v37, v41
	v_sub_f32_e32 v34, v34, v40
	v_add_f32_e32 v36, v38, v36
	v_add_f32_e32 v34, v34, v37
	v_add_f32_e32 v37, v39, v36
	v_sub_f32_e32 v38, v37, v39
	v_sub_f32_e32 v36, v36, v38
	v_add_f32_e32 v34, v34, v36
	v_add_f32_e32 v34, v37, v34
	v_cndmask_b32_e32 v34, v226, v34, vcc
	v_cmp_lt_f32_e64 vcc, |v33|, s63
	s_nop 1
	v_cndmask_b32_e32 v33, v34, v33, vcc
	v_sub_f32_e32 v32, v32, v33
	v_mul_f32_e32 v32, 0x3fb8aa3b, v32
	global_store_dword v[70:71], v32, off offset:192
	v_readlane_b32 s100, v254, 7
	s_nop 1
	v_mov_b32_e32 v33, s100
	v_fmac_f32_e32 v33, v35, v166
	v_mul_f32_e64 v34, |v33|, s94
	v_fma_f32 v35, |v33|, s94, -v34
	v_rndne_f32_e32 v36, v34
	v_fma_f32 v35, |v33|, s64, v35
	v_sub_f32_e32 v34, v34, v36
	v_add_f32_e32 v34, v34, v35
	v_exp_f32_e32 v34, v34
	v_cvt_i32_f32_e32 v35, v36
	v_cmp_ngt_f32_e64 vcc, |v33|, s58
	v_min_f32_e32 v32, 0, v33
	v_ldexp_f32 v34, v34, v35
	v_cndmask_b32_e32 v34, 0, v34, vcc
	v_cmp_nlt_f32_e64 vcc, |v33|, s59
	s_nop 1
	v_cndmask_b32_e32 v33, v226, v34, vcc
	v_add_f32_e32 v36, 1.0, v33
	v_add_f32_e32 v34, -1.0, v36
	v_sub_f32_e32 v35, v34, v36
	v_add_f32_e32 v35, 1.0, v35
	v_sub_f32_e32 v34, v33, v34
	v_add_f32_e32 v37, v34, v35
	v_frexp_mant_f32_e32 v34, v36
	v_cmp_gt_f32_e32 vcc, s77, v34
	v_cvt_f64_f32_e32 v[34:35], v36
	v_frexp_exp_i32_f64_e32 v34, v[34:35]
	v_subbrev_co_u32_e32 v34, vcc, 0, v34, vcc
	v_sub_u32_e32 v35, 0, v34
	v_ldexp_f32 v36, v36, v35
	v_ldexp_f32 v35, v37, v35
	v_add_f32_e32 v37, -1.0, v36
	v_add_f32_e32 v38, 1.0, v37
	v_sub_f32_e32 v38, v36, v38
	v_add_f32_e32 v38, v35, v38
	v_add_f32_e32 v39, v37, v38
	v_sub_f32_e32 v37, v37, v39
	v_add_f32_e32 v37, v38, v37
	v_add_f32_e32 v38, 1.0, v36
	v_add_f32_e32 v40, -1.0, v38
	v_sub_f32_e32 v36, v36, v40
	v_add_f32_e32 v35, v35, v36
	v_add_f32_e32 v36, v38, v35
	v_sub_f32_e32 v38, v38, v36
	v_add_f32_e32 v35, v35, v38
	v_rcp_f32_e32 v38, v36
	v_cvt_f32_i32_e32 v34, v34
	v_cmp_neq_f32_e32 vcc, s62, v33
	v_mul_f32_e32 v40, v39, v38
	v_mul_f32_e32 v41, v36, v40
	v_fma_f32 v42, v40, v36, -v41
	v_fmac_f32_e32 v42, v40, v35
	v_add_f32_e32 v43, v41, v42
	v_sub_f32_e32 v44, v39, v43
	v_sub_f32_e32 v39, v39, v44
	v_sub_f32_e32 v41, v43, v41
	v_sub_f32_e32 v39, v39, v43
	v_add_f32_e32 v37, v37, v39
	v_sub_f32_e32 v39, v41, v42
	v_add_f32_e32 v37, v39, v37
	v_add_f32_e32 v39, v44, v37
	v_mul_f32_e32 v41, v38, v39
	v_mul_f32_e32 v42, v36, v41
	v_fma_f32 v36, v41, v36, -v42
	v_fmac_f32_e32 v36, v41, v35
	v_sub_f32_e32 v35, v44, v39
	v_add_f32_e32 v35, v37, v35
	v_add_f32_e32 v37, v42, v36
	v_sub_f32_e32 v43, v39, v37
	v_sub_f32_e32 v39, v39, v43
	v_sub_f32_e32 v42, v37, v42
	v_sub_f32_e32 v37, v39, v37
	v_add_f32_e32 v35, v35, v37
	v_sub_f32_e32 v36, v42, v36
	v_add_f32_e32 v35, v36, v35
	v_add_f32_e32 v36, v40, v41
	v_add_f32_e32 v35, v43, v35
	v_sub_f32_e32 v37, v36, v40
	v_mul_f32_e32 v35, v38, v35
	v_sub_f32_e32 v37, v41, v37
	v_add_f32_e32 v35, v37, v35
	v_mul_f32_e32 v40, 0x3f317218, v34
	v_add_f32_e32 v37, v36, v35
	v_fma_f32 v41, v34, s78, -v40
	v_mul_f32_e32 v38, v37, v37
	v_fmac_f32_e32 v41, 0xb102e308, v34
	v_sub_f32_e32 v34, v37, v36
	v_fmamk_f32 v39, v38, 0x3e9b6dac, v185
	v_sub_f32_e32 v34, v35, v34
	v_add_f32_e32 v35, v40, v41
	v_fmaak_f32 v39, v38, v39, 0x3f2aaada
	v_sub_f32_e32 v36, v35, v40
	v_ldexp_f32 v40, v37, 1
	v_mul_f32_e32 v37, v37, v38
	v_mul_f32_e32 v37, v37, v39
	v_add_f32_e32 v38, v40, v37
	v_sub_f32_e32 v39, v38, v40
	v_ldexp_f32 v34, v34, 1
	v_sub_f32_e32 v37, v37, v39
	v_add_f32_e32 v34, v34, v37
	v_add_f32_e32 v37, v38, v34
	v_sub_f32_e32 v38, v37, v38
	v_sub_f32_e32 v34, v34, v38
	v_add_f32_e32 v38, v35, v37
	v_sub_f32_e32 v39, v38, v35
	v_sub_f32_e32 v40, v38, v39
	v_sub_f32_e32 v36, v41, v36
	v_sub_f32_e32 v35, v35, v40
	v_sub_f32_e32 v37, v37, v39
	v_add_f32_e32 v35, v37, v35
	v_add_f32_e32 v37, v36, v34
	v_sub_f32_e32 v39, v37, v36
	v_sub_f32_e32 v40, v37, v39
	v_sub_f32_e32 v36, v36, v40
	v_sub_f32_e32 v34, v34, v39
	v_add_f32_e32 v35, v37, v35
	v_add_f32_e32 v34, v34, v36
	v_add_f32_e32 v36, v38, v35
	v_sub_f32_e32 v37, v36, v38
	v_sub_f32_e32 v35, v35, v37
	v_add_f32_e32 v34, v34, v35
	v_add_f32_e32 v34, v36, v34
	v_cndmask_b32_e32 v34, v226, v34, vcc
	v_cmp_lt_f32_e64 vcc, |v33|, s63
	v_ashrrev_i32_e32 v42, 9, v164
	v_and_b32_e32 v38, -8, v42
	v_cndmask_b32_e32 v33, v34, v33, vcc
	v_sub_f32_e32 v32, v32, v33
	v_mul_f32_e32 v32, 0x3fb8aa3b, v32
	global_store_dword v[58:59], v32, off offset:192
	s_branch .LBB0_479
.Lcfl_half2:
	v_ashrrev_i32_e32 v42, 9, v164
	v_and_b32_e32 v38, -8, v42
	v_and_b32_e32 v32, 0xfcf, v164
	v_lshlrev_b32_e32 v190, 2, v32
	v_readlane_b32 s100, v254, 0
	s_nop 1
	v_mov_b32_e32 v32, s100
	v_lshl_add_u64 v[40:41], s[52:53], 0, v[190:191]
	v_fmac_f32_e32 v32, v28, v162
	v_mul_f32_e64 v33, |v32|, s94
	v_fma_f32 v34, |v32|, s94, -v33
	v_rndne_f32_e32 v35, v33
	v_fma_f32 v34, |v32|, s64, v34
	v_sub_f32_e32 v33, v33, v35
	v_add_f32_e32 v33, v33, v34
	v_exp_f32_e32 v33, v33
	v_cvt_i32_f32_e32 v34, v35
	v_cmp_ngt_f32_e64 vcc, |v32|, s58
	v_min_f32_e32 v28, 0, v32
	v_ldexp_f32 v33, v33, v34
	v_cndmask_b32_e32 v33, 0, v33, vcc
	v_cmp_nlt_f32_e64 vcc, |v32|, s59
	s_nop 1
	v_cndmask_b32_e32 v34, v226, v33, vcc
	v_add_f32_e32 v35, 1.0, v34
	v_add_f32_e32 v32, -1.0, v35
	v_sub_f32_e32 v33, v32, v35
	v_add_f32_e32 v33, 1.0, v33
	v_sub_f32_e32 v32, v34, v32
	v_add_f32_e32 v36, v32, v33
	v_frexp_mant_f32_e32 v32, v35
	v_cmp_gt_f32_e32 vcc, s77, v32
	v_cvt_f64_f32_e32 v[32:33], v35
	v_frexp_exp_i32_f64_e32 v32, v[32:33]
	v_subbrev_co_u32_e32 v32, vcc, 0, v32, vcc
	v_sub_u32_e32 v33, 0, v32
	v_ldexp_f32 v35, v35, v33
	v_ldexp_f32 v33, v36, v33
	v_add_f32_e32 v36, -1.0, v35
	v_add_f32_e32 v37, 1.0, v36
	v_sub_f32_e32 v37, v35, v37
	v_add_f32_e32 v37, v33, v37
	v_add_f32_e32 v39, v36, v37
	v_sub_f32_e32 v36, v36, v39
	v_add_f32_e32 v36, v37, v36
	v_add_f32_e32 v37, 1.0, v35
	v_add_f32_e32 v43, -1.0, v37
	v_sub_f32_e32 v35, v35, v43
	v_add_f32_e32 v33, v33, v35
	v_add_f32_e32 v35, v37, v33
	v_sub_f32_e32 v37, v37, v35
	v_add_f32_e32 v33, v33, v37
	v_rcp_f32_e32 v37, v35
	v_cvt_f32_i32_e32 v32, v32
	v_cmp_neq_f32_e32 vcc, s62, v34
	v_mul_f32_e32 v43, v39, v37
	v_mul_f32_e32 v44, v35, v43
	v_fma_f32 v45, v43, v35, -v44
	v_fmac_f32_e32 v45, v43, v33
	v_add_f32_e32 v46, v44, v45
	v_sub_f32_e32 v47, v39, v46
	v_sub_f32_e32 v39, v39, v47
	v_sub_f32_e32 v44, v46, v44
	v_sub_f32_e32 v39, v39, v46
	v_add_f32_e32 v36, v36, v39
	v_sub_f32_e32 v39, v44, v45
	v_add_f32_e32 v36, v39, v36
	v_add_f32_e32 v39, v47, v36
	v_mul_f32_e32 v44, v37, v39
	v_mul_f32_e32 v45, v35, v44
	v_fma_f32 v35, v44, v35, -v45
	v_fmac_f32_e32 v35, v44, v33
	v_sub_f32_e32 v33, v47, v39
	v_add_f32_e32 v33, v36, v33
	v_add_f32_e32 v36, v45, v35
	v_sub_f32_e32 v46, v39, v36
	v_sub_f32_e32 v39, v39, v46
	v_sub_f32_e32 v45, v36, v45
	v_sub_f32_e32 v36, v39, v36
	v_add_f32_e32 v33, v33, v36
	v_sub_f32_e32 v35, v45, v35
	v_add_f32_e32 v33, v35, v33
	v_add_f32_e32 v35, v43, v44
	v_add_f32_e32 v33, v46, v33
	v_sub_f32_e32 v36, v35, v43
	v_mul_f32_e32 v33, v37, v33
	v_sub_f32_e32 v36, v44, v36
	v_add_f32_e32 v33, v36, v33
	v_mul_f32_e32 v43, 0x3f317218, v32
	v_add_f32_e32 v36, v35, v33
	v_fma_f32 v44, v32, s78, -v43
	v_mul_f32_e32 v37, v36, v36
	v_fmac_f32_e32 v44, 0xb102e308, v32
	v_sub_f32_e32 v32, v36, v35
	v_fmamk_f32 v39, v37, 0x3e9b6dac, v185
	v_sub_f32_e32 v32, v33, v32
	v_add_f32_e32 v33, v43, v44
	v_fmaak_f32 v39, v37, v39, 0x3f2aaada
	v_sub_f32_e32 v35, v33, v43
	v_ldexp_f32 v43, v36, 1
	v_mul_f32_e32 v36, v36, v37
	v_mul_f32_e32 v36, v36, v39
	v_add_f32_e32 v37, v43, v36
	v_sub_f32_e32 v39, v37, v43
	v_ldexp_f32 v32, v32, 1
	v_sub_f32_e32 v36, v36, v39
	v_add_f32_e32 v32, v32, v36
	v_add_f32_e32 v36, v37, v32
	v_sub_f32_e32 v37, v36, v37
	v_sub_f32_e32 v32, v32, v37
	v_add_f32_e32 v37, v33, v36
	v_sub_f32_e32 v39, v37, v33
	v_sub_f32_e32 v43, v37, v39
	v_sub_f32_e32 v35, v44, v35
	v_sub_f32_e32 v33, v33, v43
	v_sub_f32_e32 v36, v36, v39
	v_add_f32_e32 v33, v36, v33
	v_add_f32_e32 v36, v35, v32
	v_sub_f32_e32 v39, v36, v35
	v_sub_f32_e32 v43, v36, v39
	v_sub_f32_e32 v35, v35, v43
	v_sub_f32_e32 v32, v32, v39
	v_add_f32_e32 v33, v36, v33
	v_add_f32_e32 v32, v32, v35
	v_add_f32_e32 v35, v37, v33
	v_sub_f32_e32 v36, v35, v37
	v_sub_f32_e32 v33, v33, v36
	v_add_f32_e32 v32, v32, v33
	v_add_f32_e32 v32, v35, v32
	v_cndmask_b32_e32 v32, v226, v32, vcc
	v_cmp_lt_f32_e64 vcc, |v34|, s63
	v_ashrrev_i32_e32 v39, 31, v38
	s_nop 0
	v_cndmask_b32_e32 v32, v32, v34, vcc
	v_sub_f32_e32 v28, v28, v32
	v_lshlrev_b64 v[32:33], 14, v[38:39]
	v_mul_f32_e32 v28, 0x3fb8aa3b, v28
	v_lshl_add_u64 v[32:33], v[40:41], 0, v[32:33]
	global_store_dword v[32:33], v28, off
	v_readlane_b32 s100, v254, 1
	s_nop 1
	v_mov_b32_e32 v28, s100
	v_fmac_f32_e32 v28, v29, v162
	v_mul_f32_e64 v29, |v28|, s94
	v_fma_f32 v35, |v28|, s94, -v29
	v_rndne_f32_e32 v36, v29
	v_fma_f32 v35, |v28|, s64, v35
	v_sub_f32_e32 v29, v29, v36
	v_add_f32_e32 v29, v29, v35
	v_exp_f32_e32 v29, v29
	v_cvt_i32_f32_e32 v35, v36
	v_cmp_ngt_f32_e64 vcc, |v28|, s58
	v_min_f32_e32 v34, 0, v28
	v_ldexp_f32 v29, v29, v35
	v_cndmask_b32_e32 v29, 0, v29, vcc
	v_cmp_nlt_f32_e64 vcc, |v28|, s59
	s_nop 1
	v_cndmask_b32_e32 v35, v226, v29, vcc
	v_add_f32_e32 v36, 1.0, v35
	v_add_f32_e32 v28, -1.0, v36
	v_sub_f32_e32 v29, v28, v36
	v_add_f32_e32 v29, 1.0, v29
	v_sub_f32_e32 v28, v35, v28
	v_add_f32_e32 v37, v28, v29
	v_frexp_mant_f32_e32 v28, v36
	v_cmp_gt_f32_e32 vcc, s77, v28
	v_cvt_f64_f32_e32 v[28:29], v36
	v_frexp_exp_i32_f64_e32 v28, v[28:29]
	v_subbrev_co_u32_e32 v28, vcc, 0, v28, vcc
	v_sub_u32_e32 v29, 0, v28
	v_ldexp_f32 v36, v36, v29
	v_ldexp_f32 v29, v37, v29
	v_add_f32_e32 v37, -1.0, v36
	v_add_f32_e32 v39, 1.0, v37
	v_sub_f32_e32 v39, v36, v39
	v_add_f32_e32 v39, v29, v39
	v_add_f32_e32 v43, v37, v39
	v_sub_f32_e32 v37, v37, v43
	v_add_f32_e32 v37, v39, v37
	v_add_f32_e32 v39, 1.0, v36
	v_add_f32_e32 v44, -1.0, v39
	v_sub_f32_e32 v36, v36, v44
	v_add_f32_e32 v29, v29, v36
	v_add_f32_e32 v36, v39, v29
	v_sub_f32_e32 v39, v39, v36
	v_add_f32_e32 v29, v29, v39
	v_rcp_f32_e32 v39, v36
	v_cvt_f32_i32_e32 v28, v28
	v_cmp_neq_f32_e32 vcc, s62, v35
	v_mul_f32_e32 v44, v43, v39
	v_mul_f32_e32 v45, v36, v44
	v_fma_f32 v46, v44, v36, -v45
	v_fmac_f32_e32 v46, v44, v29
	v_add_f32_e32 v47, v45, v46
	v_sub_f32_e32 v48, v43, v47
	v_sub_f32_e32 v43, v43, v48
	v_sub_f32_e32 v45, v47, v45
	v_sub_f32_e32 v43, v43, v47
	v_add_f32_e32 v37, v37, v43
	v_sub_f32_e32 v43, v45, v46
	v_add_f32_e32 v37, v43, v37
	v_add_f32_e32 v43, v48, v37
	v_mul_f32_e32 v45, v39, v43
	v_mul_f32_e32 v46, v36, v45
	v_fma_f32 v36, v45, v36, -v46
	v_fmac_f32_e32 v36, v45, v29
	v_sub_f32_e32 v29, v48, v43
	v_add_f32_e32 v29, v37, v29
	v_add_f32_e32 v37, v46, v36
	v_sub_f32_e32 v47, v43, v37
	v_sub_f32_e32 v43, v43, v47
	v_sub_f32_e32 v46, v37, v46
	v_sub_f32_e32 v37, v43, v37
	v_add_f32_e32 v29, v29, v37
	v_sub_f32_e32 v36, v46, v36
	v_add_f32_e32 v29, v36, v29
	v_add_f32_e32 v36, v44, v45
	v_add_f32_e32 v29, v47, v29
	v_sub_f32_e32 v37, v36, v44
	v_mul_f32_e32 v29, v39, v29
	v_sub_f32_e32 v37, v45, v37
	v_add_f32_e32 v29, v37, v29
	v_mul_f32_e32 v44, 0x3f317218, v28
	v_add_f32_e32 v37, v36, v29
	v_fma_f32 v45, v28, s78, -v44
	v_mul_f32_e32 v39, v37, v37
	v_fmac_f32_e32 v45, 0xb102e308, v28
	v_sub_f32_e32 v28, v37, v36
	v_fmamk_f32 v43, v39, 0x3e9b6dac, v185
	v_sub_f32_e32 v28, v29, v28
	v_add_f32_e32 v29, v44, v45
	v_fmaak_f32 v43, v39, v43, 0x3f2aaada
	v_sub_f32_e32 v36, v29, v44
	v_ldexp_f32 v44, v37, 1
	v_mul_f32_e32 v37, v37, v39
	v_mul_f32_e32 v37, v37, v43
	v_add_f32_e32 v39, v44, v37
	v_sub_f32_e32 v43, v39, v44
	v_ldexp_f32 v28, v28, 1
	v_sub_f32_e32 v37, v37, v43
	v_add_f32_e32 v28, v28, v37
	v_add_f32_e32 v37, v39, v28
	v_sub_f32_e32 v39, v37, v39
	v_sub_f32_e32 v28, v28, v39
	v_add_f32_e32 v39, v29, v37
	v_sub_f32_e32 v43, v39, v29
	v_sub_f32_e32 v44, v39, v43
	v_sub_f32_e32 v36, v45, v36
	v_sub_f32_e32 v29, v29, v44
	v_sub_f32_e32 v37, v37, v43
	v_add_f32_e32 v29, v37, v29
	v_add_f32_e32 v37, v36, v28
	v_sub_f32_e32 v43, v37, v36
	v_sub_f32_e32 v44, v37, v43
	v_sub_f32_e32 v36, v36, v44
	v_sub_f32_e32 v28, v28, v43
	v_add_f32_e32 v29, v37, v29
	v_add_f32_e32 v28, v28, v36
	v_add_f32_e32 v36, v39, v29
	v_sub_f32_e32 v37, v36, v39
	v_sub_f32_e32 v29, v29, v37
	v_add_f32_e32 v28, v28, v29
	v_add_f32_e32 v28, v36, v28
	v_cndmask_b32_e32 v28, v226, v28, vcc
	v_cmp_lt_f32_e64 vcc, |v35|, s63
	s_nop 1
	v_cndmask_b32_e32 v28, v28, v35, vcc
	v_sub_f32_e32 v28, v34, v28
	v_mul_f32_e32 v34, 0x3fb8aa3b, v28
	v_or_b32_e32 v28, 1, v38
	v_ashrrev_i32_e32 v29, 31, v28
	v_lshlrev_b64 v[28:29], 14, v[28:29]
	v_lshl_add_u64 v[28:29], v[40:41], 0, v[28:29]
	global_store_dword v[28:29], v34, off
	v_readlane_b32 s100, v254, 2
	s_nop 1
	v_mov_b32_e32 v34, s100
	v_fmac_f32_e32 v34, v30, v162
	v_mul_f32_e64 v35, |v34|, s94
	v_fma_f32 v36, |v34|, s94, -v35
	v_rndne_f32_e32 v37, v35
	v_fma_f32 v36, |v34|, s64, v36
	v_sub_f32_e32 v35, v35, v37
	v_add_f32_e32 v35, v35, v36
	v_exp_f32_e32 v35, v35
	v_cvt_i32_f32_e32 v36, v37
	v_cmp_ngt_f32_e64 vcc, |v34|, s58
	v_min_f32_e32 v30, 0, v34
	v_ldexp_f32 v35, v35, v36
	v_cndmask_b32_e32 v35, 0, v35, vcc
	v_cmp_nlt_f32_e64 vcc, |v34|, s59
	s_nop 1
	v_cndmask_b32_e32 v36, v226, v35, vcc
	v_add_f32_e32 v37, 1.0, v36
	v_add_f32_e32 v34, -1.0, v37
	v_sub_f32_e32 v35, v34, v37
	v_add_f32_e32 v35, 1.0, v35
	v_sub_f32_e32 v34, v36, v34
	v_add_f32_e32 v39, v34, v35
	v_frexp_mant_f32_e32 v34, v37
	v_cmp_gt_f32_e32 vcc, s77, v34
	v_cvt_f64_f32_e32 v[34:35], v37
	v_frexp_exp_i32_f64_e32 v34, v[34:35]
	v_subbrev_co_u32_e32 v34, vcc, 0, v34, vcc
	v_sub_u32_e32 v35, 0, v34
	v_ldexp_f32 v37, v37, v35
	v_ldexp_f32 v35, v39, v35
	v_add_f32_e32 v39, -1.0, v37
	v_add_f32_e32 v43, 1.0, v39
	v_sub_f32_e32 v43, v37, v43
	v_add_f32_e32 v43, v35, v43
	v_add_f32_e32 v44, v39, v43
	v_sub_f32_e32 v39, v39, v44
	v_add_f32_e32 v39, v43, v39
	v_add_f32_e32 v43, 1.0, v37
	v_add_f32_e32 v45, -1.0, v43
	v_sub_f32_e32 v37, v37, v45
	v_add_f32_e32 v35, v35, v37
	v_add_f32_e32 v37, v43, v35
	v_sub_f32_e32 v43, v43, v37
	v_add_f32_e32 v35, v35, v43
	v_rcp_f32_e32 v43, v37
	v_cvt_f32_i32_e32 v34, v34
	v_cmp_neq_f32_e32 vcc, s62, v36
	v_mul_f32_e32 v45, v44, v43
	v_mul_f32_e32 v46, v37, v45
	v_fma_f32 v47, v45, v37, -v46
	v_fmac_f32_e32 v47, v45, v35
	v_add_f32_e32 v48, v46, v47
	v_sub_f32_e32 v49, v44, v48
	v_sub_f32_e32 v44, v44, v49
	v_sub_f32_e32 v46, v48, v46
	v_sub_f32_e32 v44, v44, v48
	v_add_f32_e32 v39, v39, v44
	v_sub_f32_e32 v44, v46, v47
	v_add_f32_e32 v39, v44, v39
	v_add_f32_e32 v44, v49, v39
	v_mul_f32_e32 v46, v43, v44
	v_mul_f32_e32 v47, v37, v46
	v_fma_f32 v37, v46, v37, -v47
	v_fmac_f32_e32 v37, v46, v35
	v_sub_f32_e32 v35, v49, v44
	v_add_f32_e32 v35, v39, v35
	v_add_f32_e32 v39, v47, v37
	v_sub_f32_e32 v48, v44, v39
	v_sub_f32_e32 v44, v44, v48
	v_sub_f32_e32 v47, v39, v47
	v_sub_f32_e32 v39, v44, v39
	v_add_f32_e32 v35, v35, v39
	v_sub_f32_e32 v37, v47, v37
	v_add_f32_e32 v35, v37, v35
	v_add_f32_e32 v37, v45, v46
	v_add_f32_e32 v35, v48, v35
	v_sub_f32_e32 v39, v37, v45
	v_mul_f32_e32 v35, v43, v35
	v_sub_f32_e32 v39, v46, v39
	v_add_f32_e32 v35, v39, v35
	v_mul_f32_e32 v45, 0x3f317218, v34
	v_add_f32_e32 v39, v37, v35
	v_fma_f32 v46, v34, s78, -v45
	v_mul_f32_e32 v43, v39, v39
	v_fmac_f32_e32 v46, 0xb102e308, v34
	v_sub_f32_e32 v34, v39, v37
	v_fmamk_f32 v44, v43, 0x3e9b6dac, v185
	v_sub_f32_e32 v34, v35, v34
	v_add_f32_e32 v35, v45, v46
	v_fmaak_f32 v44, v43, v44, 0x3f2aaada
	v_sub_f32_e32 v37, v35, v45
	v_ldexp_f32 v45, v39, 1
	v_mul_f32_e32 v39, v39, v43
	v_mul_f32_e32 v39, v39, v44
	v_add_f32_e32 v43, v45, v39
	v_sub_f32_e32 v44, v43, v45
	v_ldexp_f32 v34, v34, 1
	v_sub_f32_e32 v39, v39, v44
	v_add_f32_e32 v34, v34, v39
	v_add_f32_e32 v39, v43, v34
	v_sub_f32_e32 v43, v39, v43
	v_sub_f32_e32 v34, v34, v43
	v_add_f32_e32 v43, v35, v39
	v_sub_f32_e32 v44, v43, v35
	v_sub_f32_e32 v45, v43, v44
	v_sub_f32_e32 v37, v46, v37
	v_sub_f32_e32 v35, v35, v45
	v_sub_f32_e32 v39, v39, v44
	v_add_f32_e32 v35, v39, v35
	v_add_f32_e32 v39, v37, v34
	v_sub_f32_e32 v44, v39, v37
	v_sub_f32_e32 v45, v39, v44
	v_sub_f32_e32 v37, v37, v45
	v_sub_f32_e32 v34, v34, v44
	v_add_f32_e32 v35, v39, v35
	v_add_f32_e32 v34, v34, v37
	v_add_f32_e32 v37, v43, v35
	v_sub_f32_e32 v39, v37, v43
	v_sub_f32_e32 v35, v35, v39
	v_add_f32_e32 v34, v34, v35
	v_add_f32_e32 v34, v37, v34
	v_cndmask_b32_e32 v34, v226, v34, vcc
	v_cmp_lt_f32_e64 vcc, |v36|, s63
	s_nop 1
	v_cndmask_b32_e32 v34, v34, v36, vcc
	v_sub_f32_e32 v30, v30, v34
	v_or_b32_e32 v34, 2, v38
	v_ashrrev_i32_e32 v35, 31, v34
	v_lshlrev_b64 v[34:35], 14, v[34:35]
	v_mul_f32_e32 v30, 0x3fb8aa3b, v30
	v_lshl_add_u64 v[34:35], v[40:41], 0, v[34:35]
	global_store_dword v[34:35], v30, off
	v_readlane_b32 s100, v254, 3
	s_nop 1
	v_mov_b32_e32 v30, s100
	v_fmac_f32_e32 v30, v31, v162
	v_mul_f32_e64 v31, |v30|, s94
	v_fma_f32 v37, |v30|, s94, -v31
	v_rndne_f32_e32 v39, v31
	v_fma_f32 v37, |v30|, s64, v37
	v_sub_f32_e32 v31, v31, v39
	v_add_f32_e32 v31, v31, v37
	v_exp_f32_e32 v31, v31
	v_cvt_i32_f32_e32 v37, v39
	v_cmp_ngt_f32_e64 vcc, |v30|, s58
	v_min_f32_e32 v36, 0, v30
	v_ldexp_f32 v31, v31, v37
	v_cndmask_b32_e32 v31, 0, v31, vcc
	v_cmp_nlt_f32_e64 vcc, |v30|, s59
	s_nop 1
	v_cndmask_b32_e32 v37, v226, v31, vcc
	v_add_f32_e32 v39, 1.0, v37
	v_add_f32_e32 v30, -1.0, v39
	v_sub_f32_e32 v31, v30, v39
	v_add_f32_e32 v31, 1.0, v31
	v_sub_f32_e32 v30, v37, v30
	v_add_f32_e32 v43, v30, v31
	v_frexp_mant_f32_e32 v30, v39
	v_cmp_gt_f32_e32 vcc, s77, v30
	v_cvt_f64_f32_e32 v[30:31], v39
	v_frexp_exp_i32_f64_e32 v30, v[30:31]
	v_subbrev_co_u32_e32 v30, vcc, 0, v30, vcc
	v_sub_u32_e32 v31, 0, v30
	v_ldexp_f32 v39, v39, v31
	v_ldexp_f32 v31, v43, v31
	v_add_f32_e32 v43, -1.0, v39
	v_add_f32_e32 v44, 1.0, v43
	v_sub_f32_e32 v44, v39, v44
	v_add_f32_e32 v44, v31, v44
	v_add_f32_e32 v45, v43, v44
	v_sub_f32_e32 v43, v43, v45
	v_add_f32_e32 v43, v44, v43
	v_add_f32_e32 v44, 1.0, v39
	v_add_f32_e32 v46, -1.0, v44
	v_sub_f32_e32 v39, v39, v46
	v_add_f32_e32 v31, v31, v39
	v_add_f32_e32 v39, v44, v31
	v_sub_f32_e32 v44, v44, v39
	v_add_f32_e32 v31, v31, v44
	v_rcp_f32_e32 v44, v39
	v_cvt_f32_i32_e32 v30, v30
	v_cmp_neq_f32_e32 vcc, s62, v37
	v_mul_f32_e32 v46, v45, v44
	v_mul_f32_e32 v47, v39, v46
	v_fma_f32 v48, v46, v39, -v47
	v_fmac_f32_e32 v48, v46, v31
	v_add_f32_e32 v49, v47, v48
	v_sub_f32_e32 v50, v45, v49
	v_sub_f32_e32 v45, v45, v50
	v_sub_f32_e32 v47, v49, v47
	v_sub_f32_e32 v45, v45, v49
	v_add_f32_e32 v43, v43, v45
	v_sub_f32_e32 v45, v47, v48
	v_add_f32_e32 v43, v45, v43
	v_add_f32_e32 v45, v50, v43
	v_mul_f32_e32 v47, v44, v45
	v_mul_f32_e32 v48, v39, v47
	v_fma_f32 v39, v47, v39, -v48
	v_fmac_f32_e32 v39, v47, v31
	v_sub_f32_e32 v31, v50, v45
	v_add_f32_e32 v31, v43, v31
	v_add_f32_e32 v43, v48, v39
	v_sub_f32_e32 v49, v45, v43
	v_sub_f32_e32 v45, v45, v49
	v_sub_f32_e32 v48, v43, v48
	v_sub_f32_e32 v43, v45, v43
	v_add_f32_e32 v31, v31, v43
	v_sub_f32_e32 v39, v48, v39
	v_add_f32_e32 v31, v39, v31
	v_add_f32_e32 v39, v46, v47
	v_add_f32_e32 v31, v49, v31
	v_sub_f32_e32 v43, v39, v46
	v_mul_f32_e32 v31, v44, v31
	v_sub_f32_e32 v43, v47, v43
	v_add_f32_e32 v31, v43, v31
	v_mul_f32_e32 v46, 0x3f317218, v30
	v_add_f32_e32 v43, v39, v31
	v_fma_f32 v47, v30, s78, -v46
	v_mul_f32_e32 v44, v43, v43
	v_fmac_f32_e32 v47, 0xb102e308, v30
	v_sub_f32_e32 v30, v43, v39
	v_fmamk_f32 v45, v44, 0x3e9b6dac, v185
	v_sub_f32_e32 v30, v31, v30
	v_add_f32_e32 v31, v46, v47
	v_fmaak_f32 v45, v44, v45, 0x3f2aaada
	v_sub_f32_e32 v39, v31, v46
	v_ldexp_f32 v46, v43, 1
	v_mul_f32_e32 v43, v43, v44
	v_mul_f32_e32 v43, v43, v45
	v_add_f32_e32 v44, v46, v43
	v_sub_f32_e32 v45, v44, v46
	v_ldexp_f32 v30, v30, 1
	v_sub_f32_e32 v43, v43, v45
	v_add_f32_e32 v30, v30, v43
	v_add_f32_e32 v43, v44, v30
	v_sub_f32_e32 v44, v43, v44
	v_sub_f32_e32 v30, v30, v44
	v_add_f32_e32 v44, v31, v43
	v_sub_f32_e32 v45, v44, v31
	v_sub_f32_e32 v46, v44, v45
	v_sub_f32_e32 v39, v47, v39
	v_sub_f32_e32 v31, v31, v46
	v_sub_f32_e32 v43, v43, v45
	v_add_f32_e32 v31, v43, v31
	v_add_f32_e32 v43, v39, v30
	v_sub_f32_e32 v45, v43, v39
	v_sub_f32_e32 v46, v43, v45
	v_sub_f32_e32 v39, v39, v46
	v_sub_f32_e32 v30, v30, v45
	v_add_f32_e32 v31, v43, v31
	v_add_f32_e32 v30, v30, v39
	v_add_f32_e32 v39, v44, v31
	v_sub_f32_e32 v43, v39, v44
	v_sub_f32_e32 v31, v31, v43
	v_add_f32_e32 v30, v30, v31
	v_add_f32_e32 v30, v39, v30
	v_cndmask_b32_e32 v30, v226, v30, vcc
	v_cmp_lt_f32_e64 vcc, |v37|, s63
	s_nop 1
	v_cndmask_b32_e32 v30, v30, v37, vcc
	v_sub_f32_e32 v30, v36, v30
	v_mul_f32_e32 v36, 0x3fb8aa3b, v30
	v_or_b32_e32 v30, 3, v38
	v_ashrrev_i32_e32 v31, 31, v30
	v_lshlrev_b64 v[30:31], 14, v[30:31]
	v_lshl_add_u64 v[30:31], v[40:41], 0, v[30:31]
	global_store_dword v[30:31], v36, off
	v_readlane_b32 s100, v254, 4
	s_nop 1
	v_mov_b32_e32 v36, s100
	v_fmac_f32_e32 v36, v24, v162
	v_mul_f32_e64 v37, |v36|, s94
	v_fma_f32 v39, |v36|, s94, -v37
	v_rndne_f32_e32 v43, v37
	v_fma_f32 v39, |v36|, s64, v39
	v_sub_f32_e32 v37, v37, v43
	v_add_f32_e32 v37, v37, v39
	v_exp_f32_e32 v37, v37
	v_cvt_i32_f32_e32 v39, v43
	v_cmp_ngt_f32_e64 vcc, |v36|, s58
	v_min_f32_e32 v24, 0, v36
	v_ldexp_f32 v37, v37, v39
	v_cndmask_b32_e32 v37, 0, v37, vcc
	v_cmp_nlt_f32_e64 vcc, |v36|, s59
	s_nop 1
	v_cndmask_b32_e32 v39, v226, v37, vcc
	v_add_f32_e32 v43, 1.0, v39
	v_add_f32_e32 v36, -1.0, v43
	v_sub_f32_e32 v37, v36, v43
	v_add_f32_e32 v37, 1.0, v37
	v_sub_f32_e32 v36, v39, v36
	v_add_f32_e32 v44, v36, v37
	v_frexp_mant_f32_e32 v36, v43
	v_cmp_gt_f32_e32 vcc, s77, v36
	v_cvt_f64_f32_e32 v[36:37], v43
	v_frexp_exp_i32_f64_e32 v36, v[36:37]
	v_subbrev_co_u32_e32 v36, vcc, 0, v36, vcc
	v_sub_u32_e32 v37, 0, v36
	v_ldexp_f32 v43, v43, v37
	v_ldexp_f32 v37, v44, v37
	v_add_f32_e32 v44, -1.0, v43
	v_add_f32_e32 v45, 1.0, v44
	v_sub_f32_e32 v45, v43, v45
	v_add_f32_e32 v45, v37, v45
	v_add_f32_e32 v46, v44, v45
	v_sub_f32_e32 v44, v44, v46
	v_add_f32_e32 v44, v45, v44
	v_add_f32_e32 v45, 1.0, v43
	v_add_f32_e32 v47, -1.0, v45
	v_sub_f32_e32 v43, v43, v47
	v_add_f32_e32 v37, v37, v43
	v_add_f32_e32 v43, v45, v37
	v_sub_f32_e32 v45, v45, v43
	v_add_f32_e32 v37, v37, v45
	v_rcp_f32_e32 v45, v43
	v_cvt_f32_i32_e32 v36, v36
	v_cmp_neq_f32_e32 vcc, s62, v39
	v_mul_f32_e32 v47, v46, v45
	v_mul_f32_e32 v48, v43, v47
	v_fma_f32 v49, v47, v43, -v48
	v_fmac_f32_e32 v49, v47, v37
	v_add_f32_e32 v50, v48, v49
	v_sub_f32_e32 v51, v46, v50
	v_sub_f32_e32 v46, v46, v51
	v_sub_f32_e32 v48, v50, v48
	v_sub_f32_e32 v46, v46, v50
	v_add_f32_e32 v44, v44, v46
	v_sub_f32_e32 v46, v48, v49
	v_add_f32_e32 v44, v46, v44
	v_add_f32_e32 v46, v51, v44
	v_mul_f32_e32 v48, v45, v46
	v_mul_f32_e32 v49, v43, v48
	v_fma_f32 v43, v48, v43, -v49
	v_fmac_f32_e32 v43, v48, v37
	v_sub_f32_e32 v37, v51, v46
	v_add_f32_e32 v37, v44, v37
	v_add_f32_e32 v44, v49, v43
	v_sub_f32_e32 v50, v46, v44
	v_sub_f32_e32 v46, v46, v50
	v_sub_f32_e32 v49, v44, v49
	v_sub_f32_e32 v44, v46, v44
	v_add_f32_e32 v37, v37, v44
	v_sub_f32_e32 v43, v49, v43
	v_add_f32_e32 v37, v43, v37
	v_add_f32_e32 v43, v47, v48
	v_add_f32_e32 v37, v50, v37
	v_sub_f32_e32 v44, v43, v47
	v_mul_f32_e32 v37, v45, v37
	v_sub_f32_e32 v44, v48, v44
	v_add_f32_e32 v37, v44, v37
	v_mul_f32_e32 v47, 0x3f317218, v36
	v_add_f32_e32 v44, v43, v37
	v_fma_f32 v48, v36, s78, -v47
	v_mul_f32_e32 v45, v44, v44
	v_fmac_f32_e32 v48, 0xb102e308, v36
	v_sub_f32_e32 v36, v44, v43
	v_fmamk_f32 v46, v45, 0x3e9b6dac, v185
	v_sub_f32_e32 v36, v37, v36
	v_add_f32_e32 v37, v47, v48
	v_fmaak_f32 v46, v45, v46, 0x3f2aaada
	v_sub_f32_e32 v43, v37, v47
	v_ldexp_f32 v47, v44, 1
	v_mul_f32_e32 v44, v44, v45
	v_mul_f32_e32 v44, v44, v46
	v_add_f32_e32 v45, v47, v44
	v_sub_f32_e32 v46, v45, v47
	v_ldexp_f32 v36, v36, 1
	v_sub_f32_e32 v44, v44, v46
	v_add_f32_e32 v36, v36, v44
	v_add_f32_e32 v44, v45, v36
	v_sub_f32_e32 v45, v44, v45
	v_sub_f32_e32 v36, v36, v45
	v_add_f32_e32 v45, v37, v44
	v_sub_f32_e32 v46, v45, v37
	v_sub_f32_e32 v47, v45, v46
	v_sub_f32_e32 v43, v48, v43
	v_sub_f32_e32 v37, v37, v47
	v_sub_f32_e32 v44, v44, v46
	v_add_f32_e32 v37, v44, v37
	v_add_f32_e32 v44, v43, v36
	v_sub_f32_e32 v46, v44, v43
	v_sub_f32_e32 v47, v44, v46
	v_sub_f32_e32 v43, v43, v47
	v_sub_f32_e32 v36, v36, v46
	v_add_f32_e32 v37, v44, v37
	v_add_f32_e32 v36, v36, v43
	v_add_f32_e32 v43, v45, v37
	v_sub_f32_e32 v44, v43, v45
	v_sub_f32_e32 v37, v37, v44
	v_add_f32_e32 v36, v36, v37
	v_add_f32_e32 v36, v43, v36
	v_cndmask_b32_e32 v36, v226, v36, vcc
	v_cmp_lt_f32_e64 vcc, |v39|, s63
	s_nop 1
	v_cndmask_b32_e32 v36, v36, v39, vcc
	v_sub_f32_e32 v24, v24, v36
	v_or_b32_e32 v36, 4, v38
	v_ashrrev_i32_e32 v37, 31, v36
	v_lshlrev_b64 v[36:37], 14, v[36:37]
	v_mul_f32_e32 v24, 0x3fb8aa3b, v24
	v_lshl_add_u64 v[36:37], v[40:41], 0, v[36:37]
	global_store_dword v[36:37], v24, off
	v_readlane_b32 s100, v254, 5
	s_nop 1
	v_mov_b32_e32 v24, s100
	v_fmac_f32_e32 v24, v25, v162
	v_mul_f32_e64 v25, |v24|, s94
	v_fma_f32 v43, |v24|, s94, -v25
	v_rndne_f32_e32 v44, v25
	v_fma_f32 v43, |v24|, s64, v43
	v_sub_f32_e32 v25, v25, v44
	v_add_f32_e32 v25, v25, v43
	v_exp_f32_e32 v25, v25
	v_cvt_i32_f32_e32 v43, v44
	v_cmp_ngt_f32_e64 vcc, |v24|, s58
	v_min_f32_e32 v39, 0, v24
	v_ldexp_f32 v25, v25, v43
	v_cndmask_b32_e32 v25, 0, v25, vcc
	v_cmp_nlt_f32_e64 vcc, |v24|, s59
	s_nop 1
	v_cndmask_b32_e32 v43, v226, v25, vcc
	v_add_f32_e32 v44, 1.0, v43
	v_add_f32_e32 v24, -1.0, v44
	v_sub_f32_e32 v25, v24, v44
	v_add_f32_e32 v25, 1.0, v25
	v_sub_f32_e32 v24, v43, v24
	v_add_f32_e32 v45, v24, v25
	v_frexp_mant_f32_e32 v24, v44
	v_cmp_gt_f32_e32 vcc, s77, v24
	v_cvt_f64_f32_e32 v[24:25], v44
	v_frexp_exp_i32_f64_e32 v24, v[24:25]
	v_subbrev_co_u32_e32 v24, vcc, 0, v24, vcc
	v_sub_u32_e32 v25, 0, v24
	v_ldexp_f32 v44, v44, v25
	v_ldexp_f32 v25, v45, v25
	v_add_f32_e32 v45, -1.0, v44
	v_add_f32_e32 v46, 1.0, v45
	v_sub_f32_e32 v46, v44, v46
	v_add_f32_e32 v46, v25, v46
	v_add_f32_e32 v47, v45, v46
	v_sub_f32_e32 v45, v45, v47
	v_add_f32_e32 v45, v46, v45
	v_add_f32_e32 v46, 1.0, v44
	v_add_f32_e32 v48, -1.0, v46
	v_sub_f32_e32 v44, v44, v48
	v_add_f32_e32 v25, v25, v44
	v_add_f32_e32 v44, v46, v25
	v_sub_f32_e32 v46, v46, v44
	v_add_f32_e32 v25, v25, v46
	v_rcp_f32_e32 v46, v44
	v_cvt_f32_i32_e32 v24, v24
	v_cmp_neq_f32_e32 vcc, s62, v43
	v_mul_f32_e32 v48, v47, v46
	v_mul_f32_e32 v49, v44, v48
	v_fma_f32 v50, v48, v44, -v49
	v_fmac_f32_e32 v50, v48, v25
	v_add_f32_e32 v51, v49, v50
	v_sub_f32_e32 v52, v47, v51
	v_sub_f32_e32 v47, v47, v52
	v_sub_f32_e32 v49, v51, v49
	v_sub_f32_e32 v47, v47, v51
	v_add_f32_e32 v45, v45, v47
	v_sub_f32_e32 v47, v49, v50
	v_add_f32_e32 v45, v47, v45
	v_add_f32_e32 v47, v52, v45
	v_mul_f32_e32 v49, v46, v47
	v_mul_f32_e32 v50, v44, v49
	v_fma_f32 v44, v49, v44, -v50
	v_fmac_f32_e32 v44, v49, v25
	v_sub_f32_e32 v25, v52, v47
	v_add_f32_e32 v25, v45, v25
	v_add_f32_e32 v45, v50, v44
	v_sub_f32_e32 v51, v47, v45
	v_sub_f32_e32 v47, v47, v51
	v_sub_f32_e32 v50, v45, v50
	v_sub_f32_e32 v45, v47, v45
	v_add_f32_e32 v25, v25, v45
	v_sub_f32_e32 v44, v50, v44
	v_add_f32_e32 v25, v44, v25
	v_add_f32_e32 v44, v48, v49
	v_add_f32_e32 v25, v51, v25
	v_sub_f32_e32 v45, v44, v48
	v_mul_f32_e32 v25, v46, v25
	v_sub_f32_e32 v45, v49, v45
	v_add_f32_e32 v25, v45, v25
	v_mul_f32_e32 v48, 0x3f317218, v24
	v_add_f32_e32 v45, v44, v25
	v_fma_f32 v49, v24, s78, -v48
	v_mul_f32_e32 v46, v45, v45
	v_fmac_f32_e32 v49, 0xb102e308, v24
	v_sub_f32_e32 v24, v45, v44
	v_fmamk_f32 v47, v46, 0x3e9b6dac, v185
	v_sub_f32_e32 v24, v25, v24
	v_add_f32_e32 v25, v48, v49
	v_fmaak_f32 v47, v46, v47, 0x3f2aaada
	v_sub_f32_e32 v44, v25, v48
	v_ldexp_f32 v48, v45, 1
	v_mul_f32_e32 v45, v45, v46
	v_mul_f32_e32 v45, v45, v47
	v_add_f32_e32 v46, v48, v45
	v_sub_f32_e32 v47, v46, v48
	v_ldexp_f32 v24, v24, 1
	v_sub_f32_e32 v45, v45, v47
	v_add_f32_e32 v24, v24, v45
	v_add_f32_e32 v45, v46, v24
	v_sub_f32_e32 v46, v45, v46
	v_sub_f32_e32 v24, v24, v46
	v_add_f32_e32 v46, v25, v45
	v_sub_f32_e32 v47, v46, v25
	v_sub_f32_e32 v48, v46, v47
	v_sub_f32_e32 v44, v49, v44
	v_sub_f32_e32 v25, v25, v48
	v_sub_f32_e32 v45, v45, v47
	v_add_f32_e32 v25, v45, v25
	v_add_f32_e32 v45, v44, v24
	v_sub_f32_e32 v47, v45, v44
	v_sub_f32_e32 v48, v45, v47
	v_sub_f32_e32 v44, v44, v48
	v_sub_f32_e32 v24, v24, v47
	v_add_f32_e32 v25, v45, v25
	v_add_f32_e32 v24, v24, v44
	v_add_f32_e32 v44, v46, v25
	v_sub_f32_e32 v45, v44, v46
	v_sub_f32_e32 v25, v25, v45
	v_add_f32_e32 v24, v24, v25
	v_add_f32_e32 v24, v44, v24
	v_cndmask_b32_e32 v24, v226, v24, vcc
	v_cmp_lt_f32_e64 vcc, |v43|, s63
	s_nop 1
	v_cndmask_b32_e32 v24, v24, v43, vcc
	v_sub_f32_e32 v24, v39, v24
	v_mul_f32_e32 v39, 0x3fb8aa3b, v24
	v_or_b32_e32 v24, 5, v38
	v_ashrrev_i32_e32 v25, 31, v24
	v_lshlrev_b64 v[24:25], 14, v[24:25]
	v_lshl_add_u64 v[24:25], v[40:41], 0, v[24:25]
	global_store_dword v[24:25], v39, off
	v_readlane_b32 s100, v254, 6
	s_nop 1
	v_mov_b32_e32 v39, s100
	v_or_b32_e32 v38, 6, v38
	v_fmac_f32_e32 v39, v26, v162
	v_mul_f32_e64 v43, |v39|, s94
	v_fma_f32 v44, |v39|, s94, -v43
	v_rndne_f32_e32 v45, v43
	v_fma_f32 v44, |v39|, s64, v44
	v_sub_f32_e32 v43, v43, v45
	v_add_f32_e32 v43, v43, v44
	v_exp_f32_e32 v43, v43
	v_cvt_i32_f32_e32 v44, v45
	v_cmp_ngt_f32_e64 vcc, |v39|, s58
	v_min_f32_e32 v26, 0, v39
	v_ldexp_f32 v43, v43, v44
	v_cndmask_b32_e32 v43, 0, v43, vcc
	v_cmp_nlt_f32_e64 vcc, |v39|, s59
	s_nop 1
	v_cndmask_b32_e32 v39, v226, v43, vcc
	v_add_f32_e32 v43, 1.0, v39
	v_add_f32_e32 v44, -1.0, v43
	v_sub_f32_e32 v45, v44, v43
	v_add_f32_e32 v45, 1.0, v45
	v_sub_f32_e32 v44, v39, v44
	v_add_f32_e32 v46, v44, v45
	v_frexp_mant_f32_e32 v44, v43
	v_cmp_gt_f32_e32 vcc, s77, v44
	v_cvt_f64_f32_e32 v[44:45], v43
	v_frexp_exp_i32_f64_e32 v44, v[44:45]
	v_subbrev_co_u32_e32 v44, vcc, 0, v44, vcc
	v_sub_u32_e32 v45, 0, v44
	v_ldexp_f32 v43, v43, v45
	v_ldexp_f32 v45, v46, v45
	v_add_f32_e32 v46, -1.0, v43
	v_add_f32_e32 v47, 1.0, v46
	v_sub_f32_e32 v47, v43, v47
	v_add_f32_e32 v47, v45, v47
	v_add_f32_e32 v48, v46, v47
	v_sub_f32_e32 v46, v46, v48
	v_add_f32_e32 v46, v47, v46
	v_add_f32_e32 v47, 1.0, v43
	v_add_f32_e32 v49, -1.0, v47
	v_sub_f32_e32 v43, v43, v49
	v_add_f32_e32 v43, v45, v43
	v_add_f32_e32 v45, v47, v43
	v_sub_f32_e32 v47, v47, v45
	v_add_f32_e32 v43, v43, v47
	v_rcp_f32_e32 v47, v45
	v_cvt_f32_i32_e32 v44, v44
	v_cmp_neq_f32_e32 vcc, s62, v39
	v_mul_f32_e32 v49, v48, v47
	v_mul_f32_e32 v50, v45, v49
	v_fma_f32 v51, v49, v45, -v50
	v_fmac_f32_e32 v51, v49, v43
	v_add_f32_e32 v52, v50, v51
	v_sub_f32_e32 v53, v48, v52
	v_sub_f32_e32 v48, v48, v53
	v_sub_f32_e32 v50, v52, v50
	v_sub_f32_e32 v48, v48, v52
	v_add_f32_e32 v46, v46, v48
	v_sub_f32_e32 v48, v50, v51
	v_add_f32_e32 v46, v48, v46
	v_add_f32_e32 v48, v53, v46
	v_mul_f32_e32 v50, v47, v48
	v_mul_f32_e32 v51, v45, v50
	v_fma_f32 v45, v50, v45, -v51
	v_fmac_f32_e32 v45, v50, v43
	v_sub_f32_e32 v43, v53, v48
	v_add_f32_e32 v43, v46, v43
	v_add_f32_e32 v46, v51, v45
	v_sub_f32_e32 v52, v48, v46
	v_sub_f32_e32 v48, v48, v52
	v_sub_f32_e32 v51, v46, v51
	v_sub_f32_e32 v46, v48, v46
	v_add_f32_e32 v43, v43, v46
	v_sub_f32_e32 v45, v51, v45
	v_add_f32_e32 v43, v45, v43
	v_add_f32_e32 v45, v49, v50
	v_add_f32_e32 v43, v52, v43
	v_sub_f32_e32 v46, v45, v49
	v_mul_f32_e32 v43, v47, v43
	v_sub_f32_e32 v46, v50, v46
	v_add_f32_e32 v43, v46, v43
	v_mul_f32_e32 v49, 0x3f317218, v44
	v_add_f32_e32 v46, v45, v43
	v_fma_f32 v50, v44, s78, -v49
	v_mul_f32_e32 v47, v46, v46
	v_fmac_f32_e32 v50, 0xb102e308, v44
	v_sub_f32_e32 v44, v46, v45
	v_fmamk_f32 v48, v47, 0x3e9b6dac, v185
	v_sub_f32_e32 v43, v43, v44
	v_add_f32_e32 v44, v49, v50
	v_fmaak_f32 v48, v47, v48, 0x3f2aaada
	v_sub_f32_e32 v45, v44, v49
	v_ldexp_f32 v49, v46, 1
	v_mul_f32_e32 v46, v46, v47
	v_mul_f32_e32 v46, v46, v48
	v_add_f32_e32 v47, v49, v46
	v_sub_f32_e32 v48, v47, v49
	v_ldexp_f32 v43, v43, 1
	v_sub_f32_e32 v46, v46, v48
	v_add_f32_e32 v43, v43, v46
	v_add_f32_e32 v46, v47, v43
	v_sub_f32_e32 v47, v46, v47
	v_sub_f32_e32 v43, v43, v47
	v_add_f32_e32 v47, v44, v46
	v_sub_f32_e32 v48, v47, v44
	v_sub_f32_e32 v49, v47, v48
	v_sub_f32_e32 v45, v50, v45
	v_sub_f32_e32 v44, v44, v49
	v_sub_f32_e32 v46, v46, v48
	v_add_f32_e32 v44, v46, v44
	v_add_f32_e32 v46, v45, v43
	v_sub_f32_e32 v48, v46, v45
	v_sub_f32_e32 v49, v46, v48
	v_sub_f32_e32 v45, v45, v49
	v_sub_f32_e32 v43, v43, v48
	v_add_f32_e32 v44, v46, v44
	v_add_f32_e32 v43, v43, v45
	v_add_f32_e32 v45, v47, v44
	v_sub_f32_e32 v46, v45, v47
	v_sub_f32_e32 v44, v44, v46
	v_add_f32_e32 v43, v43, v44
	v_add_f32_e32 v43, v45, v43
	v_cndmask_b32_e32 v43, v226, v43, vcc
	v_cmp_lt_f32_e64 vcc, |v39|, s63
	s_nop 1
	v_cndmask_b32_e32 v39, v43, v39, vcc
	v_sub_f32_e32 v26, v26, v39
	v_ashrrev_i32_e32 v39, 31, v38
	v_lshlrev_b64 v[38:39], 14, v[38:39]
	v_mul_f32_e32 v26, 0x3fb8aa3b, v26
	v_lshl_add_u64 v[38:39], v[40:41], 0, v[38:39]
	global_store_dword v[38:39], v26, off
	v_readlane_b32 s100, v254, 7
	s_nop 1
	v_mov_b32_e32 v26, s100
	v_fmac_f32_e32 v26, v27, v162
	v_mul_f32_e64 v27, |v26|, s94
	v_fma_f32 v44, |v26|, s94, -v27
	v_rndne_f32_e32 v45, v27
	v_fma_f32 v44, |v26|, s64, v44
	v_sub_f32_e32 v27, v27, v45
	v_add_f32_e32 v27, v27, v44
	v_exp_f32_e32 v27, v27
	v_cvt_i32_f32_e32 v44, v45
	v_cmp_ngt_f32_e64 vcc, |v26|, s58
	v_min_f32_e32 v43, 0, v26
	v_ldexp_f32 v27, v27, v44
	v_cndmask_b32_e32 v27, 0, v27, vcc
	v_cmp_nlt_f32_e64 vcc, |v26|, s59
	s_nop 1
	v_cndmask_b32_e32 v44, v226, v27, vcc
	v_add_f32_e32 v45, 1.0, v44
	v_add_f32_e32 v26, -1.0, v45
	v_sub_f32_e32 v27, v26, v45
	v_add_f32_e32 v27, 1.0, v27
	v_sub_f32_e32 v26, v44, v26
	v_add_f32_e32 v46, v26, v27
	v_frexp_mant_f32_e32 v26, v45
	v_cmp_gt_f32_e32 vcc, s77, v26
	v_cvt_f64_f32_e32 v[26:27], v45
	v_frexp_exp_i32_f64_e32 v26, v[26:27]
	v_subbrev_co_u32_e32 v26, vcc, 0, v26, vcc
	v_sub_u32_e32 v27, 0, v26
	v_ldexp_f32 v45, v45, v27
	v_ldexp_f32 v27, v46, v27
	v_add_f32_e32 v46, -1.0, v45
	v_add_f32_e32 v47, 1.0, v46
	v_sub_f32_e32 v47, v45, v47
	v_add_f32_e32 v47, v27, v47
	v_add_f32_e32 v48, v46, v47
	v_sub_f32_e32 v46, v46, v48
	v_add_f32_e32 v46, v47, v46
	v_add_f32_e32 v47, 1.0, v45
	v_add_f32_e32 v49, -1.0, v47
	v_sub_f32_e32 v45, v45, v49
	v_add_f32_e32 v27, v27, v45
	v_add_f32_e32 v45, v47, v27
	v_sub_f32_e32 v47, v47, v45
	v_add_f32_e32 v27, v27, v47
	v_rcp_f32_e32 v47, v45
	v_cvt_f32_i32_e32 v26, v26
	v_cmp_neq_f32_e32 vcc, s62, v44
	v_mul_f32_e32 v49, v48, v47
	v_mul_f32_e32 v50, v45, v49
	v_fma_f32 v51, v49, v45, -v50
	v_fmac_f32_e32 v51, v49, v27
	v_add_f32_e32 v52, v50, v51
	v_sub_f32_e32 v53, v48, v52
	v_sub_f32_e32 v48, v48, v53
	v_sub_f32_e32 v50, v52, v50
	v_sub_f32_e32 v48, v48, v52
	v_add_f32_e32 v46, v46, v48
	v_sub_f32_e32 v48, v50, v51
	v_add_f32_e32 v46, v48, v46
	v_add_f32_e32 v48, v53, v46
	v_mul_f32_e32 v50, v47, v48
	v_mul_f32_e32 v51, v45, v50
	v_fma_f32 v45, v50, v45, -v51
	v_fmac_f32_e32 v45, v50, v27
	v_sub_f32_e32 v27, v53, v48
	v_add_f32_e32 v27, v46, v27
	v_add_f32_e32 v46, v51, v45
	v_sub_f32_e32 v52, v48, v46
	v_sub_f32_e32 v48, v48, v52
	v_sub_f32_e32 v51, v46, v51
	v_sub_f32_e32 v46, v48, v46
	v_add_f32_e32 v27, v27, v46
	v_sub_f32_e32 v45, v51, v45
	v_add_f32_e32 v27, v45, v27
	v_add_f32_e32 v45, v49, v50
	v_add_f32_e32 v27, v52, v27
	v_sub_f32_e32 v46, v45, v49
	v_mul_f32_e32 v27, v47, v27
	v_sub_f32_e32 v46, v50, v46
	v_add_f32_e32 v27, v46, v27
	v_mul_f32_e32 v49, 0x3f317218, v26
	v_add_f32_e32 v46, v45, v27
	v_fma_f32 v50, v26, s78, -v49
	v_mul_f32_e32 v47, v46, v46
	v_fmac_f32_e32 v50, 0xb102e308, v26
	v_sub_f32_e32 v26, v46, v45
	v_fmamk_f32 v48, v47, 0x3e9b6dac, v185
	v_sub_f32_e32 v26, v27, v26
	v_add_f32_e32 v27, v49, v50
	v_fmaak_f32 v48, v47, v48, 0x3f2aaada
	v_sub_f32_e32 v45, v27, v49
	v_ldexp_f32 v49, v46, 1
	v_mul_f32_e32 v46, v46, v47
	v_mul_f32_e32 v46, v46, v48
	v_add_f32_e32 v47, v49, v46
	v_sub_f32_e32 v48, v47, v49
	v_ldexp_f32 v26, v26, 1
	v_sub_f32_e32 v46, v46, v48
	v_add_f32_e32 v26, v26, v46
	v_add_f32_e32 v46, v47, v26
	v_sub_f32_e32 v47, v46, v47
	v_sub_f32_e32 v26, v26, v47
	v_add_f32_e32 v47, v27, v46
	v_sub_f32_e32 v48, v47, v27
	v_sub_f32_e32 v49, v47, v48
	v_sub_f32_e32 v45, v50, v45
	v_sub_f32_e32 v27, v27, v49
	v_sub_f32_e32 v46, v46, v48
	v_add_f32_e32 v27, v46, v27
	v_add_f32_e32 v46, v45, v26
	v_sub_f32_e32 v48, v46, v45
	v_sub_f32_e32 v49, v46, v48
	v_sub_f32_e32 v45, v45, v49
	v_sub_f32_e32 v26, v26, v48
	v_add_f32_e32 v27, v46, v27
	v_add_f32_e32 v26, v26, v45
	v_add_f32_e32 v45, v47, v27
	v_sub_f32_e32 v46, v45, v47
	v_sub_f32_e32 v27, v27, v46
	v_add_f32_e32 v26, v26, v27
	v_add_f32_e32 v26, v45, v26
	v_cndmask_b32_e32 v26, v226, v26, vcc
	v_cmp_lt_f32_e64 vcc, |v44|, s63
	s_nop 1
	v_cndmask_b32_e32 v26, v26, v44, vcc
	v_sub_f32_e32 v26, v43, v26
	v_mul_f32_e32 v43, 0x3fb8aa3b, v26
	v_or_b32_e32 v26, 7, v42
	v_ashrrev_i32_e32 v27, 31, v26
	v_lshlrev_b64 v[26:27], 14, v[26:27]
	v_lshl_add_u64 v[26:27], v[40:41], 0, v[26:27]
	global_store_dword v[26:27], v43, off
	v_readlane_b32 s100, v254, 0
	s_nop 1
	v_mov_b32_e32 v40, s100
	v_fmac_f32_e32 v40, v20, v160
	v_mul_f32_e64 v41, |v40|, s94
	v_fma_f32 v42, |v40|, s94, -v41
	v_rndne_f32_e32 v43, v41
	v_fma_f32 v42, |v40|, s64, v42
	v_sub_f32_e32 v41, v41, v43
	v_add_f32_e32 v41, v41, v42
	v_exp_f32_e32 v41, v41
	v_cvt_i32_f32_e32 v42, v43
	v_cmp_ngt_f32_e64 vcc, |v40|, s58
	v_min_f32_e32 v20, 0, v40
	v_ldexp_f32 v41, v41, v42
	v_cndmask_b32_e32 v41, 0, v41, vcc
	v_cmp_nlt_f32_e64 vcc, |v40|, s59
	s_nop 1
	v_cndmask_b32_e32 v40, v226, v41, vcc
	v_add_f32_e32 v41, 1.0, v40
	v_add_f32_e32 v42, -1.0, v41
	v_sub_f32_e32 v43, v42, v41
	v_add_f32_e32 v43, 1.0, v43
	v_sub_f32_e32 v42, v40, v42
	v_add_f32_e32 v44, v42, v43
	v_frexp_mant_f32_e32 v42, v41
	v_cmp_gt_f32_e32 vcc, s77, v42
	v_cvt_f64_f32_e32 v[42:43], v41
	v_frexp_exp_i32_f64_e32 v42, v[42:43]
	v_subbrev_co_u32_e32 v42, vcc, 0, v42, vcc
	v_sub_u32_e32 v43, 0, v42
	v_ldexp_f32 v41, v41, v43
	v_ldexp_f32 v43, v44, v43
	v_add_f32_e32 v44, -1.0, v41
	v_add_f32_e32 v45, 1.0, v44
	v_sub_f32_e32 v45, v41, v45
	v_add_f32_e32 v45, v43, v45
	v_add_f32_e32 v46, v44, v45
	v_sub_f32_e32 v44, v44, v46
	v_add_f32_e32 v44, v45, v44
	v_add_f32_e32 v45, 1.0, v41
	v_add_f32_e32 v47, -1.0, v45
	v_sub_f32_e32 v41, v41, v47
	v_add_f32_e32 v41, v43, v41
	v_add_f32_e32 v43, v45, v41
	v_sub_f32_e32 v45, v45, v43
	v_add_f32_e32 v41, v41, v45
	v_rcp_f32_e32 v45, v43
	v_cvt_f32_i32_e32 v42, v42
	v_cmp_neq_f32_e32 vcc, s62, v40
	v_mul_f32_e32 v47, v46, v45
	v_mul_f32_e32 v48, v43, v47
	v_fma_f32 v49, v47, v43, -v48
	v_fmac_f32_e32 v49, v47, v41
	v_add_f32_e32 v50, v48, v49
	v_sub_f32_e32 v51, v46, v50
	v_sub_f32_e32 v46, v46, v51
	v_sub_f32_e32 v48, v50, v48
	v_sub_f32_e32 v46, v46, v50
	v_add_f32_e32 v44, v44, v46
	v_sub_f32_e32 v46, v48, v49
	v_add_f32_e32 v44, v46, v44
	v_add_f32_e32 v46, v51, v44
	v_mul_f32_e32 v48, v45, v46
	v_mul_f32_e32 v49, v43, v48
	v_fma_f32 v43, v48, v43, -v49
	v_fmac_f32_e32 v43, v48, v41
	v_sub_f32_e32 v41, v51, v46
	v_add_f32_e32 v41, v44, v41
	v_add_f32_e32 v44, v49, v43
	v_sub_f32_e32 v50, v46, v44
	v_sub_f32_e32 v46, v46, v50
	v_sub_f32_e32 v49, v44, v49
	v_sub_f32_e32 v44, v46, v44
	v_add_f32_e32 v41, v41, v44
	v_sub_f32_e32 v43, v49, v43
	v_add_f32_e32 v41, v43, v41
	v_add_f32_e32 v43, v47, v48
	v_add_f32_e32 v41, v50, v41
	v_sub_f32_e32 v44, v43, v47
	v_mul_f32_e32 v41, v45, v41
	v_sub_f32_e32 v44, v48, v44
	v_add_f32_e32 v41, v44, v41
	v_mul_f32_e32 v47, 0x3f317218, v42
	v_add_f32_e32 v44, v43, v41
	v_fma_f32 v48, v42, s78, -v47
	v_mul_f32_e32 v45, v44, v44
	v_fmac_f32_e32 v48, 0xb102e308, v42
	v_sub_f32_e32 v42, v44, v43
	v_fmamk_f32 v46, v45, 0x3e9b6dac, v185
	v_sub_f32_e32 v41, v41, v42
	v_add_f32_e32 v42, v47, v48
	v_fmaak_f32 v46, v45, v46, 0x3f2aaada
	v_sub_f32_e32 v43, v42, v47
	v_ldexp_f32 v47, v44, 1
	v_mul_f32_e32 v44, v44, v45
	v_mul_f32_e32 v44, v44, v46
	v_add_f32_e32 v45, v47, v44
	v_sub_f32_e32 v46, v45, v47
	v_ldexp_f32 v41, v41, 1
	v_sub_f32_e32 v44, v44, v46
	v_add_f32_e32 v41, v41, v44
	v_add_f32_e32 v44, v45, v41
	v_sub_f32_e32 v45, v44, v45
	v_sub_f32_e32 v41, v41, v45
	v_add_f32_e32 v45, v42, v44
	v_sub_f32_e32 v46, v45, v42
	v_sub_f32_e32 v47, v45, v46
	v_sub_f32_e32 v43, v48, v43
	v_sub_f32_e32 v42, v42, v47
	v_sub_f32_e32 v44, v44, v46
	v_add_f32_e32 v42, v44, v42
	v_add_f32_e32 v44, v43, v41
	v_sub_f32_e32 v46, v44, v43
	v_sub_f32_e32 v47, v44, v46
	v_sub_f32_e32 v43, v43, v47
	v_sub_f32_e32 v41, v41, v46
	v_add_f32_e32 v42, v44, v42
	v_add_f32_e32 v41, v41, v43
	v_add_f32_e32 v43, v45, v42
	v_sub_f32_e32 v44, v43, v45
	v_sub_f32_e32 v42, v42, v44
	v_add_f32_e32 v41, v41, v42
	v_add_f32_e32 v41, v43, v41
	v_cndmask_b32_e32 v41, v226, v41, vcc
	v_cmp_lt_f32_e64 vcc, |v40|, s63
	s_nop 1
	v_cndmask_b32_e32 v40, v41, v40, vcc
	v_sub_f32_e32 v20, v20, v40
	v_mul_f32_e32 v20, 0x3fb8aa3b, v20
	global_store_dword v[32:33], v20, off offset:64
	v_readlane_b32 s100, v254, 1
	s_nop 1
	v_mov_b32_e32 v40, s100
	v_fmac_f32_e32 v40, v21, v160
	v_mul_f32_e64 v21, |v40|, s94
	v_fma_f32 v41, |v40|, s94, -v21
	v_rndne_f32_e32 v42, v21
	v_fma_f32 v41, |v40|, s64, v41
	v_sub_f32_e32 v21, v21, v42
	v_add_f32_e32 v21, v21, v41
	v_exp_f32_e32 v21, v21
	v_cvt_i32_f32_e32 v41, v42
	v_cmp_ngt_f32_e64 vcc, |v40|, s58
	v_min_f32_e32 v20, 0, v40
	v_ldexp_f32 v21, v21, v41
	v_cndmask_b32_e32 v21, 0, v21, vcc
	v_cmp_nlt_f32_e64 vcc, |v40|, s59
	s_nop 1
	v_cndmask_b32_e32 v21, v226, v21, vcc
	v_add_f32_e32 v42, 1.0, v21
	v_add_f32_e32 v40, -1.0, v42
	v_sub_f32_e32 v41, v40, v42
	v_add_f32_e32 v41, 1.0, v41
	v_sub_f32_e32 v40, v21, v40
	v_add_f32_e32 v43, v40, v41
	v_frexp_mant_f32_e32 v40, v42
	v_cmp_gt_f32_e32 vcc, s77, v40
	v_cvt_f64_f32_e32 v[40:41], v42
	v_frexp_exp_i32_f64_e32 v40, v[40:41]
	v_subbrev_co_u32_e32 v40, vcc, 0, v40, vcc
	v_sub_u32_e32 v41, 0, v40
	v_ldexp_f32 v42, v42, v41
	v_ldexp_f32 v41, v43, v41
	v_add_f32_e32 v43, -1.0, v42
	v_add_f32_e32 v44, 1.0, v43
	v_sub_f32_e32 v44, v42, v44
	v_add_f32_e32 v44, v41, v44
	v_add_f32_e32 v45, v43, v44
	v_sub_f32_e32 v43, v43, v45
	v_add_f32_e32 v43, v44, v43
	v_add_f32_e32 v44, 1.0, v42
	v_add_f32_e32 v46, -1.0, v44
	v_sub_f32_e32 v42, v42, v46
	v_add_f32_e32 v41, v41, v42
	v_add_f32_e32 v42, v44, v41
	v_sub_f32_e32 v44, v44, v42
	v_add_f32_e32 v41, v41, v44
	v_rcp_f32_e32 v44, v42
	v_cvt_f32_i32_e32 v40, v40
	v_cmp_neq_f32_e32 vcc, s62, v21
	v_mul_f32_e32 v46, v45, v44
	v_mul_f32_e32 v47, v42, v46
	v_fma_f32 v48, v46, v42, -v47
	v_fmac_f32_e32 v48, v46, v41
	v_add_f32_e32 v49, v47, v48
	v_sub_f32_e32 v50, v45, v49
	v_sub_f32_e32 v45, v45, v50
	v_sub_f32_e32 v47, v49, v47
	v_sub_f32_e32 v45, v45, v49
	v_add_f32_e32 v43, v43, v45
	v_sub_f32_e32 v45, v47, v48
	v_add_f32_e32 v43, v45, v43
	v_add_f32_e32 v45, v50, v43
	v_mul_f32_e32 v47, v44, v45
	v_mul_f32_e32 v48, v42, v47
	v_fma_f32 v42, v47, v42, -v48
	v_fmac_f32_e32 v42, v47, v41
	v_sub_f32_e32 v41, v50, v45
	v_add_f32_e32 v41, v43, v41
	v_add_f32_e32 v43, v48, v42
	v_sub_f32_e32 v49, v45, v43
	v_sub_f32_e32 v45, v45, v49
	v_sub_f32_e32 v48, v43, v48
	v_sub_f32_e32 v43, v45, v43
	v_add_f32_e32 v41, v41, v43
	v_sub_f32_e32 v42, v48, v42
	v_add_f32_e32 v41, v42, v41
	v_add_f32_e32 v42, v46, v47
	v_add_f32_e32 v41, v49, v41
	v_sub_f32_e32 v43, v42, v46
	v_mul_f32_e32 v41, v44, v41
	v_sub_f32_e32 v43, v47, v43
	v_add_f32_e32 v41, v43, v41
	v_mul_f32_e32 v46, 0x3f317218, v40
	v_add_f32_e32 v43, v42, v41
	v_fma_f32 v47, v40, s78, -v46
	v_mul_f32_e32 v44, v43, v43
	v_fmac_f32_e32 v47, 0xb102e308, v40
	v_sub_f32_e32 v40, v43, v42
	v_fmamk_f32 v45, v44, 0x3e9b6dac, v185
	v_sub_f32_e32 v40, v41, v40
	v_add_f32_e32 v41, v46, v47
	v_fmaak_f32 v45, v44, v45, 0x3f2aaada
	v_sub_f32_e32 v42, v41, v46
	v_ldexp_f32 v46, v43, 1
	v_mul_f32_e32 v43, v43, v44
	v_mul_f32_e32 v43, v43, v45
	v_add_f32_e32 v44, v46, v43
	v_sub_f32_e32 v45, v44, v46
	v_ldexp_f32 v40, v40, 1
	v_sub_f32_e32 v43, v43, v45
	v_add_f32_e32 v40, v40, v43
	v_add_f32_e32 v43, v44, v40
	v_sub_f32_e32 v44, v43, v44
	v_sub_f32_e32 v40, v40, v44
	v_add_f32_e32 v44, v41, v43
	v_sub_f32_e32 v45, v44, v41
	v_sub_f32_e32 v46, v44, v45
	v_sub_f32_e32 v42, v47, v42
	v_sub_f32_e32 v41, v41, v46
	v_sub_f32_e32 v43, v43, v45
	v_add_f32_e32 v41, v43, v41
	v_add_f32_e32 v43, v42, v40
	v_sub_f32_e32 v45, v43, v42
	v_sub_f32_e32 v46, v43, v45
	v_sub_f32_e32 v42, v42, v46
	v_sub_f32_e32 v40, v40, v45
	v_add_f32_e32 v41, v43, v41
	v_add_f32_e32 v40, v40, v42
	v_add_f32_e32 v42, v44, v41
	v_sub_f32_e32 v43, v42, v44
	v_sub_f32_e32 v41, v41, v43
	v_add_f32_e32 v40, v40, v41
	v_add_f32_e32 v40, v42, v40
	v_cndmask_b32_e32 v40, v226, v40, vcc
	v_cmp_lt_f32_e64 vcc, |v21|, s63
	s_nop 1
	v_cndmask_b32_e32 v21, v40, v21, vcc
	v_sub_f32_e32 v20, v20, v21
	v_mul_f32_e32 v20, 0x3fb8aa3b, v20
	global_store_dword v[28:29], v20, off offset:64
	v_readlane_b32 s100, v254, 2
	s_nop 1
	v_mov_b32_e32 v21, s100
	v_fmac_f32_e32 v21, v22, v160
	v_mul_f32_e64 v22, |v21|, s94
	v_fma_f32 v40, |v21|, s94, -v22
	v_rndne_f32_e32 v41, v22
	v_fma_f32 v40, |v21|, s64, v40
	v_sub_f32_e32 v22, v22, v41
	v_add_f32_e32 v22, v22, v40
	v_exp_f32_e32 v22, v22
	v_cvt_i32_f32_e32 v40, v41
	v_cmp_ngt_f32_e64 vcc, |v21|, s58
	v_min_f32_e32 v20, 0, v21
	v_ldexp_f32 v22, v22, v40
	v_cndmask_b32_e32 v22, 0, v22, vcc
	v_cmp_nlt_f32_e64 vcc, |v21|, s59
	s_nop 1
	v_cndmask_b32_e32 v21, v226, v22, vcc
	v_add_f32_e32 v22, 1.0, v21
	v_add_f32_e32 v40, -1.0, v22
	v_sub_f32_e32 v41, v40, v22
	v_add_f32_e32 v41, 1.0, v41
	v_sub_f32_e32 v40, v21, v40
	v_add_f32_e32 v42, v40, v41
	v_frexp_mant_f32_e32 v40, v22
	v_cmp_gt_f32_e32 vcc, s77, v40
	v_cvt_f64_f32_e32 v[40:41], v22
	v_frexp_exp_i32_f64_e32 v40, v[40:41]
	v_subbrev_co_u32_e32 v40, vcc, 0, v40, vcc
	v_sub_u32_e32 v41, 0, v40
	v_ldexp_f32 v22, v22, v41
	v_ldexp_f32 v41, v42, v41
	v_add_f32_e32 v42, -1.0, v22
	v_add_f32_e32 v43, 1.0, v42
	v_sub_f32_e32 v43, v22, v43
	v_add_f32_e32 v43, v41, v43
	v_add_f32_e32 v44, v42, v43
	v_sub_f32_e32 v42, v42, v44
	v_add_f32_e32 v42, v43, v42
	v_add_f32_e32 v43, 1.0, v22
	v_add_f32_e32 v45, -1.0, v43
	v_sub_f32_e32 v22, v22, v45
	v_add_f32_e32 v22, v41, v22
	v_add_f32_e32 v41, v43, v22
	v_sub_f32_e32 v43, v43, v41
	v_add_f32_e32 v22, v22, v43
	v_rcp_f32_e32 v43, v41
	v_cvt_f32_i32_e32 v40, v40
	v_cmp_neq_f32_e32 vcc, s62, v21
	v_mul_f32_e32 v45, v44, v43
	v_mul_f32_e32 v46, v41, v45
	v_fma_f32 v47, v45, v41, -v46
	v_fmac_f32_e32 v47, v45, v22
	v_add_f32_e32 v48, v46, v47
	v_sub_f32_e32 v49, v44, v48
	v_sub_f32_e32 v44, v44, v49
	v_sub_f32_e32 v46, v48, v46
	v_sub_f32_e32 v44, v44, v48
	v_add_f32_e32 v42, v42, v44
	v_sub_f32_e32 v44, v46, v47
	v_add_f32_e32 v42, v44, v42
	v_add_f32_e32 v44, v49, v42
	v_mul_f32_e32 v46, v43, v44
	v_mul_f32_e32 v47, v41, v46
	v_fma_f32 v41, v46, v41, -v47
	v_fmac_f32_e32 v41, v46, v22
	v_sub_f32_e32 v22, v49, v44
	v_add_f32_e32 v22, v42, v22
	v_add_f32_e32 v42, v47, v41
	v_sub_f32_e32 v48, v44, v42
	v_sub_f32_e32 v44, v44, v48
	v_sub_f32_e32 v47, v42, v47
	v_sub_f32_e32 v42, v44, v42
	v_add_f32_e32 v22, v22, v42
	v_sub_f32_e32 v41, v47, v41
	v_add_f32_e32 v22, v41, v22
	v_add_f32_e32 v41, v45, v46
	v_add_f32_e32 v22, v48, v22
	v_sub_f32_e32 v42, v41, v45
	v_mul_f32_e32 v22, v43, v22
	v_sub_f32_e32 v42, v46, v42
	v_add_f32_e32 v22, v42, v22
	v_mul_f32_e32 v45, 0x3f317218, v40
	v_add_f32_e32 v42, v41, v22
	v_fma_f32 v46, v40, s78, -v45
	v_mul_f32_e32 v43, v42, v42
	v_fmac_f32_e32 v46, 0xb102e308, v40
	v_sub_f32_e32 v40, v42, v41
	v_fmamk_f32 v44, v43, 0x3e9b6dac, v185
	v_sub_f32_e32 v22, v22, v40
	v_add_f32_e32 v40, v45, v46
	v_fmaak_f32 v44, v43, v44, 0x3f2aaada
	v_sub_f32_e32 v41, v40, v45
	v_ldexp_f32 v45, v42, 1
	v_mul_f32_e32 v42, v42, v43
	v_mul_f32_e32 v42, v42, v44
	v_add_f32_e32 v43, v45, v42
	v_sub_f32_e32 v44, v43, v45
	v_ldexp_f32 v22, v22, 1
	v_sub_f32_e32 v42, v42, v44
	v_add_f32_e32 v22, v22, v42
	v_add_f32_e32 v42, v43, v22
	v_sub_f32_e32 v43, v42, v43
	v_sub_f32_e32 v22, v22, v43
	v_add_f32_e32 v43, v40, v42
	v_sub_f32_e32 v44, v43, v40
	v_sub_f32_e32 v45, v43, v44
	v_sub_f32_e32 v41, v46, v41
	v_sub_f32_e32 v40, v40, v45
	v_sub_f32_e32 v42, v42, v44
	v_add_f32_e32 v40, v42, v40
	v_add_f32_e32 v42, v41, v22
	v_sub_f32_e32 v44, v42, v41
	v_sub_f32_e32 v45, v42, v44
	v_sub_f32_e32 v41, v41, v45
	v_sub_f32_e32 v22, v22, v44
	v_add_f32_e32 v40, v42, v40
	v_add_f32_e32 v22, v22, v41
	v_add_f32_e32 v41, v43, v40
	v_sub_f32_e32 v42, v41, v43
	v_sub_f32_e32 v40, v40, v42
	v_add_f32_e32 v22, v22, v40
	v_add_f32_e32 v22, v41, v22
	v_cndmask_b32_e32 v22, v226, v22, vcc
	v_cmp_lt_f32_e64 vcc, |v21|, s63
	s_nop 1
	v_cndmask_b32_e32 v21, v22, v21, vcc
	v_sub_f32_e32 v20, v20, v21
	v_mul_f32_e32 v20, 0x3fb8aa3b, v20
	global_store_dword v[34:35], v20, off offset:64
	v_readlane_b32 s100, v254, 3
	s_nop 1
	v_mov_b32_e32 v21, s100
	v_fmac_f32_e32 v21, v23, v160
	v_mul_f32_e64 v22, |v21|, s94
	v_fma_f32 v23, |v21|, s94, -v22
	v_rndne_f32_e32 v40, v22
	v_fma_f32 v23, |v21|, s64, v23
	v_sub_f32_e32 v22, v22, v40
	v_add_f32_e32 v22, v22, v23
	v_exp_f32_e32 v22, v22
	v_cvt_i32_f32_e32 v23, v40
	v_cmp_ngt_f32_e64 vcc, |v21|, s58
	v_min_f32_e32 v20, 0, v21
	v_ldexp_f32 v22, v22, v23
	v_cndmask_b32_e32 v22, 0, v22, vcc
	v_cmp_nlt_f32_e64 vcc, |v21|, s59
	s_nop 1
	v_cndmask_b32_e32 v21, v226, v22, vcc
	v_add_f32_e32 v40, 1.0, v21
	v_add_f32_e32 v22, -1.0, v40
	v_sub_f32_e32 v23, v22, v40
	v_add_f32_e32 v23, 1.0, v23
	v_sub_f32_e32 v22, v21, v22
	v_add_f32_e32 v41, v22, v23
	v_frexp_mant_f32_e32 v22, v40
	v_cmp_gt_f32_e32 vcc, s77, v22
	v_cvt_f64_f32_e32 v[22:23], v40
	v_frexp_exp_i32_f64_e32 v22, v[22:23]
	v_subbrev_co_u32_e32 v22, vcc, 0, v22, vcc
	v_sub_u32_e32 v23, 0, v22
	v_ldexp_f32 v40, v40, v23
	v_ldexp_f32 v23, v41, v23
	v_add_f32_e32 v41, -1.0, v40
	v_add_f32_e32 v42, 1.0, v41
	v_sub_f32_e32 v42, v40, v42
	v_add_f32_e32 v42, v23, v42
	v_add_f32_e32 v43, v41, v42
	v_sub_f32_e32 v41, v41, v43
	v_add_f32_e32 v41, v42, v41
	v_add_f32_e32 v42, 1.0, v40
	v_add_f32_e32 v44, -1.0, v42
	v_sub_f32_e32 v40, v40, v44
	v_add_f32_e32 v23, v23, v40
	v_add_f32_e32 v40, v42, v23
	v_sub_f32_e32 v42, v42, v40
	v_add_f32_e32 v23, v23, v42
	v_rcp_f32_e32 v42, v40
	v_cvt_f32_i32_e32 v22, v22
	v_cmp_neq_f32_e32 vcc, s62, v21
	v_mul_f32_e32 v44, v43, v42
	v_mul_f32_e32 v45, v40, v44
	v_fma_f32 v46, v44, v40, -v45
	v_fmac_f32_e32 v46, v44, v23
	v_add_f32_e32 v47, v45, v46
	v_sub_f32_e32 v48, v43, v47
	v_sub_f32_e32 v43, v43, v48
	v_sub_f32_e32 v45, v47, v45
	v_sub_f32_e32 v43, v43, v47
	v_add_f32_e32 v41, v41, v43
	v_sub_f32_e32 v43, v45, v46
	v_add_f32_e32 v41, v43, v41
	v_add_f32_e32 v43, v48, v41
	v_mul_f32_e32 v45, v42, v43
	v_mul_f32_e32 v46, v40, v45
	v_fma_f32 v40, v45, v40, -v46
	v_fmac_f32_e32 v40, v45, v23
	v_sub_f32_e32 v23, v48, v43
	v_add_f32_e32 v23, v41, v23
	v_add_f32_e32 v41, v46, v40
	v_sub_f32_e32 v47, v43, v41
	v_sub_f32_e32 v43, v43, v47
	v_sub_f32_e32 v46, v41, v46
	v_sub_f32_e32 v41, v43, v41
	v_add_f32_e32 v23, v23, v41
	v_sub_f32_e32 v40, v46, v40
	v_add_f32_e32 v23, v40, v23
	v_add_f32_e32 v40, v44, v45
	v_add_f32_e32 v23, v47, v23
	v_sub_f32_e32 v41, v40, v44
	v_mul_f32_e32 v23, v42, v23
	v_sub_f32_e32 v41, v45, v41
	v_add_f32_e32 v23, v41, v23
	v_mul_f32_e32 v44, 0x3f317218, v22
	v_add_f32_e32 v41, v40, v23
	v_fma_f32 v45, v22, s78, -v44
	v_mul_f32_e32 v42, v41, v41
	v_fmac_f32_e32 v45, 0xb102e308, v22
	v_sub_f32_e32 v22, v41, v40
	v_fmamk_f32 v43, v42, 0x3e9b6dac, v185
	v_sub_f32_e32 v22, v23, v22
	v_add_f32_e32 v23, v44, v45
	v_fmaak_f32 v43, v42, v43, 0x3f2aaada
	v_sub_f32_e32 v40, v23, v44
	v_ldexp_f32 v44, v41, 1
	v_mul_f32_e32 v41, v41, v42
	v_mul_f32_e32 v41, v41, v43
	v_add_f32_e32 v42, v44, v41
	v_sub_f32_e32 v43, v42, v44
	v_ldexp_f32 v22, v22, 1
	v_sub_f32_e32 v41, v41, v43
	v_add_f32_e32 v22, v22, v41
	v_add_f32_e32 v41, v42, v22
	v_sub_f32_e32 v42, v41, v42
	v_sub_f32_e32 v22, v22, v42
	v_add_f32_e32 v42, v23, v41
	v_sub_f32_e32 v43, v42, v23
	v_sub_f32_e32 v44, v42, v43
	v_sub_f32_e32 v40, v45, v40
	v_sub_f32_e32 v23, v23, v44
	v_sub_f32_e32 v41, v41, v43
	v_add_f32_e32 v23, v41, v23
	v_add_f32_e32 v41, v40, v22
	v_sub_f32_e32 v43, v41, v40
	v_sub_f32_e32 v44, v41, v43
	v_sub_f32_e32 v40, v40, v44
	v_sub_f32_e32 v22, v22, v43
	v_add_f32_e32 v23, v41, v23
	v_add_f32_e32 v22, v22, v40
	v_add_f32_e32 v40, v42, v23
	v_sub_f32_e32 v41, v40, v42
	v_sub_f32_e32 v23, v23, v41
	v_add_f32_e32 v22, v22, v23
	v_add_f32_e32 v22, v40, v22
	v_cndmask_b32_e32 v22, v226, v22, vcc
	v_cmp_lt_f32_e64 vcc, |v21|, s63
	s_nop 1
	v_cndmask_b32_e32 v21, v22, v21, vcc
	v_sub_f32_e32 v20, v20, v21
	v_mul_f32_e32 v20, 0x3fb8aa3b, v20
	global_store_dword v[30:31], v20, off offset:64
	v_readlane_b32 s100, v254, 4
	s_nop 1
	v_mov_b32_e32 v20, s100
	v_fmac_f32_e32 v20, v16, v160
	v_mul_f32_e64 v21, |v20|, s94
	v_fma_f32 v22, |v20|, s94, -v21
	v_rndne_f32_e32 v23, v21
	v_fma_f32 v22, |v20|, s64, v22
	v_sub_f32_e32 v21, v21, v23
	v_add_f32_e32 v21, v21, v22
	v_exp_f32_e32 v21, v21
	v_cvt_i32_f32_e32 v22, v23
	v_cmp_ngt_f32_e64 vcc, |v20|, s58
	v_min_f32_e32 v16, 0, v20
	v_ldexp_f32 v21, v21, v22
	v_cndmask_b32_e32 v21, 0, v21, vcc
	v_cmp_nlt_f32_e64 vcc, |v20|, s59
	s_nop 1
	v_cndmask_b32_e32 v20, v226, v21, vcc
	v_add_f32_e32 v21, 1.0, v20
	v_add_f32_e32 v22, -1.0, v21
	v_sub_f32_e32 v23, v22, v21
	v_add_f32_e32 v23, 1.0, v23
	v_sub_f32_e32 v22, v20, v22
	v_add_f32_e32 v40, v22, v23
	v_frexp_mant_f32_e32 v22, v21
	v_cmp_gt_f32_e32 vcc, s77, v22
	v_cvt_f64_f32_e32 v[22:23], v21
	v_frexp_exp_i32_f64_e32 v22, v[22:23]
	v_subbrev_co_u32_e32 v22, vcc, 0, v22, vcc
	v_sub_u32_e32 v23, 0, v22
	v_ldexp_f32 v21, v21, v23
	v_ldexp_f32 v23, v40, v23
	v_add_f32_e32 v40, -1.0, v21
	v_add_f32_e32 v41, 1.0, v40
	v_sub_f32_e32 v41, v21, v41
	v_add_f32_e32 v41, v23, v41
	v_add_f32_e32 v42, v40, v41
	v_sub_f32_e32 v40, v40, v42
	v_add_f32_e32 v40, v41, v40
	v_add_f32_e32 v41, 1.0, v21
	v_add_f32_e32 v43, -1.0, v41
	v_sub_f32_e32 v21, v21, v43
	v_add_f32_e32 v21, v23, v21
	v_add_f32_e32 v23, v41, v21
	v_sub_f32_e32 v41, v41, v23
	v_add_f32_e32 v21, v21, v41
	v_rcp_f32_e32 v41, v23
	v_cvt_f32_i32_e32 v22, v22
	v_cmp_neq_f32_e32 vcc, s62, v20
	v_mul_f32_e32 v43, v42, v41
	v_mul_f32_e32 v44, v23, v43
	v_fma_f32 v45, v43, v23, -v44
	v_fmac_f32_e32 v45, v43, v21
	v_add_f32_e32 v46, v44, v45
	v_sub_f32_e32 v47, v42, v46
	v_sub_f32_e32 v42, v42, v47
	v_sub_f32_e32 v44, v46, v44
	v_sub_f32_e32 v42, v42, v46
	v_add_f32_e32 v40, v40, v42
	v_sub_f32_e32 v42, v44, v45
	v_add_f32_e32 v40, v42, v40
	v_add_f32_e32 v42, v47, v40
	v_mul_f32_e32 v44, v41, v42
	v_mul_f32_e32 v45, v23, v44
	v_fma_f32 v23, v44, v23, -v45
	v_fmac_f32_e32 v23, v44, v21
	v_sub_f32_e32 v21, v47, v42
	v_add_f32_e32 v21, v40, v21
	v_add_f32_e32 v40, v45, v23
	v_sub_f32_e32 v46, v42, v40
	v_sub_f32_e32 v42, v42, v46
	v_sub_f32_e32 v45, v40, v45
	v_sub_f32_e32 v40, v42, v40
	v_add_f32_e32 v21, v21, v40
	v_sub_f32_e32 v23, v45, v23
	v_add_f32_e32 v21, v23, v21
	v_add_f32_e32 v23, v43, v44
	v_add_f32_e32 v21, v46, v21
	v_sub_f32_e32 v40, v23, v43
	v_mul_f32_e32 v21, v41, v21
	v_sub_f32_e32 v40, v44, v40
	v_add_f32_e32 v21, v40, v21
	v_mul_f32_e32 v43, 0x3f317218, v22
	v_add_f32_e32 v40, v23, v21
	v_fma_f32 v44, v22, s78, -v43
	v_mul_f32_e32 v41, v40, v40
	v_fmac_f32_e32 v44, 0xb102e308, v22
	v_sub_f32_e32 v22, v40, v23
	v_fmamk_f32 v42, v41, 0x3e9b6dac, v185
	v_sub_f32_e32 v21, v21, v22
	v_add_f32_e32 v22, v43, v44
	v_fmaak_f32 v42, v41, v42, 0x3f2aaada
	v_sub_f32_e32 v23, v22, v43
	v_ldexp_f32 v43, v40, 1
	v_mul_f32_e32 v40, v40, v41
	v_mul_f32_e32 v40, v40, v42
	v_add_f32_e32 v41, v43, v40
	v_sub_f32_e32 v42, v41, v43
	v_ldexp_f32 v21, v21, 1
	v_sub_f32_e32 v40, v40, v42
	v_add_f32_e32 v21, v21, v40
	v_add_f32_e32 v40, v41, v21
	v_sub_f32_e32 v41, v40, v41
	v_sub_f32_e32 v21, v21, v41
	v_add_f32_e32 v41, v22, v40
	v_sub_f32_e32 v42, v41, v22
	v_sub_f32_e32 v43, v41, v42
	v_sub_f32_e32 v23, v44, v23
	v_sub_f32_e32 v22, v22, v43
	v_sub_f32_e32 v40, v40, v42
	v_add_f32_e32 v22, v40, v22
	v_add_f32_e32 v40, v23, v21
	v_sub_f32_e32 v42, v40, v23
	v_sub_f32_e32 v43, v40, v42
	v_sub_f32_e32 v23, v23, v43
	v_sub_f32_e32 v21, v21, v42
	v_add_f32_e32 v22, v40, v22
	v_add_f32_e32 v21, v21, v23
	v_add_f32_e32 v23, v41, v22
	v_sub_f32_e32 v40, v23, v41
	v_sub_f32_e32 v22, v22, v40
	v_add_f32_e32 v21, v21, v22
	v_add_f32_e32 v21, v23, v21
	v_cndmask_b32_e32 v21, v226, v21, vcc
	v_cmp_lt_f32_e64 vcc, |v20|, s63
	s_nop 1
	v_cndmask_b32_e32 v20, v21, v20, vcc
	v_sub_f32_e32 v16, v16, v20
	v_mul_f32_e32 v16, 0x3fb8aa3b, v16
	global_store_dword v[36:37], v16, off offset:64
	v_readlane_b32 s100, v254, 5
	s_nop 1
	v_mov_b32_e32 v20, s100
	v_fmac_f32_e32 v20, v17, v160
	v_mul_f32_e64 v17, |v20|, s94
	v_fma_f32 v21, |v20|, s94, -v17
	v_rndne_f32_e32 v22, v17
	v_fma_f32 v21, |v20|, s64, v21
	v_sub_f32_e32 v17, v17, v22
	v_add_f32_e32 v17, v17, v21
	v_exp_f32_e32 v17, v17
	v_cvt_i32_f32_e32 v21, v22
	v_cmp_ngt_f32_e64 vcc, |v20|, s58
	v_min_f32_e32 v16, 0, v20
	v_ldexp_f32 v17, v17, v21
	v_cndmask_b32_e32 v17, 0, v17, vcc
	v_cmp_nlt_f32_e64 vcc, |v20|, s59
	s_nop 1
	v_cndmask_b32_e32 v17, v226, v17, vcc
	v_add_f32_e32 v22, 1.0, v17
	v_add_f32_e32 v20, -1.0, v22
	v_sub_f32_e32 v21, v20, v22
	v_add_f32_e32 v21, 1.0, v21
	v_sub_f32_e32 v20, v17, v20
	v_add_f32_e32 v23, v20, v21
	v_frexp_mant_f32_e32 v20, v22
	v_cmp_gt_f32_e32 vcc, s77, v20
	v_cvt_f64_f32_e32 v[20:21], v22
	v_frexp_exp_i32_f64_e32 v20, v[20:21]
	v_subbrev_co_u32_e32 v20, vcc, 0, v20, vcc
	v_sub_u32_e32 v21, 0, v20
	v_ldexp_f32 v22, v22, v21
	v_ldexp_f32 v21, v23, v21
	v_add_f32_e32 v23, -1.0, v22
	v_add_f32_e32 v40, 1.0, v23
	v_sub_f32_e32 v40, v22, v40
	v_add_f32_e32 v40, v21, v40
	v_add_f32_e32 v41, v23, v40
	v_sub_f32_e32 v23, v23, v41
	v_add_f32_e32 v23, v40, v23
	v_add_f32_e32 v40, 1.0, v22
	v_add_f32_e32 v42, -1.0, v40
	v_sub_f32_e32 v22, v22, v42
	v_add_f32_e32 v21, v21, v22
	v_add_f32_e32 v22, v40, v21
	v_sub_f32_e32 v40, v40, v22
	v_add_f32_e32 v21, v21, v40
	v_rcp_f32_e32 v40, v22
	v_cvt_f32_i32_e32 v20, v20
	v_cmp_neq_f32_e32 vcc, s62, v17
	v_mul_f32_e32 v42, v41, v40
	v_mul_f32_e32 v43, v22, v42
	v_fma_f32 v44, v42, v22, -v43
	v_fmac_f32_e32 v44, v42, v21
	v_add_f32_e32 v45, v43, v44
	v_sub_f32_e32 v46, v41, v45
	v_sub_f32_e32 v41, v41, v46
	v_sub_f32_e32 v43, v45, v43
	v_sub_f32_e32 v41, v41, v45
	v_add_f32_e32 v23, v23, v41
	v_sub_f32_e32 v41, v43, v44
	v_add_f32_e32 v23, v41, v23
	v_add_f32_e32 v41, v46, v23
	v_mul_f32_e32 v43, v40, v41
	v_mul_f32_e32 v44, v22, v43
	v_fma_f32 v22, v43, v22, -v44
	v_fmac_f32_e32 v22, v43, v21
	v_sub_f32_e32 v21, v46, v41
	v_add_f32_e32 v21, v23, v21
	v_add_f32_e32 v23, v44, v22
	v_sub_f32_e32 v45, v41, v23
	v_sub_f32_e32 v41, v41, v45
	v_sub_f32_e32 v44, v23, v44
	v_sub_f32_e32 v23, v41, v23
	v_add_f32_e32 v21, v21, v23
	v_sub_f32_e32 v22, v44, v22
	v_add_f32_e32 v21, v22, v21
	v_add_f32_e32 v22, v42, v43
	v_add_f32_e32 v21, v45, v21
	v_sub_f32_e32 v23, v22, v42
	v_mul_f32_e32 v21, v40, v21
	v_sub_f32_e32 v23, v43, v23
	v_add_f32_e32 v21, v23, v21
	v_mul_f32_e32 v42, 0x3f317218, v20
	v_add_f32_e32 v23, v22, v21
	v_fma_f32 v43, v20, s78, -v42
	v_mul_f32_e32 v40, v23, v23
	v_fmac_f32_e32 v43, 0xb102e308, v20
	v_sub_f32_e32 v20, v23, v22
	v_fmamk_f32 v41, v40, 0x3e9b6dac, v185
	v_sub_f32_e32 v20, v21, v20
	v_add_f32_e32 v21, v42, v43
	v_fmaak_f32 v41, v40, v41, 0x3f2aaada
	v_sub_f32_e32 v22, v21, v42
	v_ldexp_f32 v42, v23, 1
	v_mul_f32_e32 v23, v23, v40
	v_mul_f32_e32 v23, v23, v41
	v_add_f32_e32 v40, v42, v23
	v_sub_f32_e32 v41, v40, v42
	v_ldexp_f32 v20, v20, 1
	v_sub_f32_e32 v23, v23, v41
	v_add_f32_e32 v20, v20, v23
	v_add_f32_e32 v23, v40, v20
	v_sub_f32_e32 v40, v23, v40
	v_sub_f32_e32 v20, v20, v40
	v_add_f32_e32 v40, v21, v23
	v_sub_f32_e32 v41, v40, v21
	v_sub_f32_e32 v42, v40, v41
	v_sub_f32_e32 v22, v43, v22
	v_sub_f32_e32 v21, v21, v42
	v_sub_f32_e32 v23, v23, v41
	v_add_f32_e32 v21, v23, v21
	v_add_f32_e32 v23, v22, v20
	v_sub_f32_e32 v41, v23, v22
	v_sub_f32_e32 v42, v23, v41
	v_sub_f32_e32 v22, v22, v42
	v_sub_f32_e32 v20, v20, v41
	v_add_f32_e32 v21, v23, v21
	v_add_f32_e32 v20, v20, v22
	v_add_f32_e32 v22, v40, v21
	v_sub_f32_e32 v23, v22, v40
	v_sub_f32_e32 v21, v21, v23
	v_add_f32_e32 v20, v20, v21
	v_add_f32_e32 v20, v22, v20
	v_cndmask_b32_e32 v20, v226, v20, vcc
	v_cmp_lt_f32_e64 vcc, |v17|, s63
	s_nop 1
	v_cndmask_b32_e32 v17, v20, v17, vcc
	v_sub_f32_e32 v16, v16, v17
	v_mul_f32_e32 v16, 0x3fb8aa3b, v16
	global_store_dword v[24:25], v16, off offset:64
	v_readlane_b32 s100, v254, 6
	s_nop 1
	v_mov_b32_e32 v17, s100
	v_fmac_f32_e32 v17, v18, v160
	v_mul_f32_e64 v18, |v17|, s94
	v_fma_f32 v20, |v17|, s94, -v18
	v_rndne_f32_e32 v21, v18
	v_fma_f32 v20, |v17|, s64, v20
	v_sub_f32_e32 v18, v18, v21
	v_add_f32_e32 v18, v18, v20
	v_exp_f32_e32 v18, v18
	v_cvt_i32_f32_e32 v20, v21
	v_cmp_ngt_f32_e64 vcc, |v17|, s58
	v_min_f32_e32 v16, 0, v17
	v_ldexp_f32 v18, v18, v20
	v_cndmask_b32_e32 v18, 0, v18, vcc
	v_cmp_nlt_f32_e64 vcc, |v17|, s59
	s_nop 1
	v_cndmask_b32_e32 v17, v226, v18, vcc
	v_add_f32_e32 v18, 1.0, v17
	v_add_f32_e32 v20, -1.0, v18
	v_sub_f32_e32 v21, v20, v18
	v_add_f32_e32 v21, 1.0, v21
	v_sub_f32_e32 v20, v17, v20
	v_add_f32_e32 v22, v20, v21
	v_frexp_mant_f32_e32 v20, v18
	v_cmp_gt_f32_e32 vcc, s77, v20
	v_cvt_f64_f32_e32 v[20:21], v18
	v_frexp_exp_i32_f64_e32 v20, v[20:21]
	v_subbrev_co_u32_e32 v20, vcc, 0, v20, vcc
	v_sub_u32_e32 v21, 0, v20
	v_ldexp_f32 v18, v18, v21
	v_ldexp_f32 v21, v22, v21
	v_add_f32_e32 v22, -1.0, v18
	v_add_f32_e32 v23, 1.0, v22
	v_sub_f32_e32 v23, v18, v23
	v_add_f32_e32 v23, v21, v23
	v_add_f32_e32 v40, v22, v23
	v_sub_f32_e32 v22, v22, v40
	v_add_f32_e32 v22, v23, v22
	v_add_f32_e32 v23, 1.0, v18
	v_add_f32_e32 v41, -1.0, v23
	v_sub_f32_e32 v18, v18, v41
	v_add_f32_e32 v18, v21, v18
	v_add_f32_e32 v21, v23, v18
	v_sub_f32_e32 v23, v23, v21
	v_add_f32_e32 v18, v18, v23
	v_rcp_f32_e32 v23, v21
	v_cvt_f32_i32_e32 v20, v20
	v_cmp_neq_f32_e32 vcc, s62, v17
	v_mul_f32_e32 v41, v40, v23
	v_mul_f32_e32 v42, v21, v41
	v_fma_f32 v43, v41, v21, -v42
	v_fmac_f32_e32 v43, v41, v18
	v_add_f32_e32 v44, v42, v43
	v_sub_f32_e32 v45, v40, v44
	v_sub_f32_e32 v40, v40, v45
	v_sub_f32_e32 v42, v44, v42
	v_sub_f32_e32 v40, v40, v44
	v_add_f32_e32 v22, v22, v40
	v_sub_f32_e32 v40, v42, v43
	v_add_f32_e32 v22, v40, v22
	v_add_f32_e32 v40, v45, v22
	v_mul_f32_e32 v42, v23, v40
	v_mul_f32_e32 v43, v21, v42
	v_fma_f32 v21, v42, v21, -v43
	v_fmac_f32_e32 v21, v42, v18
	v_sub_f32_e32 v18, v45, v40
	v_add_f32_e32 v18, v22, v18
	v_add_f32_e32 v22, v43, v21
	v_sub_f32_e32 v44, v40, v22
	v_sub_f32_e32 v40, v40, v44
	v_sub_f32_e32 v43, v22, v43
	v_sub_f32_e32 v22, v40, v22
	v_add_f32_e32 v18, v18, v22
	v_sub_f32_e32 v21, v43, v21
	v_add_f32_e32 v18, v21, v18
	v_add_f32_e32 v21, v41, v42
	v_add_f32_e32 v18, v44, v18
	v_sub_f32_e32 v22, v21, v41
	v_mul_f32_e32 v18, v23, v18
	v_sub_f32_e32 v22, v42, v22
	v_add_f32_e32 v18, v22, v18
	v_mul_f32_e32 v41, 0x3f317218, v20
	v_add_f32_e32 v22, v21, v18
	v_fma_f32 v42, v20, s78, -v41
	v_mul_f32_e32 v23, v22, v22
	v_fmac_f32_e32 v42, 0xb102e308, v20
	v_sub_f32_e32 v20, v22, v21
	v_fmamk_f32 v40, v23, 0x3e9b6dac, v185
	v_sub_f32_e32 v18, v18, v20
	v_add_f32_e32 v20, v41, v42
	v_fmaak_f32 v40, v23, v40, 0x3f2aaada
	v_sub_f32_e32 v21, v20, v41
	v_ldexp_f32 v41, v22, 1
	v_mul_f32_e32 v22, v22, v23
	v_mul_f32_e32 v22, v22, v40
	v_add_f32_e32 v23, v41, v22
	v_sub_f32_e32 v40, v23, v41
	v_ldexp_f32 v18, v18, 1
	v_sub_f32_e32 v22, v22, v40
	v_add_f32_e32 v18, v18, v22
	v_add_f32_e32 v22, v23, v18
	v_sub_f32_e32 v23, v22, v23
	v_sub_f32_e32 v18, v18, v23
	v_add_f32_e32 v23, v20, v22
	v_sub_f32_e32 v40, v23, v20
	v_sub_f32_e32 v41, v23, v40
	v_sub_f32_e32 v21, v42, v21
	v_sub_f32_e32 v20, v20, v41
	v_sub_f32_e32 v22, v22, v40
	v_add_f32_e32 v20, v22, v20
	v_add_f32_e32 v22, v21, v18
	v_sub_f32_e32 v40, v22, v21
	v_sub_f32_e32 v41, v22, v40
	v_sub_f32_e32 v21, v21, v41
	v_sub_f32_e32 v18, v18, v40
	v_add_f32_e32 v20, v22, v20
	v_add_f32_e32 v18, v18, v21
	v_add_f32_e32 v21, v23, v20
	v_sub_f32_e32 v22, v21, v23
	v_sub_f32_e32 v20, v20, v22
	v_add_f32_e32 v18, v18, v20
	v_add_f32_e32 v18, v21, v18
	v_cndmask_b32_e32 v18, v226, v18, vcc
	v_cmp_lt_f32_e64 vcc, |v17|, s63
	s_nop 1
	v_cndmask_b32_e32 v17, v18, v17, vcc
	v_sub_f32_e32 v16, v16, v17
	v_mul_f32_e32 v16, 0x3fb8aa3b, v16
	global_store_dword v[38:39], v16, off offset:64
	v_readlane_b32 s100, v254, 7
	s_nop 1
	v_mov_b32_e32 v17, s100
	v_fmac_f32_e32 v17, v19, v160
	v_mul_f32_e64 v18, |v17|, s94
	v_fma_f32 v19, |v17|, s94, -v18
	v_rndne_f32_e32 v20, v18
	v_fma_f32 v19, |v17|, s64, v19
	v_sub_f32_e32 v18, v18, v20
	v_add_f32_e32 v18, v18, v19
	v_exp_f32_e32 v18, v18
	v_cvt_i32_f32_e32 v19, v20
	v_cmp_ngt_f32_e64 vcc, |v17|, s58
	v_min_f32_e32 v16, 0, v17
	v_ldexp_f32 v18, v18, v19
	v_cndmask_b32_e32 v18, 0, v18, vcc
	v_cmp_nlt_f32_e64 vcc, |v17|, s59
	s_nop 1
	v_cndmask_b32_e32 v17, v226, v18, vcc
	v_add_f32_e32 v20, 1.0, v17
	v_add_f32_e32 v18, -1.0, v20
	v_sub_f32_e32 v19, v18, v20
	v_add_f32_e32 v19, 1.0, v19
	v_sub_f32_e32 v18, v17, v18
	v_add_f32_e32 v21, v18, v19
	v_frexp_mant_f32_e32 v18, v20
	v_cmp_gt_f32_e32 vcc, s77, v18
	v_cvt_f64_f32_e32 v[18:19], v20
	v_frexp_exp_i32_f64_e32 v18, v[18:19]
	v_subbrev_co_u32_e32 v18, vcc, 0, v18, vcc
	v_sub_u32_e32 v19, 0, v18
	v_ldexp_f32 v20, v20, v19
	v_ldexp_f32 v19, v21, v19
	v_add_f32_e32 v21, -1.0, v20
	v_add_f32_e32 v22, 1.0, v21
	v_sub_f32_e32 v22, v20, v22
	v_add_f32_e32 v22, v19, v22
	v_add_f32_e32 v23, v21, v22
	v_sub_f32_e32 v21, v21, v23
	v_add_f32_e32 v21, v22, v21
	v_add_f32_e32 v22, 1.0, v20
	v_add_f32_e32 v40, -1.0, v22
	v_sub_f32_e32 v20, v20, v40
	v_add_f32_e32 v19, v19, v20
	v_add_f32_e32 v20, v22, v19
	v_sub_f32_e32 v22, v22, v20
	v_add_f32_e32 v19, v19, v22
	v_rcp_f32_e32 v22, v20
	v_cvt_f32_i32_e32 v18, v18
	v_cmp_neq_f32_e32 vcc, s62, v17
	v_mul_f32_e32 v40, v23, v22
	v_mul_f32_e32 v41, v20, v40
	v_fma_f32 v42, v40, v20, -v41
	v_fmac_f32_e32 v42, v40, v19
	v_add_f32_e32 v43, v41, v42
	v_sub_f32_e32 v44, v23, v43
	v_sub_f32_e32 v23, v23, v44
	v_sub_f32_e32 v41, v43, v41
	v_sub_f32_e32 v23, v23, v43
	v_add_f32_e32 v21, v21, v23
	v_sub_f32_e32 v23, v41, v42
	v_add_f32_e32 v21, v23, v21
	v_add_f32_e32 v23, v44, v21
	v_mul_f32_e32 v41, v22, v23
	v_mul_f32_e32 v42, v20, v41
	v_fma_f32 v20, v41, v20, -v42
	v_fmac_f32_e32 v20, v41, v19
	v_sub_f32_e32 v19, v44, v23
	v_add_f32_e32 v19, v21, v19
	v_add_f32_e32 v21, v42, v20
	v_sub_f32_e32 v43, v23, v21
	v_sub_f32_e32 v23, v23, v43
	v_sub_f32_e32 v42, v21, v42
	v_sub_f32_e32 v21, v23, v21
	v_add_f32_e32 v19, v19, v21
	v_sub_f32_e32 v20, v42, v20
	v_add_f32_e32 v19, v20, v19
	v_add_f32_e32 v20, v40, v41
	v_add_f32_e32 v19, v43, v19
	v_sub_f32_e32 v21, v20, v40
	v_mul_f32_e32 v19, v22, v19
	v_sub_f32_e32 v21, v41, v21
	v_add_f32_e32 v19, v21, v19
	v_mul_f32_e32 v40, 0x3f317218, v18
	v_add_f32_e32 v21, v20, v19
	v_fma_f32 v41, v18, s78, -v40
	v_mul_f32_e32 v22, v21, v21
	v_fmac_f32_e32 v41, 0xb102e308, v18
	v_sub_f32_e32 v18, v21, v20
	v_fmamk_f32 v23, v22, 0x3e9b6dac, v185
	v_sub_f32_e32 v18, v19, v18
	v_add_f32_e32 v19, v40, v41
	v_fmaak_f32 v23, v22, v23, 0x3f2aaada
	v_sub_f32_e32 v20, v19, v40
	v_ldexp_f32 v40, v21, 1
	v_mul_f32_e32 v21, v21, v22
	v_mul_f32_e32 v21, v21, v23
	v_add_f32_e32 v22, v40, v21
	v_sub_f32_e32 v23, v22, v40
	v_ldexp_f32 v18, v18, 1
	v_sub_f32_e32 v21, v21, v23
	v_add_f32_e32 v18, v18, v21
	v_add_f32_e32 v21, v22, v18
	v_sub_f32_e32 v22, v21, v22
	v_sub_f32_e32 v18, v18, v22
	v_add_f32_e32 v22, v19, v21
	v_sub_f32_e32 v23, v22, v19
	v_sub_f32_e32 v40, v22, v23
	v_sub_f32_e32 v20, v41, v20
	v_sub_f32_e32 v19, v19, v40
	v_sub_f32_e32 v21, v21, v23
	v_add_f32_e32 v19, v21, v19
	v_add_f32_e32 v21, v20, v18
	v_sub_f32_e32 v23, v21, v20
	v_sub_f32_e32 v40, v21, v23
	v_sub_f32_e32 v20, v20, v40
	v_sub_f32_e32 v18, v18, v23
	v_add_f32_e32 v19, v21, v19
	v_add_f32_e32 v18, v18, v20
	v_add_f32_e32 v20, v22, v19
	v_sub_f32_e32 v21, v20, v22
	v_sub_f32_e32 v19, v19, v21
	v_add_f32_e32 v18, v18, v19
	v_add_f32_e32 v18, v20, v18
	v_cndmask_b32_e32 v18, v226, v18, vcc
	v_cmp_lt_f32_e64 vcc, |v17|, s63
	s_nop 1
	v_cndmask_b32_e32 v17, v18, v17, vcc
	v_sub_f32_e32 v16, v16, v17
	v_mul_f32_e32 v16, 0x3fb8aa3b, v16
	global_store_dword v[26:27], v16, off offset:64
	v_readlane_b32 s100, v254, 0
	s_nop 1
	v_mov_b32_e32 v16, s100
	v_fmac_f32_e32 v16, v12, v158
	v_mul_f32_e64 v17, |v16|, s94
	v_fma_f32 v18, |v16|, s94, -v17
	v_rndne_f32_e32 v19, v17
	v_fma_f32 v18, |v16|, s64, v18
	v_sub_f32_e32 v17, v17, v19
	v_add_f32_e32 v17, v17, v18
	v_exp_f32_e32 v17, v17
	v_cvt_i32_f32_e32 v18, v19
	v_cmp_ngt_f32_e64 vcc, |v16|, s58
	v_min_f32_e32 v12, 0, v16
	v_ldexp_f32 v17, v17, v18
	v_cndmask_b32_e32 v17, 0, v17, vcc
	v_cmp_nlt_f32_e64 vcc, |v16|, s59
	s_nop 1
	v_cndmask_b32_e32 v16, v226, v17, vcc
	v_add_f32_e32 v17, 1.0, v16
	v_add_f32_e32 v18, -1.0, v17
	v_sub_f32_e32 v19, v18, v17
	v_add_f32_e32 v19, 1.0, v19
	v_sub_f32_e32 v18, v16, v18
	v_add_f32_e32 v20, v18, v19
	v_frexp_mant_f32_e32 v18, v17
	v_cmp_gt_f32_e32 vcc, s77, v18
	v_cvt_f64_f32_e32 v[18:19], v17
	v_frexp_exp_i32_f64_e32 v18, v[18:19]
	v_subbrev_co_u32_e32 v18, vcc, 0, v18, vcc
	v_sub_u32_e32 v19, 0, v18
	v_ldexp_f32 v17, v17, v19
	v_ldexp_f32 v19, v20, v19
	v_add_f32_e32 v20, -1.0, v17
	v_add_f32_e32 v21, 1.0, v20
	v_sub_f32_e32 v21, v17, v21
	v_add_f32_e32 v21, v19, v21
	v_add_f32_e32 v22, v20, v21
	v_sub_f32_e32 v20, v20, v22
	v_add_f32_e32 v20, v21, v20
	v_add_f32_e32 v21, 1.0, v17
	v_add_f32_e32 v23, -1.0, v21
	v_sub_f32_e32 v17, v17, v23
	v_add_f32_e32 v17, v19, v17
	v_add_f32_e32 v19, v21, v17
	v_sub_f32_e32 v21, v21, v19
	v_add_f32_e32 v17, v17, v21
	v_rcp_f32_e32 v21, v19
	v_cvt_f32_i32_e32 v18, v18
	v_cmp_neq_f32_e32 vcc, s62, v16
	v_mul_f32_e32 v23, v22, v21
	v_mul_f32_e32 v40, v19, v23
	v_fma_f32 v41, v23, v19, -v40
	v_fmac_f32_e32 v41, v23, v17
	v_add_f32_e32 v42, v40, v41
	v_sub_f32_e32 v43, v22, v42
	v_sub_f32_e32 v22, v22, v43
	v_sub_f32_e32 v40, v42, v40
	v_sub_f32_e32 v22, v22, v42
	v_add_f32_e32 v20, v20, v22
	v_sub_f32_e32 v22, v40, v41
	v_add_f32_e32 v20, v22, v20
	v_add_f32_e32 v22, v43, v20
	v_mul_f32_e32 v40, v21, v22
	v_mul_f32_e32 v41, v19, v40
	v_fma_f32 v19, v40, v19, -v41
	v_fmac_f32_e32 v19, v40, v17
	v_sub_f32_e32 v17, v43, v22
	v_add_f32_e32 v17, v20, v17
	v_add_f32_e32 v20, v41, v19
	v_sub_f32_e32 v42, v22, v20
	v_sub_f32_e32 v22, v22, v42
	v_sub_f32_e32 v41, v20, v41
	v_sub_f32_e32 v20, v22, v20
	v_add_f32_e32 v17, v17, v20
	v_sub_f32_e32 v19, v41, v19
	v_add_f32_e32 v17, v19, v17
	v_add_f32_e32 v19, v23, v40
	v_add_f32_e32 v17, v42, v17
	v_sub_f32_e32 v20, v19, v23
	v_mul_f32_e32 v17, v21, v17
	v_sub_f32_e32 v20, v40, v20
	v_add_f32_e32 v17, v20, v17
	v_mul_f32_e32 v23, 0x3f317218, v18
	v_add_f32_e32 v20, v19, v17
	v_fma_f32 v40, v18, s78, -v23
	v_mul_f32_e32 v21, v20, v20
	v_fmac_f32_e32 v40, 0xb102e308, v18
	v_sub_f32_e32 v18, v20, v19
	v_fmamk_f32 v22, v21, 0x3e9b6dac, v185
	v_sub_f32_e32 v17, v17, v18
	v_add_f32_e32 v18, v23, v40
	v_fmaak_f32 v22, v21, v22, 0x3f2aaada
	v_sub_f32_e32 v19, v18, v23
	v_ldexp_f32 v23, v20, 1
	v_mul_f32_e32 v20, v20, v21
	v_mul_f32_e32 v20, v20, v22
	v_add_f32_e32 v21, v23, v20
	v_sub_f32_e32 v22, v21, v23
	v_ldexp_f32 v17, v17, 1
	v_sub_f32_e32 v20, v20, v22
	v_add_f32_e32 v17, v17, v20
	v_add_f32_e32 v20, v21, v17
	v_sub_f32_e32 v21, v20, v21
	v_sub_f32_e32 v17, v17, v21
	v_add_f32_e32 v21, v18, v20
	v_sub_f32_e32 v22, v21, v18
	v_sub_f32_e32 v23, v21, v22
	v_sub_f32_e32 v19, v40, v19
	v_sub_f32_e32 v18, v18, v23
	v_sub_f32_e32 v20, v20, v22
	v_add_f32_e32 v18, v20, v18
	v_add_f32_e32 v20, v19, v17
	v_sub_f32_e32 v22, v20, v19
	v_sub_f32_e32 v23, v20, v22
	v_sub_f32_e32 v19, v19, v23
	v_sub_f32_e32 v17, v17, v22
	v_add_f32_e32 v18, v20, v18
	v_add_f32_e32 v17, v17, v19
	v_add_f32_e32 v19, v21, v18
	v_sub_f32_e32 v20, v19, v21
	v_sub_f32_e32 v18, v18, v20
	v_add_f32_e32 v17, v17, v18
	v_add_f32_e32 v17, v19, v17
	v_cndmask_b32_e32 v17, v226, v17, vcc
	v_cmp_lt_f32_e64 vcc, |v16|, s63
	s_nop 1
	v_cndmask_b32_e32 v16, v17, v16, vcc
	v_sub_f32_e32 v12, v12, v16
	v_mul_f32_e32 v12, 0x3fb8aa3b, v12
	global_store_dword v[32:33], v12, off offset:128
	v_readlane_b32 s100, v254, 1
	s_nop 1
	v_mov_b32_e32 v16, s100
	v_fmac_f32_e32 v16, v13, v158
	v_mul_f32_e64 v13, |v16|, s94
	v_fma_f32 v17, |v16|, s94, -v13
	v_rndne_f32_e32 v18, v13
	v_fma_f32 v17, |v16|, s64, v17
	v_sub_f32_e32 v13, v13, v18
	v_add_f32_e32 v13, v13, v17
	v_exp_f32_e32 v13, v13
	v_cvt_i32_f32_e32 v17, v18
	v_cmp_ngt_f32_e64 vcc, |v16|, s58
	v_min_f32_e32 v12, 0, v16
	v_ldexp_f32 v13, v13, v17
	v_cndmask_b32_e32 v13, 0, v13, vcc
	v_cmp_nlt_f32_e64 vcc, |v16|, s59
	s_nop 1
	v_cndmask_b32_e32 v13, v226, v13, vcc
	v_add_f32_e32 v18, 1.0, v13
	v_add_f32_e32 v16, -1.0, v18
	v_sub_f32_e32 v17, v16, v18
	v_add_f32_e32 v17, 1.0, v17
	v_sub_f32_e32 v16, v13, v16
	v_add_f32_e32 v19, v16, v17
	v_frexp_mant_f32_e32 v16, v18
	v_cmp_gt_f32_e32 vcc, s77, v16
	v_cvt_f64_f32_e32 v[16:17], v18
	v_frexp_exp_i32_f64_e32 v16, v[16:17]
	v_subbrev_co_u32_e32 v16, vcc, 0, v16, vcc
	v_sub_u32_e32 v17, 0, v16
	v_ldexp_f32 v18, v18, v17
	v_ldexp_f32 v17, v19, v17
	v_add_f32_e32 v19, -1.0, v18
	v_add_f32_e32 v20, 1.0, v19
	v_sub_f32_e32 v20, v18, v20
	v_add_f32_e32 v20, v17, v20
	v_add_f32_e32 v21, v19, v20
	v_sub_f32_e32 v19, v19, v21
	v_add_f32_e32 v19, v20, v19
	v_add_f32_e32 v20, 1.0, v18
	v_add_f32_e32 v22, -1.0, v20
	v_sub_f32_e32 v18, v18, v22
	v_add_f32_e32 v17, v17, v18
	v_add_f32_e32 v18, v20, v17
	v_sub_f32_e32 v20, v20, v18
	v_add_f32_e32 v17, v17, v20
	v_rcp_f32_e32 v20, v18
	v_cvt_f32_i32_e32 v16, v16
	v_cmp_neq_f32_e32 vcc, s62, v13
	v_mul_f32_e32 v22, v21, v20
	v_mul_f32_e32 v23, v18, v22
	v_fma_f32 v40, v22, v18, -v23
	v_fmac_f32_e32 v40, v22, v17
	v_add_f32_e32 v41, v23, v40
	v_sub_f32_e32 v42, v21, v41
	v_sub_f32_e32 v21, v21, v42
	v_sub_f32_e32 v23, v41, v23
	v_sub_f32_e32 v21, v21, v41
	v_add_f32_e32 v19, v19, v21
	v_sub_f32_e32 v21, v23, v40
	v_add_f32_e32 v19, v21, v19
	v_add_f32_e32 v21, v42, v19
	v_mul_f32_e32 v23, v20, v21
	v_mul_f32_e32 v40, v18, v23
	v_fma_f32 v18, v23, v18, -v40
	v_fmac_f32_e32 v18, v23, v17
	v_sub_f32_e32 v17, v42, v21
	v_add_f32_e32 v17, v19, v17
	v_add_f32_e32 v19, v40, v18
	v_sub_f32_e32 v41, v21, v19
	v_sub_f32_e32 v21, v21, v41
	v_sub_f32_e32 v40, v19, v40
	v_sub_f32_e32 v19, v21, v19
	v_add_f32_e32 v17, v17, v19
	v_sub_f32_e32 v18, v40, v18
	v_add_f32_e32 v17, v18, v17
	v_add_f32_e32 v18, v22, v23
	v_add_f32_e32 v17, v41, v17
	v_sub_f32_e32 v19, v18, v22
	v_mul_f32_e32 v17, v20, v17
	v_sub_f32_e32 v19, v23, v19
	v_add_f32_e32 v17, v19, v17
	v_mul_f32_e32 v22, 0x3f317218, v16
	v_add_f32_e32 v19, v18, v17
	v_fma_f32 v23, v16, s78, -v22
	v_mul_f32_e32 v20, v19, v19
	v_fmac_f32_e32 v23, 0xb102e308, v16
	v_sub_f32_e32 v16, v19, v18
	v_fmamk_f32 v21, v20, 0x3e9b6dac, v185
	v_sub_f32_e32 v16, v17, v16
	v_add_f32_e32 v17, v22, v23
	v_fmaak_f32 v21, v20, v21, 0x3f2aaada
	v_sub_f32_e32 v18, v17, v22
	v_ldexp_f32 v22, v19, 1
	v_mul_f32_e32 v19, v19, v20
	v_mul_f32_e32 v19, v19, v21
	v_add_f32_e32 v20, v22, v19
	v_sub_f32_e32 v21, v20, v22
	v_ldexp_f32 v16, v16, 1
	v_sub_f32_e32 v19, v19, v21
	v_add_f32_e32 v16, v16, v19
	v_add_f32_e32 v19, v20, v16
	v_sub_f32_e32 v20, v19, v20
	v_sub_f32_e32 v16, v16, v20
	v_add_f32_e32 v20, v17, v19
	v_sub_f32_e32 v21, v20, v17
	v_sub_f32_e32 v22, v20, v21
	v_sub_f32_e32 v18, v23, v18
	v_sub_f32_e32 v17, v17, v22
	v_sub_f32_e32 v19, v19, v21
	v_add_f32_e32 v17, v19, v17
	v_add_f32_e32 v19, v18, v16
	v_sub_f32_e32 v21, v19, v18
	v_sub_f32_e32 v22, v19, v21
	v_sub_f32_e32 v18, v18, v22
	v_sub_f32_e32 v16, v16, v21
	v_add_f32_e32 v17, v19, v17
	v_add_f32_e32 v16, v16, v18
	v_add_f32_e32 v18, v20, v17
	v_sub_f32_e32 v19, v18, v20
	v_sub_f32_e32 v17, v17, v19
	v_add_f32_e32 v16, v16, v17
	v_add_f32_e32 v16, v18, v16
	v_cndmask_b32_e32 v16, v226, v16, vcc
	v_cmp_lt_f32_e64 vcc, |v13|, s63
	s_nop 1
	v_cndmask_b32_e32 v13, v16, v13, vcc
	v_sub_f32_e32 v12, v12, v13
	v_mul_f32_e32 v12, 0x3fb8aa3b, v12
	global_store_dword v[28:29], v12, off offset:128
	v_readlane_b32 s100, v254, 2
	s_nop 1
	v_mov_b32_e32 v13, s100
	v_fmac_f32_e32 v13, v14, v158
	v_mul_f32_e64 v14, |v13|, s94
	v_fma_f32 v16, |v13|, s94, -v14
	v_rndne_f32_e32 v17, v14
	v_fma_f32 v16, |v13|, s64, v16
	v_sub_f32_e32 v14, v14, v17
	v_add_f32_e32 v14, v14, v16
	v_exp_f32_e32 v14, v14
	v_cvt_i32_f32_e32 v16, v17
	v_cmp_ngt_f32_e64 vcc, |v13|, s58
	v_min_f32_e32 v12, 0, v13
	v_ldexp_f32 v14, v14, v16
	v_cndmask_b32_e32 v14, 0, v14, vcc
	v_cmp_nlt_f32_e64 vcc, |v13|, s59
	s_nop 1
	v_cndmask_b32_e32 v13, v226, v14, vcc
	v_add_f32_e32 v14, 1.0, v13
	v_add_f32_e32 v16, -1.0, v14
	v_sub_f32_e32 v17, v16, v14
	v_add_f32_e32 v17, 1.0, v17
	v_sub_f32_e32 v16, v13, v16
	v_add_f32_e32 v18, v16, v17
	v_frexp_mant_f32_e32 v16, v14
	v_cmp_gt_f32_e32 vcc, s77, v16
	v_cvt_f64_f32_e32 v[16:17], v14
	v_frexp_exp_i32_f64_e32 v16, v[16:17]
	v_subbrev_co_u32_e32 v16, vcc, 0, v16, vcc
	v_sub_u32_e32 v17, 0, v16
	v_ldexp_f32 v14, v14, v17
	v_ldexp_f32 v17, v18, v17
	v_add_f32_e32 v18, -1.0, v14
	v_add_f32_e32 v19, 1.0, v18
	v_sub_f32_e32 v19, v14, v19
	v_add_f32_e32 v19, v17, v19
	v_add_f32_e32 v20, v18, v19
	v_sub_f32_e32 v18, v18, v20
	v_add_f32_e32 v18, v19, v18
	v_add_f32_e32 v19, 1.0, v14
	v_add_f32_e32 v21, -1.0, v19
	v_sub_f32_e32 v14, v14, v21
	v_add_f32_e32 v14, v17, v14
	v_add_f32_e32 v17, v19, v14
	v_sub_f32_e32 v19, v19, v17
	v_add_f32_e32 v14, v14, v19
	v_rcp_f32_e32 v19, v17
	v_cvt_f32_i32_e32 v16, v16
	v_cmp_neq_f32_e32 vcc, s62, v13
	v_mul_f32_e32 v21, v20, v19
	v_mul_f32_e32 v22, v17, v21
	v_fma_f32 v23, v21, v17, -v22
	v_fmac_f32_e32 v23, v21, v14
	v_add_f32_e32 v40, v22, v23
	v_sub_f32_e32 v41, v20, v40
	v_sub_f32_e32 v20, v20, v41
	v_sub_f32_e32 v22, v40, v22
	v_sub_f32_e32 v20, v20, v40
	v_add_f32_e32 v18, v18, v20
	v_sub_f32_e32 v20, v22, v23
	v_add_f32_e32 v18, v20, v18
	v_add_f32_e32 v20, v41, v18
	v_mul_f32_e32 v22, v19, v20
	v_mul_f32_e32 v23, v17, v22
	v_fma_f32 v17, v22, v17, -v23
	v_fmac_f32_e32 v17, v22, v14
	v_sub_f32_e32 v14, v41, v20
	v_add_f32_e32 v14, v18, v14
	v_add_f32_e32 v18, v23, v17
	v_sub_f32_e32 v40, v20, v18
	v_sub_f32_e32 v20, v20, v40
	v_sub_f32_e32 v23, v18, v23
	v_sub_f32_e32 v18, v20, v18
	v_add_f32_e32 v14, v14, v18
	v_sub_f32_e32 v17, v23, v17
	v_add_f32_e32 v14, v17, v14
	v_add_f32_e32 v17, v21, v22
	v_add_f32_e32 v14, v40, v14
	v_sub_f32_e32 v18, v17, v21
	v_mul_f32_e32 v14, v19, v14
	v_sub_f32_e32 v18, v22, v18
	v_add_f32_e32 v14, v18, v14
	v_mul_f32_e32 v21, 0x3f317218, v16
	v_add_f32_e32 v18, v17, v14
	v_fma_f32 v22, v16, s78, -v21
	v_mul_f32_e32 v19, v18, v18
	v_fmac_f32_e32 v22, 0xb102e308, v16
	v_sub_f32_e32 v16, v18, v17
	v_fmamk_f32 v20, v19, 0x3e9b6dac, v185
	v_sub_f32_e32 v14, v14, v16
	v_add_f32_e32 v16, v21, v22
	v_fmaak_f32 v20, v19, v20, 0x3f2aaada
	v_sub_f32_e32 v17, v16, v21
	v_ldexp_f32 v21, v18, 1
	v_mul_f32_e32 v18, v18, v19
	v_mul_f32_e32 v18, v18, v20
	v_add_f32_e32 v19, v21, v18
	v_sub_f32_e32 v20, v19, v21
	v_ldexp_f32 v14, v14, 1
	v_sub_f32_e32 v18, v18, v20
	v_add_f32_e32 v14, v14, v18
	v_add_f32_e32 v18, v19, v14
	v_sub_f32_e32 v19, v18, v19
	v_sub_f32_e32 v14, v14, v19
	v_add_f32_e32 v19, v16, v18
	v_sub_f32_e32 v20, v19, v16
	v_sub_f32_e32 v21, v19, v20
	v_sub_f32_e32 v17, v22, v17
	v_sub_f32_e32 v16, v16, v21
	v_sub_f32_e32 v18, v18, v20
	v_add_f32_e32 v16, v18, v16
	v_add_f32_e32 v18, v17, v14
	v_sub_f32_e32 v20, v18, v17
	v_sub_f32_e32 v21, v18, v20
	v_sub_f32_e32 v17, v17, v21
	v_sub_f32_e32 v14, v14, v20
	v_add_f32_e32 v16, v18, v16
	v_add_f32_e32 v14, v14, v17
	v_add_f32_e32 v17, v19, v16
	v_sub_f32_e32 v18, v17, v19
	v_sub_f32_e32 v16, v16, v18
	v_add_f32_e32 v14, v14, v16
	v_add_f32_e32 v14, v17, v14
	v_cndmask_b32_e32 v14, v226, v14, vcc
	v_cmp_lt_f32_e64 vcc, |v13|, s63
	s_nop 1
	v_cndmask_b32_e32 v13, v14, v13, vcc
	v_sub_f32_e32 v12, v12, v13
	v_mul_f32_e32 v12, 0x3fb8aa3b, v12
	global_store_dword v[34:35], v12, off offset:128
	v_readlane_b32 s100, v254, 3
	s_nop 1
	v_mov_b32_e32 v13, s100
	v_fmac_f32_e32 v13, v15, v158
	v_mul_f32_e64 v14, |v13|, s94
	v_fma_f32 v15, |v13|, s94, -v14
	v_rndne_f32_e32 v16, v14
	v_fma_f32 v15, |v13|, s64, v15
	v_sub_f32_e32 v14, v14, v16
	v_add_f32_e32 v14, v14, v15
	v_exp_f32_e32 v14, v14
	v_cvt_i32_f32_e32 v15, v16
	v_cmp_ngt_f32_e64 vcc, |v13|, s58
	v_min_f32_e32 v12, 0, v13
	v_ldexp_f32 v14, v14, v15
	v_cndmask_b32_e32 v14, 0, v14, vcc
	v_cmp_nlt_f32_e64 vcc, |v13|, s59
	s_nop 1
	v_cndmask_b32_e32 v13, v226, v14, vcc
	v_add_f32_e32 v16, 1.0, v13
	v_add_f32_e32 v14, -1.0, v16
	v_sub_f32_e32 v15, v14, v16
	v_add_f32_e32 v15, 1.0, v15
	v_sub_f32_e32 v14, v13, v14
	v_add_f32_e32 v17, v14, v15
	v_frexp_mant_f32_e32 v14, v16
	v_cmp_gt_f32_e32 vcc, s77, v14
	v_cvt_f64_f32_e32 v[14:15], v16
	v_frexp_exp_i32_f64_e32 v14, v[14:15]
	v_subbrev_co_u32_e32 v14, vcc, 0, v14, vcc
	v_sub_u32_e32 v15, 0, v14
	v_ldexp_f32 v16, v16, v15
	v_ldexp_f32 v15, v17, v15
	v_add_f32_e32 v17, -1.0, v16
	v_add_f32_e32 v18, 1.0, v17
	v_sub_f32_e32 v18, v16, v18
	v_add_f32_e32 v18, v15, v18
	v_add_f32_e32 v19, v17, v18
	v_sub_f32_e32 v17, v17, v19
	v_add_f32_e32 v17, v18, v17
	v_add_f32_e32 v18, 1.0, v16
	v_add_f32_e32 v20, -1.0, v18
	v_sub_f32_e32 v16, v16, v20
	v_add_f32_e32 v15, v15, v16
	v_add_f32_e32 v16, v18, v15
	v_sub_f32_e32 v18, v18, v16
	v_add_f32_e32 v15, v15, v18
	v_rcp_f32_e32 v18, v16
	v_cvt_f32_i32_e32 v14, v14
	v_cmp_neq_f32_e32 vcc, s62, v13
	v_mul_f32_e32 v20, v19, v18
	v_mul_f32_e32 v21, v16, v20
	v_fma_f32 v22, v20, v16, -v21
	v_fmac_f32_e32 v22, v20, v15
	v_add_f32_e32 v23, v21, v22
	v_sub_f32_e32 v40, v19, v23
	v_sub_f32_e32 v19, v19, v40
	v_sub_f32_e32 v21, v23, v21
	v_sub_f32_e32 v19, v19, v23
	v_add_f32_e32 v17, v17, v19
	v_sub_f32_e32 v19, v21, v22
	v_add_f32_e32 v17, v19, v17
	v_add_f32_e32 v19, v40, v17
	v_mul_f32_e32 v21, v18, v19
	v_mul_f32_e32 v22, v16, v21
	v_fma_f32 v16, v21, v16, -v22
	v_fmac_f32_e32 v16, v21, v15
	v_sub_f32_e32 v15, v40, v19
	v_add_f32_e32 v15, v17, v15
	v_add_f32_e32 v17, v22, v16
	v_sub_f32_e32 v23, v19, v17
	v_sub_f32_e32 v19, v19, v23
	v_sub_f32_e32 v22, v17, v22
	v_sub_f32_e32 v17, v19, v17
	v_add_f32_e32 v15, v15, v17
	v_sub_f32_e32 v16, v22, v16
	v_add_f32_e32 v15, v16, v15
	v_add_f32_e32 v16, v20, v21
	v_add_f32_e32 v15, v23, v15
	v_sub_f32_e32 v17, v16, v20
	v_mul_f32_e32 v15, v18, v15
	v_sub_f32_e32 v17, v21, v17
	v_add_f32_e32 v15, v17, v15
	v_mul_f32_e32 v20, 0x3f317218, v14
	v_add_f32_e32 v17, v16, v15
	v_fma_f32 v21, v14, s78, -v20
	v_mul_f32_e32 v18, v17, v17
	v_fmac_f32_e32 v21, 0xb102e308, v14
	v_sub_f32_e32 v14, v17, v16
	v_fmamk_f32 v19, v18, 0x3e9b6dac, v185
	v_sub_f32_e32 v14, v15, v14
	v_add_f32_e32 v15, v20, v21
	v_fmaak_f32 v19, v18, v19, 0x3f2aaada
	v_sub_f32_e32 v16, v15, v20
	v_ldexp_f32 v20, v17, 1
	v_mul_f32_e32 v17, v17, v18
	v_mul_f32_e32 v17, v17, v19
	v_add_f32_e32 v18, v20, v17
	v_sub_f32_e32 v19, v18, v20
	v_ldexp_f32 v14, v14, 1
	v_sub_f32_e32 v17, v17, v19
	v_add_f32_e32 v14, v14, v17
	v_add_f32_e32 v17, v18, v14
	v_sub_f32_e32 v18, v17, v18
	v_sub_f32_e32 v14, v14, v18
	v_add_f32_e32 v18, v15, v17
	v_sub_f32_e32 v19, v18, v15
	v_sub_f32_e32 v20, v18, v19
	v_sub_f32_e32 v16, v21, v16
	v_sub_f32_e32 v15, v15, v20
	v_sub_f32_e32 v17, v17, v19
	v_add_f32_e32 v15, v17, v15
	v_add_f32_e32 v17, v16, v14
	v_sub_f32_e32 v19, v17, v16
	v_sub_f32_e32 v20, v17, v19
	v_sub_f32_e32 v16, v16, v20
	v_sub_f32_e32 v14, v14, v19
	v_add_f32_e32 v15, v17, v15
	v_add_f32_e32 v14, v14, v16
	v_add_f32_e32 v16, v18, v15
	v_sub_f32_e32 v17, v16, v18
	v_sub_f32_e32 v15, v15, v17
	v_add_f32_e32 v14, v14, v15
	v_add_f32_e32 v14, v16, v14
	v_cndmask_b32_e32 v14, v226, v14, vcc
	v_cmp_lt_f32_e64 vcc, |v13|, s63
	s_nop 1
	v_cndmask_b32_e32 v13, v14, v13, vcc
	v_sub_f32_e32 v12, v12, v13
	v_mul_f32_e32 v12, 0x3fb8aa3b, v12
	global_store_dword v[30:31], v12, off offset:128
	v_readlane_b32 s100, v254, 4
	s_nop 1
	v_mov_b32_e32 v12, s100
	v_fmac_f32_e32 v12, v8, v158
	v_mul_f32_e64 v13, |v12|, s94
	v_fma_f32 v14, |v12|, s94, -v13
	v_rndne_f32_e32 v15, v13
	v_fma_f32 v14, |v12|, s64, v14
	v_sub_f32_e32 v13, v13, v15
	v_add_f32_e32 v13, v13, v14
	v_exp_f32_e32 v13, v13
	v_cvt_i32_f32_e32 v14, v15
	v_cmp_ngt_f32_e64 vcc, |v12|, s58
	v_min_f32_e32 v8, 0, v12
	v_ldexp_f32 v13, v13, v14
	v_cndmask_b32_e32 v13, 0, v13, vcc
	v_cmp_nlt_f32_e64 vcc, |v12|, s59
	s_nop 1
	v_cndmask_b32_e32 v12, v226, v13, vcc
	v_add_f32_e32 v13, 1.0, v12
	v_add_f32_e32 v14, -1.0, v13
	v_sub_f32_e32 v15, v14, v13
	v_add_f32_e32 v15, 1.0, v15
	v_sub_f32_e32 v14, v12, v14
	v_add_f32_e32 v16, v14, v15
	v_frexp_mant_f32_e32 v14, v13
	v_cmp_gt_f32_e32 vcc, s77, v14
	v_cvt_f64_f32_e32 v[14:15], v13
	v_frexp_exp_i32_f64_e32 v14, v[14:15]
	v_subbrev_co_u32_e32 v14, vcc, 0, v14, vcc
	v_sub_u32_e32 v15, 0, v14
	v_ldexp_f32 v13, v13, v15
	v_ldexp_f32 v15, v16, v15
	v_add_f32_e32 v16, -1.0, v13
	v_add_f32_e32 v17, 1.0, v16
	v_sub_f32_e32 v17, v13, v17
	v_add_f32_e32 v17, v15, v17
	v_add_f32_e32 v18, v16, v17
	v_sub_f32_e32 v16, v16, v18
	v_add_f32_e32 v16, v17, v16
	v_add_f32_e32 v17, 1.0, v13
	v_add_f32_e32 v19, -1.0, v17
	v_sub_f32_e32 v13, v13, v19
	v_add_f32_e32 v13, v15, v13
	v_add_f32_e32 v15, v17, v13
	v_sub_f32_e32 v17, v17, v15
	v_add_f32_e32 v13, v13, v17
	v_rcp_f32_e32 v17, v15
	v_cvt_f32_i32_e32 v14, v14
	v_cmp_neq_f32_e32 vcc, s62, v12
	v_mul_f32_e32 v19, v18, v17
	v_mul_f32_e32 v20, v15, v19
	v_fma_f32 v21, v19, v15, -v20
	v_fmac_f32_e32 v21, v19, v13
	v_add_f32_e32 v22, v20, v21
	v_sub_f32_e32 v23, v18, v22
	v_sub_f32_e32 v18, v18, v23
	v_sub_f32_e32 v20, v22, v20
	v_sub_f32_e32 v18, v18, v22
	v_add_f32_e32 v16, v16, v18
	v_sub_f32_e32 v18, v20, v21
	v_add_f32_e32 v16, v18, v16
	v_add_f32_e32 v18, v23, v16
	v_mul_f32_e32 v20, v17, v18
	v_mul_f32_e32 v21, v15, v20
	v_fma_f32 v15, v20, v15, -v21
	v_fmac_f32_e32 v15, v20, v13
	v_sub_f32_e32 v13, v23, v18
	v_add_f32_e32 v13, v16, v13
	v_add_f32_e32 v16, v21, v15
	v_sub_f32_e32 v22, v18, v16
	v_sub_f32_e32 v18, v18, v22
	v_sub_f32_e32 v21, v16, v21
	v_sub_f32_e32 v16, v18, v16
	v_add_f32_e32 v13, v13, v16
	v_sub_f32_e32 v15, v21, v15
	v_add_f32_e32 v13, v15, v13
	v_add_f32_e32 v15, v19, v20
	v_add_f32_e32 v13, v22, v13
	v_sub_f32_e32 v16, v15, v19
	v_mul_f32_e32 v13, v17, v13
	v_sub_f32_e32 v16, v20, v16
	v_add_f32_e32 v13, v16, v13
	v_mul_f32_e32 v19, 0x3f317218, v14
	v_add_f32_e32 v16, v15, v13
	v_fma_f32 v20, v14, s78, -v19
	v_mul_f32_e32 v17, v16, v16
	v_fmac_f32_e32 v20, 0xb102e308, v14
	v_sub_f32_e32 v14, v16, v15
	v_fmamk_f32 v18, v17, 0x3e9b6dac, v185
	v_sub_f32_e32 v13, v13, v14
	v_add_f32_e32 v14, v19, v20
	v_fmaak_f32 v18, v17, v18, 0x3f2aaada
	v_sub_f32_e32 v15, v14, v19
	v_ldexp_f32 v19, v16, 1
	v_mul_f32_e32 v16, v16, v17
	v_mul_f32_e32 v16, v16, v18
	v_add_f32_e32 v17, v19, v16
	v_sub_f32_e32 v18, v17, v19
	v_ldexp_f32 v13, v13, 1
	v_sub_f32_e32 v16, v16, v18
	v_add_f32_e32 v13, v13, v16
	v_add_f32_e32 v16, v17, v13
	v_sub_f32_e32 v17, v16, v17
	v_sub_f32_e32 v13, v13, v17
	v_add_f32_e32 v17, v14, v16
	v_sub_f32_e32 v18, v17, v14
	v_sub_f32_e32 v19, v17, v18
	v_sub_f32_e32 v15, v20, v15
	v_sub_f32_e32 v14, v14, v19
	v_sub_f32_e32 v16, v16, v18
	v_add_f32_e32 v14, v16, v14
	v_add_f32_e32 v16, v15, v13
	v_sub_f32_e32 v18, v16, v15
	v_sub_f32_e32 v19, v16, v18
	v_sub_f32_e32 v15, v15, v19
	v_sub_f32_e32 v13, v13, v18
	v_add_f32_e32 v14, v16, v14
	v_add_f32_e32 v13, v13, v15
	v_add_f32_e32 v15, v17, v14
	v_sub_f32_e32 v16, v15, v17
	v_sub_f32_e32 v14, v14, v16
	v_add_f32_e32 v13, v13, v14
	v_add_f32_e32 v13, v15, v13
	v_cndmask_b32_e32 v13, v226, v13, vcc
	v_cmp_lt_f32_e64 vcc, |v12|, s63
	s_nop 1
	v_cndmask_b32_e32 v12, v13, v12, vcc
	v_sub_f32_e32 v8, v8, v12
	v_mul_f32_e32 v8, 0x3fb8aa3b, v8
	global_store_dword v[36:37], v8, off offset:128
	v_readlane_b32 s100, v254, 5
	s_nop 1
	v_mov_b32_e32 v12, s100
	v_fmac_f32_e32 v12, v9, v158
	v_mul_f32_e64 v9, |v12|, s94
	v_fma_f32 v13, |v12|, s94, -v9
	v_rndne_f32_e32 v14, v9
	v_fma_f32 v13, |v12|, s64, v13
	v_sub_f32_e32 v9, v9, v14
	v_add_f32_e32 v9, v9, v13
	v_exp_f32_e32 v9, v9
	v_cvt_i32_f32_e32 v13, v14
	v_cmp_ngt_f32_e64 vcc, |v12|, s58
	v_min_f32_e32 v8, 0, v12
	v_ldexp_f32 v9, v9, v13
	v_cndmask_b32_e32 v9, 0, v9, vcc
	v_cmp_nlt_f32_e64 vcc, |v12|, s59
	s_nop 1
	v_cndmask_b32_e32 v9, v226, v9, vcc
	v_add_f32_e32 v14, 1.0, v9
	v_add_f32_e32 v12, -1.0, v14
	v_sub_f32_e32 v13, v12, v14
	v_add_f32_e32 v13, 1.0, v13
	v_sub_f32_e32 v12, v9, v12
	v_add_f32_e32 v15, v12, v13
	v_frexp_mant_f32_e32 v12, v14
	v_cmp_gt_f32_e32 vcc, s77, v12
	v_cvt_f64_f32_e32 v[12:13], v14
	v_frexp_exp_i32_f64_e32 v12, v[12:13]
	v_subbrev_co_u32_e32 v12, vcc, 0, v12, vcc
	v_sub_u32_e32 v13, 0, v12
	v_ldexp_f32 v14, v14, v13
	v_ldexp_f32 v13, v15, v13
	v_add_f32_e32 v15, -1.0, v14
	v_add_f32_e32 v16, 1.0, v15
	v_sub_f32_e32 v16, v14, v16
	v_add_f32_e32 v16, v13, v16
	v_add_f32_e32 v17, v15, v16
	v_sub_f32_e32 v15, v15, v17
	v_add_f32_e32 v15, v16, v15
	v_add_f32_e32 v16, 1.0, v14
	v_add_f32_e32 v18, -1.0, v16
	v_sub_f32_e32 v14, v14, v18
	v_add_f32_e32 v13, v13, v14
	v_add_f32_e32 v14, v16, v13
	v_sub_f32_e32 v16, v16, v14
	v_add_f32_e32 v13, v13, v16
	v_rcp_f32_e32 v16, v14
	v_cvt_f32_i32_e32 v12, v12
	v_cmp_neq_f32_e32 vcc, s62, v9
	v_mul_f32_e32 v18, v17, v16
	v_mul_f32_e32 v19, v14, v18
	v_fma_f32 v20, v18, v14, -v19
	v_fmac_f32_e32 v20, v18, v13
	v_add_f32_e32 v21, v19, v20
	v_sub_f32_e32 v22, v17, v21
	v_sub_f32_e32 v17, v17, v22
	v_sub_f32_e32 v19, v21, v19
	v_sub_f32_e32 v17, v17, v21
	v_add_f32_e32 v15, v15, v17
	v_sub_f32_e32 v17, v19, v20
	v_add_f32_e32 v15, v17, v15
	v_add_f32_e32 v17, v22, v15
	v_mul_f32_e32 v19, v16, v17
	v_mul_f32_e32 v20, v14, v19
	v_fma_f32 v14, v19, v14, -v20
	v_fmac_f32_e32 v14, v19, v13
	v_sub_f32_e32 v13, v22, v17
	v_add_f32_e32 v13, v15, v13
	v_add_f32_e32 v15, v20, v14
	v_sub_f32_e32 v21, v17, v15
	v_sub_f32_e32 v17, v17, v21
	v_sub_f32_e32 v20, v15, v20
	v_sub_f32_e32 v15, v17, v15
	v_add_f32_e32 v13, v13, v15
	v_sub_f32_e32 v14, v20, v14
	v_add_f32_e32 v13, v14, v13
	v_add_f32_e32 v14, v18, v19
	v_add_f32_e32 v13, v21, v13
	v_sub_f32_e32 v15, v14, v18
	v_mul_f32_e32 v13, v16, v13
	v_sub_f32_e32 v15, v19, v15
	v_add_f32_e32 v13, v15, v13
	v_mul_f32_e32 v18, 0x3f317218, v12
	v_add_f32_e32 v15, v14, v13
	v_fma_f32 v19, v12, s78, -v18
	v_mul_f32_e32 v16, v15, v15
	v_fmac_f32_e32 v19, 0xb102e308, v12
	v_sub_f32_e32 v12, v15, v14
	v_fmamk_f32 v17, v16, 0x3e9b6dac, v185
	v_sub_f32_e32 v12, v13, v12
	v_add_f32_e32 v13, v18, v19
	v_fmaak_f32 v17, v16, v17, 0x3f2aaada
	v_sub_f32_e32 v14, v13, v18
	v_ldexp_f32 v18, v15, 1
	v_mul_f32_e32 v15, v15, v16
	v_mul_f32_e32 v15, v15, v17
	v_add_f32_e32 v16, v18, v15
	v_sub_f32_e32 v17, v16, v18
	v_ldexp_f32 v12, v12, 1
	v_sub_f32_e32 v15, v15, v17
	v_add_f32_e32 v12, v12, v15
	v_add_f32_e32 v15, v16, v12
	v_sub_f32_e32 v16, v15, v16
	v_sub_f32_e32 v12, v12, v16
	v_add_f32_e32 v16, v13, v15
	v_sub_f32_e32 v17, v16, v13
	v_sub_f32_e32 v18, v16, v17
	v_sub_f32_e32 v14, v19, v14
	v_sub_f32_e32 v13, v13, v18
	v_sub_f32_e32 v15, v15, v17
	v_add_f32_e32 v13, v15, v13
	v_add_f32_e32 v15, v14, v12
	v_sub_f32_e32 v17, v15, v14
	v_sub_f32_e32 v18, v15, v17
	v_sub_f32_e32 v14, v14, v18
	v_sub_f32_e32 v12, v12, v17
	v_add_f32_e32 v13, v15, v13
	v_add_f32_e32 v12, v12, v14
	v_add_f32_e32 v14, v16, v13
	v_sub_f32_e32 v15, v14, v16
	v_sub_f32_e32 v13, v13, v15
	v_add_f32_e32 v12, v12, v13
	v_add_f32_e32 v12, v14, v12
	v_cndmask_b32_e32 v12, v226, v12, vcc
	v_cmp_lt_f32_e64 vcc, |v9|, s63
	s_nop 1
	v_cndmask_b32_e32 v9, v12, v9, vcc
	v_sub_f32_e32 v8, v8, v9
	v_mul_f32_e32 v8, 0x3fb8aa3b, v8
	global_store_dword v[24:25], v8, off offset:128
	v_readlane_b32 s100, v254, 6
	s_nop 1
	v_mov_b32_e32 v9, s100
	v_fmac_f32_e32 v9, v10, v158
	v_mul_f32_e64 v10, |v9|, s94
	v_fma_f32 v12, |v9|, s94, -v10
	v_rndne_f32_e32 v13, v10
	v_fma_f32 v12, |v9|, s64, v12
	v_sub_f32_e32 v10, v10, v13
	v_add_f32_e32 v10, v10, v12
	v_exp_f32_e32 v10, v10
	v_cvt_i32_f32_e32 v12, v13
	v_cmp_ngt_f32_e64 vcc, |v9|, s58
	v_min_f32_e32 v8, 0, v9
	v_ldexp_f32 v10, v10, v12
	v_cndmask_b32_e32 v10, 0, v10, vcc
	v_cmp_nlt_f32_e64 vcc, |v9|, s59
	s_nop 1
	v_cndmask_b32_e32 v9, v226, v10, vcc
	v_add_f32_e32 v10, 1.0, v9
	v_add_f32_e32 v12, -1.0, v10
	v_sub_f32_e32 v13, v12, v10
	v_add_f32_e32 v13, 1.0, v13
	v_sub_f32_e32 v12, v9, v12
	v_add_f32_e32 v14, v12, v13
	v_frexp_mant_f32_e32 v12, v10
	v_cmp_gt_f32_e32 vcc, s77, v12
	v_cvt_f64_f32_e32 v[12:13], v10
	v_frexp_exp_i32_f64_e32 v12, v[12:13]
	v_subbrev_co_u32_e32 v12, vcc, 0, v12, vcc
	v_sub_u32_e32 v13, 0, v12
	v_ldexp_f32 v10, v10, v13
	v_ldexp_f32 v13, v14, v13
	v_add_f32_e32 v14, -1.0, v10
	v_add_f32_e32 v15, 1.0, v14
	v_sub_f32_e32 v15, v10, v15
	v_add_f32_e32 v15, v13, v15
	v_add_f32_e32 v16, v14, v15
	v_sub_f32_e32 v14, v14, v16
	v_add_f32_e32 v14, v15, v14
	v_add_f32_e32 v15, 1.0, v10
	v_add_f32_e32 v17, -1.0, v15
	v_sub_f32_e32 v10, v10, v17
	v_add_f32_e32 v10, v13, v10
	v_add_f32_e32 v13, v15, v10
	v_sub_f32_e32 v15, v15, v13
	v_add_f32_e32 v10, v10, v15
	v_rcp_f32_e32 v15, v13
	v_cvt_f32_i32_e32 v12, v12
	v_cmp_neq_f32_e32 vcc, s62, v9
	v_mul_f32_e32 v17, v16, v15
	v_mul_f32_e32 v18, v13, v17
	v_fma_f32 v19, v17, v13, -v18
	v_fmac_f32_e32 v19, v17, v10
	v_add_f32_e32 v20, v18, v19
	v_sub_f32_e32 v21, v16, v20
	v_sub_f32_e32 v16, v16, v21
	v_sub_f32_e32 v18, v20, v18
	v_sub_f32_e32 v16, v16, v20
	v_add_f32_e32 v14, v14, v16
	v_sub_f32_e32 v16, v18, v19
	v_add_f32_e32 v14, v16, v14
	v_add_f32_e32 v16, v21, v14
	v_mul_f32_e32 v18, v15, v16
	v_mul_f32_e32 v19, v13, v18
	v_fma_f32 v13, v18, v13, -v19
	v_fmac_f32_e32 v13, v18, v10
	v_sub_f32_e32 v10, v21, v16
	v_add_f32_e32 v10, v14, v10
	v_add_f32_e32 v14, v19, v13
	v_sub_f32_e32 v20, v16, v14
	v_sub_f32_e32 v16, v16, v20
	v_sub_f32_e32 v19, v14, v19
	v_sub_f32_e32 v14, v16, v14
	v_add_f32_e32 v10, v10, v14
	v_sub_f32_e32 v13, v19, v13
	v_add_f32_e32 v10, v13, v10
	v_add_f32_e32 v13, v17, v18
	v_add_f32_e32 v10, v20, v10
	v_sub_f32_e32 v14, v13, v17
	v_mul_f32_e32 v10, v15, v10
	v_sub_f32_e32 v14, v18, v14
	v_add_f32_e32 v10, v14, v10
	v_mul_f32_e32 v17, 0x3f317218, v12
	v_add_f32_e32 v14, v13, v10
	v_fma_f32 v18, v12, s78, -v17
	v_mul_f32_e32 v15, v14, v14
	v_fmac_f32_e32 v18, 0xb102e308, v12
	v_sub_f32_e32 v12, v14, v13
	v_fmamk_f32 v16, v15, 0x3e9b6dac, v185
	v_sub_f32_e32 v10, v10, v12
	v_add_f32_e32 v12, v17, v18
	v_fmaak_f32 v16, v15, v16, 0x3f2aaada
	v_sub_f32_e32 v13, v12, v17
	v_ldexp_f32 v17, v14, 1
	v_mul_f32_e32 v14, v14, v15
	v_mul_f32_e32 v14, v14, v16
	v_add_f32_e32 v15, v17, v14
	v_sub_f32_e32 v16, v15, v17
	v_ldexp_f32 v10, v10, 1
	v_sub_f32_e32 v14, v14, v16
	v_add_f32_e32 v10, v10, v14
	v_add_f32_e32 v14, v15, v10
	v_sub_f32_e32 v15, v14, v15
	v_sub_f32_e32 v10, v10, v15
	v_add_f32_e32 v15, v12, v14
	v_sub_f32_e32 v16, v15, v12
	v_sub_f32_e32 v17, v15, v16
	v_sub_f32_e32 v13, v18, v13
	v_sub_f32_e32 v12, v12, v17
	v_sub_f32_e32 v14, v14, v16
	v_add_f32_e32 v12, v14, v12
	v_add_f32_e32 v14, v13, v10
	v_sub_f32_e32 v16, v14, v13
	v_sub_f32_e32 v17, v14, v16
	v_sub_f32_e32 v13, v13, v17
	v_sub_f32_e32 v10, v10, v16
	v_add_f32_e32 v12, v14, v12
	v_add_f32_e32 v10, v10, v13
	v_add_f32_e32 v13, v15, v12
	v_sub_f32_e32 v14, v13, v15
	v_sub_f32_e32 v12, v12, v14
	v_add_f32_e32 v10, v10, v12
	v_add_f32_e32 v10, v13, v10
	v_cndmask_b32_e32 v10, v226, v10, vcc
	v_cmp_lt_f32_e64 vcc, |v9|, s63
	s_nop 1
	v_cndmask_b32_e32 v9, v10, v9, vcc
	v_sub_f32_e32 v8, v8, v9
	v_mul_f32_e32 v8, 0x3fb8aa3b, v8
	global_store_dword v[38:39], v8, off offset:128
	v_readlane_b32 s100, v254, 7
	s_nop 1
	v_mov_b32_e32 v9, s100
	v_fmac_f32_e32 v9, v11, v158
	v_mul_f32_e64 v10, |v9|, s94
	v_fma_f32 v11, |v9|, s94, -v10
	v_rndne_f32_e32 v12, v10
	v_fma_f32 v11, |v9|, s64, v11
	v_sub_f32_e32 v10, v10, v12
	v_add_f32_e32 v10, v10, v11
	v_exp_f32_e32 v10, v10
	v_cvt_i32_f32_e32 v11, v12
	v_cmp_ngt_f32_e64 vcc, |v9|, s58
	v_min_f32_e32 v8, 0, v9
	v_ldexp_f32 v10, v10, v11
	v_cndmask_b32_e32 v10, 0, v10, vcc
	v_cmp_nlt_f32_e64 vcc, |v9|, s59
	s_nop 1
	v_cndmask_b32_e32 v9, v226, v10, vcc
	v_add_f32_e32 v12, 1.0, v9
	v_add_f32_e32 v10, -1.0, v12
	v_sub_f32_e32 v11, v10, v12
	v_add_f32_e32 v11, 1.0, v11
	v_sub_f32_e32 v10, v9, v10
	v_add_f32_e32 v13, v10, v11
	v_frexp_mant_f32_e32 v10, v12
	v_cmp_gt_f32_e32 vcc, s77, v10
	v_cvt_f64_f32_e32 v[10:11], v12
	v_frexp_exp_i32_f64_e32 v10, v[10:11]
	v_subbrev_co_u32_e32 v10, vcc, 0, v10, vcc
	v_sub_u32_e32 v11, 0, v10
	v_ldexp_f32 v12, v12, v11
	v_ldexp_f32 v11, v13, v11
	v_add_f32_e32 v13, -1.0, v12
	v_add_f32_e32 v14, 1.0, v13
	v_sub_f32_e32 v14, v12, v14
	v_add_f32_e32 v14, v11, v14
	v_add_f32_e32 v15, v13, v14
	v_sub_f32_e32 v13, v13, v15
	v_add_f32_e32 v13, v14, v13
	v_add_f32_e32 v14, 1.0, v12
	v_add_f32_e32 v16, -1.0, v14
	v_sub_f32_e32 v12, v12, v16
	v_add_f32_e32 v11, v11, v12
	v_add_f32_e32 v12, v14, v11
	v_sub_f32_e32 v14, v14, v12
	v_add_f32_e32 v11, v11, v14
	v_rcp_f32_e32 v14, v12
	v_cvt_f32_i32_e32 v10, v10
	v_cmp_neq_f32_e32 vcc, s62, v9
	v_mul_f32_e32 v16, v15, v14
	v_mul_f32_e32 v17, v12, v16
	v_fma_f32 v18, v16, v12, -v17
	v_fmac_f32_e32 v18, v16, v11
	v_add_f32_e32 v19, v17, v18
	v_sub_f32_e32 v20, v15, v19
	v_sub_f32_e32 v15, v15, v20
	v_sub_f32_e32 v17, v19, v17
	v_sub_f32_e32 v15, v15, v19
	v_add_f32_e32 v13, v13, v15
	v_sub_f32_e32 v15, v17, v18
	v_add_f32_e32 v13, v15, v13
	v_add_f32_e32 v15, v20, v13
	v_mul_f32_e32 v17, v14, v15
	v_mul_f32_e32 v18, v12, v17
	v_fma_f32 v12, v17, v12, -v18
	v_fmac_f32_e32 v12, v17, v11
	v_sub_f32_e32 v11, v20, v15
	v_add_f32_e32 v11, v13, v11
	v_add_f32_e32 v13, v18, v12
	v_sub_f32_e32 v19, v15, v13
	v_sub_f32_e32 v15, v15, v19
	v_sub_f32_e32 v18, v13, v18
	v_sub_f32_e32 v13, v15, v13
	v_add_f32_e32 v11, v11, v13
	v_sub_f32_e32 v12, v18, v12
	v_add_f32_e32 v11, v12, v11
	v_add_f32_e32 v12, v16, v17
	v_add_f32_e32 v11, v19, v11
	v_sub_f32_e32 v13, v12, v16
	v_mul_f32_e32 v11, v14, v11
	v_sub_f32_e32 v13, v17, v13
	v_add_f32_e32 v11, v13, v11
	v_mul_f32_e32 v16, 0x3f317218, v10
	v_add_f32_e32 v13, v12, v11
	v_fma_f32 v17, v10, s78, -v16
	v_mul_f32_e32 v14, v13, v13
	v_fmac_f32_e32 v17, 0xb102e308, v10
	v_sub_f32_e32 v10, v13, v12
	v_fmamk_f32 v15, v14, 0x3e9b6dac, v185
	v_sub_f32_e32 v10, v11, v10
	v_add_f32_e32 v11, v16, v17
	v_fmaak_f32 v15, v14, v15, 0x3f2aaada
	v_sub_f32_e32 v12, v11, v16
	v_ldexp_f32 v16, v13, 1
	v_mul_f32_e32 v13, v13, v14
	v_mul_f32_e32 v13, v13, v15
	v_add_f32_e32 v14, v16, v13
	v_sub_f32_e32 v15, v14, v16
	v_ldexp_f32 v10, v10, 1
	v_sub_f32_e32 v13, v13, v15
	v_add_f32_e32 v10, v10, v13
	v_add_f32_e32 v13, v14, v10
	v_sub_f32_e32 v14, v13, v14
	v_sub_f32_e32 v10, v10, v14
	v_add_f32_e32 v14, v11, v13
	v_sub_f32_e32 v15, v14, v11
	v_sub_f32_e32 v16, v14, v15
	v_sub_f32_e32 v12, v17, v12
	v_sub_f32_e32 v11, v11, v16
	v_sub_f32_e32 v13, v13, v15
	v_add_f32_e32 v11, v13, v11
	v_add_f32_e32 v13, v12, v10
	v_sub_f32_e32 v15, v13, v12
	v_sub_f32_e32 v16, v13, v15
	v_sub_f32_e32 v12, v12, v16
	v_sub_f32_e32 v10, v10, v15
	v_add_f32_e32 v11, v13, v11
	v_add_f32_e32 v10, v10, v12
	v_add_f32_e32 v12, v14, v11
	v_sub_f32_e32 v13, v12, v14
	v_sub_f32_e32 v11, v11, v13
	v_add_f32_e32 v10, v10, v11
	v_add_f32_e32 v10, v12, v10
	v_cndmask_b32_e32 v10, v226, v10, vcc
	v_cmp_lt_f32_e64 vcc, |v9|, s63
	s_nop 1
	v_cndmask_b32_e32 v9, v10, v9, vcc
	v_sub_f32_e32 v8, v8, v9
	v_mul_f32_e32 v8, 0x3fb8aa3b, v8
	global_store_dword v[26:27], v8, off offset:128
	v_readlane_b32 s100, v254, 0
	s_nop 1
	v_mov_b32_e32 v8, s100
	v_fmac_f32_e32 v8, v4, v156
	v_mul_f32_e64 v9, |v8|, s94
	v_fma_f32 v10, |v8|, s94, -v9
	v_rndne_f32_e32 v11, v9
	v_fma_f32 v10, |v8|, s64, v10
	v_sub_f32_e32 v9, v9, v11
	v_add_f32_e32 v9, v9, v10
	v_exp_f32_e32 v9, v9
	v_cvt_i32_f32_e32 v10, v11
	v_cmp_ngt_f32_e64 vcc, |v8|, s58
	v_min_f32_e32 v4, 0, v8
	v_ldexp_f32 v9, v9, v10
	v_cndmask_b32_e32 v9, 0, v9, vcc
	v_cmp_nlt_f32_e64 vcc, |v8|, s59
	s_nop 1
	v_cndmask_b32_e32 v8, v226, v9, vcc
	v_add_f32_e32 v9, 1.0, v8
	v_add_f32_e32 v10, -1.0, v9
	v_sub_f32_e32 v11, v10, v9
	v_add_f32_e32 v11, 1.0, v11
	v_sub_f32_e32 v10, v8, v10
	v_add_f32_e32 v12, v10, v11
	v_frexp_mant_f32_e32 v10, v9
	v_cmp_gt_f32_e32 vcc, s77, v10
	v_cvt_f64_f32_e32 v[10:11], v9
	v_frexp_exp_i32_f64_e32 v10, v[10:11]
	v_subbrev_co_u32_e32 v10, vcc, 0, v10, vcc
	v_sub_u32_e32 v11, 0, v10
	v_ldexp_f32 v9, v9, v11
	v_ldexp_f32 v11, v12, v11
	v_add_f32_e32 v12, -1.0, v9
	v_add_f32_e32 v13, 1.0, v12
	v_sub_f32_e32 v13, v9, v13
	v_add_f32_e32 v13, v11, v13
	v_add_f32_e32 v14, v12, v13
	v_sub_f32_e32 v12, v12, v14
	v_add_f32_e32 v12, v13, v12
	v_add_f32_e32 v13, 1.0, v9
	v_add_f32_e32 v15, -1.0, v13
	v_sub_f32_e32 v9, v9, v15
	v_add_f32_e32 v9, v11, v9
	v_add_f32_e32 v11, v13, v9
	v_sub_f32_e32 v13, v13, v11
	v_add_f32_e32 v9, v9, v13
	v_rcp_f32_e32 v13, v11
	v_cvt_f32_i32_e32 v10, v10
	v_cmp_neq_f32_e32 vcc, s62, v8
	v_mul_f32_e32 v15, v14, v13
	v_mul_f32_e32 v16, v11, v15
	v_fma_f32 v17, v15, v11, -v16
	v_fmac_f32_e32 v17, v15, v9
	v_add_f32_e32 v18, v16, v17
	v_sub_f32_e32 v19, v14, v18
	v_sub_f32_e32 v14, v14, v19
	v_sub_f32_e32 v16, v18, v16
	v_sub_f32_e32 v14, v14, v18
	v_add_f32_e32 v12, v12, v14
	v_sub_f32_e32 v14, v16, v17
	v_add_f32_e32 v12, v14, v12
	v_add_f32_e32 v14, v19, v12
	v_mul_f32_e32 v16, v13, v14
	v_mul_f32_e32 v17, v11, v16
	v_fma_f32 v11, v16, v11, -v17
	v_fmac_f32_e32 v11, v16, v9
	v_sub_f32_e32 v9, v19, v14
	v_add_f32_e32 v9, v12, v9
	v_add_f32_e32 v12, v17, v11
	v_sub_f32_e32 v18, v14, v12
	v_sub_f32_e32 v14, v14, v18
	v_sub_f32_e32 v17, v12, v17
	v_sub_f32_e32 v12, v14, v12
	v_add_f32_e32 v9, v9, v12
	v_sub_f32_e32 v11, v17, v11
	v_add_f32_e32 v9, v11, v9
	v_add_f32_e32 v11, v15, v16
	v_add_f32_e32 v9, v18, v9
	v_sub_f32_e32 v12, v11, v15
	v_mul_f32_e32 v9, v13, v9
	v_sub_f32_e32 v12, v16, v12
	v_add_f32_e32 v9, v12, v9
	v_mul_f32_e32 v15, 0x3f317218, v10
	v_add_f32_e32 v12, v11, v9
	v_fma_f32 v16, v10, s78, -v15
	v_mul_f32_e32 v13, v12, v12
	v_fmac_f32_e32 v16, 0xb102e308, v10
	v_sub_f32_e32 v10, v12, v11
	v_fmamk_f32 v14, v13, 0x3e9b6dac, v185
	v_sub_f32_e32 v9, v9, v10
	v_add_f32_e32 v10, v15, v16
	v_fmaak_f32 v14, v13, v14, 0x3f2aaada
	v_sub_f32_e32 v11, v10, v15
	v_ldexp_f32 v15, v12, 1
	v_mul_f32_e32 v12, v12, v13
	v_mul_f32_e32 v12, v12, v14
	v_add_f32_e32 v13, v15, v12
	v_sub_f32_e32 v14, v13, v15
	v_ldexp_f32 v9, v9, 1
	v_sub_f32_e32 v12, v12, v14
	v_add_f32_e32 v9, v9, v12
	v_add_f32_e32 v12, v13, v9
	v_sub_f32_e32 v13, v12, v13
	v_sub_f32_e32 v9, v9, v13
	v_add_f32_e32 v13, v10, v12
	v_sub_f32_e32 v14, v13, v10
	v_sub_f32_e32 v15, v13, v14
	v_sub_f32_e32 v11, v16, v11
	v_sub_f32_e32 v10, v10, v15
	v_sub_f32_e32 v12, v12, v14
	v_add_f32_e32 v10, v12, v10
	v_add_f32_e32 v12, v11, v9
	v_sub_f32_e32 v14, v12, v11
	v_sub_f32_e32 v15, v12, v14
	v_sub_f32_e32 v11, v11, v15
	v_sub_f32_e32 v9, v9, v14
	v_add_f32_e32 v10, v12, v10
	v_add_f32_e32 v9, v9, v11
	v_add_f32_e32 v11, v13, v10
	v_sub_f32_e32 v12, v11, v13
	v_sub_f32_e32 v10, v10, v12
	v_add_f32_e32 v9, v9, v10
	v_add_f32_e32 v9, v11, v9
	v_cndmask_b32_e32 v9, v226, v9, vcc
	v_cmp_lt_f32_e64 vcc, |v8|, s63
	s_nop 1
	v_cndmask_b32_e32 v8, v9, v8, vcc
	v_sub_f32_e32 v4, v4, v8
	v_mul_f32_e32 v4, 0x3fb8aa3b, v4
	global_store_dword v[32:33], v4, off offset:192
	v_readlane_b32 s100, v254, 1
	s_nop 1
	v_mov_b32_e32 v8, s100
	v_fmac_f32_e32 v8, v5, v156
	v_mul_f32_e64 v5, |v8|, s94
	v_fma_f32 v9, |v8|, s94, -v5
	v_rndne_f32_e32 v10, v5
	v_fma_f32 v9, |v8|, s64, v9
	v_sub_f32_e32 v5, v5, v10
	v_add_f32_e32 v5, v5, v9
	v_exp_f32_e32 v5, v5
	v_cvt_i32_f32_e32 v9, v10
	v_cmp_ngt_f32_e64 vcc, |v8|, s58
	v_min_f32_e32 v4, 0, v8
	v_ldexp_f32 v5, v5, v9
	v_cndmask_b32_e32 v5, 0, v5, vcc
	v_cmp_nlt_f32_e64 vcc, |v8|, s59
	s_nop 1
	v_cndmask_b32_e32 v5, v226, v5, vcc
	v_add_f32_e32 v10, 1.0, v5
	v_add_f32_e32 v8, -1.0, v10
	v_sub_f32_e32 v9, v8, v10
	v_add_f32_e32 v9, 1.0, v9
	v_sub_f32_e32 v8, v5, v8
	v_add_f32_e32 v11, v8, v9
	v_frexp_mant_f32_e32 v8, v10
	v_cmp_gt_f32_e32 vcc, s77, v8
	v_cvt_f64_f32_e32 v[8:9], v10
	v_frexp_exp_i32_f64_e32 v8, v[8:9]
	v_subbrev_co_u32_e32 v8, vcc, 0, v8, vcc
	v_sub_u32_e32 v9, 0, v8
	v_ldexp_f32 v10, v10, v9
	v_ldexp_f32 v9, v11, v9
	v_add_f32_e32 v11, -1.0, v10
	v_add_f32_e32 v12, 1.0, v11
	v_sub_f32_e32 v12, v10, v12
	v_add_f32_e32 v12, v9, v12
	v_add_f32_e32 v13, v11, v12
	v_sub_f32_e32 v11, v11, v13
	v_add_f32_e32 v11, v12, v11
	v_add_f32_e32 v12, 1.0, v10
	v_add_f32_e32 v14, -1.0, v12
	v_sub_f32_e32 v10, v10, v14
	v_add_f32_e32 v9, v9, v10
	v_add_f32_e32 v10, v12, v9
	v_sub_f32_e32 v12, v12, v10
	v_add_f32_e32 v9, v9, v12
	v_rcp_f32_e32 v12, v10
	v_cvt_f32_i32_e32 v8, v8
	v_cmp_neq_f32_e32 vcc, s62, v5
	v_mul_f32_e32 v14, v13, v12
	v_mul_f32_e32 v15, v10, v14
	v_fma_f32 v16, v14, v10, -v15
	v_fmac_f32_e32 v16, v14, v9
	v_add_f32_e32 v17, v15, v16
	v_sub_f32_e32 v18, v13, v17
	v_sub_f32_e32 v13, v13, v18
	v_sub_f32_e32 v15, v17, v15
	v_sub_f32_e32 v13, v13, v17
	v_add_f32_e32 v11, v11, v13
	v_sub_f32_e32 v13, v15, v16
	v_add_f32_e32 v11, v13, v11
	v_add_f32_e32 v13, v18, v11
	v_mul_f32_e32 v15, v12, v13
	v_mul_f32_e32 v16, v10, v15
	v_fma_f32 v10, v15, v10, -v16
	v_fmac_f32_e32 v10, v15, v9
	v_sub_f32_e32 v9, v18, v13
	v_add_f32_e32 v9, v11, v9
	v_add_f32_e32 v11, v16, v10
	v_sub_f32_e32 v17, v13, v11
	v_sub_f32_e32 v13, v13, v17
	v_sub_f32_e32 v16, v11, v16
	v_sub_f32_e32 v11, v13, v11
	v_add_f32_e32 v9, v9, v11
	v_sub_f32_e32 v10, v16, v10
	v_add_f32_e32 v9, v10, v9
	v_add_f32_e32 v10, v14, v15
	v_add_f32_e32 v9, v17, v9
	v_sub_f32_e32 v11, v10, v14
	v_mul_f32_e32 v9, v12, v9
	v_sub_f32_e32 v11, v15, v11
	v_add_f32_e32 v9, v11, v9
	v_mul_f32_e32 v14, 0x3f317218, v8
	v_add_f32_e32 v11, v10, v9
	v_fma_f32 v15, v8, s78, -v14
	v_mul_f32_e32 v12, v11, v11
	v_fmac_f32_e32 v15, 0xb102e308, v8
	v_sub_f32_e32 v8, v11, v10
	v_fmamk_f32 v13, v12, 0x3e9b6dac, v185
	v_sub_f32_e32 v8, v9, v8
	v_add_f32_e32 v9, v14, v15
	v_fmaak_f32 v13, v12, v13, 0x3f2aaada
	v_sub_f32_e32 v10, v9, v14
	v_ldexp_f32 v14, v11, 1
	v_mul_f32_e32 v11, v11, v12
	v_mul_f32_e32 v11, v11, v13
	v_add_f32_e32 v12, v14, v11
	v_sub_f32_e32 v13, v12, v14
	v_ldexp_f32 v8, v8, 1
	v_sub_f32_e32 v11, v11, v13
	v_add_f32_e32 v8, v8, v11
	v_add_f32_e32 v11, v12, v8
	v_sub_f32_e32 v12, v11, v12
	v_sub_f32_e32 v8, v8, v12
	v_add_f32_e32 v12, v9, v11
	v_sub_f32_e32 v13, v12, v9
	v_sub_f32_e32 v14, v12, v13
	v_sub_f32_e32 v10, v15, v10
	v_sub_f32_e32 v9, v9, v14
	v_sub_f32_e32 v11, v11, v13
	v_add_f32_e32 v9, v11, v9
	v_add_f32_e32 v11, v10, v8
	v_sub_f32_e32 v13, v11, v10
	v_sub_f32_e32 v14, v11, v13
	v_sub_f32_e32 v10, v10, v14
	v_sub_f32_e32 v8, v8, v13
	v_add_f32_e32 v9, v11, v9
	v_add_f32_e32 v8, v8, v10
	v_add_f32_e32 v10, v12, v9
	v_sub_f32_e32 v11, v10, v12
	v_sub_f32_e32 v9, v9, v11
	v_add_f32_e32 v8, v8, v9
	v_add_f32_e32 v8, v10, v8
	v_cndmask_b32_e32 v8, v226, v8, vcc
	v_cmp_lt_f32_e64 vcc, |v5|, s63
	s_nop 1
	v_cndmask_b32_e32 v5, v8, v5, vcc
	v_sub_f32_e32 v4, v4, v5
	v_mul_f32_e32 v4, 0x3fb8aa3b, v4
	global_store_dword v[28:29], v4, off offset:192
	v_readlane_b32 s100, v254, 2
	s_nop 1
	v_mov_b32_e32 v5, s100
	v_fmac_f32_e32 v5, v6, v156
	v_mul_f32_e64 v6, |v5|, s94
	v_fma_f32 v8, |v5|, s94, -v6
	v_rndne_f32_e32 v9, v6
	v_fma_f32 v8, |v5|, s64, v8
	v_sub_f32_e32 v6, v6, v9
	v_add_f32_e32 v6, v6, v8
	v_exp_f32_e32 v6, v6
	v_cvt_i32_f32_e32 v8, v9
	v_cmp_ngt_f32_e64 vcc, |v5|, s58
	v_min_f32_e32 v4, 0, v5
	v_ldexp_f32 v6, v6, v8
	v_cndmask_b32_e32 v6, 0, v6, vcc
	v_cmp_nlt_f32_e64 vcc, |v5|, s59
	s_nop 1
	v_cndmask_b32_e32 v5, v226, v6, vcc
	v_add_f32_e32 v6, 1.0, v5
	v_add_f32_e32 v8, -1.0, v6
	v_sub_f32_e32 v9, v8, v6
	v_add_f32_e32 v9, 1.0, v9
	v_sub_f32_e32 v8, v5, v8
	v_add_f32_e32 v10, v8, v9
	v_frexp_mant_f32_e32 v8, v6
	v_cmp_gt_f32_e32 vcc, s77, v8
	v_cvt_f64_f32_e32 v[8:9], v6
	v_frexp_exp_i32_f64_e32 v8, v[8:9]
	v_subbrev_co_u32_e32 v8, vcc, 0, v8, vcc
	v_sub_u32_e32 v9, 0, v8
	v_ldexp_f32 v6, v6, v9
	v_ldexp_f32 v9, v10, v9
	v_add_f32_e32 v10, -1.0, v6
	v_add_f32_e32 v11, 1.0, v10
	v_sub_f32_e32 v11, v6, v11
	v_add_f32_e32 v11, v9, v11
	v_add_f32_e32 v12, v10, v11
	v_sub_f32_e32 v10, v10, v12
	v_add_f32_e32 v10, v11, v10
	v_add_f32_e32 v11, 1.0, v6
	v_add_f32_e32 v13, -1.0, v11
	v_sub_f32_e32 v6, v6, v13
	v_add_f32_e32 v6, v9, v6
	v_add_f32_e32 v9, v11, v6
	v_sub_f32_e32 v11, v11, v9
	v_add_f32_e32 v6, v6, v11
	v_rcp_f32_e32 v11, v9
	v_cvt_f32_i32_e32 v8, v8
	v_cmp_neq_f32_e32 vcc, s62, v5
	v_mul_f32_e32 v13, v12, v11
	v_mul_f32_e32 v14, v9, v13
	v_fma_f32 v15, v13, v9, -v14
	v_fmac_f32_e32 v15, v13, v6
	v_add_f32_e32 v16, v14, v15
	v_sub_f32_e32 v17, v12, v16
	v_sub_f32_e32 v12, v12, v17
	v_sub_f32_e32 v14, v16, v14
	v_sub_f32_e32 v12, v12, v16
	v_add_f32_e32 v10, v10, v12
	v_sub_f32_e32 v12, v14, v15
	v_add_f32_e32 v10, v12, v10
	v_add_f32_e32 v12, v17, v10
	v_mul_f32_e32 v14, v11, v12
	v_mul_f32_e32 v15, v9, v14
	v_fma_f32 v9, v14, v9, -v15
	v_fmac_f32_e32 v9, v14, v6
	v_sub_f32_e32 v6, v17, v12
	v_add_f32_e32 v6, v10, v6
	v_add_f32_e32 v10, v15, v9
	v_sub_f32_e32 v16, v12, v10
	v_sub_f32_e32 v12, v12, v16
	v_sub_f32_e32 v15, v10, v15
	v_sub_f32_e32 v10, v12, v10
	v_add_f32_e32 v6, v6, v10
	v_sub_f32_e32 v9, v15, v9
	v_add_f32_e32 v6, v9, v6
	v_add_f32_e32 v9, v13, v14
	v_add_f32_e32 v6, v16, v6
	v_sub_f32_e32 v10, v9, v13
	v_mul_f32_e32 v6, v11, v6
	v_sub_f32_e32 v10, v14, v10
	v_add_f32_e32 v6, v10, v6
	v_mul_f32_e32 v13, 0x3f317218, v8
	v_add_f32_e32 v10, v9, v6
	v_fma_f32 v14, v8, s78, -v13
	v_mul_f32_e32 v11, v10, v10
	v_fmac_f32_e32 v14, 0xb102e308, v8
	v_sub_f32_e32 v8, v10, v9
	v_fmamk_f32 v12, v11, 0x3e9b6dac, v185
	v_sub_f32_e32 v6, v6, v8
	v_add_f32_e32 v8, v13, v14
	v_fmaak_f32 v12, v11, v12, 0x3f2aaada
	v_sub_f32_e32 v9, v8, v13
	v_ldexp_f32 v13, v10, 1
	v_mul_f32_e32 v10, v10, v11
	v_mul_f32_e32 v10, v10, v12
	v_add_f32_e32 v11, v13, v10
	v_sub_f32_e32 v12, v11, v13
	v_ldexp_f32 v6, v6, 1
	v_sub_f32_e32 v10, v10, v12
	v_add_f32_e32 v6, v6, v10
	v_add_f32_e32 v10, v11, v6
	v_sub_f32_e32 v11, v10, v11
	v_sub_f32_e32 v6, v6, v11
	v_add_f32_e32 v11, v8, v10
	v_sub_f32_e32 v12, v11, v8
	v_sub_f32_e32 v13, v11, v12
	v_sub_f32_e32 v9, v14, v9
	v_sub_f32_e32 v8, v8, v13
	v_sub_f32_e32 v10, v10, v12
	v_add_f32_e32 v8, v10, v8
	v_add_f32_e32 v10, v9, v6
	v_sub_f32_e32 v12, v10, v9
	v_sub_f32_e32 v13, v10, v12
	v_sub_f32_e32 v9, v9, v13
	v_sub_f32_e32 v6, v6, v12
	v_add_f32_e32 v8, v10, v8
	v_add_f32_e32 v6, v6, v9
	v_add_f32_e32 v9, v11, v8
	v_sub_f32_e32 v10, v9, v11
	v_sub_f32_e32 v8, v8, v10
	v_add_f32_e32 v6, v6, v8
	v_add_f32_e32 v6, v9, v6
	v_cndmask_b32_e32 v6, v226, v6, vcc
	v_cmp_lt_f32_e64 vcc, |v5|, s63
	s_nop 1
	v_cndmask_b32_e32 v5, v6, v5, vcc
	v_sub_f32_e32 v4, v4, v5
	v_mul_f32_e32 v4, 0x3fb8aa3b, v4
	global_store_dword v[34:35], v4, off offset:192
	v_readlane_b32 s100, v254, 3
	s_nop 1
	v_mov_b32_e32 v5, s100
	v_fmac_f32_e32 v5, v7, v156
	v_mul_f32_e64 v6, |v5|, s94
	v_fma_f32 v7, |v5|, s94, -v6
	v_rndne_f32_e32 v8, v6
	v_fma_f32 v7, |v5|, s64, v7
	v_sub_f32_e32 v6, v6, v8
	v_add_f32_e32 v6, v6, v7
	v_exp_f32_e32 v6, v6
	v_cvt_i32_f32_e32 v7, v8
	v_cmp_ngt_f32_e64 vcc, |v5|, s58
	v_min_f32_e32 v4, 0, v5
	v_ldexp_f32 v6, v6, v7
	v_cndmask_b32_e32 v6, 0, v6, vcc
	v_cmp_nlt_f32_e64 vcc, |v5|, s59
	s_nop 1
	v_cndmask_b32_e32 v5, v226, v6, vcc
	v_add_f32_e32 v8, 1.0, v5
	v_add_f32_e32 v6, -1.0, v8
	v_sub_f32_e32 v7, v6, v8
	v_add_f32_e32 v7, 1.0, v7
	v_sub_f32_e32 v6, v5, v6
	v_add_f32_e32 v9, v6, v7
	v_frexp_mant_f32_e32 v6, v8
	v_cmp_gt_f32_e32 vcc, s77, v6
	v_cvt_f64_f32_e32 v[6:7], v8
	v_frexp_exp_i32_f64_e32 v6, v[6:7]
	v_subbrev_co_u32_e32 v6, vcc, 0, v6, vcc
	v_sub_u32_e32 v7, 0, v6
	v_ldexp_f32 v8, v8, v7
	v_ldexp_f32 v7, v9, v7
	v_add_f32_e32 v9, -1.0, v8
	v_add_f32_e32 v10, 1.0, v9
	v_sub_f32_e32 v10, v8, v10
	v_add_f32_e32 v10, v7, v10
	v_add_f32_e32 v11, v9, v10
	v_sub_f32_e32 v9, v9, v11
	v_add_f32_e32 v9, v10, v9
	v_add_f32_e32 v10, 1.0, v8
	v_add_f32_e32 v12, -1.0, v10
	v_sub_f32_e32 v8, v8, v12
	v_add_f32_e32 v7, v7, v8
	v_add_f32_e32 v8, v10, v7
	v_sub_f32_e32 v10, v10, v8
	v_add_f32_e32 v7, v7, v10
	v_rcp_f32_e32 v10, v8
	v_cvt_f32_i32_e32 v6, v6
	v_cmp_neq_f32_e32 vcc, s62, v5
	v_mul_f32_e32 v12, v11, v10
	v_mul_f32_e32 v13, v8, v12
	v_fma_f32 v14, v12, v8, -v13
	v_fmac_f32_e32 v14, v12, v7
	v_add_f32_e32 v15, v13, v14
	v_sub_f32_e32 v16, v11, v15
	v_sub_f32_e32 v11, v11, v16
	v_sub_f32_e32 v13, v15, v13
	v_sub_f32_e32 v11, v11, v15
	v_add_f32_e32 v9, v9, v11
	v_sub_f32_e32 v11, v13, v14
	v_add_f32_e32 v9, v11, v9
	v_add_f32_e32 v11, v16, v9
	v_mul_f32_e32 v13, v10, v11
	v_mul_f32_e32 v14, v8, v13
	v_fma_f32 v8, v13, v8, -v14
	v_fmac_f32_e32 v8, v13, v7
	v_sub_f32_e32 v7, v16, v11
	v_add_f32_e32 v7, v9, v7
	v_add_f32_e32 v9, v14, v8
	v_sub_f32_e32 v15, v11, v9
	v_sub_f32_e32 v11, v11, v15
	v_sub_f32_e32 v14, v9, v14
	v_sub_f32_e32 v9, v11, v9
	v_add_f32_e32 v7, v7, v9
	v_sub_f32_e32 v8, v14, v8
	v_add_f32_e32 v7, v8, v7
	v_add_f32_e32 v8, v12, v13
	v_add_f32_e32 v7, v15, v7
	v_sub_f32_e32 v9, v8, v12
	v_mul_f32_e32 v7, v10, v7
	v_sub_f32_e32 v9, v13, v9
	v_add_f32_e32 v7, v9, v7
	v_mul_f32_e32 v12, 0x3f317218, v6
	v_add_f32_e32 v9, v8, v7
	v_fma_f32 v13, v6, s78, -v12
	v_mul_f32_e32 v10, v9, v9
	v_fmac_f32_e32 v13, 0xb102e308, v6
	v_sub_f32_e32 v6, v9, v8
	v_fmamk_f32 v11, v10, 0x3e9b6dac, v185
	v_sub_f32_e32 v6, v7, v6
	v_add_f32_e32 v7, v12, v13
	v_fmaak_f32 v11, v10, v11, 0x3f2aaada
	v_sub_f32_e32 v8, v7, v12
	v_ldexp_f32 v12, v9, 1
	v_mul_f32_e32 v9, v9, v10
	v_mul_f32_e32 v9, v9, v11
	v_add_f32_e32 v10, v12, v9
	v_sub_f32_e32 v11, v10, v12
	v_ldexp_f32 v6, v6, 1
	v_sub_f32_e32 v9, v9, v11
	v_add_f32_e32 v6, v6, v9
	v_add_f32_e32 v9, v10, v6
	v_sub_f32_e32 v10, v9, v10
	v_sub_f32_e32 v6, v6, v10
	v_add_f32_e32 v10, v7, v9
	v_sub_f32_e32 v11, v10, v7
	v_sub_f32_e32 v12, v10, v11
	v_sub_f32_e32 v8, v13, v8
	v_sub_f32_e32 v7, v7, v12
	v_sub_f32_e32 v9, v9, v11
	v_add_f32_e32 v7, v9, v7
	v_add_f32_e32 v9, v8, v6
	v_sub_f32_e32 v11, v9, v8
	v_sub_f32_e32 v12, v9, v11
	v_sub_f32_e32 v8, v8, v12
	v_sub_f32_e32 v6, v6, v11
	v_add_f32_e32 v7, v9, v7
	v_add_f32_e32 v6, v6, v8
	v_add_f32_e32 v8, v10, v7
	v_sub_f32_e32 v9, v8, v10
	v_sub_f32_e32 v7, v7, v9
	v_add_f32_e32 v6, v6, v7
	v_add_f32_e32 v6, v8, v6
	v_cndmask_b32_e32 v6, v226, v6, vcc
	v_cmp_lt_f32_e64 vcc, |v5|, s63
	s_nop 1
	v_cndmask_b32_e32 v5, v6, v5, vcc
	v_sub_f32_e32 v4, v4, v5
	v_mul_f32_e32 v4, 0x3fb8aa3b, v4
	global_store_dword v[30:31], v4, off offset:192
	v_readlane_b32 s100, v254, 4
	s_nop 1
	v_mov_b32_e32 v4, s100
	v_fmac_f32_e32 v4, v0, v156
	v_mul_f32_e64 v5, |v4|, s94
	v_fma_f32 v6, |v4|, s94, -v5
	v_rndne_f32_e32 v7, v5
	v_fma_f32 v6, |v4|, s64, v6
	v_sub_f32_e32 v5, v5, v7
	v_add_f32_e32 v5, v5, v6
	v_exp_f32_e32 v5, v5
	v_cvt_i32_f32_e32 v6, v7
	v_cmp_ngt_f32_e64 vcc, |v4|, s58
	v_min_f32_e32 v0, 0, v4
	v_ldexp_f32 v5, v5, v6
	v_cndmask_b32_e32 v5, 0, v5, vcc
	v_cmp_nlt_f32_e64 vcc, |v4|, s59
	s_nop 1
	v_cndmask_b32_e32 v4, v226, v5, vcc
	v_add_f32_e32 v5, 1.0, v4
	v_add_f32_e32 v6, -1.0, v5
	v_sub_f32_e32 v7, v6, v5
	v_add_f32_e32 v7, 1.0, v7
	v_sub_f32_e32 v6, v4, v6
	v_add_f32_e32 v8, v6, v7
	v_frexp_mant_f32_e32 v6, v5
	v_cmp_gt_f32_e32 vcc, s77, v6
	v_cvt_f64_f32_e32 v[6:7], v5
	v_frexp_exp_i32_f64_e32 v6, v[6:7]
	v_subbrev_co_u32_e32 v6, vcc, 0, v6, vcc
	v_sub_u32_e32 v7, 0, v6
	v_ldexp_f32 v5, v5, v7
	v_ldexp_f32 v7, v8, v7
	v_add_f32_e32 v8, -1.0, v5
	v_add_f32_e32 v9, 1.0, v8
	v_sub_f32_e32 v9, v5, v9
	v_add_f32_e32 v9, v7, v9
	v_add_f32_e32 v10, v8, v9
	v_sub_f32_e32 v8, v8, v10
	v_add_f32_e32 v8, v9, v8
	v_add_f32_e32 v9, 1.0, v5
	v_add_f32_e32 v11, -1.0, v9
	v_sub_f32_e32 v5, v5, v11
	v_add_f32_e32 v5, v7, v5
	v_add_f32_e32 v7, v9, v5
	v_sub_f32_e32 v9, v9, v7
	v_add_f32_e32 v5, v5, v9
	v_rcp_f32_e32 v9, v7
	v_cvt_f32_i32_e32 v6, v6
	v_cmp_neq_f32_e32 vcc, s62, v4
	v_mul_f32_e32 v11, v10, v9
	v_mul_f32_e32 v12, v7, v11
	v_fma_f32 v13, v11, v7, -v12
	v_fmac_f32_e32 v13, v11, v5
	v_add_f32_e32 v14, v12, v13
	v_sub_f32_e32 v15, v10, v14
	v_sub_f32_e32 v10, v10, v15
	v_sub_f32_e32 v12, v14, v12
	v_sub_f32_e32 v10, v10, v14
	v_add_f32_e32 v8, v8, v10
	v_sub_f32_e32 v10, v12, v13
	v_add_f32_e32 v8, v10, v8
	v_add_f32_e32 v10, v15, v8
	v_mul_f32_e32 v12, v9, v10
	v_mul_f32_e32 v13, v7, v12
	v_fma_f32 v7, v12, v7, -v13
	v_fmac_f32_e32 v7, v12, v5
	v_sub_f32_e32 v5, v15, v10
	v_add_f32_e32 v5, v8, v5
	v_add_f32_e32 v8, v13, v7
	v_sub_f32_e32 v14, v10, v8
	v_sub_f32_e32 v10, v10, v14
	v_sub_f32_e32 v13, v8, v13
	v_sub_f32_e32 v8, v10, v8
	v_add_f32_e32 v5, v5, v8
	v_sub_f32_e32 v7, v13, v7
	v_add_f32_e32 v5, v7, v5
	v_add_f32_e32 v7, v11, v12
	v_add_f32_e32 v5, v14, v5
	v_sub_f32_e32 v8, v7, v11
	v_mul_f32_e32 v5, v9, v5
	v_sub_f32_e32 v8, v12, v8
	v_add_f32_e32 v5, v8, v5
	v_mul_f32_e32 v11, 0x3f317218, v6
	v_add_f32_e32 v8, v7, v5
	v_fma_f32 v12, v6, s78, -v11
	v_mul_f32_e32 v9, v8, v8
	v_fmac_f32_e32 v12, 0xb102e308, v6
	v_sub_f32_e32 v6, v8, v7
	v_fmamk_f32 v10, v9, 0x3e9b6dac, v185
	v_sub_f32_e32 v5, v5, v6
	v_add_f32_e32 v6, v11, v12
	v_fmaak_f32 v10, v9, v10, 0x3f2aaada
	v_sub_f32_e32 v7, v6, v11
	v_ldexp_f32 v11, v8, 1
	v_mul_f32_e32 v8, v8, v9
	v_mul_f32_e32 v8, v8, v10
	v_add_f32_e32 v9, v11, v8
	v_sub_f32_e32 v10, v9, v11
	v_ldexp_f32 v5, v5, 1
	v_sub_f32_e32 v8, v8, v10
	v_add_f32_e32 v5, v5, v8
	v_add_f32_e32 v8, v9, v5
	v_sub_f32_e32 v9, v8, v9
	v_sub_f32_e32 v5, v5, v9
	v_add_f32_e32 v9, v6, v8
	v_sub_f32_e32 v10, v9, v6
	v_sub_f32_e32 v11, v9, v10
	v_sub_f32_e32 v7, v12, v7
	v_sub_f32_e32 v6, v6, v11
	v_sub_f32_e32 v8, v8, v10
	v_add_f32_e32 v6, v8, v6
	v_add_f32_e32 v8, v7, v5
	v_sub_f32_e32 v10, v8, v7
	v_sub_f32_e32 v11, v8, v10
	v_sub_f32_e32 v7, v7, v11
	v_sub_f32_e32 v5, v5, v10
	v_add_f32_e32 v6, v8, v6
	v_add_f32_e32 v5, v5, v7
	v_add_f32_e32 v7, v9, v6
	v_sub_f32_e32 v8, v7, v9
	v_sub_f32_e32 v6, v6, v8
	v_add_f32_e32 v5, v5, v6
	v_add_f32_e32 v5, v7, v5
	v_cndmask_b32_e32 v5, v226, v5, vcc
	v_cmp_lt_f32_e64 vcc, |v4|, s63
	s_nop 1
	v_cndmask_b32_e32 v4, v5, v4, vcc
	v_sub_f32_e32 v0, v0, v4
	v_mul_f32_e32 v0, 0x3fb8aa3b, v0
	global_store_dword v[36:37], v0, off offset:192
	v_readlane_b32 s100, v254, 5
	s_nop 1
	v_mov_b32_e32 v4, s100
	v_fmac_f32_e32 v4, v1, v156
	v_mul_f32_e64 v1, |v4|, s94
	v_fma_f32 v5, |v4|, s94, -v1
	v_rndne_f32_e32 v6, v1
	v_fma_f32 v5, |v4|, s64, v5
	v_sub_f32_e32 v1, v1, v6
	v_add_f32_e32 v1, v1, v5
	v_exp_f32_e32 v1, v1
	v_cvt_i32_f32_e32 v5, v6
	v_cmp_ngt_f32_e64 vcc, |v4|, s58
	v_min_f32_e32 v0, 0, v4
	v_ldexp_f32 v1, v1, v5
	v_cndmask_b32_e32 v1, 0, v1, vcc
	v_cmp_nlt_f32_e64 vcc, |v4|, s59
	s_nop 1
	v_cndmask_b32_e32 v1, v226, v1, vcc
	v_add_f32_e32 v6, 1.0, v1
	v_add_f32_e32 v4, -1.0, v6
	v_sub_f32_e32 v5, v4, v6
	v_add_f32_e32 v5, 1.0, v5
	v_sub_f32_e32 v4, v1, v4
	v_add_f32_e32 v7, v4, v5
	v_frexp_mant_f32_e32 v4, v6
	v_cmp_gt_f32_e32 vcc, s77, v4
	v_cvt_f64_f32_e32 v[4:5], v6
	v_frexp_exp_i32_f64_e32 v4, v[4:5]
	v_subbrev_co_u32_e32 v4, vcc, 0, v4, vcc
	v_sub_u32_e32 v5, 0, v4
	v_ldexp_f32 v6, v6, v5
	v_ldexp_f32 v5, v7, v5
	v_add_f32_e32 v7, -1.0, v6
	v_add_f32_e32 v8, 1.0, v7
	v_sub_f32_e32 v8, v6, v8
	v_add_f32_e32 v8, v5, v8
	v_add_f32_e32 v9, v7, v8
	v_sub_f32_e32 v7, v7, v9
	v_add_f32_e32 v7, v8, v7
	v_add_f32_e32 v8, 1.0, v6
	v_add_f32_e32 v10, -1.0, v8
	v_sub_f32_e32 v6, v6, v10
	v_add_f32_e32 v5, v5, v6
	v_add_f32_e32 v6, v8, v5
	v_sub_f32_e32 v8, v8, v6
	v_add_f32_e32 v5, v5, v8
	v_rcp_f32_e32 v8, v6
	v_cvt_f32_i32_e32 v4, v4
	v_cmp_neq_f32_e32 vcc, s62, v1
	v_mul_f32_e32 v10, v9, v8
	v_mul_f32_e32 v11, v6, v10
	v_fma_f32 v12, v10, v6, -v11
	v_fmac_f32_e32 v12, v10, v5
	v_add_f32_e32 v13, v11, v12
	v_sub_f32_e32 v14, v9, v13
	v_sub_f32_e32 v9, v9, v14
	v_sub_f32_e32 v11, v13, v11
	v_sub_f32_e32 v9, v9, v13
	v_add_f32_e32 v7, v7, v9
	v_sub_f32_e32 v9, v11, v12
	v_add_f32_e32 v7, v9, v7
	v_add_f32_e32 v9, v14, v7
	v_mul_f32_e32 v11, v8, v9
	v_mul_f32_e32 v12, v6, v11
	v_fma_f32 v6, v11, v6, -v12
	v_fmac_f32_e32 v6, v11, v5
	v_sub_f32_e32 v5, v14, v9
	v_add_f32_e32 v5, v7, v5
	v_add_f32_e32 v7, v12, v6
	v_sub_f32_e32 v13, v9, v7
	v_sub_f32_e32 v9, v9, v13
	v_sub_f32_e32 v12, v7, v12
	v_sub_f32_e32 v7, v9, v7
	v_add_f32_e32 v5, v5, v7
	v_sub_f32_e32 v6, v12, v6
	v_add_f32_e32 v5, v6, v5
	v_add_f32_e32 v6, v10, v11
	v_add_f32_e32 v5, v13, v5
	v_sub_f32_e32 v7, v6, v10
	v_mul_f32_e32 v5, v8, v5
	v_sub_f32_e32 v7, v11, v7
	v_add_f32_e32 v5, v7, v5
	v_mul_f32_e32 v10, 0x3f317218, v4
	v_add_f32_e32 v7, v6, v5
	v_fma_f32 v11, v4, s78, -v10
	v_mul_f32_e32 v8, v7, v7
	v_fmac_f32_e32 v11, 0xb102e308, v4
	v_sub_f32_e32 v4, v7, v6
	v_fmamk_f32 v9, v8, 0x3e9b6dac, v185
	v_sub_f32_e32 v4, v5, v4
	v_add_f32_e32 v5, v10, v11
	v_fmaak_f32 v9, v8, v9, 0x3f2aaada
	v_sub_f32_e32 v6, v5, v10
	v_ldexp_f32 v10, v7, 1
	v_mul_f32_e32 v7, v7, v8
	v_mul_f32_e32 v7, v7, v9
	v_add_f32_e32 v8, v10, v7
	v_sub_f32_e32 v9, v8, v10
	v_ldexp_f32 v4, v4, 1
	v_sub_f32_e32 v7, v7, v9
	v_add_f32_e32 v4, v4, v7
	v_add_f32_e32 v7, v8, v4
	v_sub_f32_e32 v8, v7, v8
	v_sub_f32_e32 v4, v4, v8
	v_add_f32_e32 v8, v5, v7
	v_sub_f32_e32 v9, v8, v5
	v_sub_f32_e32 v10, v8, v9
	v_sub_f32_e32 v6, v11, v6
	v_sub_f32_e32 v5, v5, v10
	v_sub_f32_e32 v7, v7, v9
	v_add_f32_e32 v5, v7, v5
	v_add_f32_e32 v7, v6, v4
	v_sub_f32_e32 v9, v7, v6
	v_sub_f32_e32 v10, v7, v9
	v_sub_f32_e32 v6, v6, v10
	v_sub_f32_e32 v4, v4, v9
	v_add_f32_e32 v5, v7, v5
	v_add_f32_e32 v4, v4, v6
	v_add_f32_e32 v6, v8, v5
	v_sub_f32_e32 v7, v6, v8
	v_sub_f32_e32 v5, v5, v7
	v_add_f32_e32 v4, v4, v5
	v_add_f32_e32 v4, v6, v4
	v_cndmask_b32_e32 v4, v226, v4, vcc
	v_cmp_lt_f32_e64 vcc, |v1|, s63
	s_nop 1
	v_cndmask_b32_e32 v1, v4, v1, vcc
	v_sub_f32_e32 v0, v0, v1
	v_mul_f32_e32 v0, 0x3fb8aa3b, v0
	global_store_dword v[24:25], v0, off offset:192
	v_readlane_b32 s100, v254, 6
	s_nop 1
	v_mov_b32_e32 v1, s100
	v_fmac_f32_e32 v1, v2, v156
	v_mul_f32_e64 v2, |v1|, s94
	v_fma_f32 v4, |v1|, s94, -v2
	v_rndne_f32_e32 v5, v2
	v_fma_f32 v4, |v1|, s64, v4
	v_sub_f32_e32 v2, v2, v5
	v_add_f32_e32 v2, v2, v4
	v_exp_f32_e32 v2, v2
	v_cvt_i32_f32_e32 v4, v5
	v_cmp_ngt_f32_e64 vcc, |v1|, s58
	v_min_f32_e32 v0, 0, v1
	v_ldexp_f32 v2, v2, v4
	v_cndmask_b32_e32 v2, 0, v2, vcc
	v_cmp_nlt_f32_e64 vcc, |v1|, s59
	s_nop 1
	v_cndmask_b32_e32 v1, v226, v2, vcc
	v_add_f32_e32 v2, 1.0, v1
	v_add_f32_e32 v4, -1.0, v2
	v_sub_f32_e32 v5, v4, v2
	v_add_f32_e32 v5, 1.0, v5
	v_sub_f32_e32 v4, v1, v4
	v_add_f32_e32 v6, v4, v5
	v_frexp_mant_f32_e32 v4, v2
	v_cmp_gt_f32_e32 vcc, s77, v4
	v_cvt_f64_f32_e32 v[4:5], v2
	v_frexp_exp_i32_f64_e32 v4, v[4:5]
	v_subbrev_co_u32_e32 v4, vcc, 0, v4, vcc
	v_sub_u32_e32 v5, 0, v4
	v_ldexp_f32 v2, v2, v5
	v_ldexp_f32 v5, v6, v5
	v_add_f32_e32 v6, -1.0, v2
	v_add_f32_e32 v7, 1.0, v6
	v_sub_f32_e32 v7, v2, v7
	v_add_f32_e32 v7, v5, v7
	v_add_f32_e32 v8, v6, v7
	v_sub_f32_e32 v6, v6, v8
	v_add_f32_e32 v6, v7, v6
	v_add_f32_e32 v7, 1.0, v2
	v_add_f32_e32 v9, -1.0, v7
	v_sub_f32_e32 v2, v2, v9
	v_add_f32_e32 v2, v5, v2
	v_add_f32_e32 v5, v7, v2
	v_sub_f32_e32 v7, v7, v5
	v_add_f32_e32 v2, v2, v7
	v_rcp_f32_e32 v7, v5
	v_cvt_f32_i32_e32 v4, v4
	v_cmp_neq_f32_e32 vcc, s62, v1
	v_mul_f32_e32 v9, v8, v7
	v_mul_f32_e32 v10, v5, v9
	v_fma_f32 v11, v9, v5, -v10
	v_fmac_f32_e32 v11, v9, v2
	v_add_f32_e32 v12, v10, v11
	v_sub_f32_e32 v13, v8, v12
	v_sub_f32_e32 v8, v8, v13
	v_sub_f32_e32 v10, v12, v10
	v_sub_f32_e32 v8, v8, v12
	v_add_f32_e32 v6, v6, v8
	v_sub_f32_e32 v8, v10, v11
	v_add_f32_e32 v6, v8, v6
	v_add_f32_e32 v8, v13, v6
	v_mul_f32_e32 v10, v7, v8
	v_mul_f32_e32 v11, v5, v10
	v_fma_f32 v5, v10, v5, -v11
	v_fmac_f32_e32 v5, v10, v2
	v_sub_f32_e32 v2, v13, v8
	v_add_f32_e32 v2, v6, v2
	v_add_f32_e32 v6, v11, v5
	v_sub_f32_e32 v12, v8, v6
	v_sub_f32_e32 v8, v8, v12
	v_sub_f32_e32 v11, v6, v11
	v_sub_f32_e32 v6, v8, v6
	v_add_f32_e32 v2, v2, v6
	v_sub_f32_e32 v5, v11, v5
	v_add_f32_e32 v2, v5, v2
	v_add_f32_e32 v5, v9, v10
	v_add_f32_e32 v2, v12, v2
	v_sub_f32_e32 v6, v5, v9
	v_mul_f32_e32 v2, v7, v2
	v_sub_f32_e32 v6, v10, v6
	v_add_f32_e32 v2, v6, v2
	v_mul_f32_e32 v9, 0x3f317218, v4
	v_add_f32_e32 v6, v5, v2
	v_fma_f32 v10, v4, s78, -v9
	v_mul_f32_e32 v7, v6, v6
	v_fmac_f32_e32 v10, 0xb102e308, v4
	v_sub_f32_e32 v4, v6, v5
	v_fmamk_f32 v8, v7, 0x3e9b6dac, v185
	v_sub_f32_e32 v2, v2, v4
	v_add_f32_e32 v4, v9, v10
	v_fmaak_f32 v8, v7, v8, 0x3f2aaada
	v_sub_f32_e32 v5, v4, v9
	v_ldexp_f32 v9, v6, 1
	v_mul_f32_e32 v6, v6, v7
	v_mul_f32_e32 v6, v6, v8
	v_add_f32_e32 v7, v9, v6
	v_sub_f32_e32 v8, v7, v9
	v_ldexp_f32 v2, v2, 1
	v_sub_f32_e32 v6, v6, v8
	v_add_f32_e32 v2, v2, v6
	v_add_f32_e32 v6, v7, v2
	v_sub_f32_e32 v7, v6, v7
	v_sub_f32_e32 v2, v2, v7
	v_add_f32_e32 v7, v4, v6
	v_sub_f32_e32 v8, v7, v4
	v_sub_f32_e32 v9, v7, v8
	v_sub_f32_e32 v5, v10, v5
	v_sub_f32_e32 v4, v4, v9
	v_sub_f32_e32 v6, v6, v8
	v_add_f32_e32 v4, v6, v4
	v_add_f32_e32 v6, v5, v2
	v_sub_f32_e32 v8, v6, v5
	v_sub_f32_e32 v9, v6, v8
	v_sub_f32_e32 v5, v5, v9
	v_sub_f32_e32 v2, v2, v8
	v_add_f32_e32 v4, v6, v4
	v_add_f32_e32 v2, v2, v5
	v_add_f32_e32 v5, v7, v4
	v_sub_f32_e32 v6, v5, v7
	v_sub_f32_e32 v4, v4, v6
	v_add_f32_e32 v2, v2, v4
	v_add_f32_e32 v2, v5, v2
	v_cndmask_b32_e32 v2, v226, v2, vcc
	v_cmp_lt_f32_e64 vcc, |v1|, s63
	s_nop 1
	v_cndmask_b32_e32 v1, v2, v1, vcc
	v_sub_f32_e32 v0, v0, v1
	v_mul_f32_e32 v0, 0x3fb8aa3b, v0
	global_store_dword v[38:39], v0, off offset:192
	v_readlane_b32 s100, v254, 7
	s_nop 1
	v_mov_b32_e32 v1, s100
	v_fmac_f32_e32 v1, v3, v156
	v_mul_f32_e64 v2, |v1|, s94
	v_fma_f32 v3, |v1|, s94, -v2
	v_rndne_f32_e32 v4, v2
	v_fma_f32 v3, |v1|, s64, v3
	v_sub_f32_e32 v2, v2, v4
	v_add_f32_e32 v2, v2, v3
	v_exp_f32_e32 v2, v2
	v_cvt_i32_f32_e32 v3, v4
	v_cmp_ngt_f32_e64 vcc, |v1|, s58
	v_min_f32_e32 v0, 0, v1
	v_ldexp_f32 v2, v2, v3
	v_cndmask_b32_e32 v2, 0, v2, vcc
	v_cmp_nlt_f32_e64 vcc, |v1|, s59
	s_nop 1
	v_cndmask_b32_e32 v1, v226, v2, vcc
	v_add_f32_e32 v4, 1.0, v1
	v_add_f32_e32 v2, -1.0, v4
	v_sub_f32_e32 v3, v2, v4
	v_add_f32_e32 v3, 1.0, v3
	v_sub_f32_e32 v2, v1, v2
	v_add_f32_e32 v5, v2, v3
	v_frexp_mant_f32_e32 v2, v4
	v_cmp_gt_f32_e32 vcc, s77, v2
	v_cvt_f64_f32_e32 v[2:3], v4
	v_frexp_exp_i32_f64_e32 v2, v[2:3]
	v_subbrev_co_u32_e32 v2, vcc, 0, v2, vcc
	v_sub_u32_e32 v3, 0, v2
	v_ldexp_f32 v4, v4, v3
	v_ldexp_f32 v3, v5, v3
	v_add_f32_e32 v5, -1.0, v4
	v_add_f32_e32 v6, 1.0, v5
	v_sub_f32_e32 v6, v4, v6
	v_add_f32_e32 v6, v3, v6
	v_add_f32_e32 v7, v5, v6
	v_sub_f32_e32 v5, v5, v7
	v_add_f32_e32 v5, v6, v5
	v_add_f32_e32 v6, 1.0, v4
	v_add_f32_e32 v8, -1.0, v6
	v_sub_f32_e32 v4, v4, v8
	v_add_f32_e32 v3, v3, v4
	v_add_f32_e32 v4, v6, v3
	v_sub_f32_e32 v6, v6, v4
	v_add_f32_e32 v3, v3, v6
	v_rcp_f32_e32 v6, v4
	v_cvt_f32_i32_e32 v2, v2
	v_cmp_neq_f32_e32 vcc, s62, v1
	v_mul_f32_e32 v8, v7, v6
	v_mul_f32_e32 v9, v4, v8
	v_fma_f32 v10, v8, v4, -v9
	v_fmac_f32_e32 v10, v8, v3
	v_add_f32_e32 v11, v9, v10
	v_sub_f32_e32 v12, v7, v11
	v_sub_f32_e32 v7, v7, v12
	v_sub_f32_e32 v9, v11, v9
	v_sub_f32_e32 v7, v7, v11
	v_add_f32_e32 v5, v5, v7
	v_sub_f32_e32 v7, v9, v10
	v_add_f32_e32 v5, v7, v5
	v_add_f32_e32 v7, v12, v5
	v_mul_f32_e32 v9, v6, v7
	v_mul_f32_e32 v10, v4, v9
	v_fma_f32 v4, v9, v4, -v10
	v_fmac_f32_e32 v4, v9, v3
	v_sub_f32_e32 v3, v12, v7
	v_add_f32_e32 v3, v5, v3
	v_add_f32_e32 v5, v10, v4
	v_sub_f32_e32 v11, v7, v5
	v_sub_f32_e32 v7, v7, v11
	v_sub_f32_e32 v10, v5, v10
	v_sub_f32_e32 v5, v7, v5
	v_add_f32_e32 v3, v3, v5
	v_sub_f32_e32 v4, v10, v4
	v_add_f32_e32 v3, v4, v3
	v_add_f32_e32 v4, v8, v9
	v_add_f32_e32 v3, v11, v3
	v_sub_f32_e32 v5, v4, v8
	v_mul_f32_e32 v3, v6, v3
	v_sub_f32_e32 v5, v9, v5
	v_add_f32_e32 v3, v5, v3
	v_mul_f32_e32 v8, 0x3f317218, v2
	v_add_f32_e32 v5, v4, v3
	v_fma_f32 v9, v2, s78, -v8
	v_mul_f32_e32 v6, v5, v5
	v_fmac_f32_e32 v9, 0xb102e308, v2
	v_sub_f32_e32 v2, v5, v4
	v_fmamk_f32 v7, v6, 0x3e9b6dac, v185
	v_sub_f32_e32 v2, v3, v2
	v_add_f32_e32 v3, v8, v9
	v_fmaak_f32 v7, v6, v7, 0x3f2aaada
	v_sub_f32_e32 v4, v3, v8
	v_ldexp_f32 v8, v5, 1
	v_mul_f32_e32 v5, v5, v6
	v_mul_f32_e32 v5, v5, v7
	v_add_f32_e32 v6, v8, v5
	v_sub_f32_e32 v7, v6, v8
	v_ldexp_f32 v2, v2, 1
	v_sub_f32_e32 v5, v5, v7
	v_add_f32_e32 v2, v2, v5
	v_add_f32_e32 v5, v6, v2
	v_sub_f32_e32 v6, v5, v6
	v_sub_f32_e32 v2, v2, v6
	v_add_f32_e32 v6, v3, v5
	v_sub_f32_e32 v7, v6, v3
	v_sub_f32_e32 v8, v6, v7
	v_sub_f32_e32 v4, v9, v4
	v_sub_f32_e32 v3, v3, v8
	v_sub_f32_e32 v5, v5, v7
	v_add_f32_e32 v3, v5, v3
	v_add_f32_e32 v5, v4, v2
	v_sub_f32_e32 v7, v5, v4
	v_sub_f32_e32 v8, v5, v7
	v_sub_f32_e32 v4, v4, v8
	v_sub_f32_e32 v2, v2, v7
	v_add_f32_e32 v3, v5, v3
	v_add_f32_e32 v2, v2, v4
	v_add_f32_e32 v4, v6, v3
	v_sub_f32_e32 v5, v4, v6
	v_sub_f32_e32 v3, v3, v5
	v_add_f32_e32 v2, v2, v3
	v_add_f32_e32 v2, v4, v2
	v_cndmask_b32_e32 v2, v226, v2, vcc
	v_cmp_lt_f32_e64 vcc, |v1|, s63
	s_nop 1
	v_cndmask_b32_e32 v1, v2, v1, vcc
	v_sub_f32_e32 v0, v0, v1
	v_mul_f32_e32 v0, 0x3fb8aa3b, v0
	global_store_dword v[26:27], v0, off offset:192
